# speedup vs baseline: 1.0032x; 1.0032x over previous
; #define WAIT_V(n) asm volatile("s_waitcnt vmcnt(" #n ")" ::: "memory")
; #define WAIT_L(n) asm volatile("s_waitcnt lgkmcnt(" #n ")" ::: "memory")
; #define BAR __builtin_amdgcn_s_barrier()
; #define SCHED __builtin_amdgcn_sched_barrier(0)
; #define STAGE(P, BASE, br, kt) do { const char* _g = (const char*)((BASE) + (size_t)(br) * GK + (kt) * BK); \
;     __builtin_amdgcn_global_load_lds((const unsigned*)(_g + voff0), (unsigned*)((char*)(P) + tx * 16), 16, 0, 0); \
;     __builtin_amdgcn_global_load_lds((const unsigned*)(_g + voff1), (unsigned*)((char*)(P) + tx * 16 + 8192), 16, 0, 0); } while (0)
; #define LDA(dst, b, h) _Pragma("unroll") for (int m = 0; m < 4; ++m) _Pragma("unroll") for (int k = 0; k < 2; ++k) \
;     dst[m][k] = *reinterpret_cast<const bf16x8*>((char*)shm + abase + (((b) * 2 + (h)) * 16384 + (m * 2 + k) * 1024))
; #define LDB(dst, b, h) _Pragma("unroll") for (int n = 0; n < 2; ++n) _Pragma("unroll") for (int k = 0; k < 2; ++k) \
;     dst[n][k] = *reinterpret_cast<const bf16x8*>((char*)shm + bbase + (((b) * 2 + (h)) * 16384 + (n * 2 + k) * 1024))
; template <bool SWAP>
; __device__ __forceinline__ void gemm_main(const u16* __restrict__ A, const u16* __restrict__ Bt, int brow, int bcol,
;                                           u16* shm, f32x4 (&acc)[2][2][4][2]) {
;     ...
;   for (int t = 0; t < nt - 2; t += 2) {
;     LDB(B0, 0, 0); SCHED; LDA(At, 0, 0); STAGE(SA(1, 1), A, brow + HALF, t + 1);
;     WAIT_L(8); BAR; WAIT_L(0); MMA(0, 0, At, B0); BAR; SCHED;
;     LDB(B1, 0, 1); STAGE(SB(0, 0), Bt, bcol, t + 2);
;     BAR; WAIT_L(0); MMA(0, 1, At, B1); BAR;
;     LDA(At, 0, 1); STAGE(SA(0, 0), A, brow, t + 2);
;     BAR; WAIT_L(0); MMA(1, 0, At, B0); BAR; SCHED;
;     STAGE(SB(0, 1), Bt, bcol + HALF, t + 2);
;     WAIT_V(6); BAR; MMA(1, 1, At, B1); BAR;
;     LDB(B0, 1, 0); SCHED; LDA(At, 1, 0); STAGE(SA(0, 1), A, brow + HALF, t + 2);
.LBB0_84:
	ds_read_b128 v[176:179], v128 offset:1024
	ds_read_b128 v[184:187], v128 offset:3072
	ds_read_b128 v[192:195], v128 offset:5120
	ds_read_b128 v[200:203], v128 offset:7168
	v_add_u32_e32 v211, 0, v146
	v_add_u32_e32 v153, 0xc000, v211
	s_add_u32 m0, s29, 0xc000
	s_nop 0
	s_add_u32 vcc_lo, s26, s6
	s_addc_u32 vcc_hi, s27, s7
	global_load_lds_dwordx4 v134, vcc
	v_add_u32_e32 v154, 0xe000, v211
	v_lshl_add_u64 v[224:225], s[26:27], 0, v[136:137]
	s_add_u32 m0, s29, 0xe000
	s_nop 0
	global_load_lds_dwordx4 v136, vcc
	s_waitcnt lgkmcnt(8)
	s_barrier
	s_waitcnt lgkmcnt(0)
	v_mfma_f32_16x16x32_bf16 v[124:127], v[172:175], v[156:159], v[124:127]
	v_mfma_f32_16x16x32_bf16 v[120:123], v[172:175], v[164:167], v[120:123]
	v_mfma_f32_16x16x32_bf16 v[116:119], v[180:183], v[156:159], v[116:119]
	v_mfma_f32_16x16x32_bf16 v[112:115], v[180:183], v[164:167], v[112:115]
	v_mfma_f32_16x16x32_bf16 v[108:111], v[188:191], v[156:159], v[108:111]
	v_mfma_f32_16x16x32_bf16 v[104:107], v[188:191], v[164:167], v[104:107]
	v_mfma_f32_16x16x32_bf16 v[100:103], v[196:199], v[156:159], v[100:103]
	v_mfma_f32_16x16x32_bf16 v[96:99], v[196:199], v[164:167], v[96:99]
	v_mfma_f32_16x16x32_bf16 v[124:127], v[176:179], v[160:163], v[124:127]
	v_mfma_f32_16x16x32_bf16 v[120:123], v[176:179], v[168:171], v[120:123]
	v_mfma_f32_16x16x32_bf16 v[116:119], v[184:187], v[160:163], v[116:119]
	v_mfma_f32_16x16x32_bf16 v[112:115], v[184:187], v[168:171], v[112:115]
	v_mfma_f32_16x16x32_bf16 v[108:111], v[192:195], v[160:163], v[108:111]
	v_mfma_f32_16x16x32_bf16 v[104:107], v[192:195], v[168:171], v[104:107]
	v_mfma_f32_16x16x32_bf16 v[100:103], v[200:203], v[160:163], v[100:103]
	v_mfma_f32_16x16x32_bf16 v[96:99], v[200:203], v[168:171], v[96:99]
	s_barrier
	ds_read_b128 v[204:207], v145 offset:16384
	ds_read_b128 v[212:215], v145 offset:17408
	ds_read_b128 v[216:219], v145 offset:18432
	ds_read_b128 v[220:223], v145 offset:19456
	v_lshl_add_u64 v[226:227], s[26:27], 0, v[130:131]
	s_add_u32 m0, s29, s44
	s_nop 0
	s_add_u32 vcc_lo, s26, s8
	s_addc_u32 vcc_hi, s27, s9
	global_load_lds_dwordx4 v130, vcc
	v_lshl_add_u64 v[228:229], s[26:27], 0, v[132:133]
	s_add_u32 m0, s29, s44
	s_add_u32 m0, m0, 0x2000
	s_nop 0
	global_load_lds_dwordx4 v132, vcc
	s_barrier
	s_waitcnt lgkmcnt(0)
	v_mfma_f32_16x16x32_bf16 v[92:95], v[172:175], v[204:207], v[92:95]
	v_mfma_f32_16x16x32_bf16 v[88:91], v[172:175], v[216:219], v[88:91]
	v_mfma_f32_16x16x32_bf16 v[84:87], v[180:183], v[204:207], v[84:87]
	v_mfma_f32_16x16x32_bf16 v[80:83], v[180:183], v[216:219], v[80:83]
	v_mfma_f32_16x16x32_bf16 v[76:79], v[188:191], v[204:207], v[76:79]
	v_mfma_f32_16x16x32_bf16 v[72:75], v[188:191], v[216:219], v[72:75]
	v_mfma_f32_16x16x32_bf16 v[68:71], v[196:199], v[204:207], v[68:71]
	v_mfma_f32_16x16x32_bf16 v[64:67], v[196:199], v[216:219], v[64:67]
	v_mfma_f32_16x16x32_bf16 v[92:95], v[176:179], v[212:215], v[92:95]
	ds_read_b128 v[172:175], v128 offset:16384
	v_mfma_f32_16x16x32_bf16 v[88:91], v[176:179], v[220:223], v[88:91]
	v_mfma_f32_16x16x32_bf16 v[84:87], v[184:187], v[212:215], v[84:87]
	ds_read_b128 v[180:183], v128 offset:18432
	v_mfma_f32_16x16x32_bf16 v[80:83], v[184:187], v[220:223], v[80:83]
	v_mfma_f32_16x16x32_bf16 v[76:79], v[192:195], v[212:215], v[76:79]
	ds_read_b128 v[188:191], v128 offset:20480
	v_mfma_f32_16x16x32_bf16 v[72:75], v[192:195], v[220:223], v[72:75]
	v_mfma_f32_16x16x32_bf16 v[68:71], v[200:203], v[212:215], v[68:71]
	ds_read_b128 v[196:199], v128 offset:22528
	v_mfma_f32_16x16x32_bf16 v[64:67], v[200:203], v[220:223], v[64:67]
	s_barrier
	ds_read_b128 v[176:179], v128 offset:17408
	ds_read_b128 v[184:187], v128 offset:19456
	ds_read_b128 v[192:195], v128 offset:21504
	ds_read_b128 v[200:203], v128 offset:23552
	s_add_u32 m0, s29, 0x0
	s_nop 0
	s_add_u32 vcc_lo, s26, s10
	s_addc_u32 vcc_hi, s27, s11
	global_load_lds_dwordx4 v134, vcc
	s_add_u32 m0, s29, 0x2000
	s_nop 0
	global_load_lds_dwordx4 v136, vcc
	s_waitcnt vmcnt(8)
	s_barrier
	s_waitcnt lgkmcnt(0)
	v_mfma_f32_16x16x32_bf16 v[60:63], v[172:175], v[156:159], v[60:63]
	v_mfma_f32_16x16x32_bf16 v[56:59], v[172:175], v[164:167], v[56:59]
	v_mfma_f32_16x16x32_bf16 v[52:55], v[180:183], v[156:159], v[52:55]
	v_mfma_f32_16x16x32_bf16 v[48:51], v[180:183], v[164:167], v[48:51]
	v_mfma_f32_16x16x32_bf16 v[44:47], v[188:191], v[156:159], v[44:47]
	v_mfma_f32_16x16x32_bf16 v[40:43], v[188:191], v[164:167], v[40:43]
	v_mfma_f32_16x16x32_bf16 v[36:39], v[196:199], v[156:159], v[36:39]
	v_mfma_f32_16x16x32_bf16 v[32:35], v[196:199], v[164:167], v[32:35]
	v_mfma_f32_16x16x32_bf16 v[60:63], v[176:179], v[160:163], v[60:63]
	v_mfma_f32_16x16x32_bf16 v[56:59], v[176:179], v[168:171], v[56:59]
	v_mfma_f32_16x16x32_bf16 v[52:55], v[184:187], v[160:163], v[52:55]
	v_mfma_f32_16x16x32_bf16 v[48:51], v[184:187], v[168:171], v[48:51]
	v_mfma_f32_16x16x32_bf16 v[44:47], v[192:195], v[160:163], v[44:47]
	v_mfma_f32_16x16x32_bf16 v[40:43], v[192:195], v[168:171], v[40:43]
	v_mfma_f32_16x16x32_bf16 v[36:39], v[200:203], v[160:163], v[36:39]
	v_mfma_f32_16x16x32_bf16 v[32:35], v[200:203], v[168:171], v[32:35]
	s_barrier
	ds_read_b128 v[156:159], v145 offset:32768
	ds_read_b128 v[160:163], v145 offset:33792
	ds_read_b128 v[164:167], v145 offset:34816
	ds_read_b128 v[168:171], v145 offset:35840
	s_add_u32 m0, s29, s45
	s_nop 0
	s_add_u32 vcc_lo, s26, s12
	s_addc_u32 vcc_hi, s27, s13
	global_load_lds_dwordx4 v130, vcc
	s_add_u32 m0, s29, s45
	s_add_u32 m0, m0, 0x2000
	s_nop 0
	global_load_lds_dwordx4 v132, vcc
	s_waitcnt vmcnt(6)
	s_barrier
; #define WAIT_V(n) asm volatile("s_waitcnt vmcnt(" #n ")" ::: "memory")
; #define WAIT_L(n) asm volatile("s_waitcnt lgkmcnt(" #n ")" ::: "memory")
; #define BAR __builtin_amdgcn_s_barrier()
; #define SCHED __builtin_amdgcn_sched_barrier(0)
; #define STAGE(P, BASE, br, kt) do { const char* _g = (const char*)((BASE) + (size_t)(br) * GK + (kt) * BK); \
;     __builtin_amdgcn_global_load_lds((const unsigned*)(_g + voff0), (unsigned*)((char*)(P) + tx * 16), 16, 0, 0); \
;     __builtin_amdgcn_global_load_lds((const unsigned*)(_g + voff1), (unsigned*)((char*)(P) + tx * 16 + 8192), 16, 0, 0); } while (0)
; #define LDA(dst, b, h) _Pragma("unroll") for (int m = 0; m < 4; ++m) _Pragma("unroll") for (int k = 0; k < 2; ++k) \
;     dst[m][k] = *reinterpret_cast<const bf16x8*>((char*)shm + abase + (((b) * 2 + (h)) * 16384 + (m * 2 + k) * 1024))
; #define LDB(dst, b, h) _Pragma("unroll") for (int n = 0; n < 2; ++n) _Pragma("unroll") for (int k = 0; k < 2; ++k) \
;     dst[n][k] = *reinterpret_cast<const bf16x8*>((char*)shm + bbase + (((b) * 2 + (h)) * 16384 + (n * 2 + k) * 1024))
; template <bool SWAP>
; __device__ __forceinline__ void gemm_main(const u16* __restrict__ A, const u16* __restrict__ Bt, int brow, int bcol,
;                                           u16* shm, f32x4 (&acc)[2][2][4][2]) {
;     ...
;     WAIT_V(6); BAR; MMA(1, 1, At, B1); BAR;
;     LDB(B0, 1, 0); SCHED; LDA(At, 1, 0); STAGE(SA(0, 1), A, brow + HALF, t + 2);
;     WAIT_L(8); BAR; WAIT_L(0); MMA(0, 0, At, B0); BAR; SCHED;
;     LDB(B1, 1, 1); STAGE(SB(1, 0), Bt, bcol, t + 3);
;     BAR; WAIT_L(0); MMA(0, 1, At, B1); BAR;
;     LDA(At, 1, 1); STAGE(SA(1, 0), A, brow, t + 3);
;     BAR; WAIT_L(0); MMA(1, 0, At, B0); BAR; SCHED;
	v_mfma_f32_16x16x32_bf16 v[28:31], v[172:175], v[204:207], v[28:31]
	v_mfma_f32_16x16x32_bf16 v[24:27], v[172:175], v[216:219], v[24:27]
	v_mfma_f32_16x16x32_bf16 v[20:23], v[180:183], v[204:207], v[20:23]
	v_mfma_f32_16x16x32_bf16 v[16:19], v[180:183], v[216:219], v[16:19]
	v_mfma_f32_16x16x32_bf16 v[12:15], v[188:191], v[204:207], v[12:15]
	v_mfma_f32_16x16x32_bf16 v[8:11], v[188:191], v[216:219], v[8:11]
	v_mfma_f32_16x16x32_bf16 v[4:7], v[196:199], v[204:207], v[4:7]
	v_mfma_f32_16x16x32_bf16 v[0:3], v[196:199], v[216:219], v[0:3]
	v_mfma_f32_16x16x32_bf16 v[28:31], v[176:179], v[212:215], v[28:31]
	ds_read_b128 v[172:175], v128 offset:32768
	v_mfma_f32_16x16x32_bf16 v[24:27], v[176:179], v[220:223], v[24:27]
	v_mfma_f32_16x16x32_bf16 v[20:23], v[184:187], v[212:215], v[20:23]
	ds_read_b128 v[180:183], v128 offset:34816
	v_mfma_f32_16x16x32_bf16 v[16:19], v[184:187], v[220:223], v[16:19]
	v_mfma_f32_16x16x32_bf16 v[12:15], v[192:195], v[212:215], v[12:15]
	ds_read_b128 v[188:191], v128 offset:36864
	v_mfma_f32_16x16x32_bf16 v[8:11], v[192:195], v[220:223], v[8:11]
	v_mfma_f32_16x16x32_bf16 v[4:7], v[200:203], v[212:215], v[4:7]
	ds_read_b128 v[196:199], v128 offset:38912
	v_mfma_f32_16x16x32_bf16 v[0:3], v[200:203], v[220:223], v[0:3]
	s_barrier
	ds_read_b128 v[176:179], v128 offset:33792
	ds_read_b128 v[184:187], v128 offset:35840
	ds_read_b128 v[192:195], v128 offset:37888
	ds_read_b128 v[200:203], v128 offset:39936
	s_add_u32 m0, s29, 0x4000
	s_nop 0
	s_add_u32 vcc_lo, s26, s14
	s_addc_u32 vcc_hi, s27, s15
	global_load_lds_dwordx4 v134, vcc
	s_add_u32 m0, s29, 0x6000
	s_nop 0
	global_load_lds_dwordx4 v136, vcc
	s_waitcnt lgkmcnt(8)
	s_barrier
	s_waitcnt lgkmcnt(0)
	v_mfma_f32_16x16x32_bf16 v[124:127], v[172:175], v[156:159], v[124:127]
	v_mfma_f32_16x16x32_bf16 v[120:123], v[172:175], v[164:167], v[120:123]
	v_mfma_f32_16x16x32_bf16 v[116:119], v[180:183], v[156:159], v[116:119]
	v_mfma_f32_16x16x32_bf16 v[112:115], v[180:183], v[164:167], v[112:115]
	v_mfma_f32_16x16x32_bf16 v[108:111], v[188:191], v[156:159], v[108:111]
	v_mfma_f32_16x16x32_bf16 v[104:107], v[188:191], v[164:167], v[104:107]
	v_mfma_f32_16x16x32_bf16 v[100:103], v[196:199], v[156:159], v[100:103]
	v_mfma_f32_16x16x32_bf16 v[96:99], v[196:199], v[164:167], v[96:99]
	v_mfma_f32_16x16x32_bf16 v[124:127], v[176:179], v[160:163], v[124:127]
	v_mfma_f32_16x16x32_bf16 v[120:123], v[176:179], v[168:171], v[120:123]
	v_mfma_f32_16x16x32_bf16 v[116:119], v[184:187], v[160:163], v[116:119]
	v_mfma_f32_16x16x32_bf16 v[112:115], v[184:187], v[168:171], v[112:115]
	v_mfma_f32_16x16x32_bf16 v[108:111], v[192:195], v[160:163], v[108:111]
	v_mfma_f32_16x16x32_bf16 v[104:107], v[192:195], v[168:171], v[104:107]
	v_mfma_f32_16x16x32_bf16 v[100:103], v[200:203], v[160:163], v[100:103]
	v_mfma_f32_16x16x32_bf16 v[96:99], v[200:203], v[168:171], v[96:99]
	s_barrier
	ds_read_b128 v[204:207], v145 offset:49152
	ds_read_b128 v[212:215], v145 offset:50176
	ds_read_b128 v[216:219], v145 offset:51200
	ds_read_b128 v[220:223], v145 offset:52224
	s_add_u32 m0, s29, s52
	s_nop 0
	s_add_u32 vcc_lo, s26, s16
	s_addc_u32 vcc_hi, s27, s17
	global_load_lds_dwordx4 v130, vcc
	v_lshl_add_u64 v[230:231], v[228:229], 0, s[16:17]
	s_add_u32 m0, s29, s52
	s_add_u32 m0, m0, 0x2000
	s_nop 0
	global_load_lds_dwordx4 v132, vcc
	s_barrier
	s_waitcnt lgkmcnt(0)
	v_mfma_f32_16x16x32_bf16 v[92:95], v[172:175], v[204:207], v[92:95]
	v_mfma_f32_16x16x32_bf16 v[88:91], v[172:175], v[216:219], v[88:91]
	v_mfma_f32_16x16x32_bf16 v[84:87], v[180:183], v[204:207], v[84:87]
	v_mfma_f32_16x16x32_bf16 v[80:83], v[180:183], v[216:219], v[80:83]
	v_mfma_f32_16x16x32_bf16 v[76:79], v[188:191], v[204:207], v[76:79]
	v_mfma_f32_16x16x32_bf16 v[72:75], v[188:191], v[216:219], v[72:75]
	v_mfma_f32_16x16x32_bf16 v[68:71], v[196:199], v[204:207], v[68:71]
	v_mfma_f32_16x16x32_bf16 v[64:67], v[196:199], v[216:219], v[64:67]
	v_mfma_f32_16x16x32_bf16 v[92:95], v[176:179], v[212:215], v[92:95]
	ds_read_b128 v[172:175], v128 offset:49152
	v_mfma_f32_16x16x32_bf16 v[88:91], v[176:179], v[220:223], v[88:91]
	v_mfma_f32_16x16x32_bf16 v[84:87], v[184:187], v[212:215], v[84:87]
	ds_read_b128 v[180:183], v128 offset:51200
	v_mfma_f32_16x16x32_bf16 v[80:83], v[184:187], v[220:223], v[80:83]
	v_mfma_f32_16x16x32_bf16 v[76:79], v[192:195], v[212:215], v[76:79]
	ds_read_b128 v[188:191], v128 offset:53248
	v_mfma_f32_16x16x32_bf16 v[72:75], v[192:195], v[220:223], v[72:75]
	v_mfma_f32_16x16x32_bf16 v[68:71], v[200:203], v[212:215], v[68:71]
	ds_read_b128 v[196:199], v128 offset:55296
	v_mfma_f32_16x16x32_bf16 v[64:67], v[200:203], v[220:223], v[64:67]
	s_barrier
	ds_read_b128 v[176:179], v128 offset:50176
	ds_read_b128 v[184:187], v128 offset:52224
	ds_read_b128 v[192:195], v128 offset:54272
	ds_read_b128 v[200:203], v128 offset:56320
	s_add_u32 m0, s29, 0x8000
	s_nop 0
	s_add_u32 vcc_lo, s26, s18
	s_addc_u32 vcc_hi, s27, s19
	global_load_lds_dwordx4 v134, vcc
	v_lshl_add_u64 v[208:209], v[224:225], 0, s[18:19]
	s_add_u32 m0, s29, 0xa000
	s_nop 0
	global_load_lds_dwordx4 v136, vcc
	s_waitcnt vmcnt(8)
	s_barrier
; #define WAIT_V(n) asm volatile("s_waitcnt vmcnt(" #n ")" ::: "memory")
; #define WAIT_L(n) asm volatile("s_waitcnt lgkmcnt(" #n ")" ::: "memory")
; #define BAR __builtin_amdgcn_s_barrier()
; #define SCHED __builtin_amdgcn_sched_barrier(0)
; #define STAGE(P, BASE, br, kt) do { const char* _g = (const char*)((BASE) + (size_t)(br) * GK + (kt) * BK); \
;     __builtin_amdgcn_global_load_lds((const unsigned*)(_g + voff0), (unsigned*)((char*)(P) + tx * 16), 16, 0, 0); \
;     __builtin_amdgcn_global_load_lds((const unsigned*)(_g + voff1), (unsigned*)((char*)(P) + tx * 16 + 8192), 16, 0, 0); } while (0)
; #define LDA(dst, b, h) _Pragma("unroll") for (int m = 0; m < 4; ++m) _Pragma("unroll") for (int k = 0; k < 2; ++k) \
;     dst[m][k] = *reinterpret_cast<const bf16x8*>((char*)shm + abase + (((b) * 2 + (h)) * 16384 + (m * 2 + k) * 1024))
; #define LDB(dst, b, h) _Pragma("unroll") for (int n = 0; n < 2; ++n) _Pragma("unroll") for (int k = 0; k < 2; ++k) \
;     dst[n][k] = *reinterpret_cast<const bf16x8*>((char*)shm + bbase + (((b) * 2 + (h)) * 16384 + (n * 2 + k) * 1024))
; template <bool SWAP>
; __device__ __forceinline__ void gemm_main(const u16* __restrict__ A, const u16* __restrict__ Bt, int brow, int bcol,
;                                           u16* shm, f32x4 (&acc)[2][2][4][2]) {
;     ...
;     BAR; WAIT_L(0); MMA(1, 0, At, B0); BAR; SCHED;
;     STAGE(SB(1, 1), Bt, bcol + HALF, t + 3);
;     WAIT_V(6); BAR; MMA(1, 1, At, B1); BAR;
;   }
;   { LDB(B0, 0, 0); LDA(At, 0, 0); STAGE(SA(1, 1), A, brow + HALF, nt - 1);
;     BAR; WAIT_L(0); MMA(0, 0, At, B0); BAR;
	s_waitcnt lgkmcnt(0)
	v_mfma_f32_16x16x32_bf16 v[60:63], v[172:175], v[156:159], v[60:63]
	v_mfma_f32_16x16x32_bf16 v[56:59], v[172:175], v[164:167], v[56:59]
	v_mfma_f32_16x16x32_bf16 v[52:55], v[180:183], v[156:159], v[52:55]
	v_mfma_f32_16x16x32_bf16 v[48:51], v[180:183], v[164:167], v[48:51]
	v_mfma_f32_16x16x32_bf16 v[44:47], v[188:191], v[156:159], v[44:47]
	v_mfma_f32_16x16x32_bf16 v[40:43], v[188:191], v[164:167], v[40:43]
	v_mfma_f32_16x16x32_bf16 v[36:39], v[196:199], v[156:159], v[36:39]
	v_mfma_f32_16x16x32_bf16 v[32:35], v[196:199], v[164:167], v[32:35]
	v_mfma_f32_16x16x32_bf16 v[60:63], v[176:179], v[160:163], v[60:63]
	v_mfma_f32_16x16x32_bf16 v[56:59], v[176:179], v[168:171], v[56:59]
	v_mfma_f32_16x16x32_bf16 v[52:55], v[184:187], v[160:163], v[52:55]
	v_mfma_f32_16x16x32_bf16 v[48:51], v[184:187], v[168:171], v[48:51]
	v_mfma_f32_16x16x32_bf16 v[44:47], v[192:195], v[160:163], v[44:47]
	v_mfma_f32_16x16x32_bf16 v[40:43], v[192:195], v[168:171], v[40:43]
	v_mfma_f32_16x16x32_bf16 v[36:39], v[200:203], v[160:163], v[36:39]
	v_mfma_f32_16x16x32_bf16 v[32:35], v[200:203], v[168:171], v[32:35]
	s_barrier
	ds_read_b128 v[156:159], v145
	ds_read_b128 v[160:163], v145 offset:1024
	ds_read_b128 v[164:167], v145 offset:2048
	ds_read_b128 v[168:171], v145 offset:3072
	s_add_u32 m0, s29, s53
	s_nop 0
	s_add_u32 vcc_lo, s26, s20
	s_addc_u32 vcc_hi, s27, s21
	global_load_lds_dwordx4 v130, vcc
	v_lshl_add_u64 v[254:255], v[228:229], 0, s[20:21]
	s_add_u32 m0, s29, s53
	s_add_u32 m0, m0, 0x2000
	s_nop 0
	global_load_lds_dwordx4 v132, vcc
	s_waitcnt vmcnt(6)
	s_barrier
	v_mfma_f32_16x16x32_bf16 v[28:31], v[172:175], v[204:207], v[28:31]
	v_mfma_f32_16x16x32_bf16 v[24:27], v[172:175], v[216:219], v[24:27]
	v_mfma_f32_16x16x32_bf16 v[20:23], v[180:183], v[204:207], v[20:23]
	v_mfma_f32_16x16x32_bf16 v[16:19], v[180:183], v[216:219], v[16:19]
	v_mfma_f32_16x16x32_bf16 v[12:15], v[188:191], v[204:207], v[12:15]
	v_mfma_f32_16x16x32_bf16 v[8:11], v[188:191], v[216:219], v[8:11]
	v_mfma_f32_16x16x32_bf16 v[4:7], v[196:199], v[204:207], v[4:7]
	v_mfma_f32_16x16x32_bf16 v[0:3], v[196:199], v[216:219], v[0:3]
	v_mfma_f32_16x16x32_bf16 v[28:31], v[176:179], v[212:215], v[28:31]
	ds_read_b128 v[172:175], v128
	v_mfma_f32_16x16x32_bf16 v[24:27], v[176:179], v[220:223], v[24:27]
	v_mfma_f32_16x16x32_bf16 v[20:23], v[184:187], v[212:215], v[20:23]
	ds_read_b128 v[180:183], v128 offset:2048
	v_mfma_f32_16x16x32_bf16 v[16:19], v[184:187], v[220:223], v[16:19]
	v_mfma_f32_16x16x32_bf16 v[12:15], v[192:195], v[212:215], v[12:15]
	ds_read_b128 v[188:191], v128 offset:4096
	v_mfma_f32_16x16x32_bf16 v[8:11], v[192:195], v[220:223], v[8:11]
	v_mfma_f32_16x16x32_bf16 v[4:7], v[200:203], v[212:215], v[4:7]
	ds_read_b128 v[196:199], v128 offset:6144
	v_mfma_f32_16x16x32_bf16 v[0:3], v[200:203], v[220:223], v[0:3]
	s_add_i32 s28, s28, 2
	s_add_u32 s26, s26, 0x100
	s_addc_u32 s27, s27, 0
	s_cmp_lt_u32 s28, 28
	s_barrier
	s_cbranch_scc1 .LBB0_84
	v_lshlrev_b32_e32 v130, 3, v147
	v_lshlrev_b32_e32 v131, 5, v147
	v_and_b32_e32 v130, 0xffff0, v130
	v_and_b32_e32 v131, 32, v131
	v_add_u32_e32 v131, v131, v149
	v_add_lshl_u32 v130, v148, v130, 12
	s_add_u32 s4, s37, s4
	v_lshl_add_u32 v155, v131, 1, v130
	v_lshlrev_b32_e32 v130, 3, v150
	v_lshlrev_b32_e32 v131, 5, v150
	s_addc_u32 s27, s38, 0
	v_and_b32_e32 v130, 0xffff0, v130
	v_and_b32_e32 v131, 32, v131
	s_add_u32 s26, s4, 0x80f80
	v_readfirstlane_b32 s4, v153
	v_add_u32_e32 v131, v131, v152
	v_add_lshl_u32 v130, v151, v130, 12
	s_addc_u32 s27, s27, 0
	s_mov_b32 m0, s4
	v_readfirstlane_b32 s4, v154
	v_lshl_add_u32 v150, v131, 1, v130
	ds_read_b128 v[130:133], v145
	ds_read_b128 v[134:137], v145 offset:1024
	ds_read_b128 v[146:149], v145 offset:2048
	ds_read_b128 v[156:159], v145 offset:3072
	ds_read_b128 v[160:163], v128
	ds_read_b128 v[164:167], v128 offset:1024
	ds_read_b128 v[168:171], v128 offset:2048
	ds_read_b128 v[172:175], v128 offset:3072
	ds_read_b128 v[176:179], v128 offset:4096
	ds_read_b128 v[180:183], v128 offset:5120
	ds_read_b128 v[184:187], v128 offset:6144
	ds_read_b128 v[188:191], v128 offset:7168
	global_load_lds_dwordx4 v155, s[26:27]
	s_mov_b32 m0, s4
	s_nop 0
	global_load_lds_dwordx4 v150, s[26:27]
	s_barrier
	s_waitcnt lgkmcnt(0)
	s_setprio 1
	s_waitcnt lgkmcnt(0)
	v_mfma_f32_16x16x32_bf16 v[124:127], v[160:163], v[130:133], v[124:127]
	v_mfma_f32_16x16x32_bf16 v[116:119], v[168:171], v[130:133], v[116:119]
	v_mfma_f32_16x16x32_bf16 v[108:111], v[176:179], v[130:133], v[108:111]
	v_mfma_f32_16x16x32_bf16 v[100:103], v[184:187], v[130:133], v[100:103]
	v_mfma_f32_16x16x32_bf16 v[96:99], v[184:187], v[146:149], v[96:99]
	v_mfma_f32_16x16x32_bf16 v[124:127], v[164:167], v[134:137], v[124:127]
	v_mfma_f32_16x16x32_bf16 v[120:123], v[160:163], v[146:149], v[120:123]
	v_mfma_f32_16x16x32_bf16 v[116:119], v[172:175], v[134:137], v[116:119]
	v_mfma_f32_16x16x32_bf16 v[112:115], v[168:171], v[146:149], v[112:115]
	v_mfma_f32_16x16x32_bf16 v[108:111], v[180:183], v[134:137], v[108:111]
	v_mfma_f32_16x16x32_bf16 v[104:107], v[176:179], v[146:149], v[104:107]
	v_mfma_f32_16x16x32_bf16 v[100:103], v[188:191], v[134:137], v[100:103]
	v_mfma_f32_16x16x32_bf16 v[96:99], v[188:191], v[156:159], v[96:99]
	v_mfma_f32_16x16x32_bf16 v[150:153], v[164:167], v[156:159], v[120:123]
	v_mfma_f32_16x16x32_bf16 v[192:195], v[172:175], v[156:159], v[112:115]
	v_mfma_f32_16x16x32_bf16 v[196:199], v[180:183], v[156:159], v[104:107]
	s_setprio 0
	s_barrier
	s_nop 0
	ds_read_b128 v[104:107], v145 offset:16384
	ds_read_b128 v[112:115], v145 offset:17408
	ds_read_b128 v[120:123], v145 offset:18432
	ds_read_b128 v[200:203], v145 offset:19456
	s_barrier
; #define WAIT_V(n) asm volatile("s_waitcnt vmcnt(" #n ")" ::: "memory")
; #define WAIT_L(n) asm volatile("s_waitcnt lgkmcnt(" #n ")" ::: "memory")
; #define BAR __builtin_amdgcn_s_barrier()
; #define LDA(dst, b, h) _Pragma("unroll") for (int m = 0; m < 4; ++m) _Pragma("unroll") for (int k = 0; k < 2; ++k) \
;     dst[m][k] = *reinterpret_cast<const bf16x8*>((char*)shm + abase + (((b) * 2 + (h)) * 16384 + (m * 2 + k) * 1024))
; #define LDB(dst, b, h) _Pragma("unroll") for (int n = 0; n < 2; ++n) _Pragma("unroll") for (int k = 0; k < 2; ++k) \
;     dst[n][k] = *reinterpret_cast<const bf16x8*>((char*)shm + bbase + (((b) * 2 + (h)) * 16384 + (n * 2 + k) * 1024))
; template <bool SWAP>
; __device__ __forceinline__ void gemm_main(const u16* __restrict__ A, const u16* __restrict__ Bt, int brow, int bcol,
;                                           u16* shm, f32x4 (&acc)[2][2][4][2]) {
;     ...
;     LDB(B1, 0, 1); BAR; WAIT_L(0); MMA(0, 1, At, B1); BAR;
;     LDA(At, 0, 1); WAIT_V(4); BAR; WAIT_L(0); MMA(1, 0, At, B0); MMA(1, 1, At, B1); BAR; }
;   { LDB(B0, 1, 0); LDA(At, 1, 0); WAIT_V(2); BAR; WAIT_L(0); MMA(0, 0, At, B0); BAR;
	s_waitcnt lgkmcnt(0)
	s_setprio 1
	s_waitcnt lgkmcnt(0)
	v_mfma_f32_16x16x32_bf16 v[84:87], v[168:171], v[104:107], v[84:87]
	v_mfma_f32_16x16x32_bf16 v[76:79], v[176:179], v[104:107], v[76:79]
	v_mfma_f32_16x16x32_bf16 v[68:71], v[184:187], v[104:107], v[68:71]
	v_mfma_f32_16x16x32_bf16 v[92:95], v[160:163], v[104:107], v[92:95]
	v_mfma_f32_16x16x32_bf16 v[88:91], v[160:163], v[120:123], v[88:91]
	v_mfma_f32_16x16x32_bf16 v[84:87], v[172:175], v[112:115], v[84:87]
	v_mfma_f32_16x16x32_bf16 v[80:83], v[168:171], v[120:123], v[80:83]
	v_mfma_f32_16x16x32_bf16 v[76:79], v[180:183], v[112:115], v[76:79]
	v_mfma_f32_16x16x32_bf16 v[72:75], v[176:179], v[120:123], v[72:75]
	v_mfma_f32_16x16x32_bf16 v[68:71], v[188:191], v[112:115], v[68:71]
	v_mfma_f32_16x16x32_bf16 v[64:67], v[184:187], v[120:123], v[64:67]
	v_mfma_f32_16x16x32_bf16 v[204:207], v[164:167], v[112:115], v[92:95]
	v_mfma_f32_16x16x32_bf16 v[160:163], v[164:167], v[200:203], v[88:91]
	v_mfma_f32_16x16x32_bf16 v[164:167], v[172:175], v[200:203], v[80:83]
	v_mfma_f32_16x16x32_bf16 v[168:171], v[180:183], v[200:203], v[72:75]
	v_mfma_f32_16x16x32_bf16 v[172:175], v[188:191], v[200:203], v[64:67]
	s_setprio 0
	s_barrier
	s_nop 0
	ds_read_b128 v[64:67], v128 offset:16384
	ds_read_b128 v[72:75], v128 offset:17408
	ds_read_b128 v[80:83], v128 offset:18432
	ds_read_b128 v[88:91], v128 offset:19456
	ds_read_b128 v[92:95], v128 offset:20480
	ds_read_b128 v[176:179], v128 offset:21504
	ds_read_b128 v[180:183], v128 offset:22528
	ds_read_b128 v[184:187], v128 offset:23552
	s_waitcnt vmcnt(4)
	s_barrier
	s_waitcnt lgkmcnt(0)
	s_setprio 1
	s_waitcnt lgkmcnt(0)
	v_mfma_f32_16x16x32_bf16 v[60:63], v[64:67], v[130:133], v[60:63]
	v_mfma_f32_16x16x32_bf16 v[52:55], v[80:83], v[130:133], v[52:55]
	v_mfma_f32_16x16x32_bf16 v[44:47], v[92:95], v[130:133], v[44:47]
	v_mfma_f32_16x16x32_bf16 v[36:39], v[180:183], v[130:133], v[36:39]
	v_mfma_f32_16x16x32_bf16 v[60:63], v[72:75], v[134:137], v[60:63]
	v_mfma_f32_16x16x32_bf16 v[56:59], v[64:67], v[146:149], v[56:59]
	v_mfma_f32_16x16x32_bf16 v[52:55], v[88:91], v[134:137], v[52:55]
	v_mfma_f32_16x16x32_bf16 v[48:51], v[80:83], v[146:149], v[48:51]
	v_mfma_f32_16x16x32_bf16 v[44:47], v[176:179], v[134:137], v[44:47]
	v_mfma_f32_16x16x32_bf16 v[40:43], v[92:95], v[146:149], v[40:43]
	v_mfma_f32_16x16x32_bf16 v[36:39], v[184:187], v[134:137], v[36:39]
	v_mfma_f32_16x16x32_bf16 v[32:35], v[180:183], v[146:149], v[32:35]
	v_mfma_f32_16x16x32_bf16 v[188:191], v[72:75], v[156:159], v[56:59]
	v_mfma_f32_16x16x32_bf16 v[212:215], v[88:91], v[156:159], v[48:51]
	v_mfma_f32_16x16x32_bf16 v[216:219], v[176:179], v[156:159], v[40:43]
	v_mfma_f32_16x16x32_bf16 v[130:133], v[184:187], v[156:159], v[32:35]
	s_setprio 0
	s_setprio 1
	v_mfma_f32_16x16x32_bf16 v[28:31], v[64:67], v[104:107], v[28:31]
	v_mfma_f32_16x16x32_bf16 v[20:23], v[80:83], v[104:107], v[20:23]
	v_mfma_f32_16x16x32_bf16 v[12:15], v[92:95], v[104:107], v[12:15]
	v_mfma_f32_16x16x32_bf16 v[4:7], v[180:183], v[104:107], v[4:7]
	v_mfma_f32_16x16x32_bf16 v[28:31], v[72:75], v[112:115], v[28:31]
	v_mfma_f32_16x16x32_bf16 v[24:27], v[64:67], v[120:123], v[24:27]
	v_mfma_f32_16x16x32_bf16 v[20:23], v[88:91], v[112:115], v[20:23]
	v_mfma_f32_16x16x32_bf16 v[16:19], v[80:83], v[120:123], v[16:19]
	v_mfma_f32_16x16x32_bf16 v[12:15], v[176:179], v[112:115], v[12:15]
	v_mfma_f32_16x16x32_bf16 v[8:11], v[92:95], v[120:123], v[8:11]
	v_mfma_f32_16x16x32_bf16 v[4:7], v[184:187], v[112:115], v[4:7]
	v_mfma_f32_16x16x32_bf16 v[0:3], v[180:183], v[120:123], v[0:3]
	v_mfma_f32_16x16x32_bf16 v[134:137], v[72:75], v[200:203], v[24:27]
	v_mfma_f32_16x16x32_bf16 v[146:149], v[88:91], v[200:203], v[16:19]
	v_mfma_f32_16x16x32_bf16 v[154:157], v[176:179], v[200:203], v[8:11]
	v_mfma_f32_16x16x32_bf16 v[176:179], v[184:187], v[200:203], v[0:3]
	s_setprio 0
	s_barrier
	s_nop 1
	ds_read_b128 v[0:3], v145 offset:32768
	ds_read_b128 v[8:11], v145 offset:33792
	ds_read_b128 v[16:19], v145 offset:34816
	ds_read_b128 v[24:27], v145 offset:35840
	ds_read_b128 v[32:35], v128 offset:32768
	ds_read_b128 v[40:43], v128 offset:33792
	ds_read_b128 v[48:51], v128 offset:34816
	ds_read_b128 v[56:59], v128 offset:35840
	ds_read_b128 v[64:67], v128 offset:36864
	ds_read_b128 v[180:183], v128 offset:37888
	ds_read_b128 v[184:187], v128 offset:38912
	ds_read_b128 v[200:203], v128 offset:39936
	s_waitcnt vmcnt(2)
	s_barrier
; #define WAIT_V(n) asm volatile("s_waitcnt vmcnt(" #n ")" ::: "memory")
; #define WAIT_L(n) asm volatile("s_waitcnt lgkmcnt(" #n ")" ::: "memory")
; #define BAR __builtin_amdgcn_s_barrier()
; #define LDA(dst, b, h) _Pragma("unroll") for (int m = 0; m < 4; ++m) _Pragma("unroll") for (int k = 0; k < 2; ++k) \
;     dst[m][k] = *reinterpret_cast<const bf16x8*>((char*)shm + abase + (((b) * 2 + (h)) * 16384 + (m * 2 + k) * 1024))
; #define LDB(dst, b, h) _Pragma("unroll") for (int n = 0; n < 2; ++n) _Pragma("unroll") for (int k = 0; k < 2; ++k) \
;     dst[n][k] = *reinterpret_cast<const bf16x8*>((char*)shm + bbase + (((b) * 2 + (h)) * 16384 + (n * 2 + k) * 1024))
; template <bool SWAP>
; __device__ __forceinline__ void gemm_main(const u16* __restrict__ A, const u16* __restrict__ Bt, int brow, int bcol,
;                                           u16* shm, f32x4 (&acc)[2][2][4][2]) {
;     ...
;   { LDB(B0, 1, 0); LDA(At, 1, 0); WAIT_V(2); BAR; WAIT_L(0); MMA(0, 0, At, B0); BAR;
;     LDB(B1, 1, 1); WAIT_V(0); BAR; WAIT_L(0); MMA(0, 1, At, B1); BAR;
;     LDA(At, 1, 1); BAR; WAIT_L(0); MMA(1, 0, At, B0); MMA(1, 1, At, B1); BAR; }
;   if (wr == 0) BAR;
	s_waitcnt lgkmcnt(0)
	s_setprio 1
	s_waitcnt lgkmcnt(0)
	v_mfma_f32_16x16x32_bf16 v[72:75], v[32:35], v[0:3], v[124:127]
	v_mfma_f32_16x16x32_bf16 v[120:123], v[40:43], v[8:11], v[72:75]
	v_mfma_f32_16x16x32_bf16 v[72:75], v[32:35], v[16:19], v[150:153]
	v_mfma_f32_16x16x32_bf16 v[112:115], v[40:43], v[24:27], v[72:75]
	v_mfma_f32_16x16x32_bf16 v[72:75], v[48:51], v[0:3], v[116:119]
	v_mfma_f32_16x16x32_bf16 v[124:127], v[56:59], v[8:11], v[72:75]
	v_mfma_f32_16x16x32_bf16 v[72:75], v[48:51], v[16:19], v[192:195]
	v_mfma_f32_16x16x32_bf16 v[116:119], v[56:59], v[24:27], v[72:75]
	v_mfma_f32_16x16x32_bf16 v[72:75], v[64:67], v[0:3], v[108:111]
	v_mfma_f32_16x16x32_bf16 v[104:107], v[180:183], v[8:11], v[72:75]
	v_mfma_f32_16x16x32_bf16 v[72:75], v[64:67], v[16:19], v[196:199]
	v_mfma_f32_16x16x32_bf16 v[92:95], v[180:183], v[24:27], v[72:75]
	v_mfma_f32_16x16x32_bf16 v[72:75], v[184:187], v[0:3], v[100:103]
	v_mfma_f32_16x16x32_bf16 v[108:111], v[200:203], v[8:11], v[72:75]
	v_mfma_f32_16x16x32_bf16 v[72:75], v[184:187], v[16:19], v[96:99]
	v_mfma_f32_16x16x32_bf16 v[100:103], v[200:203], v[24:27], v[72:75]
	s_setprio 0
	s_barrier
	ds_read_b128 v[150:153], v145 offset:49152
	ds_read_b128 v[192:195], v145 offset:50176
	ds_read_b128 v[196:199], v145 offset:51200
	ds_read_b128 v[220:223], v145 offset:52224
	s_waitcnt vmcnt(0)
	s_barrier
	s_waitcnt lgkmcnt(0)
	s_setprio 1
	s_waitcnt lgkmcnt(0)
	v_mfma_f32_16x16x32_bf16 v[72:75], v[32:35], v[150:153], v[204:207]
	v_mfma_f32_16x16x32_bf16 v[32:35], v[32:35], v[196:199], v[160:163]
	v_mfma_f32_16x16x32_bf16 v[80:83], v[40:43], v[220:223], v[32:35]
	v_mfma_f32_16x16x32_bf16 v[32:35], v[48:51], v[150:153], v[84:87]
	v_mfma_f32_16x16x32_bf16 v[96:99], v[56:59], v[192:195], v[32:35]
	v_mfma_f32_16x16x32_bf16 v[32:35], v[48:51], v[196:199], v[164:167]
	v_mfma_f32_16x16x32_bf16 v[84:87], v[56:59], v[220:223], v[32:35]
	v_mfma_f32_16x16x32_bf16 v[32:35], v[64:67], v[150:153], v[76:79]
	v_mfma_f32_16x16x32_bf16 v[88:91], v[40:43], v[192:195], v[72:75]
	v_mfma_f32_16x16x32_bf16 v[72:75], v[180:183], v[192:195], v[32:35]
	v_mfma_f32_16x16x32_bf16 v[32:35], v[64:67], v[196:199], v[168:171]
	v_mfma_f32_16x16x32_bf16 v[64:67], v[180:183], v[220:223], v[32:35]
	v_mfma_f32_16x16x32_bf16 v[32:35], v[184:187], v[150:153], v[68:71]
	v_mfma_f32_16x16x32_bf16 v[76:79], v[200:203], v[192:195], v[32:35]
	v_mfma_f32_16x16x32_bf16 v[32:35], v[184:187], v[196:199], v[172:175]
	v_mfma_f32_16x16x32_bf16 v[68:71], v[200:203], v[220:223], v[32:35]
	s_setprio 0
	s_barrier
	ds_read_b128 v[158:161], v128 offset:49152
	ds_read_b128 v[162:165], v128 offset:50176
	ds_read_b128 v[166:169], v128 offset:51200
	ds_read_b128 v[170:173], v128 offset:52224
	ds_read_b128 v[180:183], v128 offset:53248
	ds_read_b128 v[184:187], v128 offset:54272
	ds_read_b128 v[200:203], v128 offset:55296
	ds_read_b128 v[204:207], v128 offset:56320
	s_barrier
	s_waitcnt lgkmcnt(0)
	s_setprio 1
	s_waitcnt lgkmcnt(0)
	v_mfma_f32_16x16x32_bf16 v[32:35], v[158:161], v[0:3], v[60:63]
	v_mfma_f32_16x16x32_bf16 v[56:59], v[162:165], v[8:11], v[32:35]
	v_mfma_f32_16x16x32_bf16 v[32:35], v[158:161], v[16:19], v[188:191]
	v_mfma_f32_16x16x32_bf16 v[48:51], v[162:165], v[24:27], v[32:35]
	v_mfma_f32_16x16x32_bf16 v[32:35], v[166:169], v[0:3], v[52:55]
	v_mfma_f32_16x16x32_bf16 v[60:63], v[170:173], v[8:11], v[32:35]
	v_mfma_f32_16x16x32_bf16 v[32:35], v[166:169], v[16:19], v[212:215]
	v_mfma_f32_16x16x32_bf16 v[52:55], v[170:173], v[24:27], v[32:35]
	v_mfma_f32_16x16x32_bf16 v[32:35], v[180:183], v[0:3], v[44:47]
	v_mfma_f32_16x16x32_bf16 v[0:3], v[200:203], v[0:3], v[36:39]
	v_mfma_f32_16x16x32_bf16 v[40:43], v[184:187], v[8:11], v[32:35]
	v_mfma_f32_16x16x32_bf16 v[32:35], v[180:183], v[16:19], v[216:219]
	v_mfma_f32_16x16x32_bf16 v[44:47], v[204:207], v[8:11], v[0:3]
	v_mfma_f32_16x16x32_bf16 v[0:3], v[200:203], v[16:19], v[130:133]
	v_mfma_f32_16x16x32_bf16 v[32:35], v[184:187], v[24:27], v[32:35]
	v_mfma_f32_16x16x32_bf16 v[36:39], v[204:207], v[24:27], v[0:3]
	s_setprio 0
	s_setprio 1
	v_mfma_f32_16x16x32_bf16 v[0:3], v[158:161], v[150:153], v[28:31]
	v_mfma_f32_16x16x32_bf16 v[24:27], v[162:165], v[192:195], v[0:3]
	v_mfma_f32_16x16x32_bf16 v[0:3], v[158:161], v[196:199], v[134:137]
	v_mfma_f32_16x16x32_bf16 v[16:19], v[162:165], v[220:223], v[0:3]
	v_mfma_f32_16x16x32_bf16 v[0:3], v[166:169], v[150:153], v[20:23]
	v_mfma_f32_16x16x32_bf16 v[28:31], v[170:173], v[192:195], v[0:3]
	v_mfma_f32_16x16x32_bf16 v[0:3], v[166:169], v[196:199], v[146:149]
	v_mfma_f32_16x16x32_bf16 v[20:23], v[170:173], v[220:223], v[0:3]
	v_mfma_f32_16x16x32_bf16 v[0:3], v[180:183], v[150:153], v[12:15]
	v_mfma_f32_16x16x32_bf16 v[4:7], v[200:203], v[150:153], v[4:7]
	v_mfma_f32_16x16x32_bf16 v[8:11], v[184:187], v[192:195], v[0:3]
	v_mfma_f32_16x16x32_bf16 v[0:3], v[180:183], v[196:199], v[154:157]
	v_mfma_f32_16x16x32_bf16 v[12:15], v[204:207], v[192:195], v[4:7]
	v_mfma_f32_16x16x32_bf16 v[4:7], v[200:203], v[196:199], v[176:179]
	v_mfma_f32_16x16x32_bf16 v[0:3], v[184:187], v[220:223], v[0:3]
	v_mfma_f32_16x16x32_bf16 v[4:7], v[204:207], v[220:223], v[4:7]
	s_setprio 0
	v_cmp_gt_u32_e32 vcc, s55, v144
	s_barrier
	s_and_saveexec_b64 s[26:27], vcc
	s_cbranch_execz .LBB0_87
	s_barrier

; #define WAIT_V(n) asm volatile("s_waitcnt vmcnt(" #n ")" ::: "memory")
; #define WAIT_L(n) asm volatile("s_waitcnt lgkmcnt(" #n ")" ::: "memory")
; #define BAR __builtin_amdgcn_s_barrier()
; #define SCHED __builtin_amdgcn_sched_barrier(0)
; #define STAGE(P, BASE, br, kt) do { const char* _g = (const char*)((BASE) + (size_t)(br) * GK + (kt) * BK); \
;     __builtin_amdgcn_global_load_lds((const unsigned*)(_g + voff0), (unsigned*)((char*)(P) + tx * 16), 16, 0, 0); \
;     __builtin_amdgcn_global_load_lds((const unsigned*)(_g + voff1), (unsigned*)((char*)(P) + tx * 16 + 8192), 16, 0, 0); } while (0)
; #define LDA(dst, b, h) _Pragma("unroll") for (int m = 0; m < 4; ++m) _Pragma("unroll") for (int k = 0; k < 2; ++k) \
;     dst[m][k] = *reinterpret_cast<const bf16x8*>((char*)shm + abase + (((b) * 2 + (h)) * 16384 + (m * 2 + k) * 1024))
; #define LDB(dst, b, h) _Pragma("unroll") for (int n = 0; n < 2; ++n) _Pragma("unroll") for (int k = 0; k < 2; ++k) \
;     dst[n][k] = *reinterpret_cast<const bf16x8*>((char*)shm + bbase + (((b) * 2 + (h)) * 16384 + (n * 2 + k) * 1024))
; template <bool SWAP>
; __device__ __forceinline__ void gemm_main(const u16* __restrict__ A, const u16* __restrict__ Bt, int brow, int bcol,
;                                           u16* shm, f32x4 (&acc)[2][2][4][2]) {
;     ...
;   for (int t = 0; t < nt - 2; t += 2) {
;     LDB(B0, 0, 0); SCHED; LDA(At, 0, 0); STAGE(SA(1, 1), A, brow + HALF, t + 1);
;     WAIT_L(8); BAR; WAIT_L(0); MMA(0, 0, At, B0); BAR; SCHED;
;     LDB(B1, 0, 1); STAGE(SB(0, 0), Bt, bcol, t + 2);
;     BAR; WAIT_L(0); MMA(0, 1, At, B1); BAR;
;     LDA(At, 0, 1); STAGE(SA(0, 0), A, brow, t + 2);
;     BAR; WAIT_L(0); MMA(1, 0, At, B0); BAR; SCHED;
;     STAGE(SB(0, 1), Bt, bcol + HALF, t + 2);
;     WAIT_V(6); BAR; MMA(1, 1, At, B1); BAR;
;     LDB(B0, 1, 0); SCHED; LDA(At, 1, 0); STAGE(SA(0, 1), A, brow + HALF, t + 2);
.LBB0_94:
	ds_read_b128 v[176:179], v145 offset:1024
	ds_read_b128 v[184:187], v145 offset:3072
	ds_read_b128 v[192:195], v145 offset:5120
	ds_read_b128 v[200:203], v145 offset:7168
	v_add_u32_e32 v128, 0, v147
	v_add_u32_e32 v154, 0xc000, v128
	v_add_u32_e32 v155, 0xe000, v128
	s_add_u32 m0, s25, 0xc000
	v_lshl_add_u64 v[224:225], s[28:29], 0, v[132:133]
	s_add_u32 vcc_lo, s28, s6
	s_addc_u32 vcc_hi, s29, s7
	global_load_lds_dwordx4 v136, vcc
	s_add_u32 m0, s25, 0xe000
	s_nop 0
	global_load_lds_dwordx4 v132, vcc
	s_waitcnt lgkmcnt(8)
	s_barrier
	s_waitcnt lgkmcnt(0)
	v_mfma_f32_16x16x32_bf16 v[124:127], v[156:159], v[172:175], v[124:127]
	v_mfma_f32_16x16x32_bf16 v[120:123], v[164:167], v[172:175], v[120:123]
	v_mfma_f32_16x16x32_bf16 v[116:119], v[156:159], v[180:183], v[116:119]
	v_mfma_f32_16x16x32_bf16 v[112:115], v[164:167], v[180:183], v[112:115]
	v_mfma_f32_16x16x32_bf16 v[108:111], v[156:159], v[188:191], v[108:111]
	v_mfma_f32_16x16x32_bf16 v[104:107], v[164:167], v[188:191], v[104:107]
	v_mfma_f32_16x16x32_bf16 v[100:103], v[156:159], v[196:199], v[100:103]
	v_mfma_f32_16x16x32_bf16 v[96:99], v[164:167], v[196:199], v[96:99]
	v_mfma_f32_16x16x32_bf16 v[124:127], v[160:163], v[176:179], v[124:127]
	v_mfma_f32_16x16x32_bf16 v[120:123], v[168:171], v[176:179], v[120:123]
	v_mfma_f32_16x16x32_bf16 v[116:119], v[160:163], v[184:187], v[116:119]
	v_mfma_f32_16x16x32_bf16 v[112:115], v[168:171], v[184:187], v[112:115]
	v_mfma_f32_16x16x32_bf16 v[108:111], v[160:163], v[192:195], v[108:111]
	v_mfma_f32_16x16x32_bf16 v[104:107], v[168:171], v[192:195], v[104:107]
	v_mfma_f32_16x16x32_bf16 v[100:103], v[160:163], v[200:203], v[100:103]
	v_mfma_f32_16x16x32_bf16 v[96:99], v[168:171], v[200:203], v[96:99]
	s_barrier
	ds_read_b128 v[204:207], v146 offset:16384
	ds_read_b128 v[212:215], v146 offset:17408
	ds_read_b128 v[216:219], v146 offset:18432
	ds_read_b128 v[220:223], v146 offset:19456
	v_lshl_add_u64 v[226:227], s[28:29], 0, v[134:135]
	s_add_u32 m0, s25, s44
	s_nop 0
	s_add_u32 vcc_lo, s28, s8
	s_addc_u32 vcc_hi, s29, s9
	global_load_lds_dwordx4 v134, vcc
	v_lshl_add_u64 v[228:229], s[28:29], 0, v[130:131]
	s_add_u32 m0, s25, s44
	s_add_u32 m0, m0, 0x2000
	s_nop 0
	global_load_lds_dwordx4 v130, vcc
	s_barrier
	s_waitcnt lgkmcnt(0)
	v_mfma_f32_16x16x32_bf16 v[92:95], v[204:207], v[172:175], v[92:95]
	v_mfma_f32_16x16x32_bf16 v[88:91], v[216:219], v[172:175], v[88:91]
	v_mfma_f32_16x16x32_bf16 v[84:87], v[204:207], v[180:183], v[84:87]
	v_mfma_f32_16x16x32_bf16 v[80:83], v[216:219], v[180:183], v[80:83]
	v_mfma_f32_16x16x32_bf16 v[76:79], v[204:207], v[188:191], v[76:79]
	v_mfma_f32_16x16x32_bf16 v[72:75], v[216:219], v[188:191], v[72:75]
	v_mfma_f32_16x16x32_bf16 v[68:71], v[204:207], v[196:199], v[68:71]
	v_mfma_f32_16x16x32_bf16 v[64:67], v[216:219], v[196:199], v[64:67]
	v_mfma_f32_16x16x32_bf16 v[92:95], v[212:215], v[176:179], v[92:95]
	ds_read_b128 v[172:175], v145 offset:16384
	v_mfma_f32_16x16x32_bf16 v[88:91], v[220:223], v[176:179], v[88:91]
	v_mfma_f32_16x16x32_bf16 v[84:87], v[212:215], v[184:187], v[84:87]
	ds_read_b128 v[180:183], v145 offset:18432
	v_mfma_f32_16x16x32_bf16 v[80:83], v[220:223], v[184:187], v[80:83]
	v_mfma_f32_16x16x32_bf16 v[76:79], v[212:215], v[192:195], v[76:79]
	ds_read_b128 v[188:191], v145 offset:20480
	v_mfma_f32_16x16x32_bf16 v[72:75], v[220:223], v[192:195], v[72:75]
	v_mfma_f32_16x16x32_bf16 v[68:71], v[212:215], v[200:203], v[68:71]
	ds_read_b128 v[196:199], v145 offset:22528
	v_mfma_f32_16x16x32_bf16 v[64:67], v[220:223], v[200:203], v[64:67]
	s_barrier
	ds_read_b128 v[176:179], v145 offset:17408
	ds_read_b128 v[184:187], v145 offset:19456
	ds_read_b128 v[192:195], v145 offset:21504
	ds_read_b128 v[200:203], v145 offset:23552
	s_add_u32 m0, s25, 0x0
	s_nop 0
	s_add_u32 vcc_lo, s28, s10
	s_addc_u32 vcc_hi, s29, s11
	global_load_lds_dwordx4 v136, vcc
	s_add_u32 m0, s25, 0x2000
	s_nop 0
	global_load_lds_dwordx4 v132, vcc
	s_waitcnt vmcnt(8)
	s_barrier
	s_waitcnt lgkmcnt(0)
	v_mfma_f32_16x16x32_bf16 v[60:63], v[156:159], v[172:175], v[60:63]
	v_mfma_f32_16x16x32_bf16 v[56:59], v[164:167], v[172:175], v[56:59]
	v_mfma_f32_16x16x32_bf16 v[52:55], v[156:159], v[180:183], v[52:55]
	v_mfma_f32_16x16x32_bf16 v[48:51], v[164:167], v[180:183], v[48:51]
	v_mfma_f32_16x16x32_bf16 v[44:47], v[156:159], v[188:191], v[44:47]
	v_mfma_f32_16x16x32_bf16 v[40:43], v[164:167], v[188:191], v[40:43]
	v_mfma_f32_16x16x32_bf16 v[36:39], v[156:159], v[196:199], v[36:39]
	v_mfma_f32_16x16x32_bf16 v[32:35], v[164:167], v[196:199], v[32:35]
	v_mfma_f32_16x16x32_bf16 v[60:63], v[160:163], v[176:179], v[60:63]
	v_mfma_f32_16x16x32_bf16 v[56:59], v[168:171], v[176:179], v[56:59]
	v_mfma_f32_16x16x32_bf16 v[52:55], v[160:163], v[184:187], v[52:55]
	v_mfma_f32_16x16x32_bf16 v[48:51], v[168:171], v[184:187], v[48:51]
	v_mfma_f32_16x16x32_bf16 v[44:47], v[160:163], v[192:195], v[44:47]
	v_mfma_f32_16x16x32_bf16 v[40:43], v[168:171], v[192:195], v[40:43]
	v_mfma_f32_16x16x32_bf16 v[36:39], v[160:163], v[200:203], v[36:39]
	v_mfma_f32_16x16x32_bf16 v[32:35], v[168:171], v[200:203], v[32:35]
	s_barrier
	ds_read_b128 v[156:159], v146 offset:32768
	ds_read_b128 v[160:163], v146 offset:33792
	ds_read_b128 v[164:167], v146 offset:34816
	ds_read_b128 v[168:171], v146 offset:35840
	s_add_u32 m0, s25, s45
	s_nop 0
	s_add_u32 vcc_lo, s28, s12
	s_addc_u32 vcc_hi, s29, s13
	global_load_lds_dwordx4 v134, vcc
	s_add_u32 m0, s25, s45
	s_add_u32 m0, m0, 0x2000
	s_nop 0
	global_load_lds_dwordx4 v130, vcc
	s_waitcnt vmcnt(6)
	s_barrier
; #define WAIT_V(n) asm volatile("s_waitcnt vmcnt(" #n ")" ::: "memory")
; #define WAIT_L(n) asm volatile("s_waitcnt lgkmcnt(" #n ")" ::: "memory")
; #define BAR __builtin_amdgcn_s_barrier()
; #define SCHED __builtin_amdgcn_sched_barrier(0)
; #define STAGE(P, BASE, br, kt) do { const char* _g = (const char*)((BASE) + (size_t)(br) * GK + (kt) * BK); \
;     __builtin_amdgcn_global_load_lds((const unsigned*)(_g + voff0), (unsigned*)((char*)(P) + tx * 16), 16, 0, 0); \
;     __builtin_amdgcn_global_load_lds((const unsigned*)(_g + voff1), (unsigned*)((char*)(P) + tx * 16 + 8192), 16, 0, 0); } while (0)
; #define LDA(dst, b, h) _Pragma("unroll") for (int m = 0; m < 4; ++m) _Pragma("unroll") for (int k = 0; k < 2; ++k) \
;     dst[m][k] = *reinterpret_cast<const bf16x8*>((char*)shm + abase + (((b) * 2 + (h)) * 16384 + (m * 2 + k) * 1024))
; #define LDB(dst, b, h) _Pragma("unroll") for (int n = 0; n < 2; ++n) _Pragma("unroll") for (int k = 0; k < 2; ++k) \
;     dst[n][k] = *reinterpret_cast<const bf16x8*>((char*)shm + bbase + (((b) * 2 + (h)) * 16384 + (n * 2 + k) * 1024))
; template <bool SWAP>
; __device__ __forceinline__ void gemm_main(const u16* __restrict__ A, const u16* __restrict__ Bt, int brow, int bcol,
;                                           u16* shm, f32x4 (&acc)[2][2][4][2]) {
;     ...
;     WAIT_V(6); BAR; MMA(1, 1, At, B1); BAR;
;     LDB(B0, 1, 0); SCHED; LDA(At, 1, 0); STAGE(SA(0, 1), A, brow + HALF, t + 2);
;     WAIT_L(8); BAR; WAIT_L(0); MMA(0, 0, At, B0); BAR; SCHED;
;     LDB(B1, 1, 1); STAGE(SB(1, 0), Bt, bcol, t + 3);
;     BAR; WAIT_L(0); MMA(0, 1, At, B1); BAR;
;     LDA(At, 1, 1); STAGE(SA(1, 0), A, brow, t + 3);
;     BAR; WAIT_L(0); MMA(1, 0, At, B0); BAR; SCHED;
	v_mfma_f32_16x16x32_bf16 v[28:31], v[204:207], v[172:175], v[28:31]
	v_mfma_f32_16x16x32_bf16 v[24:27], v[216:219], v[172:175], v[24:27]
	v_mfma_f32_16x16x32_bf16 v[20:23], v[204:207], v[180:183], v[20:23]
	v_mfma_f32_16x16x32_bf16 v[16:19], v[216:219], v[180:183], v[16:19]
	v_mfma_f32_16x16x32_bf16 v[12:15], v[204:207], v[188:191], v[12:15]
	v_mfma_f32_16x16x32_bf16 v[8:11], v[216:219], v[188:191], v[8:11]
	v_mfma_f32_16x16x32_bf16 v[4:7], v[204:207], v[196:199], v[4:7]
	v_mfma_f32_16x16x32_bf16 v[0:3], v[216:219], v[196:199], v[0:3]
	v_mfma_f32_16x16x32_bf16 v[28:31], v[212:215], v[176:179], v[28:31]
	ds_read_b128 v[172:175], v145 offset:32768
	v_mfma_f32_16x16x32_bf16 v[24:27], v[220:223], v[176:179], v[24:27]
	v_mfma_f32_16x16x32_bf16 v[20:23], v[212:215], v[184:187], v[20:23]
	ds_read_b128 v[180:183], v145 offset:34816
	v_mfma_f32_16x16x32_bf16 v[16:19], v[220:223], v[184:187], v[16:19]
	v_mfma_f32_16x16x32_bf16 v[12:15], v[212:215], v[192:195], v[12:15]
	ds_read_b128 v[188:191], v145 offset:36864
	v_mfma_f32_16x16x32_bf16 v[8:11], v[220:223], v[192:195], v[8:11]
	v_mfma_f32_16x16x32_bf16 v[4:7], v[212:215], v[200:203], v[4:7]
	ds_read_b128 v[196:199], v145 offset:38912
	v_mfma_f32_16x16x32_bf16 v[0:3], v[220:223], v[200:203], v[0:3]
	s_barrier
	ds_read_b128 v[176:179], v145 offset:33792
	ds_read_b128 v[184:187], v145 offset:35840
	ds_read_b128 v[192:195], v145 offset:37888
	ds_read_b128 v[200:203], v145 offset:39936
	s_add_u32 m0, s25, 0x4000
	s_nop 0
	s_add_u32 vcc_lo, s28, s14
	s_addc_u32 vcc_hi, s29, s15
	global_load_lds_dwordx4 v136, vcc
	s_add_u32 m0, s25, 0x6000
	s_nop 0
	global_load_lds_dwordx4 v132, vcc
	s_waitcnt lgkmcnt(8)
	s_barrier
	s_waitcnt lgkmcnt(0)
	v_mfma_f32_16x16x32_bf16 v[124:127], v[156:159], v[172:175], v[124:127]
	v_mfma_f32_16x16x32_bf16 v[120:123], v[164:167], v[172:175], v[120:123]
	v_mfma_f32_16x16x32_bf16 v[116:119], v[156:159], v[180:183], v[116:119]
	v_mfma_f32_16x16x32_bf16 v[112:115], v[164:167], v[180:183], v[112:115]
	v_mfma_f32_16x16x32_bf16 v[108:111], v[156:159], v[188:191], v[108:111]
	v_mfma_f32_16x16x32_bf16 v[104:107], v[164:167], v[188:191], v[104:107]
	v_mfma_f32_16x16x32_bf16 v[100:103], v[156:159], v[196:199], v[100:103]
	v_mfma_f32_16x16x32_bf16 v[96:99], v[164:167], v[196:199], v[96:99]
	v_mfma_f32_16x16x32_bf16 v[124:127], v[160:163], v[176:179], v[124:127]
	v_mfma_f32_16x16x32_bf16 v[120:123], v[168:171], v[176:179], v[120:123]
	v_mfma_f32_16x16x32_bf16 v[116:119], v[160:163], v[184:187], v[116:119]
	v_mfma_f32_16x16x32_bf16 v[112:115], v[168:171], v[184:187], v[112:115]
	v_mfma_f32_16x16x32_bf16 v[108:111], v[160:163], v[192:195], v[108:111]
	v_mfma_f32_16x16x32_bf16 v[104:107], v[168:171], v[192:195], v[104:107]
	v_mfma_f32_16x16x32_bf16 v[100:103], v[160:163], v[200:203], v[100:103]
	v_mfma_f32_16x16x32_bf16 v[96:99], v[168:171], v[200:203], v[96:99]
	s_barrier
	ds_read_b128 v[204:207], v146 offset:49152
	ds_read_b128 v[212:215], v146 offset:50176
	ds_read_b128 v[216:219], v146 offset:51200
	ds_read_b128 v[220:223], v146 offset:52224
	s_add_u32 m0, s25, s52
	s_nop 0
	s_add_u32 vcc_lo, s28, s16
	s_addc_u32 vcc_hi, s29, s17
	global_load_lds_dwordx4 v134, vcc
	v_lshl_add_u64 v[230:231], v[228:229], 0, s[16:17]
	s_add_u32 m0, s25, s52
	s_add_u32 m0, m0, 0x2000
	s_nop 0
	global_load_lds_dwordx4 v130, vcc
	s_barrier
	s_waitcnt lgkmcnt(0)
	v_mfma_f32_16x16x32_bf16 v[92:95], v[204:207], v[172:175], v[92:95]
	v_mfma_f32_16x16x32_bf16 v[88:91], v[216:219], v[172:175], v[88:91]
	v_mfma_f32_16x16x32_bf16 v[84:87], v[204:207], v[180:183], v[84:87]
	v_mfma_f32_16x16x32_bf16 v[80:83], v[216:219], v[180:183], v[80:83]
	v_mfma_f32_16x16x32_bf16 v[76:79], v[204:207], v[188:191], v[76:79]
	v_mfma_f32_16x16x32_bf16 v[72:75], v[216:219], v[188:191], v[72:75]
	v_mfma_f32_16x16x32_bf16 v[68:71], v[204:207], v[196:199], v[68:71]
	v_mfma_f32_16x16x32_bf16 v[64:67], v[216:219], v[196:199], v[64:67]
	v_mfma_f32_16x16x32_bf16 v[92:95], v[212:215], v[176:179], v[92:95]
	ds_read_b128 v[172:175], v145 offset:49152
	v_mfma_f32_16x16x32_bf16 v[88:91], v[220:223], v[176:179], v[88:91]
	v_mfma_f32_16x16x32_bf16 v[84:87], v[212:215], v[184:187], v[84:87]
	ds_read_b128 v[180:183], v145 offset:51200
	v_mfma_f32_16x16x32_bf16 v[80:83], v[220:223], v[184:187], v[80:83]
	v_mfma_f32_16x16x32_bf16 v[76:79], v[212:215], v[192:195], v[76:79]
	ds_read_b128 v[188:191], v145 offset:53248
	v_mfma_f32_16x16x32_bf16 v[72:75], v[220:223], v[192:195], v[72:75]
	v_mfma_f32_16x16x32_bf16 v[68:71], v[212:215], v[200:203], v[68:71]
	ds_read_b128 v[196:199], v145 offset:55296
	v_mfma_f32_16x16x32_bf16 v[64:67], v[220:223], v[200:203], v[64:67]
	s_barrier
	ds_read_b128 v[176:179], v145 offset:50176
	ds_read_b128 v[184:187], v145 offset:52224
	ds_read_b128 v[192:195], v145 offset:54272
	ds_read_b128 v[200:203], v145 offset:56320
	s_add_u32 m0, s25, 0x8000
	s_nop 0
	s_add_u32 vcc_lo, s28, s18
	s_addc_u32 vcc_hi, s29, s19
	global_load_lds_dwordx4 v136, vcc
	v_lshl_add_u64 v[208:209], v[224:225], 0, s[18:19]
	s_add_u32 m0, s25, 0xa000
	s_nop 0
	global_load_lds_dwordx4 v132, vcc
	s_waitcnt vmcnt(8)
	s_barrier
; #define WAIT_V(n) asm volatile("s_waitcnt vmcnt(" #n ")" ::: "memory")
; #define WAIT_L(n) asm volatile("s_waitcnt lgkmcnt(" #n ")" ::: "memory")
; #define BAR __builtin_amdgcn_s_barrier()
; #define SCHED __builtin_amdgcn_sched_barrier(0)
; #define STAGE(P, BASE, br, kt) do { const char* _g = (const char*)((BASE) + (size_t)(br) * GK + (kt) * BK); \
;     __builtin_amdgcn_global_load_lds((const unsigned*)(_g + voff0), (unsigned*)((char*)(P) + tx * 16), 16, 0, 0); \
;     __builtin_amdgcn_global_load_lds((const unsigned*)(_g + voff1), (unsigned*)((char*)(P) + tx * 16 + 8192), 16, 0, 0); } while (0)
; #define LDA(dst, b, h) _Pragma("unroll") for (int m = 0; m < 4; ++m) _Pragma("unroll") for (int k = 0; k < 2; ++k) \
;     dst[m][k] = *reinterpret_cast<const bf16x8*>((char*)shm + abase + (((b) * 2 + (h)) * 16384 + (m * 2 + k) * 1024))
; #define LDB(dst, b, h) _Pragma("unroll") for (int n = 0; n < 2; ++n) _Pragma("unroll") for (int k = 0; k < 2; ++k) \
;     dst[n][k] = *reinterpret_cast<const bf16x8*>((char*)shm + bbase + (((b) * 2 + (h)) * 16384 + (n * 2 + k) * 1024))
; template <bool SWAP>
; __device__ __forceinline__ void gemm_main(const u16* __restrict__ A, const u16* __restrict__ Bt, int brow, int bcol,
;                                           u16* shm, f32x4 (&acc)[2][2][4][2]) {
;     ...
;     BAR; WAIT_L(0); MMA(1, 0, At, B0); BAR; SCHED;
;     STAGE(SB(1, 1), Bt, bcol + HALF, t + 3);
;     WAIT_V(6); BAR; MMA(1, 1, At, B1); BAR;
;   }
;   { LDB(B0, 0, 0); LDA(At, 0, 0); STAGE(SA(1, 1), A, brow + HALF, nt - 1);
;     BAR; WAIT_L(0); MMA(0, 0, At, B0); BAR;
	s_waitcnt lgkmcnt(0)
	v_mfma_f32_16x16x32_bf16 v[60:63], v[156:159], v[172:175], v[60:63]
	v_mfma_f32_16x16x32_bf16 v[56:59], v[164:167], v[172:175], v[56:59]
	v_mfma_f32_16x16x32_bf16 v[52:55], v[156:159], v[180:183], v[52:55]
	v_mfma_f32_16x16x32_bf16 v[48:51], v[164:167], v[180:183], v[48:51]
	v_mfma_f32_16x16x32_bf16 v[44:47], v[156:159], v[188:191], v[44:47]
	v_mfma_f32_16x16x32_bf16 v[40:43], v[164:167], v[188:191], v[40:43]
	v_mfma_f32_16x16x32_bf16 v[36:39], v[156:159], v[196:199], v[36:39]
	v_mfma_f32_16x16x32_bf16 v[32:35], v[164:167], v[196:199], v[32:35]
	v_mfma_f32_16x16x32_bf16 v[60:63], v[160:163], v[176:179], v[60:63]
	v_mfma_f32_16x16x32_bf16 v[56:59], v[168:171], v[176:179], v[56:59]
	v_mfma_f32_16x16x32_bf16 v[52:55], v[160:163], v[184:187], v[52:55]
	v_mfma_f32_16x16x32_bf16 v[48:51], v[168:171], v[184:187], v[48:51]
	v_mfma_f32_16x16x32_bf16 v[44:47], v[160:163], v[192:195], v[44:47]
	v_mfma_f32_16x16x32_bf16 v[40:43], v[168:171], v[192:195], v[40:43]
	v_mfma_f32_16x16x32_bf16 v[36:39], v[160:163], v[200:203], v[36:39]
	v_mfma_f32_16x16x32_bf16 v[32:35], v[168:171], v[200:203], v[32:35]
	s_barrier
	ds_read_b128 v[156:159], v146
	ds_read_b128 v[160:163], v146 offset:1024
	ds_read_b128 v[164:167], v146 offset:2048
	ds_read_b128 v[168:171], v146 offset:3072
	s_add_u32 m0, s25, s53
	s_nop 0
	s_add_u32 vcc_lo, s28, s20
	s_addc_u32 vcc_hi, s29, s21
	global_load_lds_dwordx4 v134, vcc
	v_lshl_add_u64 v[254:255], v[228:229], 0, s[20:21]
	s_add_u32 m0, s25, s53
	s_add_u32 m0, m0, 0x2000
	s_nop 0
	global_load_lds_dwordx4 v130, vcc
	s_waitcnt vmcnt(6)
	s_barrier
	v_mfma_f32_16x16x32_bf16 v[28:31], v[204:207], v[172:175], v[28:31]
	v_mfma_f32_16x16x32_bf16 v[24:27], v[216:219], v[172:175], v[24:27]
	v_mfma_f32_16x16x32_bf16 v[20:23], v[204:207], v[180:183], v[20:23]
	v_mfma_f32_16x16x32_bf16 v[16:19], v[216:219], v[180:183], v[16:19]
	v_mfma_f32_16x16x32_bf16 v[12:15], v[204:207], v[188:191], v[12:15]
	v_mfma_f32_16x16x32_bf16 v[8:11], v[216:219], v[188:191], v[8:11]
	v_mfma_f32_16x16x32_bf16 v[4:7], v[204:207], v[196:199], v[4:7]
	v_mfma_f32_16x16x32_bf16 v[0:3], v[216:219], v[196:199], v[0:3]
	v_mfma_f32_16x16x32_bf16 v[28:31], v[212:215], v[176:179], v[28:31]
	ds_read_b128 v[172:175], v145
	v_mfma_f32_16x16x32_bf16 v[24:27], v[220:223], v[176:179], v[24:27]
	v_mfma_f32_16x16x32_bf16 v[20:23], v[212:215], v[184:187], v[20:23]
	ds_read_b128 v[180:183], v145 offset:2048
	v_mfma_f32_16x16x32_bf16 v[16:19], v[220:223], v[184:187], v[16:19]
	v_mfma_f32_16x16x32_bf16 v[12:15], v[212:215], v[192:195], v[12:15]
	ds_read_b128 v[188:191], v145 offset:4096
	v_mfma_f32_16x16x32_bf16 v[8:11], v[220:223], v[192:195], v[8:11]
	v_mfma_f32_16x16x32_bf16 v[4:7], v[212:215], v[200:203], v[4:7]
	ds_read_b128 v[196:199], v145 offset:6144
	v_mfma_f32_16x16x32_bf16 v[0:3], v[220:223], v[200:203], v[0:3]
	s_add_i32 s4, s4, 2
	s_add_u32 s28, s28, 0x100
	s_addc_u32 s29, s29, 0
	s_cmp_lt_u32 s4, 28
	s_barrier
	s_cbranch_scc1 .LBB0_94
	v_lshlrev_b32_e32 v128, 3, v148
	v_lshlrev_b32_e32 v130, 5, v148
	v_and_b32_e32 v128, 0xffff0, v128
	v_and_b32_e32 v130, 32, v130
	s_or_b32 s28, s26, 0x80
	v_add_u32_e32 v130, v130, v150
	v_add_lshl_u32 v128, v149, v128, 12
	s_ashr_i32 s29, s28, 31
	v_lshl_add_u32 v128, v130, 1, v128
	v_lshlrev_b32_e32 v130, 3, v151
	v_lshlrev_b32_e32 v131, 5, v151
	s_lshl_b64 s[28:29], s[28:29], 12
	v_and_b32_e32 v130, 0xffff0, v130
	v_and_b32_e32 v131, 32, v131
	s_add_u32 s28, s37, s28
	v_add_u32_e32 v131, v131, v153
	v_add_lshl_u32 v130, v152, v130, 12
	s_addc_u32 s29, s38, s29
	v_lshl_add_u32 v152, v131, 1, v130
	v_mov_b32_e32 v153, v129
	v_lshl_add_u64 v[192:193], s[28:29], 0, v[128:129]
	v_readfirstlane_b32 s4, v154
	v_lshl_add_u64 v[192:193], v[192:193], 0, s[22:23]
	s_mov_b32 m0, s4
	v_lshl_add_u64 v[152:153], s[28:29], 0, v[152:153]
	v_readfirstlane_b32 s4, v155
	ds_read_b128 v[130:133], v146
	ds_read_b128 v[134:137], v146 offset:1024
	ds_read_b128 v[148:151], v146 offset:2048
	ds_read_b128 v[156:159], v146 offset:3072
	ds_read_b128 v[160:163], v145
	ds_read_b128 v[164:167], v145 offset:1024
	ds_read_b128 v[168:171], v145 offset:2048
	ds_read_b128 v[172:175], v145 offset:3072
	ds_read_b128 v[176:179], v145 offset:4096
	ds_read_b128 v[180:183], v145 offset:5120
	ds_read_b128 v[184:187], v145 offset:6144
	ds_read_b128 v[188:191], v145 offset:7168
	global_load_lds_dwordx4 v[192:193], off
	v_lshl_add_u64 v[152:153], v[152:153], 0, s[22:23]
	s_mov_b32 m0, s4
	s_nop 0
	global_load_lds_dwordx4 v[152:153], off
	s_barrier
	s_waitcnt lgkmcnt(0)
	s_setprio 1
	s_waitcnt lgkmcnt(0)
	v_mfma_f32_16x16x32_bf16 v[124:127], v[130:133], v[160:163], v[124:127]
	v_mfma_f32_16x16x32_bf16 v[116:119], v[130:133], v[168:171], v[116:119]
	v_mfma_f32_16x16x32_bf16 v[108:111], v[130:133], v[176:179], v[108:111]
	v_mfma_f32_16x16x32_bf16 v[100:103], v[130:133], v[184:187], v[100:103]
	v_mfma_f32_16x16x32_bf16 v[124:127], v[134:137], v[164:167], v[124:127]
	v_mfma_f32_16x16x32_bf16 v[120:123], v[148:151], v[160:163], v[120:123]
	v_mfma_f32_16x16x32_bf16 v[116:119], v[134:137], v[172:175], v[116:119]
	v_mfma_f32_16x16x32_bf16 v[112:115], v[148:151], v[168:171], v[112:115]
	v_mfma_f32_16x16x32_bf16 v[108:111], v[134:137], v[180:183], v[108:111]
	v_mfma_f32_16x16x32_bf16 v[104:107], v[148:151], v[176:179], v[104:107]
	v_mfma_f32_16x16x32_bf16 v[100:103], v[134:137], v[188:191], v[100:103]
	v_mfma_f32_16x16x32_bf16 v[96:99], v[148:151], v[184:187], v[96:99]
	v_mfma_f32_16x16x32_bf16 v[152:155], v[156:159], v[164:167], v[120:123]
	v_mfma_f32_16x16x32_bf16 v[192:195], v[156:159], v[172:175], v[112:115]
	v_mfma_f32_16x16x32_bf16 v[196:199], v[156:159], v[180:183], v[104:107]
	v_mfma_f32_16x16x32_bf16 v[200:203], v[156:159], v[188:191], v[96:99]
	s_setprio 0
	s_barrier
; #define WAIT_V(n) asm volatile("s_waitcnt vmcnt(" #n ")" ::: "memory")
; #define WAIT_L(n) asm volatile("s_waitcnt lgkmcnt(" #n ")" ::: "memory")
; #define BAR __builtin_amdgcn_s_barrier()
; #define LDA(dst, b, h) _Pragma("unroll") for (int m = 0; m < 4; ++m) _Pragma("unroll") for (int k = 0; k < 2; ++k) \
;     dst[m][k] = *reinterpret_cast<const bf16x8*>((char*)shm + abase + (((b) * 2 + (h)) * 16384 + (m * 2 + k) * 1024))
; #define LDB(dst, b, h) _Pragma("unroll") for (int n = 0; n < 2; ++n) _Pragma("unroll") for (int k = 0; k < 2; ++k) \
;     dst[n][k] = *reinterpret_cast<const bf16x8*>((char*)shm + bbase + (((b) * 2 + (h)) * 16384 + (n * 2 + k) * 1024))
; template <bool SWAP>
; __device__ __forceinline__ void gemm_main(const u16* __restrict__ A, const u16* __restrict__ Bt, int brow, int bcol,
;                                           u16* shm, f32x4 (&acc)[2][2][4][2]) {
;     ...
;     LDB(B1, 0, 1); BAR; WAIT_L(0); MMA(0, 1, At, B1); BAR;
;     LDA(At, 0, 1); WAIT_V(4); BAR; WAIT_L(0); MMA(1, 0, At, B0); MMA(1, 1, At, B1); BAR; }
;   { LDB(B0, 1, 0); LDA(At, 1, 0); WAIT_V(2); BAR; WAIT_L(0); MMA(0, 0, At, B0); BAR;
	s_nop 1
	ds_read_b128 v[96:99], v146 offset:16384
	ds_read_b128 v[104:107], v146 offset:17408
	ds_read_b128 v[112:115], v146 offset:18432
	ds_read_b128 v[120:123], v146 offset:19456
	s_barrier
	s_waitcnt lgkmcnt(0)
	s_setprio 1
	s_waitcnt lgkmcnt(0)
	v_mfma_f32_16x16x32_bf16 v[92:95], v[96:99], v[160:163], v[92:95]
	v_mfma_f32_16x16x32_bf16 v[84:87], v[96:99], v[168:171], v[84:87]
	v_mfma_f32_16x16x32_bf16 v[76:79], v[96:99], v[176:179], v[76:79]
	v_mfma_f32_16x16x32_bf16 v[68:71], v[96:99], v[184:187], v[68:71]
	v_mfma_f32_16x16x32_bf16 v[92:95], v[104:107], v[164:167], v[92:95]
	v_mfma_f32_16x16x32_bf16 v[88:91], v[112:115], v[160:163], v[88:91]
	v_mfma_f32_16x16x32_bf16 v[84:87], v[104:107], v[172:175], v[84:87]
	v_mfma_f32_16x16x32_bf16 v[80:83], v[112:115], v[168:171], v[80:83]
	v_mfma_f32_16x16x32_bf16 v[76:79], v[104:107], v[180:183], v[76:79]
	v_mfma_f32_16x16x32_bf16 v[72:75], v[112:115], v[176:179], v[72:75]
	v_mfma_f32_16x16x32_bf16 v[68:71], v[104:107], v[188:191], v[68:71]
	v_mfma_f32_16x16x32_bf16 v[64:67], v[112:115], v[184:187], v[64:67]
	v_mfma_f32_16x16x32_bf16 v[160:163], v[120:123], v[164:167], v[88:91]
	v_mfma_f32_16x16x32_bf16 v[164:167], v[120:123], v[172:175], v[80:83]
	v_mfma_f32_16x16x32_bf16 v[168:171], v[120:123], v[180:183], v[72:75]
	v_mfma_f32_16x16x32_bf16 v[172:175], v[120:123], v[188:191], v[64:67]
	s_setprio 0
	s_barrier
	s_nop 1
	ds_read_b128 v[64:67], v145 offset:16384
	ds_read_b128 v[72:75], v145 offset:17408
	ds_read_b128 v[80:83], v145 offset:18432
	ds_read_b128 v[88:91], v145 offset:19456
	ds_read_b128 v[176:179], v145 offset:20480
	ds_read_b128 v[180:183], v145 offset:21504
	ds_read_b128 v[184:187], v145 offset:22528
	ds_read_b128 v[188:191], v145 offset:23552
	s_waitcnt vmcnt(4)
	s_barrier
	s_waitcnt lgkmcnt(0)
	s_setprio 1
	s_waitcnt lgkmcnt(0)
	v_mfma_f32_16x16x32_bf16 v[60:63], v[130:133], v[64:67], v[60:63]
	v_mfma_f32_16x16x32_bf16 v[52:55], v[130:133], v[80:83], v[52:55]
	v_mfma_f32_16x16x32_bf16 v[44:47], v[130:133], v[176:179], v[44:47]
	v_mfma_f32_16x16x32_bf16 v[36:39], v[130:133], v[184:187], v[36:39]
	v_mfma_f32_16x16x32_bf16 v[60:63], v[134:137], v[72:75], v[60:63]
	v_mfma_f32_16x16x32_bf16 v[56:59], v[148:151], v[64:67], v[56:59]
	v_mfma_f32_16x16x32_bf16 v[52:55], v[134:137], v[88:91], v[52:55]
	v_mfma_f32_16x16x32_bf16 v[48:51], v[148:151], v[80:83], v[48:51]
	v_mfma_f32_16x16x32_bf16 v[44:47], v[134:137], v[180:183], v[44:47]
	v_mfma_f32_16x16x32_bf16 v[40:43], v[148:151], v[176:179], v[40:43]
	v_mfma_f32_16x16x32_bf16 v[36:39], v[134:137], v[188:191], v[36:39]
	v_mfma_f32_16x16x32_bf16 v[32:35], v[148:151], v[184:187], v[32:35]
	v_mfma_f32_16x16x32_bf16 v[204:207], v[156:159], v[72:75], v[56:59]
	v_mfma_f32_16x16x32_bf16 v[212:215], v[156:159], v[88:91], v[48:51]
	v_mfma_f32_16x16x32_bf16 v[216:219], v[156:159], v[180:183], v[40:43]
	v_mfma_f32_16x16x32_bf16 v[130:133], v[156:159], v[188:191], v[32:35]
	s_setprio 0
	s_setprio 1
	v_mfma_f32_16x16x32_bf16 v[28:31], v[96:99], v[64:67], v[28:31]
	v_mfma_f32_16x16x32_bf16 v[20:23], v[96:99], v[80:83], v[20:23]
	v_mfma_f32_16x16x32_bf16 v[12:15], v[96:99], v[176:179], v[12:15]
	v_mfma_f32_16x16x32_bf16 v[4:7], v[96:99], v[184:187], v[4:7]
	v_mfma_f32_16x16x32_bf16 v[28:31], v[104:107], v[72:75], v[28:31]
	v_mfma_f32_16x16x32_bf16 v[24:27], v[112:115], v[64:67], v[24:27]
	v_mfma_f32_16x16x32_bf16 v[20:23], v[104:107], v[88:91], v[20:23]
	v_mfma_f32_16x16x32_bf16 v[16:19], v[112:115], v[80:83], v[16:19]
	v_mfma_f32_16x16x32_bf16 v[12:15], v[104:107], v[180:183], v[12:15]
	v_mfma_f32_16x16x32_bf16 v[8:11], v[112:115], v[176:179], v[8:11]
	v_mfma_f32_16x16x32_bf16 v[4:7], v[104:107], v[188:191], v[4:7]
	v_mfma_f32_16x16x32_bf16 v[0:3], v[112:115], v[184:187], v[0:3]
	v_mfma_f32_16x16x32_bf16 v[134:137], v[120:123], v[72:75], v[24:27]
	v_mfma_f32_16x16x32_bf16 v[148:151], v[120:123], v[88:91], v[16:19]
	v_mfma_f32_16x16x32_bf16 v[156:159], v[120:123], v[180:183], v[8:11]
	v_mfma_f32_16x16x32_bf16 v[176:179], v[120:123], v[188:191], v[0:3]
	s_setprio 0
	s_barrier
	s_nop 1
	ds_read_b128 v[0:3], v146 offset:32768
	ds_read_b128 v[8:11], v146 offset:33792
	ds_read_b128 v[16:19], v146 offset:34816
	ds_read_b128 v[24:27], v146 offset:35840
	ds_read_b128 v[32:35], v145 offset:32768
	ds_read_b128 v[40:43], v145 offset:33792
	ds_read_b128 v[48:51], v145 offset:34816
	ds_read_b128 v[56:59], v145 offset:35840
	ds_read_b128 v[64:67], v145 offset:36864
	ds_read_b128 v[180:183], v145 offset:37888
	ds_read_b128 v[184:187], v145 offset:38912
	ds_read_b128 v[188:191], v145 offset:39936
	s_waitcnt vmcnt(2)
	s_barrier
; #define WAIT_V(n) asm volatile("s_waitcnt vmcnt(" #n ")" ::: "memory")
; #define WAIT_L(n) asm volatile("s_waitcnt lgkmcnt(" #n ")" ::: "memory")
; #define BAR __builtin_amdgcn_s_barrier()
; #define LDA(dst, b, h) _Pragma("unroll") for (int m = 0; m < 4; ++m) _Pragma("unroll") for (int k = 0; k < 2; ++k) \
;     dst[m][k] = *reinterpret_cast<const bf16x8*>((char*)shm + abase + (((b) * 2 + (h)) * 16384 + (m * 2 + k) * 1024))
; #define LDB(dst, b, h) _Pragma("unroll") for (int n = 0; n < 2; ++n) _Pragma("unroll") for (int k = 0; k < 2; ++k) \
;     dst[n][k] = *reinterpret_cast<const bf16x8*>((char*)shm + bbase + (((b) * 2 + (h)) * 16384 + (n * 2 + k) * 1024))
; template <bool SWAP>
; __device__ __forceinline__ void gemm_main(const u16* __restrict__ A, const u16* __restrict__ Bt, int brow, int bcol,
;                                           u16* shm, f32x4 (&acc)[2][2][4][2]) {
;     ...
;   { LDB(B0, 1, 0); LDA(At, 1, 0); WAIT_V(2); BAR; WAIT_L(0); MMA(0, 0, At, B0); BAR;
;     LDB(B1, 1, 1); WAIT_V(0); BAR; WAIT_L(0); MMA(0, 1, At, B1); BAR;
;     LDA(At, 1, 1); BAR; WAIT_L(0); MMA(1, 0, At, B0); MMA(1, 1, At, B1); BAR; }
;   if (wr == 0) BAR;
	s_waitcnt lgkmcnt(0)
	s_setprio 1
	s_waitcnt lgkmcnt(0)
	v_mfma_f32_16x16x32_bf16 v[72:75], v[0:3], v[32:35], v[124:127]
	v_mfma_f32_16x16x32_bf16 v[120:123], v[8:11], v[40:43], v[72:75]
	v_mfma_f32_16x16x32_bf16 v[72:75], v[16:19], v[32:35], v[152:155]
	v_mfma_f32_16x16x32_bf16 v[124:127], v[24:27], v[40:43], v[72:75]
	v_mfma_f32_16x16x32_bf16 v[72:75], v[0:3], v[48:51], v[116:119]
	v_mfma_f32_16x16x32_bf16 v[112:115], v[8:11], v[56:59], v[72:75]
	v_mfma_f32_16x16x32_bf16 v[72:75], v[16:19], v[48:51], v[192:195]
	v_mfma_f32_16x16x32_bf16 v[116:119], v[24:27], v[56:59], v[72:75]
	v_mfma_f32_16x16x32_bf16 v[72:75], v[0:3], v[64:67], v[108:111]
	v_mfma_f32_16x16x32_bf16 v[104:107], v[8:11], v[180:183], v[72:75]
	v_mfma_f32_16x16x32_bf16 v[72:75], v[16:19], v[64:67], v[196:199]
	v_mfma_f32_16x16x32_bf16 v[108:111], v[24:27], v[180:183], v[72:75]
	v_mfma_f32_16x16x32_bf16 v[72:75], v[0:3], v[184:187], v[100:103]
	v_mfma_f32_16x16x32_bf16 v[96:99], v[8:11], v[188:191], v[72:75]
	v_mfma_f32_16x16x32_bf16 v[72:75], v[16:19], v[184:187], v[200:203]
	v_mfma_f32_16x16x32_bf16 v[100:103], v[24:27], v[188:191], v[72:75]
	s_setprio 0
	s_barrier
	ds_read_b128 v[152:155], v146 offset:49152
	ds_read_b128 v[192:195], v146 offset:50176
	ds_read_b128 v[196:199], v146 offset:51200
	ds_read_b128 v[200:203], v146 offset:52224
	s_waitcnt vmcnt(0)
	s_barrier
	s_waitcnt lgkmcnt(0)
	s_setprio 1
	s_waitcnt lgkmcnt(0)
	v_mfma_f32_16x16x32_bf16 v[72:75], v[152:155], v[32:35], v[92:95]
	v_mfma_f32_16x16x32_bf16 v[32:35], v[196:199], v[32:35], v[160:163]
	v_mfma_f32_16x16x32_bf16 v[92:95], v[200:203], v[40:43], v[32:35]
	v_mfma_f32_16x16x32_bf16 v[32:35], v[152:155], v[48:51], v[84:87]
	v_mfma_f32_16x16x32_bf16 v[80:83], v[192:195], v[56:59], v[32:35]
	v_mfma_f32_16x16x32_bf16 v[32:35], v[196:199], v[48:51], v[164:167]
	v_mfma_f32_16x16x32_bf16 v[84:87], v[200:203], v[56:59], v[32:35]
	v_mfma_f32_16x16x32_bf16 v[32:35], v[152:155], v[64:67], v[76:79]
	v_mfma_f32_16x16x32_bf16 v[88:91], v[192:195], v[40:43], v[72:75]
	v_mfma_f32_16x16x32_bf16 v[72:75], v[192:195], v[180:183], v[32:35]
	v_mfma_f32_16x16x32_bf16 v[32:35], v[196:199], v[64:67], v[168:171]
	v_mfma_f32_16x16x32_bf16 v[76:79], v[200:203], v[180:183], v[32:35]
	v_mfma_f32_16x16x32_bf16 v[32:35], v[152:155], v[184:187], v[68:71]
	v_mfma_f32_16x16x32_bf16 v[64:67], v[192:195], v[188:191], v[32:35]
	v_mfma_f32_16x16x32_bf16 v[32:35], v[196:199], v[184:187], v[172:175]
	v_mfma_f32_16x16x32_bf16 v[68:71], v[200:203], v[188:191], v[32:35]
	s_setprio 0
	s_barrier
	ds_read_b128 v[160:163], v145 offset:49152
	ds_read_b128 v[164:167], v145 offset:50176
	ds_read_b128 v[168:171], v145 offset:51200
	ds_read_b128 v[172:175], v145 offset:52224
	ds_read_b128 v[180:183], v145 offset:53248
	ds_read_b128 v[184:187], v145 offset:54272
	ds_read_b128 v[188:191], v145 offset:55296
	ds_read_b128 v[220:223], v145 offset:56320
	s_barrier
	s_waitcnt lgkmcnt(0)
	s_setprio 1
	s_waitcnt lgkmcnt(0)
	v_mfma_f32_16x16x32_bf16 v[32:35], v[0:3], v[160:163], v[60:63]
	v_mfma_f32_16x16x32_bf16 v[56:59], v[8:11], v[164:167], v[32:35]
	v_mfma_f32_16x16x32_bf16 v[32:35], v[16:19], v[160:163], v[204:207]
	v_mfma_f32_16x16x32_bf16 v[60:63], v[24:27], v[164:167], v[32:35]
	v_mfma_f32_16x16x32_bf16 v[32:35], v[0:3], v[168:171], v[52:55]
	v_mfma_f32_16x16x32_bf16 v[48:51], v[8:11], v[172:175], v[32:35]
	v_mfma_f32_16x16x32_bf16 v[32:35], v[16:19], v[168:171], v[212:215]
	v_mfma_f32_16x16x32_bf16 v[52:55], v[24:27], v[172:175], v[32:35]
	v_mfma_f32_16x16x32_bf16 v[32:35], v[0:3], v[180:183], v[44:47]
	v_mfma_f32_16x16x32_bf16 v[40:43], v[8:11], v[184:187], v[32:35]
	v_mfma_f32_16x16x32_bf16 v[32:35], v[16:19], v[180:183], v[216:219]
	v_mfma_f32_16x16x32_bf16 v[0:3], v[0:3], v[188:191], v[36:39]
	v_mfma_f32_16x16x32_bf16 v[44:47], v[24:27], v[184:187], v[32:35]
	v_mfma_f32_16x16x32_bf16 v[32:35], v[8:11], v[220:223], v[0:3]
	v_mfma_f32_16x16x32_bf16 v[0:3], v[16:19], v[188:191], v[130:133]
	v_mfma_f32_16x16x32_bf16 v[36:39], v[24:27], v[220:223], v[0:3]
	s_setprio 0
	s_setprio 1
	v_mfma_f32_16x16x32_bf16 v[0:3], v[152:155], v[160:163], v[28:31]
	v_mfma_f32_16x16x32_bf16 v[24:27], v[192:195], v[164:167], v[0:3]
	v_mfma_f32_16x16x32_bf16 v[0:3], v[196:199], v[160:163], v[134:137]
	v_mfma_f32_16x16x32_bf16 v[28:31], v[200:203], v[164:167], v[0:3]
	v_mfma_f32_16x16x32_bf16 v[0:3], v[152:155], v[168:171], v[20:23]
	v_mfma_f32_16x16x32_bf16 v[16:19], v[192:195], v[172:175], v[0:3]
	v_mfma_f32_16x16x32_bf16 v[0:3], v[196:199], v[168:171], v[148:151]
	v_mfma_f32_16x16x32_bf16 v[20:23], v[200:203], v[172:175], v[0:3]
	v_mfma_f32_16x16x32_bf16 v[0:3], v[152:155], v[180:183], v[12:15]
	v_mfma_f32_16x16x32_bf16 v[8:11], v[192:195], v[184:187], v[0:3]
	v_mfma_f32_16x16x32_bf16 v[0:3], v[196:199], v[180:183], v[156:159]
	v_mfma_f32_16x16x32_bf16 v[12:15], v[200:203], v[184:187], v[0:3]
	v_mfma_f32_16x16x32_bf16 v[0:3], v[152:155], v[188:191], v[4:7]
	v_mfma_f32_16x16x32_bf16 v[4:7], v[196:199], v[188:191], v[176:179]
	v_mfma_f32_16x16x32_bf16 v[0:3], v[192:195], v[220:223], v[0:3]
	v_mfma_f32_16x16x32_bf16 v[4:7], v[200:203], v[220:223], v[4:7]
	s_setprio 0
	v_cmp_gt_u32_e32 vcc, s55, v144
	s_barrier
	s_and_saveexec_b64 s[28:29], vcc
	s_cbranch_execz .LBB0_97
	s_barrier

; #define WAIT_V(n) asm volatile("s_waitcnt vmcnt(" #n ")" ::: "memory")
; #define WAIT_L(n) asm volatile("s_waitcnt lgkmcnt(" #n ")" ::: "memory")
; #define BAR __builtin_amdgcn_s_barrier()
; #define SCHED __builtin_amdgcn_sched_barrier(0)
; #define STAGE(P, BASE, br, kt) do { const char* _g = (const char*)((BASE) + (size_t)(br) * GK + (kt) * BK); \
;     __builtin_amdgcn_global_load_lds((const unsigned*)(_g + voff0), (unsigned*)((char*)(P) + tx * 16), 16, 0, 0); \
;     __builtin_amdgcn_global_load_lds((const unsigned*)(_g + voff1), (unsigned*)((char*)(P) + tx * 16 + 8192), 16, 0, 0); } while (0)
; #define LDA(dst, b, h) _Pragma("unroll") for (int m = 0; m < 4; ++m) _Pragma("unroll") for (int k = 0; k < 2; ++k) \
;     dst[m][k] = *reinterpret_cast<const bf16x8*>((char*)shm + abase + (((b) * 2 + (h)) * 16384 + (m * 2 + k) * 1024))
; #define LDB(dst, b, h) _Pragma("unroll") for (int n = 0; n < 2; ++n) _Pragma("unroll") for (int k = 0; k < 2; ++k) \
;     dst[n][k] = *reinterpret_cast<const bf16x8*>((char*)shm + bbase + (((b) * 2 + (h)) * 16384 + (n * 2 + k) * 1024))
; template <bool SWAP>
; __device__ __forceinline__ void gemm_main(const u16* __restrict__ A, const u16* __restrict__ Bt, int brow, int bcol,
;                                           u16* shm, f32x4 (&acc)[2][2][4][2]) {
;     ...
;   for (int t = 0; t < nt - 2; t += 2) {
;     LDB(B0, 0, 0); SCHED; LDA(At, 0, 0); STAGE(SA(1, 1), A, brow + HALF, t + 1);
;     WAIT_L(8); BAR; WAIT_L(0); MMA(0, 0, At, B0); BAR; SCHED;
;     LDB(B1, 0, 1); STAGE(SB(0, 0), Bt, bcol, t + 2);
;     BAR; WAIT_L(0); MMA(0, 1, At, B1); BAR;
;     LDA(At, 0, 1); STAGE(SA(0, 0), A, brow, t + 2);
;     BAR; WAIT_L(0); MMA(1, 0, At, B0); BAR; SCHED;
;     STAGE(SB(0, 1), Bt, bcol + HALF, t + 2);
;     WAIT_V(6); BAR; MMA(1, 1, At, B1); BAR;
;     LDB(B0, 1, 0); SCHED; LDA(At, 1, 0); STAGE(SA(0, 1), A, brow + HALF, t + 2);
.LBB0_114:
	ds_read_b128 v[182:185], v137 offset:1024
	ds_read_b128 v[194:197], v137 offset:3072
	ds_read_b128 v[202:205], v137 offset:5120
	ds_read_b128 v[222:225], v137 offset:7168
	v_add_u32_e32 v192, 0, v153
	v_add_u32_e32 v160, 0xc000, v192
	v_add_u32_e32 v161, 0xe000, v192
	s_add_u32 m0, s4, 0xc000
	v_lshl_add_u64 v[242:243], s[0:1], 0, v[134:135]
	s_add_u32 vcc_lo, s0, s82
	s_addc_u32 vcc_hi, s1, s83
	global_load_lds_dwordx4 v132, vcc
	s_add_u32 m0, s4, 0xe000
	s_nop 0
	global_load_lds_dwordx4 v134, vcc
	s_waitcnt lgkmcnt(8)
	s_barrier
	s_waitcnt lgkmcnt(0)
	v_mfma_f32_16x16x32_bf16 v[124:127], v[178:181], v[162:165], v[124:127]
	v_mfma_f32_16x16x32_bf16 v[120:123], v[178:181], v[170:173], v[120:123]
	v_mfma_f32_16x16x32_bf16 v[116:119], v[186:189], v[162:165], v[116:119]
	v_mfma_f32_16x16x32_bf16 v[112:115], v[186:189], v[170:173], v[112:115]
	v_mfma_f32_16x16x32_bf16 v[108:111], v[198:201], v[162:165], v[108:111]
	v_mfma_f32_16x16x32_bf16 v[104:107], v[198:201], v[170:173], v[104:107]
	v_mfma_f32_16x16x32_bf16 v[100:103], v[206:209], v[162:165], v[100:103]
	v_mfma_f32_16x16x32_bf16 v[96:99], v[206:209], v[170:173], v[96:99]
	v_mfma_f32_16x16x32_bf16 v[124:127], v[182:185], v[166:169], v[124:127]
	v_mfma_f32_16x16x32_bf16 v[120:123], v[182:185], v[174:177], v[120:123]
	v_mfma_f32_16x16x32_bf16 v[116:119], v[194:197], v[166:169], v[116:119]
	v_mfma_f32_16x16x32_bf16 v[112:115], v[194:197], v[174:177], v[112:115]
	v_mfma_f32_16x16x32_bf16 v[108:111], v[202:205], v[166:169], v[108:111]
	v_mfma_f32_16x16x32_bf16 v[104:107], v[202:205], v[174:177], v[104:107]
	v_mfma_f32_16x16x32_bf16 v[100:103], v[222:225], v[166:169], v[100:103]
	v_mfma_f32_16x16x32_bf16 v[96:99], v[222:225], v[174:177], v[96:99]
	s_barrier
	ds_read_b128 v[226:229], v152 offset:16384
	ds_read_b128 v[230:233], v152 offset:17408
	ds_read_b128 v[234:237], v152 offset:18432
	ds_read_b128 v[238:241], v152 offset:19456
	v_lshl_add_u64 v[244:245], s[0:1], 0, v[128:129]
	s_add_u32 m0, s4, s28
	s_nop 0
	s_add_u32 vcc_lo, s0, s74
	s_addc_u32 vcc_hi, s1, s75
	global_load_lds_dwordx4 v128, vcc
	v_lshl_add_u64 v[246:247], s[0:1], 0, v[130:131]
	s_add_u32 m0, s4, s28
	s_add_u32 m0, m0, 0x2000
	s_nop 0
	global_load_lds_dwordx4 v130, vcc
	s_barrier
	s_waitcnt lgkmcnt(0)
	v_mfma_f32_16x16x32_bf16 v[92:95], v[178:181], v[226:229], v[92:95]
	v_mfma_f32_16x16x32_bf16 v[88:91], v[178:181], v[234:237], v[88:91]
	v_mfma_f32_16x16x32_bf16 v[84:87], v[186:189], v[226:229], v[84:87]
	v_mfma_f32_16x16x32_bf16 v[80:83], v[186:189], v[234:237], v[80:83]
	v_mfma_f32_16x16x32_bf16 v[76:79], v[198:201], v[226:229], v[76:79]
	v_mfma_f32_16x16x32_bf16 v[72:75], v[198:201], v[234:237], v[72:75]
	v_mfma_f32_16x16x32_bf16 v[68:71], v[206:209], v[226:229], v[68:71]
	v_mfma_f32_16x16x32_bf16 v[64:67], v[206:209], v[234:237], v[64:67]
	v_mfma_f32_16x16x32_bf16 v[92:95], v[182:185], v[230:233], v[92:95]
	ds_read_b128 v[178:181], v137 offset:16384
	v_mfma_f32_16x16x32_bf16 v[88:91], v[182:185], v[238:241], v[88:91]
	v_mfma_f32_16x16x32_bf16 v[84:87], v[194:197], v[230:233], v[84:87]
	ds_read_b128 v[186:189], v137 offset:18432
	v_mfma_f32_16x16x32_bf16 v[80:83], v[194:197], v[238:241], v[80:83]
	v_mfma_f32_16x16x32_bf16 v[76:79], v[202:205], v[230:233], v[76:79]
	ds_read_b128 v[198:201], v137 offset:20480
	v_mfma_f32_16x16x32_bf16 v[72:75], v[202:205], v[238:241], v[72:75]
	v_mfma_f32_16x16x32_bf16 v[68:71], v[222:225], v[230:233], v[68:71]
	ds_read_b128 v[206:209], v137 offset:22528
	v_mfma_f32_16x16x32_bf16 v[64:67], v[222:225], v[238:241], v[64:67]
	s_barrier
	ds_read_b128 v[182:185], v137 offset:17408
	ds_read_b128 v[194:197], v137 offset:19456
	ds_read_b128 v[202:205], v137 offset:21504
	ds_read_b128 v[222:225], v137 offset:23552
	s_add_u32 m0, s4, 0x0
	s_nop 0
	s_add_u32 vcc_lo, s0, s76
	s_addc_u32 vcc_hi, s1, s77
	global_load_lds_dwordx4 v132, vcc
	s_add_u32 m0, s4, 0x2000
	s_nop 0
	global_load_lds_dwordx4 v134, vcc
	s_waitcnt vmcnt(8)
	s_barrier
	s_waitcnt lgkmcnt(0)
	v_mfma_f32_16x16x32_bf16 v[60:63], v[178:181], v[162:165], v[60:63]
	v_mfma_f32_16x16x32_bf16 v[56:59], v[178:181], v[170:173], v[56:59]
	v_mfma_f32_16x16x32_bf16 v[52:55], v[186:189], v[162:165], v[52:55]
	v_mfma_f32_16x16x32_bf16 v[48:51], v[186:189], v[170:173], v[48:51]
	v_mfma_f32_16x16x32_bf16 v[44:47], v[198:201], v[162:165], v[44:47]
	v_mfma_f32_16x16x32_bf16 v[40:43], v[198:201], v[170:173], v[40:43]
	v_mfma_f32_16x16x32_bf16 v[36:39], v[206:209], v[162:165], v[36:39]
	v_mfma_f32_16x16x32_bf16 v[32:35], v[206:209], v[170:173], v[32:35]
	v_mfma_f32_16x16x32_bf16 v[60:63], v[182:185], v[166:169], v[60:63]
	v_mfma_f32_16x16x32_bf16 v[56:59], v[182:185], v[174:177], v[56:59]
	v_mfma_f32_16x16x32_bf16 v[52:55], v[194:197], v[166:169], v[52:55]
	v_mfma_f32_16x16x32_bf16 v[48:51], v[194:197], v[174:177], v[48:51]
	v_mfma_f32_16x16x32_bf16 v[44:47], v[202:205], v[166:169], v[44:47]
	v_mfma_f32_16x16x32_bf16 v[40:43], v[202:205], v[174:177], v[40:43]
	v_mfma_f32_16x16x32_bf16 v[36:39], v[222:225], v[166:169], v[36:39]
	v_mfma_f32_16x16x32_bf16 v[32:35], v[222:225], v[174:177], v[32:35]
	s_barrier
	ds_read_b128 v[162:165], v152 offset:32768
	ds_read_b128 v[166:169], v152 offset:33792
	ds_read_b128 v[170:173], v152 offset:34816
	ds_read_b128 v[174:177], v152 offset:35840
	s_add_u32 m0, s4, s29
	s_nop 0
	s_add_u32 vcc_lo, s0, s70
	s_addc_u32 vcc_hi, s1, s71
	global_load_lds_dwordx4 v128, vcc
	s_add_u32 m0, s4, s29
	s_add_u32 m0, m0, 0x2000
	s_nop 0
	global_load_lds_dwordx4 v130, vcc
	s_waitcnt vmcnt(6)
	s_barrier
; #define WAIT_V(n) asm volatile("s_waitcnt vmcnt(" #n ")" ::: "memory")
; #define WAIT_L(n) asm volatile("s_waitcnt lgkmcnt(" #n ")" ::: "memory")
; #define BAR __builtin_amdgcn_s_barrier()
; #define SCHED __builtin_amdgcn_sched_barrier(0)
; #define STAGE(P, BASE, br, kt) do { const char* _g = (const char*)((BASE) + (size_t)(br) * GK + (kt) * BK); \
;     __builtin_amdgcn_global_load_lds((const unsigned*)(_g + voff0), (unsigned*)((char*)(P) + tx * 16), 16, 0, 0); \
;     __builtin_amdgcn_global_load_lds((const unsigned*)(_g + voff1), (unsigned*)((char*)(P) + tx * 16 + 8192), 16, 0, 0); } while (0)
; #define LDA(dst, b, h) _Pragma("unroll") for (int m = 0; m < 4; ++m) _Pragma("unroll") for (int k = 0; k < 2; ++k) \
;     dst[m][k] = *reinterpret_cast<const bf16x8*>((char*)shm + abase + (((b) * 2 + (h)) * 16384 + (m * 2 + k) * 1024))
; #define LDB(dst, b, h) _Pragma("unroll") for (int n = 0; n < 2; ++n) _Pragma("unroll") for (int k = 0; k < 2; ++k) \
;     dst[n][k] = *reinterpret_cast<const bf16x8*>((char*)shm + bbase + (((b) * 2 + (h)) * 16384 + (n * 2 + k) * 1024))
; template <bool SWAP>
; __device__ __forceinline__ void gemm_main(const u16* __restrict__ A, const u16* __restrict__ Bt, int brow, int bcol,
;                                           u16* shm, f32x4 (&acc)[2][2][4][2]) {
;     ...
;     WAIT_V(6); BAR; MMA(1, 1, At, B1); BAR;
;     LDB(B0, 1, 0); SCHED; LDA(At, 1, 0); STAGE(SA(0, 1), A, brow + HALF, t + 2);
;     WAIT_L(8); BAR; WAIT_L(0); MMA(0, 0, At, B0); BAR; SCHED;
;     LDB(B1, 1, 1); STAGE(SB(1, 0), Bt, bcol, t + 3);
;     BAR; WAIT_L(0); MMA(0, 1, At, B1); BAR;
;     LDA(At, 1, 1); STAGE(SA(1, 0), A, brow, t + 3);
;     BAR; WAIT_L(0); MMA(1, 0, At, B0); BAR; SCHED;
	v_mfma_f32_16x16x32_bf16 v[28:31], v[178:181], v[226:229], v[28:31]
	v_mfma_f32_16x16x32_bf16 v[24:27], v[178:181], v[234:237], v[24:27]
	v_mfma_f32_16x16x32_bf16 v[20:23], v[186:189], v[226:229], v[20:23]
	v_mfma_f32_16x16x32_bf16 v[16:19], v[186:189], v[234:237], v[16:19]
	v_mfma_f32_16x16x32_bf16 v[12:15], v[198:201], v[226:229], v[12:15]
	v_mfma_f32_16x16x32_bf16 v[8:11], v[198:201], v[234:237], v[8:11]
	v_mfma_f32_16x16x32_bf16 v[4:7], v[206:209], v[226:229], v[4:7]
	v_mfma_f32_16x16x32_bf16 v[0:3], v[206:209], v[234:237], v[0:3]
	v_mfma_f32_16x16x32_bf16 v[28:31], v[182:185], v[230:233], v[28:31]
	ds_read_b128 v[178:181], v137 offset:32768
	v_mfma_f32_16x16x32_bf16 v[24:27], v[182:185], v[238:241], v[24:27]
	v_mfma_f32_16x16x32_bf16 v[20:23], v[194:197], v[230:233], v[20:23]
	ds_read_b128 v[186:189], v137 offset:34816
	v_mfma_f32_16x16x32_bf16 v[16:19], v[194:197], v[238:241], v[16:19]
	v_mfma_f32_16x16x32_bf16 v[12:15], v[202:205], v[230:233], v[12:15]
	ds_read_b128 v[198:201], v137 offset:36864
	v_mfma_f32_16x16x32_bf16 v[8:11], v[202:205], v[238:241], v[8:11]
	v_mfma_f32_16x16x32_bf16 v[4:7], v[222:225], v[230:233], v[4:7]
	ds_read_b128 v[206:209], v137 offset:38912
	v_mfma_f32_16x16x32_bf16 v[0:3], v[222:225], v[238:241], v[0:3]
	s_barrier
	ds_read_b128 v[182:185], v137 offset:33792
	ds_read_b128 v[194:197], v137 offset:35840
	ds_read_b128 v[202:205], v137 offset:37888
	ds_read_b128 v[222:225], v137 offset:39936
	s_add_u32 m0, s4, 0x4000
	s_nop 0
	s_add_u32 vcc_lo, s0, s96
	s_addc_u32 vcc_hi, s1, s97
	global_load_lds_dwordx4 v132, vcc
	s_add_u32 m0, s4, 0x6000
	s_nop 0
	global_load_lds_dwordx4 v134, vcc
	s_waitcnt lgkmcnt(8)
	s_barrier
	s_waitcnt lgkmcnt(0)
	v_mfma_f32_16x16x32_bf16 v[124:127], v[178:181], v[162:165], v[124:127]
	v_mfma_f32_16x16x32_bf16 v[120:123], v[178:181], v[170:173], v[120:123]
	v_mfma_f32_16x16x32_bf16 v[116:119], v[186:189], v[162:165], v[116:119]
	v_mfma_f32_16x16x32_bf16 v[112:115], v[186:189], v[170:173], v[112:115]
	v_mfma_f32_16x16x32_bf16 v[108:111], v[198:201], v[162:165], v[108:111]
	v_mfma_f32_16x16x32_bf16 v[104:107], v[198:201], v[170:173], v[104:107]
	v_mfma_f32_16x16x32_bf16 v[100:103], v[206:209], v[162:165], v[100:103]
	v_mfma_f32_16x16x32_bf16 v[96:99], v[206:209], v[170:173], v[96:99]
	v_mfma_f32_16x16x32_bf16 v[124:127], v[182:185], v[166:169], v[124:127]
	v_mfma_f32_16x16x32_bf16 v[120:123], v[182:185], v[174:177], v[120:123]
	v_mfma_f32_16x16x32_bf16 v[116:119], v[194:197], v[166:169], v[116:119]
	v_mfma_f32_16x16x32_bf16 v[112:115], v[194:197], v[174:177], v[112:115]
	v_mfma_f32_16x16x32_bf16 v[108:111], v[202:205], v[166:169], v[108:111]
	v_mfma_f32_16x16x32_bf16 v[104:107], v[202:205], v[174:177], v[104:107]
	v_mfma_f32_16x16x32_bf16 v[100:103], v[222:225], v[166:169], v[100:103]
	v_mfma_f32_16x16x32_bf16 v[96:99], v[222:225], v[174:177], v[96:99]
	s_barrier
	ds_read_b128 v[226:229], v152 offset:49152
	ds_read_b128 v[230:233], v152 offset:50176
	ds_read_b128 v[234:237], v152 offset:51200
	ds_read_b128 v[238:241], v152 offset:52224
	v_add_u32_e32 v250, s30, v153
	v_add_u32_e32 v250, 0x2000, v250
	s_add_u32 m0, s4, s30
	s_nop 0
	s_add_u32 vcc_lo, s0, s34
	s_addc_u32 vcc_hi, s1, s35
	global_load_lds_dwordx4 v128, vcc
	v_lshl_add_u64 v[248:249], v[246:247], 0, s[34:35]
	s_add_u32 m0, s4, s30
	s_add_u32 m0, m0, 0x2000
	s_nop 0
	global_load_lds_dwordx4 v130, vcc
	s_barrier
	s_waitcnt lgkmcnt(0)
	v_mfma_f32_16x16x32_bf16 v[92:95], v[178:181], v[226:229], v[92:95]
	v_mfma_f32_16x16x32_bf16 v[88:91], v[178:181], v[234:237], v[88:91]
	v_mfma_f32_16x16x32_bf16 v[84:87], v[186:189], v[226:229], v[84:87]
	v_mfma_f32_16x16x32_bf16 v[80:83], v[186:189], v[234:237], v[80:83]
	v_mfma_f32_16x16x32_bf16 v[76:79], v[198:201], v[226:229], v[76:79]
	v_mfma_f32_16x16x32_bf16 v[72:75], v[198:201], v[234:237], v[72:75]
	v_mfma_f32_16x16x32_bf16 v[68:71], v[206:209], v[226:229], v[68:71]
	v_mfma_f32_16x16x32_bf16 v[64:67], v[206:209], v[234:237], v[64:67]
	v_mfma_f32_16x16x32_bf16 v[92:95], v[182:185], v[230:233], v[92:95]
	ds_read_b128 v[178:181], v137 offset:49152
	v_mfma_f32_16x16x32_bf16 v[88:91], v[182:185], v[238:241], v[88:91]
	v_mfma_f32_16x16x32_bf16 v[84:87], v[194:197], v[230:233], v[84:87]
	ds_read_b128 v[186:189], v137 offset:51200
	v_mfma_f32_16x16x32_bf16 v[80:83], v[194:197], v[238:241], v[80:83]
	v_mfma_f32_16x16x32_bf16 v[76:79], v[202:205], v[230:233], v[76:79]
	ds_read_b128 v[198:201], v137 offset:53248
	v_mfma_f32_16x16x32_bf16 v[72:75], v[202:205], v[238:241], v[72:75]
	v_mfma_f32_16x16x32_bf16 v[68:71], v[222:225], v[230:233], v[68:71]
	ds_read_b128 v[206:209], v137 offset:55296
	v_mfma_f32_16x16x32_bf16 v[64:67], v[222:225], v[238:241], v[64:67]
	s_barrier
	ds_read_b128 v[182:185], v137 offset:50176
	ds_read_b128 v[194:197], v137 offset:52224
	ds_read_b128 v[202:205], v137 offset:54272
	ds_read_b128 v[222:225], v137 offset:56320
	v_add_u32_e32 v248, 0x8000, v192
	s_add_u32 m0, s4, 0x8000
	s_nop 0
	s_add_u32 vcc_lo, s0, s36
	s_addc_u32 vcc_hi, s1, s37
	global_load_lds_dwordx4 v132, vcc
	s_add_u32 m0, s4, 0xa000
	s_nop 0
	global_load_lds_dwordx4 v134, vcc
	s_waitcnt vmcnt(8)
	s_barrier
; #define WAIT_V(n) asm volatile("s_waitcnt vmcnt(" #n ")" ::: "memory")
; #define WAIT_L(n) asm volatile("s_waitcnt lgkmcnt(" #n ")" ::: "memory")
; #define BAR __builtin_amdgcn_s_barrier()
; #define SCHED __builtin_amdgcn_sched_barrier(0)
; #define STAGE(P, BASE, br, kt) do { const char* _g = (const char*)((BASE) + (size_t)(br) * GK + (kt) * BK); \
;     __builtin_amdgcn_global_load_lds((const unsigned*)(_g + voff0), (unsigned*)((char*)(P) + tx * 16), 16, 0, 0); \
;     __builtin_amdgcn_global_load_lds((const unsigned*)(_g + voff1), (unsigned*)((char*)(P) + tx * 16 + 8192), 16, 0, 0); } while (0)
; #define LDA(dst, b, h) _Pragma("unroll") for (int m = 0; m < 4; ++m) _Pragma("unroll") for (int k = 0; k < 2; ++k) \
;     dst[m][k] = *reinterpret_cast<const bf16x8*>((char*)shm + abase + (((b) * 2 + (h)) * 16384 + (m * 2 + k) * 1024))
; #define LDB(dst, b, h) _Pragma("unroll") for (int n = 0; n < 2; ++n) _Pragma("unroll") for (int k = 0; k < 2; ++k) \
;     dst[n][k] = *reinterpret_cast<const bf16x8*>((char*)shm + bbase + (((b) * 2 + (h)) * 16384 + (n * 2 + k) * 1024))
; template <bool SWAP>
; __device__ __forceinline__ void gemm_main(const u16* __restrict__ A, const u16* __restrict__ Bt, int brow, int bcol,
;                                           u16* shm, f32x4 (&acc)[2][2][4][2]) {
;     ...
;     BAR; WAIT_L(0); MMA(1, 0, At, B0); BAR; SCHED;
;     STAGE(SB(1, 1), Bt, bcol + HALF, t + 3);
;     WAIT_V(6); BAR; MMA(1, 1, At, B1); BAR;
;   }
;   { LDB(B0, 0, 0); LDA(At, 0, 0); STAGE(SA(1, 1), A, brow + HALF, nt - 1);
;     BAR; WAIT_L(0); MMA(0, 0, At, B0); BAR;
; __device__ __forceinline__ void phase_inproj1(const Params& p, char* smem) {
;     ...
;       gemm_main<false>(A, Bt, brow, nt * 256, (u16*)smem, acc);
;       if (nt < 16) {
	s_waitcnt lgkmcnt(0)
	v_mfma_f32_16x16x32_bf16 v[60:63], v[178:181], v[162:165], v[60:63]
	v_mfma_f32_16x16x32_bf16 v[56:59], v[178:181], v[170:173], v[56:59]
	v_mfma_f32_16x16x32_bf16 v[52:55], v[186:189], v[162:165], v[52:55]
	v_mfma_f32_16x16x32_bf16 v[48:51], v[186:189], v[170:173], v[48:51]
	v_mfma_f32_16x16x32_bf16 v[44:47], v[198:201], v[162:165], v[44:47]
	v_mfma_f32_16x16x32_bf16 v[40:43], v[198:201], v[170:173], v[40:43]
	v_mfma_f32_16x16x32_bf16 v[36:39], v[206:209], v[162:165], v[36:39]
	v_mfma_f32_16x16x32_bf16 v[32:35], v[206:209], v[170:173], v[32:35]
	v_mfma_f32_16x16x32_bf16 v[60:63], v[182:185], v[166:169], v[60:63]
	v_mfma_f32_16x16x32_bf16 v[56:59], v[182:185], v[174:177], v[56:59]
	v_mfma_f32_16x16x32_bf16 v[52:55], v[194:197], v[166:169], v[52:55]
	v_mfma_f32_16x16x32_bf16 v[48:51], v[194:197], v[174:177], v[48:51]
	v_mfma_f32_16x16x32_bf16 v[44:47], v[202:205], v[166:169], v[44:47]
	v_mfma_f32_16x16x32_bf16 v[40:43], v[202:205], v[174:177], v[40:43]
	v_mfma_f32_16x16x32_bf16 v[36:39], v[222:225], v[166:169], v[36:39]
	v_mfma_f32_16x16x32_bf16 v[32:35], v[222:225], v[174:177], v[32:35]
	s_barrier
	ds_read_b128 v[162:165], v152
	ds_read_b128 v[166:169], v152 offset:1024
	ds_read_b128 v[170:173], v152 offset:2048
	ds_read_b128 v[174:177], v152 offset:3072
	s_add_u32 m0, s4, s31
	s_nop 0
	s_add_u32 vcc_lo, s0, s64
	s_addc_u32 vcc_hi, s1, s65
	global_load_lds_dwordx4 v128, vcc
	v_lshl_add_u64 v[254:255], v[246:247], 0, s[64:65]
	s_add_u32 m0, s4, s31
	s_add_u32 m0, m0, 0x2000
	s_nop 0
	global_load_lds_dwordx4 v130, vcc
	s_waitcnt vmcnt(6)
	s_barrier
	v_mfma_f32_16x16x32_bf16 v[28:31], v[178:181], v[226:229], v[28:31]
	v_mfma_f32_16x16x32_bf16 v[24:27], v[178:181], v[234:237], v[24:27]
	v_mfma_f32_16x16x32_bf16 v[20:23], v[186:189], v[226:229], v[20:23]
	v_mfma_f32_16x16x32_bf16 v[16:19], v[186:189], v[234:237], v[16:19]
	v_mfma_f32_16x16x32_bf16 v[12:15], v[198:201], v[226:229], v[12:15]
	v_mfma_f32_16x16x32_bf16 v[8:11], v[198:201], v[234:237], v[8:11]
	v_mfma_f32_16x16x32_bf16 v[4:7], v[206:209], v[226:229], v[4:7]
	v_mfma_f32_16x16x32_bf16 v[0:3], v[206:209], v[234:237], v[0:3]
	v_mfma_f32_16x16x32_bf16 v[28:31], v[182:185], v[230:233], v[28:31]
	ds_read_b128 v[178:181], v137
	v_mfma_f32_16x16x32_bf16 v[24:27], v[182:185], v[238:241], v[24:27]
	v_mfma_f32_16x16x32_bf16 v[20:23], v[194:197], v[230:233], v[20:23]
	ds_read_b128 v[186:189], v137 offset:2048
	v_mfma_f32_16x16x32_bf16 v[16:19], v[194:197], v[238:241], v[16:19]
	v_mfma_f32_16x16x32_bf16 v[12:15], v[202:205], v[230:233], v[12:15]
	ds_read_b128 v[198:201], v137 offset:4096
	v_mfma_f32_16x16x32_bf16 v[8:11], v[202:205], v[238:241], v[8:11]
	v_mfma_f32_16x16x32_bf16 v[4:7], v[222:225], v[230:233], v[4:7]
	ds_read_b128 v[206:209], v137 offset:6144
	v_mfma_f32_16x16x32_bf16 v[0:3], v[222:225], v[238:241], v[0:3]
	s_add_i32 s3, s3, 2
	s_add_u32 s0, s0, 0x100
	s_addc_u32 s1, s1, 0
	s_cmp_lt_u32 s3, 28
	s_barrier
	s_cbranch_scc1 .LBB0_114
	v_lshlrev_b32_e32 v128, 3, v154
	v_lshlrev_b32_e32 v129, 5, v154
	v_and_b32_e32 v128, 0xffff0, v128
	v_and_b32_e32 v129, 32, v129
	s_or_b32 s0, s24, 0x80
	v_add_u32_e32 v129, v129, v156
	v_add_lshl_u32 v128, v155, v128, 12
	s_ashr_i32 s1, s0, 31
	v_lshl_add_u32 v192, v129, 1, v128
	v_lshlrev_b32_e32 v128, 3, v157
	v_lshlrev_b32_e32 v129, 5, v157
	s_mov_b32 s22, s0
	s_lshl_b64 s[0:1], s[0:1], 12
	v_readlane_b32 s4, v253, 35
	v_and_b32_e32 v128, 0xffff0, v128
	v_and_b32_e32 v129, 32, v129
	v_readlane_b32 s5, v253, 36
	s_add_u32 s0, s4, s0
	v_add_u32_e32 v129, v129, v159
	v_add_lshl_u32 v128, v158, v128, 12
	s_addc_u32 s1, s5, s1
	v_lshl_add_u32 v158, v129, 1, v128
	v_mov_b32_e32 v159, v193
	v_lshl_add_u64 v[190:191], s[0:1], 0, v[192:193]
	s_mov_b64 s[4:5], 0xf80
	v_readfirstlane_b32 s3, v160
	v_lshl_add_u64 v[190:191], v[190:191], 0, s[4:5]
	s_mov_b32 m0, s3
	v_lshl_add_u64 v[158:159], s[0:1], 0, v[158:159]
	v_readfirstlane_b32 s0, v161
	ds_read_b128 v[128:131], v152
	ds_read_b128 v[132:135], v152 offset:1024
	ds_read_b128 v[154:157], v152 offset:2048
	ds_read_b128 v[162:165], v152 offset:3072
	ds_read_b128 v[166:169], v137
	ds_read_b128 v[170:173], v137 offset:1024
	ds_read_b128 v[174:177], v137 offset:2048
	ds_read_b128 v[178:181], v137 offset:3072
	ds_read_b128 v[182:185], v137 offset:4096
	ds_read_b128 v[186:189], v137 offset:5120
	ds_read_b128 v[194:197], v137 offset:6144
	ds_read_b128 v[198:201], v137 offset:7168
	global_load_lds_dwordx4 v[190:191], off
	v_lshl_add_u64 v[158:159], v[158:159], 0, s[4:5]
	s_mov_b32 m0, s0
	s_nop 0
	global_load_lds_dwordx4 v[158:159], off
	s_barrier
	s_waitcnt lgkmcnt(0)
	s_setprio 1
	s_waitcnt lgkmcnt(0)
	v_mfma_f32_16x16x32_bf16 v[124:127], v[166:169], v[128:131], v[124:127]
	v_mfma_f32_16x16x32_bf16 v[120:123], v[166:169], v[154:157], v[120:123]
	v_mfma_f32_16x16x32_bf16 v[116:119], v[174:177], v[128:131], v[116:119]
	v_mfma_f32_16x16x32_bf16 v[112:115], v[174:177], v[154:157], v[112:115]
	v_mfma_f32_16x16x32_bf16 v[108:111], v[182:185], v[128:131], v[108:111]
	v_mfma_f32_16x16x32_bf16 v[104:107], v[182:185], v[154:157], v[104:107]
	v_mfma_f32_16x16x32_bf16 v[100:103], v[194:197], v[128:131], v[100:103]
	v_mfma_f32_16x16x32_bf16 v[96:99], v[194:197], v[154:157], v[96:99]
	v_mfma_f32_16x16x32_bf16 v[124:127], v[170:173], v[132:135], v[124:127]
	v_mfma_f32_16x16x32_bf16 v[120:123], v[170:173], v[162:165], v[120:123]
	v_mfma_f32_16x16x32_bf16 v[116:119], v[178:181], v[132:135], v[116:119]
	v_mfma_f32_16x16x32_bf16 v[112:115], v[178:181], v[162:165], v[112:115]
	v_mfma_f32_16x16x32_bf16 v[108:111], v[186:189], v[132:135], v[108:111]
	v_mfma_f32_16x16x32_bf16 v[104:107], v[186:189], v[162:165], v[104:107]
	v_mfma_f32_16x16x32_bf16 v[100:103], v[198:201], v[132:135], v[100:103]
	v_mfma_f32_16x16x32_bf16 v[96:99], v[198:201], v[162:165], v[96:99]
	s_setprio 0
	s_barrier
; #define WAIT_V(n) asm volatile("s_waitcnt vmcnt(" #n ")" ::: "memory")
; #define WAIT_L(n) asm volatile("s_waitcnt lgkmcnt(" #n ")" ::: "memory")
; #define BAR __builtin_amdgcn_s_barrier()
; #define LDA(dst, b, h) _Pragma("unroll") for (int m = 0; m < 4; ++m) _Pragma("unroll") for (int k = 0; k < 2; ++k) \
;     dst[m][k] = *reinterpret_cast<const bf16x8*>((char*)shm + abase + (((b) * 2 + (h)) * 16384 + (m * 2 + k) * 1024))
; #define LDB(dst, b, h) _Pragma("unroll") for (int n = 0; n < 2; ++n) _Pragma("unroll") for (int k = 0; k < 2; ++k) \
;     dst[n][k] = *reinterpret_cast<const bf16x8*>((char*)shm + bbase + (((b) * 2 + (h)) * 16384 + (n * 2 + k) * 1024))
; template <bool SWAP>
; __device__ __forceinline__ void gemm_main(const u16* __restrict__ A, const u16* __restrict__ Bt, int brow, int bcol,
;                                           u16* shm, f32x4 (&acc)[2][2][4][2]) {
;     ...
;     LDB(B1, 0, 1); BAR; WAIT_L(0); MMA(0, 1, At, B1); BAR;
;     LDA(At, 0, 1); WAIT_V(4); BAR; WAIT_L(0); MMA(1, 0, At, B0); MMA(1, 1, At, B1); BAR; }
;   { LDB(B0, 1, 0); LDA(At, 1, 0); WAIT_V(2); BAR; WAIT_L(0); MMA(0, 0, At, B0); BAR;
	ds_read_b128 v[158:161], v152 offset:16384
	ds_read_b128 v[202:205], v152 offset:17408
	ds_read_b128 v[206:209], v152 offset:18432
	ds_read_b128 v[222:225], v152 offset:19456
	s_barrier
	s_waitcnt lgkmcnt(0)
	s_setprio 1
	s_waitcnt lgkmcnt(0)
	v_mfma_f32_16x16x32_bf16 v[92:95], v[166:169], v[158:161], v[92:95]
	v_mfma_f32_16x16x32_bf16 v[88:91], v[166:169], v[206:209], v[88:91]
	v_mfma_f32_16x16x32_bf16 v[84:87], v[174:177], v[158:161], v[84:87]
	v_mfma_f32_16x16x32_bf16 v[80:83], v[174:177], v[206:209], v[80:83]
	v_mfma_f32_16x16x32_bf16 v[76:79], v[182:185], v[158:161], v[76:79]
	v_mfma_f32_16x16x32_bf16 v[72:75], v[182:185], v[206:209], v[72:75]
	v_mfma_f32_16x16x32_bf16 v[68:71], v[194:197], v[158:161], v[68:71]
	v_mfma_f32_16x16x32_bf16 v[64:67], v[194:197], v[206:209], v[64:67]
	v_mfma_f32_16x16x32_bf16 v[92:95], v[170:173], v[202:205], v[92:95]
	v_mfma_f32_16x16x32_bf16 v[88:91], v[170:173], v[222:225], v[88:91]
	v_mfma_f32_16x16x32_bf16 v[84:87], v[178:181], v[202:205], v[84:87]
	v_mfma_f32_16x16x32_bf16 v[80:83], v[178:181], v[222:225], v[80:83]
	v_mfma_f32_16x16x32_bf16 v[76:79], v[186:189], v[202:205], v[76:79]
	v_mfma_f32_16x16x32_bf16 v[72:75], v[186:189], v[222:225], v[72:75]
	v_mfma_f32_16x16x32_bf16 v[68:71], v[198:201], v[202:205], v[68:71]
	v_mfma_f32_16x16x32_bf16 v[64:67], v[198:201], v[222:225], v[64:67]
	s_setprio 0
	s_barrier
	ds_read_b128 v[166:169], v137 offset:16384
	ds_read_b128 v[170:173], v137 offset:17408
	ds_read_b128 v[174:177], v137 offset:18432
	ds_read_b128 v[178:181], v137 offset:19456
	ds_read_b128 v[182:185], v137 offset:20480
	ds_read_b128 v[186:189], v137 offset:21504
	ds_read_b128 v[194:197], v137 offset:22528
	ds_read_b128 v[198:201], v137 offset:23552
	s_waitcnt vmcnt(4)
	s_barrier
	s_waitcnt lgkmcnt(0)
	s_setprio 1
	s_waitcnt lgkmcnt(0)
	v_mfma_f32_16x16x32_bf16 v[60:63], v[166:169], v[128:131], v[60:63]
	v_mfma_f32_16x16x32_bf16 v[56:59], v[166:169], v[154:157], v[56:59]
	v_mfma_f32_16x16x32_bf16 v[52:55], v[174:177], v[128:131], v[52:55]
	v_mfma_f32_16x16x32_bf16 v[48:51], v[174:177], v[154:157], v[48:51]
	v_mfma_f32_16x16x32_bf16 v[44:47], v[182:185], v[128:131], v[44:47]
	v_mfma_f32_16x16x32_bf16 v[40:43], v[182:185], v[154:157], v[40:43]
	v_mfma_f32_16x16x32_bf16 v[36:39], v[194:197], v[128:131], v[36:39]
	v_mfma_f32_16x16x32_bf16 v[32:35], v[194:197], v[154:157], v[32:35]
	v_mfma_f32_16x16x32_bf16 v[60:63], v[170:173], v[132:135], v[60:63]
	v_mfma_f32_16x16x32_bf16 v[56:59], v[170:173], v[162:165], v[56:59]
	v_mfma_f32_16x16x32_bf16 v[52:55], v[178:181], v[132:135], v[52:55]
	v_mfma_f32_16x16x32_bf16 v[48:51], v[178:181], v[162:165], v[48:51]
	v_mfma_f32_16x16x32_bf16 v[44:47], v[186:189], v[132:135], v[44:47]
	v_mfma_f32_16x16x32_bf16 v[40:43], v[186:189], v[162:165], v[40:43]
	v_mfma_f32_16x16x32_bf16 v[36:39], v[198:201], v[132:135], v[36:39]
	v_mfma_f32_16x16x32_bf16 v[32:35], v[198:201], v[162:165], v[32:35]
	s_setprio 0
	s_setprio 1
	v_mfma_f32_16x16x32_bf16 v[28:31], v[166:169], v[158:161], v[28:31]
	v_mfma_f32_16x16x32_bf16 v[24:27], v[166:169], v[206:209], v[24:27]
	v_mfma_f32_16x16x32_bf16 v[20:23], v[174:177], v[158:161], v[20:23]
	v_mfma_f32_16x16x32_bf16 v[16:19], v[174:177], v[206:209], v[16:19]
	v_mfma_f32_16x16x32_bf16 v[12:15], v[182:185], v[158:161], v[12:15]
	v_mfma_f32_16x16x32_bf16 v[8:11], v[182:185], v[206:209], v[8:11]
	v_mfma_f32_16x16x32_bf16 v[4:7], v[194:197], v[158:161], v[4:7]
	v_mfma_f32_16x16x32_bf16 v[0:3], v[194:197], v[206:209], v[0:3]
	v_mfma_f32_16x16x32_bf16 v[28:31], v[170:173], v[202:205], v[28:31]
	v_mfma_f32_16x16x32_bf16 v[24:27], v[170:173], v[222:225], v[24:27]
	v_mfma_f32_16x16x32_bf16 v[20:23], v[178:181], v[202:205], v[20:23]
	v_mfma_f32_16x16x32_bf16 v[16:19], v[178:181], v[222:225], v[16:19]
	v_mfma_f32_16x16x32_bf16 v[12:15], v[186:189], v[202:205], v[12:15]
	v_mfma_f32_16x16x32_bf16 v[8:11], v[186:189], v[222:225], v[8:11]
	v_mfma_f32_16x16x32_bf16 v[4:7], v[198:201], v[202:205], v[4:7]
	v_mfma_f32_16x16x32_bf16 v[0:3], v[198:201], v[222:225], v[0:3]
	s_setprio 0
	s_barrier
	ds_read_b128 v[128:131], v152 offset:32768
	ds_read_b128 v[132:135], v152 offset:33792
	ds_read_b128 v[154:157], v152 offset:34816
	ds_read_b128 v[158:161], v152 offset:35840
	ds_read_b128 v[162:165], v137 offset:32768
	ds_read_b128 v[166:169], v137 offset:33792
	ds_read_b128 v[170:173], v137 offset:34816
	ds_read_b128 v[174:177], v137 offset:35840
	ds_read_b128 v[178:181], v137 offset:36864
	ds_read_b128 v[182:185], v137 offset:37888
	ds_read_b128 v[186:189], v137 offset:38912
	ds_read_b128 v[194:197], v137 offset:39936
	s_waitcnt vmcnt(2)
	s_barrier
; #define WAIT_V(n) asm volatile("s_waitcnt vmcnt(" #n ")" ::: "memory")
; #define WAIT_L(n) asm volatile("s_waitcnt lgkmcnt(" #n ")" ::: "memory")
; #define BAR __builtin_amdgcn_s_barrier()
; #define LDA(dst, b, h) _Pragma("unroll") for (int m = 0; m < 4; ++m) _Pragma("unroll") for (int k = 0; k < 2; ++k) \
;     dst[m][k] = *reinterpret_cast<const bf16x8*>((char*)shm + abase + (((b) * 2 + (h)) * 16384 + (m * 2 + k) * 1024))
; #define LDB(dst, b, h) _Pragma("unroll") for (int n = 0; n < 2; ++n) _Pragma("unroll") for (int k = 0; k < 2; ++k) \
;     dst[n][k] = *reinterpret_cast<const bf16x8*>((char*)shm + bbase + (((b) * 2 + (h)) * 16384 + (n * 2 + k) * 1024))
; template <bool SWAP>
; __device__ __forceinline__ void gemm_main(const u16* __restrict__ A, const u16* __restrict__ Bt, int brow, int bcol,
;                                           u16* shm, f32x4 (&acc)[2][2][4][2]) {
;     ...
;   { LDB(B0, 1, 0); LDA(At, 1, 0); WAIT_V(2); BAR; WAIT_L(0); MMA(0, 0, At, B0); BAR;
;     LDB(B1, 1, 1); WAIT_V(0); BAR; WAIT_L(0); MMA(0, 1, At, B1); BAR;
;     LDA(At, 1, 1); BAR; WAIT_L(0); MMA(1, 0, At, B0); MMA(1, 1, At, B1); BAR; }
;   if (wr == 0) BAR;
; __device__ __forceinline__ void phase_inproj1(const Params& p, char* smem) {
;     ...
;       gemm_main<false>(A, Bt, brow, nt * 256, (u16*)smem, acc);
;       if (nt < 16) {
	s_waitcnt lgkmcnt(0)
	s_setprio 1
	s_waitcnt lgkmcnt(0)
	v_mfma_f32_16x16x32_bf16 v[124:127], v[162:165], v[128:131], v[124:127]
	v_mfma_f32_16x16x32_bf16 v[120:123], v[162:165], v[154:157], v[120:123]
	v_mfma_f32_16x16x32_bf16 v[116:119], v[170:173], v[128:131], v[116:119]
	v_mfma_f32_16x16x32_bf16 v[112:115], v[170:173], v[154:157], v[112:115]
	v_mfma_f32_16x16x32_bf16 v[108:111], v[178:181], v[128:131], v[108:111]
	v_mfma_f32_16x16x32_bf16 v[104:107], v[178:181], v[154:157], v[104:107]
	v_mfma_f32_16x16x32_bf16 v[100:103], v[186:189], v[128:131], v[100:103]
	v_mfma_f32_16x16x32_bf16 v[96:99], v[186:189], v[154:157], v[96:99]
	v_mfma_f32_16x16x32_bf16 v[124:127], v[166:169], v[132:135], v[124:127]
	v_mfma_f32_16x16x32_bf16 v[120:123], v[166:169], v[158:161], v[120:123]
	v_mfma_f32_16x16x32_bf16 v[116:119], v[174:177], v[132:135], v[116:119]
	v_mfma_f32_16x16x32_bf16 v[112:115], v[174:177], v[158:161], v[112:115]
	v_mfma_f32_16x16x32_bf16 v[108:111], v[182:185], v[132:135], v[108:111]
	v_mfma_f32_16x16x32_bf16 v[104:107], v[182:185], v[158:161], v[104:107]
	v_mfma_f32_16x16x32_bf16 v[100:103], v[194:197], v[132:135], v[100:103]
	v_mfma_f32_16x16x32_bf16 v[96:99], v[194:197], v[158:161], v[96:99]
	s_setprio 0
	s_barrier
	ds_read_b128 v[198:201], v152 offset:49152
	ds_read_b128 v[202:205], v152 offset:50176
	ds_read_b128 v[206:209], v152 offset:51200
	ds_read_b128 v[222:225], v152 offset:52224
	s_waitcnt vmcnt(0)
	s_barrier
	s_waitcnt lgkmcnt(0)
	s_setprio 1
	s_waitcnt lgkmcnt(0)
	v_mfma_f32_16x16x32_bf16 v[92:95], v[162:165], v[198:201], v[92:95]
	v_mfma_f32_16x16x32_bf16 v[88:91], v[162:165], v[206:209], v[88:91]
	v_mfma_f32_16x16x32_bf16 v[84:87], v[170:173], v[198:201], v[84:87]
	v_mfma_f32_16x16x32_bf16 v[80:83], v[170:173], v[206:209], v[80:83]
	v_mfma_f32_16x16x32_bf16 v[76:79], v[178:181], v[198:201], v[76:79]
	v_mfma_f32_16x16x32_bf16 v[72:75], v[178:181], v[206:209], v[72:75]
	v_mfma_f32_16x16x32_bf16 v[68:71], v[186:189], v[198:201], v[68:71]
	v_mfma_f32_16x16x32_bf16 v[64:67], v[186:189], v[206:209], v[64:67]
	v_mfma_f32_16x16x32_bf16 v[92:95], v[166:169], v[202:205], v[92:95]
	v_mfma_f32_16x16x32_bf16 v[88:91], v[166:169], v[222:225], v[88:91]
	v_mfma_f32_16x16x32_bf16 v[84:87], v[174:177], v[202:205], v[84:87]
	v_mfma_f32_16x16x32_bf16 v[80:83], v[174:177], v[222:225], v[80:83]
	v_mfma_f32_16x16x32_bf16 v[76:79], v[182:185], v[202:205], v[76:79]
	v_mfma_f32_16x16x32_bf16 v[72:75], v[182:185], v[222:225], v[72:75]
	v_mfma_f32_16x16x32_bf16 v[68:71], v[194:197], v[202:205], v[68:71]
	v_mfma_f32_16x16x32_bf16 v[64:67], v[194:197], v[222:225], v[64:67]
	s_setprio 0
	s_barrier
	ds_read_b128 v[162:165], v137 offset:49152
	ds_read_b128 v[166:169], v137 offset:50176
	ds_read_b128 v[170:173], v137 offset:51200
	ds_read_b128 v[174:177], v137 offset:52224
	ds_read_b128 v[178:181], v137 offset:53248
	ds_read_b128 v[182:185], v137 offset:54272
	ds_read_b128 v[186:189], v137 offset:55296
	ds_read_b128 v[194:197], v137 offset:56320
	s_barrier
	s_waitcnt lgkmcnt(0)
	s_setprio 1
	s_waitcnt lgkmcnt(0)
	v_mfma_f32_16x16x32_bf16 v[60:63], v[162:165], v[128:131], v[60:63]
	v_mfma_f32_16x16x32_bf16 v[56:59], v[162:165], v[154:157], v[56:59]
	v_mfma_f32_16x16x32_bf16 v[52:55], v[170:173], v[128:131], v[52:55]
	v_mfma_f32_16x16x32_bf16 v[48:51], v[170:173], v[154:157], v[48:51]
	v_mfma_f32_16x16x32_bf16 v[44:47], v[178:181], v[128:131], v[44:47]
	v_mfma_f32_16x16x32_bf16 v[40:43], v[178:181], v[154:157], v[40:43]
	v_mfma_f32_16x16x32_bf16 v[36:39], v[186:189], v[128:131], v[36:39]
	v_mfma_f32_16x16x32_bf16 v[32:35], v[186:189], v[154:157], v[32:35]
	v_mfma_f32_16x16x32_bf16 v[60:63], v[166:169], v[132:135], v[60:63]
	v_mfma_f32_16x16x32_bf16 v[56:59], v[166:169], v[158:161], v[56:59]
	v_mfma_f32_16x16x32_bf16 v[52:55], v[174:177], v[132:135], v[52:55]
	v_mfma_f32_16x16x32_bf16 v[48:51], v[174:177], v[158:161], v[48:51]
	v_mfma_f32_16x16x32_bf16 v[44:47], v[182:185], v[132:135], v[44:47]
	v_mfma_f32_16x16x32_bf16 v[40:43], v[182:185], v[158:161], v[40:43]
	v_mfma_f32_16x16x32_bf16 v[36:39], v[194:197], v[132:135], v[36:39]
	v_mfma_f32_16x16x32_bf16 v[32:35], v[194:197], v[158:161], v[32:35]
	s_setprio 0
	s_setprio 1
	v_mfma_f32_16x16x32_bf16 v[28:31], v[162:165], v[198:201], v[28:31]
	v_mfma_f32_16x16x32_bf16 v[24:27], v[162:165], v[206:209], v[24:27]
	v_mfma_f32_16x16x32_bf16 v[20:23], v[170:173], v[198:201], v[20:23]
	v_mfma_f32_16x16x32_bf16 v[16:19], v[170:173], v[206:209], v[16:19]
	v_mfma_f32_16x16x32_bf16 v[12:15], v[178:181], v[198:201], v[12:15]
	v_mfma_f32_16x16x32_bf16 v[8:11], v[178:181], v[206:209], v[8:11]
	v_mfma_f32_16x16x32_bf16 v[4:7], v[186:189], v[198:201], v[4:7]
	v_mfma_f32_16x16x32_bf16 v[0:3], v[186:189], v[206:209], v[0:3]
	v_mfma_f32_16x16x32_bf16 v[28:31], v[166:169], v[202:205], v[28:31]
	v_mfma_f32_16x16x32_bf16 v[24:27], v[166:169], v[222:225], v[24:27]
	v_mfma_f32_16x16x32_bf16 v[20:23], v[174:177], v[202:205], v[20:23]
	v_mfma_f32_16x16x32_bf16 v[16:19], v[174:177], v[222:225], v[16:19]
	v_mfma_f32_16x16x32_bf16 v[12:15], v[182:185], v[202:205], v[12:15]
	v_mfma_f32_16x16x32_bf16 v[8:11], v[182:185], v[222:225], v[8:11]
	v_mfma_f32_16x16x32_bf16 v[4:7], v[194:197], v[202:205], v[4:7]
	v_mfma_f32_16x16x32_bf16 v[0:3], v[194:197], v[222:225], v[0:3]
	s_setprio 0
	s_movk_i32 s0, 0x100
	v_cmp_gt_u32_e32 vcc, s0, v136
	s_barrier
	s_and_saveexec_b64 s[0:1], vcc
	s_cbranch_execz .LBB0_118
	s_barrier
	s_or_b64 exec, exec, s[0:1]
	s_cmp_gt_u32 s2, 15
	s_mov_b64 s[0:1], -1
	s_cbranch_scc1 .LBB0_119

; #define WAIT_V(n) asm volatile("s_waitcnt vmcnt(" #n ")" ::: "memory")
; #define WAIT_L(n) asm volatile("s_waitcnt lgkmcnt(" #n ")" ::: "memory")
; #define BAR __builtin_amdgcn_s_barrier()
; #define SCHED __builtin_amdgcn_sched_barrier(0)
; #define STAGE(P, BASE, br, kt) do { const char* _g = (const char*)((BASE) + (size_t)(br) * GK + (kt) * BK); \
;     __builtin_amdgcn_global_load_lds((const unsigned*)(_g + voff0), (unsigned*)((char*)(P) + tx * 16), 16, 0, 0); \
;     __builtin_amdgcn_global_load_lds((const unsigned*)(_g + voff1), (unsigned*)((char*)(P) + tx * 16 + 8192), 16, 0, 0); } while (0)
; #define LDA(dst, b, h) _Pragma("unroll") for (int m = 0; m < 4; ++m) _Pragma("unroll") for (int k = 0; k < 2; ++k) \
;     dst[m][k] = *reinterpret_cast<const bf16x8*>((char*)shm + abase + (((b) * 2 + (h)) * 16384 + (m * 2 + k) * 1024))
; #define LDB(dst, b, h) _Pragma("unroll") for (int n = 0; n < 2; ++n) _Pragma("unroll") for (int k = 0; k < 2; ++k) \
;     dst[n][k] = *reinterpret_cast<const bf16x8*>((char*)shm + bbase + (((b) * 2 + (h)) * 16384 + (n * 2 + k) * 1024))
; template <bool SWAP>
; __device__ __forceinline__ void gemm_main(const u16* __restrict__ A, const u16* __restrict__ Bt, int brow, int bcol,
;                                           u16* shm, f32x4 (&acc)[2][2][4][2]) {
;     ...
;   for (int t = 0; t < nt - 2; t += 2) {
;     LDB(B0, 0, 0); SCHED; LDA(At, 0, 0); STAGE(SA(1, 1), A, brow + HALF, t + 1);
;     WAIT_L(8); BAR; WAIT_L(0); MMA(0, 0, At, B0); BAR; SCHED;
;     LDB(B1, 0, 1); STAGE(SB(0, 0), Bt, bcol, t + 2);
;     BAR; WAIT_L(0); MMA(0, 1, At, B1); BAR;
;     LDA(At, 0, 1); STAGE(SA(0, 0), A, brow, t + 2);
;     BAR; WAIT_L(0); MMA(1, 0, At, B0); BAR; SCHED;
;     STAGE(SB(0, 1), Bt, bcol + HALF, t + 2);
;     WAIT_V(6); BAR; MMA(1, 1, At, B1); BAR;
;     LDB(B0, 1, 0); SCHED; LDA(At, 1, 0); STAGE(SA(0, 1), A, brow + HALF, t + 2);
.LBB0_200:
	ds_read_b128 v[182:185], v137 offset:1024
	ds_read_b128 v[194:197], v137 offset:3072
	ds_read_b128 v[202:205], v137 offset:5120
	ds_read_b128 v[222:225], v137 offset:7168
	v_add_u32_e32 v192, 0, v153
	v_add_u32_e32 v160, 0xc000, v192
	v_add_u32_e32 v161, 0xe000, v192
	s_add_u32 m0, s3, 0xc000
	v_lshl_add_u64 v[242:243], s[0:1], 0, v[134:135]
	s_add_u32 vcc_lo, s0, s82
	s_addc_u32 vcc_hi, s1, s83
	global_load_lds_dwordx4 v132, vcc
	s_add_u32 m0, s3, 0xe000
	s_nop 0
	global_load_lds_dwordx4 v134, vcc
	s_waitcnt lgkmcnt(8)
	s_barrier
	s_waitcnt lgkmcnt(0)
	v_mfma_f32_16x16x32_bf16 v[124:127], v[162:165], v[178:181], v[124:127]
	v_mfma_f32_16x16x32_bf16 v[120:123], v[170:173], v[178:181], v[120:123]
	v_mfma_f32_16x16x32_bf16 v[116:119], v[162:165], v[186:189], v[116:119]
	v_mfma_f32_16x16x32_bf16 v[112:115], v[170:173], v[186:189], v[112:115]
	v_mfma_f32_16x16x32_bf16 v[108:111], v[162:165], v[198:201], v[108:111]
	v_mfma_f32_16x16x32_bf16 v[104:107], v[170:173], v[198:201], v[104:107]
	v_mfma_f32_16x16x32_bf16 v[100:103], v[162:165], v[206:209], v[100:103]
	v_mfma_f32_16x16x32_bf16 v[96:99], v[170:173], v[206:209], v[96:99]
	v_mfma_f32_16x16x32_bf16 v[124:127], v[166:169], v[182:185], v[124:127]
	v_mfma_f32_16x16x32_bf16 v[120:123], v[174:177], v[182:185], v[120:123]
	v_mfma_f32_16x16x32_bf16 v[116:119], v[166:169], v[194:197], v[116:119]
	v_mfma_f32_16x16x32_bf16 v[112:115], v[174:177], v[194:197], v[112:115]
	v_mfma_f32_16x16x32_bf16 v[108:111], v[166:169], v[202:205], v[108:111]
	v_mfma_f32_16x16x32_bf16 v[104:107], v[174:177], v[202:205], v[104:107]
	v_mfma_f32_16x16x32_bf16 v[100:103], v[166:169], v[222:225], v[100:103]
	v_mfma_f32_16x16x32_bf16 v[96:99], v[174:177], v[222:225], v[96:99]
	s_barrier
	ds_read_b128 v[226:229], v152 offset:16384
	ds_read_b128 v[230:233], v152 offset:17408
	ds_read_b128 v[234:237], v152 offset:18432
	ds_read_b128 v[238:241], v152 offset:19456
	v_lshl_add_u64 v[244:245], s[0:1], 0, v[128:129]
	s_add_u32 m0, s3, s28
	s_nop 0
	s_add_u32 vcc_lo, s0, s74
	s_addc_u32 vcc_hi, s1, s75
	global_load_lds_dwordx4 v128, vcc
	v_lshl_add_u64 v[246:247], s[0:1], 0, v[130:131]
	s_add_u32 m0, s3, s28
	s_add_u32 m0, m0, 0x2000
	s_nop 0
	global_load_lds_dwordx4 v130, vcc
	s_barrier
	s_waitcnt lgkmcnt(0)
	v_mfma_f32_16x16x32_bf16 v[92:95], v[226:229], v[178:181], v[92:95]
	v_mfma_f32_16x16x32_bf16 v[88:91], v[234:237], v[178:181], v[88:91]
	v_mfma_f32_16x16x32_bf16 v[84:87], v[226:229], v[186:189], v[84:87]
	v_mfma_f32_16x16x32_bf16 v[80:83], v[234:237], v[186:189], v[80:83]
	v_mfma_f32_16x16x32_bf16 v[76:79], v[226:229], v[198:201], v[76:79]
	v_mfma_f32_16x16x32_bf16 v[72:75], v[234:237], v[198:201], v[72:75]
	v_mfma_f32_16x16x32_bf16 v[68:71], v[226:229], v[206:209], v[68:71]
	v_mfma_f32_16x16x32_bf16 v[64:67], v[234:237], v[206:209], v[64:67]
	v_mfma_f32_16x16x32_bf16 v[92:95], v[230:233], v[182:185], v[92:95]
	ds_read_b128 v[178:181], v137 offset:16384
	v_mfma_f32_16x16x32_bf16 v[88:91], v[238:241], v[182:185], v[88:91]
	v_mfma_f32_16x16x32_bf16 v[84:87], v[230:233], v[194:197], v[84:87]
	ds_read_b128 v[186:189], v137 offset:18432
	v_mfma_f32_16x16x32_bf16 v[80:83], v[238:241], v[194:197], v[80:83]
	v_mfma_f32_16x16x32_bf16 v[76:79], v[230:233], v[202:205], v[76:79]
	ds_read_b128 v[198:201], v137 offset:20480
	v_mfma_f32_16x16x32_bf16 v[72:75], v[238:241], v[202:205], v[72:75]
	v_mfma_f32_16x16x32_bf16 v[68:71], v[230:233], v[222:225], v[68:71]
	ds_read_b128 v[206:209], v137 offset:22528
	v_mfma_f32_16x16x32_bf16 v[64:67], v[238:241], v[222:225], v[64:67]
	s_barrier
	ds_read_b128 v[182:185], v137 offset:17408
	ds_read_b128 v[194:197], v137 offset:19456
	ds_read_b128 v[202:205], v137 offset:21504
	ds_read_b128 v[222:225], v137 offset:23552
	s_add_u32 m0, s3, 0x0
	s_nop 0
	s_add_u32 vcc_lo, s0, s76
	s_addc_u32 vcc_hi, s1, s77
	global_load_lds_dwordx4 v132, vcc
	s_add_u32 m0, s3, 0x2000
	s_nop 0
	global_load_lds_dwordx4 v134, vcc
	s_waitcnt vmcnt(8)
	s_barrier
	s_waitcnt lgkmcnt(0)
	v_mfma_f32_16x16x32_bf16 v[60:63], v[162:165], v[178:181], v[60:63]
	v_mfma_f32_16x16x32_bf16 v[56:59], v[170:173], v[178:181], v[56:59]
	v_mfma_f32_16x16x32_bf16 v[52:55], v[162:165], v[186:189], v[52:55]
	v_mfma_f32_16x16x32_bf16 v[48:51], v[170:173], v[186:189], v[48:51]
	v_mfma_f32_16x16x32_bf16 v[44:47], v[162:165], v[198:201], v[44:47]
	v_mfma_f32_16x16x32_bf16 v[40:43], v[170:173], v[198:201], v[40:43]
	v_mfma_f32_16x16x32_bf16 v[36:39], v[162:165], v[206:209], v[36:39]
	v_mfma_f32_16x16x32_bf16 v[32:35], v[170:173], v[206:209], v[32:35]
	v_mfma_f32_16x16x32_bf16 v[60:63], v[166:169], v[182:185], v[60:63]
	v_mfma_f32_16x16x32_bf16 v[56:59], v[174:177], v[182:185], v[56:59]
	v_mfma_f32_16x16x32_bf16 v[52:55], v[166:169], v[194:197], v[52:55]
	v_mfma_f32_16x16x32_bf16 v[48:51], v[174:177], v[194:197], v[48:51]
	v_mfma_f32_16x16x32_bf16 v[44:47], v[166:169], v[202:205], v[44:47]
	v_mfma_f32_16x16x32_bf16 v[40:43], v[174:177], v[202:205], v[40:43]
	v_mfma_f32_16x16x32_bf16 v[36:39], v[166:169], v[222:225], v[36:39]
	v_mfma_f32_16x16x32_bf16 v[32:35], v[174:177], v[222:225], v[32:35]
	s_barrier
	ds_read_b128 v[162:165], v152 offset:32768
	ds_read_b128 v[166:169], v152 offset:33792
	ds_read_b128 v[170:173], v152 offset:34816
	ds_read_b128 v[174:177], v152 offset:35840
	s_add_u32 m0, s3, s29
	s_nop 0
	s_add_u32 vcc_lo, s0, s70
	s_addc_u32 vcc_hi, s1, s71
	global_load_lds_dwordx4 v128, vcc
	s_add_u32 m0, s3, s29
	s_add_u32 m0, m0, 0x2000
	s_nop 0
	global_load_lds_dwordx4 v130, vcc
	s_waitcnt vmcnt(6)
	s_barrier
; #define WAIT_V(n) asm volatile("s_waitcnt vmcnt(" #n ")" ::: "memory")
; #define WAIT_L(n) asm volatile("s_waitcnt lgkmcnt(" #n ")" ::: "memory")
; #define BAR __builtin_amdgcn_s_barrier()
; #define SCHED __builtin_amdgcn_sched_barrier(0)
; #define STAGE(P, BASE, br, kt) do { const char* _g = (const char*)((BASE) + (size_t)(br) * GK + (kt) * BK); \
;     __builtin_amdgcn_global_load_lds((const unsigned*)(_g + voff0), (unsigned*)((char*)(P) + tx * 16), 16, 0, 0); \
;     __builtin_amdgcn_global_load_lds((const unsigned*)(_g + voff1), (unsigned*)((char*)(P) + tx * 16 + 8192), 16, 0, 0); } while (0)
; #define LDA(dst, b, h) _Pragma("unroll") for (int m = 0; m < 4; ++m) _Pragma("unroll") for (int k = 0; k < 2; ++k) \
;     dst[m][k] = *reinterpret_cast<const bf16x8*>((char*)shm + abase + (((b) * 2 + (h)) * 16384 + (m * 2 + k) * 1024))
; #define LDB(dst, b, h) _Pragma("unroll") for (int n = 0; n < 2; ++n) _Pragma("unroll") for (int k = 0; k < 2; ++k) \
;     dst[n][k] = *reinterpret_cast<const bf16x8*>((char*)shm + bbase + (((b) * 2 + (h)) * 16384 + (n * 2 + k) * 1024))
; template <bool SWAP>
; __device__ __forceinline__ void gemm_main(const u16* __restrict__ A, const u16* __restrict__ Bt, int brow, int bcol,
;                                           u16* shm, f32x4 (&acc)[2][2][4][2]) {
;     ...
;     WAIT_V(6); BAR; MMA(1, 1, At, B1); BAR;
;     LDB(B0, 1, 0); SCHED; LDA(At, 1, 0); STAGE(SA(0, 1), A, brow + HALF, t + 2);
;     WAIT_L(8); BAR; WAIT_L(0); MMA(0, 0, At, B0); BAR; SCHED;
;     LDB(B1, 1, 1); STAGE(SB(1, 0), Bt, bcol, t + 3);
;     BAR; WAIT_L(0); MMA(0, 1, At, B1); BAR;
;     LDA(At, 1, 1); STAGE(SA(1, 0), A, brow, t + 3);
;     BAR; WAIT_L(0); MMA(1, 0, At, B0); BAR; SCHED;
	v_mfma_f32_16x16x32_bf16 v[28:31], v[226:229], v[178:181], v[28:31]
	v_mfma_f32_16x16x32_bf16 v[24:27], v[234:237], v[178:181], v[24:27]
	v_mfma_f32_16x16x32_bf16 v[20:23], v[226:229], v[186:189], v[20:23]
	v_mfma_f32_16x16x32_bf16 v[16:19], v[234:237], v[186:189], v[16:19]
	v_mfma_f32_16x16x32_bf16 v[12:15], v[226:229], v[198:201], v[12:15]
	v_mfma_f32_16x16x32_bf16 v[8:11], v[234:237], v[198:201], v[8:11]
	v_mfma_f32_16x16x32_bf16 v[4:7], v[226:229], v[206:209], v[4:7]
	v_mfma_f32_16x16x32_bf16 v[0:3], v[234:237], v[206:209], v[0:3]
	v_mfma_f32_16x16x32_bf16 v[28:31], v[230:233], v[182:185], v[28:31]
	ds_read_b128 v[178:181], v137 offset:32768
	v_mfma_f32_16x16x32_bf16 v[24:27], v[238:241], v[182:185], v[24:27]
	v_mfma_f32_16x16x32_bf16 v[20:23], v[230:233], v[194:197], v[20:23]
	ds_read_b128 v[186:189], v137 offset:34816
	v_mfma_f32_16x16x32_bf16 v[16:19], v[238:241], v[194:197], v[16:19]
	v_mfma_f32_16x16x32_bf16 v[12:15], v[230:233], v[202:205], v[12:15]
	ds_read_b128 v[198:201], v137 offset:36864
	v_mfma_f32_16x16x32_bf16 v[8:11], v[238:241], v[202:205], v[8:11]
	v_mfma_f32_16x16x32_bf16 v[4:7], v[230:233], v[222:225], v[4:7]
	ds_read_b128 v[206:209], v137 offset:38912
	v_mfma_f32_16x16x32_bf16 v[0:3], v[238:241], v[222:225], v[0:3]
	s_barrier
	ds_read_b128 v[182:185], v137 offset:33792
	ds_read_b128 v[194:197], v137 offset:35840
	ds_read_b128 v[202:205], v137 offset:37888
	ds_read_b128 v[222:225], v137 offset:39936
	s_add_u32 m0, s3, 0x4000
	s_nop 0
	s_add_u32 vcc_lo, s0, s96
	s_addc_u32 vcc_hi, s1, s97
	global_load_lds_dwordx4 v132, vcc
	s_add_u32 m0, s3, 0x6000
	s_nop 0
	global_load_lds_dwordx4 v134, vcc
	s_waitcnt lgkmcnt(8)
	s_barrier
	s_waitcnt lgkmcnt(0)
	v_mfma_f32_16x16x32_bf16 v[124:127], v[162:165], v[178:181], v[124:127]
	v_mfma_f32_16x16x32_bf16 v[120:123], v[170:173], v[178:181], v[120:123]
	v_mfma_f32_16x16x32_bf16 v[116:119], v[162:165], v[186:189], v[116:119]
	v_mfma_f32_16x16x32_bf16 v[112:115], v[170:173], v[186:189], v[112:115]
	v_mfma_f32_16x16x32_bf16 v[108:111], v[162:165], v[198:201], v[108:111]
	v_mfma_f32_16x16x32_bf16 v[104:107], v[170:173], v[198:201], v[104:107]
	v_mfma_f32_16x16x32_bf16 v[100:103], v[162:165], v[206:209], v[100:103]
	v_mfma_f32_16x16x32_bf16 v[96:99], v[170:173], v[206:209], v[96:99]
	v_mfma_f32_16x16x32_bf16 v[124:127], v[166:169], v[182:185], v[124:127]
	v_mfma_f32_16x16x32_bf16 v[120:123], v[174:177], v[182:185], v[120:123]
	v_mfma_f32_16x16x32_bf16 v[116:119], v[166:169], v[194:197], v[116:119]
	v_mfma_f32_16x16x32_bf16 v[112:115], v[174:177], v[194:197], v[112:115]
	v_mfma_f32_16x16x32_bf16 v[108:111], v[166:169], v[202:205], v[108:111]
	v_mfma_f32_16x16x32_bf16 v[104:107], v[174:177], v[202:205], v[104:107]
	v_mfma_f32_16x16x32_bf16 v[100:103], v[166:169], v[222:225], v[100:103]
	v_mfma_f32_16x16x32_bf16 v[96:99], v[174:177], v[222:225], v[96:99]
	s_barrier
	ds_read_b128 v[226:229], v152 offset:49152
	ds_read_b128 v[230:233], v152 offset:50176
	ds_read_b128 v[234:237], v152 offset:51200
	ds_read_b128 v[238:241], v152 offset:52224
	v_add_u32_e32 v250, s30, v153
	v_add_u32_e32 v250, 0x2000, v250
	s_add_u32 m0, s3, s30
	s_nop 0
	s_add_u32 vcc_lo, s0, s34
	s_addc_u32 vcc_hi, s1, s35
	global_load_lds_dwordx4 v128, vcc
	v_lshl_add_u64 v[248:249], v[246:247], 0, s[34:35]
	s_add_u32 m0, s3, s30
	s_add_u32 m0, m0, 0x2000
	s_nop 0
	global_load_lds_dwordx4 v130, vcc
	s_barrier
	s_waitcnt lgkmcnt(0)
	v_mfma_f32_16x16x32_bf16 v[92:95], v[226:229], v[178:181], v[92:95]
	v_mfma_f32_16x16x32_bf16 v[88:91], v[234:237], v[178:181], v[88:91]
	v_mfma_f32_16x16x32_bf16 v[84:87], v[226:229], v[186:189], v[84:87]
	v_mfma_f32_16x16x32_bf16 v[80:83], v[234:237], v[186:189], v[80:83]
	v_mfma_f32_16x16x32_bf16 v[76:79], v[226:229], v[198:201], v[76:79]
	v_mfma_f32_16x16x32_bf16 v[72:75], v[234:237], v[198:201], v[72:75]
	v_mfma_f32_16x16x32_bf16 v[68:71], v[226:229], v[206:209], v[68:71]
	v_mfma_f32_16x16x32_bf16 v[64:67], v[234:237], v[206:209], v[64:67]
	v_mfma_f32_16x16x32_bf16 v[92:95], v[230:233], v[182:185], v[92:95]
	ds_read_b128 v[178:181], v137 offset:49152
	v_mfma_f32_16x16x32_bf16 v[88:91], v[238:241], v[182:185], v[88:91]
	v_mfma_f32_16x16x32_bf16 v[84:87], v[230:233], v[194:197], v[84:87]
	ds_read_b128 v[186:189], v137 offset:51200
	v_mfma_f32_16x16x32_bf16 v[80:83], v[238:241], v[194:197], v[80:83]
	v_mfma_f32_16x16x32_bf16 v[76:79], v[230:233], v[202:205], v[76:79]
	ds_read_b128 v[198:201], v137 offset:53248
	v_mfma_f32_16x16x32_bf16 v[72:75], v[238:241], v[202:205], v[72:75]
	v_mfma_f32_16x16x32_bf16 v[68:71], v[230:233], v[222:225], v[68:71]
	ds_read_b128 v[206:209], v137 offset:55296
	v_mfma_f32_16x16x32_bf16 v[64:67], v[238:241], v[222:225], v[64:67]
	s_barrier
	ds_read_b128 v[182:185], v137 offset:50176
	ds_read_b128 v[194:197], v137 offset:52224
	ds_read_b128 v[202:205], v137 offset:54272
	ds_read_b128 v[222:225], v137 offset:56320
	v_add_u32_e32 v248, 0x8000, v192
	s_add_u32 m0, s3, 0x8000
	s_nop 0
	s_add_u32 vcc_lo, s0, s36
	s_addc_u32 vcc_hi, s1, s37
	global_load_lds_dwordx4 v132, vcc
	s_add_u32 m0, s3, 0xa000
	s_nop 0
	global_load_lds_dwordx4 v134, vcc
	s_waitcnt vmcnt(8)
	s_barrier
; #define WAIT_V(n) asm volatile("s_waitcnt vmcnt(" #n ")" ::: "memory")
; #define WAIT_L(n) asm volatile("s_waitcnt lgkmcnt(" #n ")" ::: "memory")
; #define BAR __builtin_amdgcn_s_barrier()
; #define SCHED __builtin_amdgcn_sched_barrier(0)
; #define STAGE(P, BASE, br, kt) do { const char* _g = (const char*)((BASE) + (size_t)(br) * GK + (kt) * BK); \
;     __builtin_amdgcn_global_load_lds((const unsigned*)(_g + voff0), (unsigned*)((char*)(P) + tx * 16), 16, 0, 0); \
;     __builtin_amdgcn_global_load_lds((const unsigned*)(_g + voff1), (unsigned*)((char*)(P) + tx * 16 + 8192), 16, 0, 0); } while (0)
; #define LDA(dst, b, h) _Pragma("unroll") for (int m = 0; m < 4; ++m) _Pragma("unroll") for (int k = 0; k < 2; ++k) \
;     dst[m][k] = *reinterpret_cast<const bf16x8*>((char*)shm + abase + (((b) * 2 + (h)) * 16384 + (m * 2 + k) * 1024))
; #define LDB(dst, b, h) _Pragma("unroll") for (int n = 0; n < 2; ++n) _Pragma("unroll") for (int k = 0; k < 2; ++k) \
;     dst[n][k] = *reinterpret_cast<const bf16x8*>((char*)shm + bbase + (((b) * 2 + (h)) * 16384 + (n * 2 + k) * 1024))
; template <bool SWAP>
; __device__ __forceinline__ void gemm_main(const u16* __restrict__ A, const u16* __restrict__ Bt, int brow, int bcol,
;                                           u16* shm, f32x4 (&acc)[2][2][4][2]) {
;     ...
;     BAR; WAIT_L(0); MMA(1, 0, At, B0); BAR; SCHED;
;     STAGE(SB(1, 1), Bt, bcol + HALF, t + 3);
;     WAIT_V(6); BAR; MMA(1, 1, At, B1); BAR;
;   }
;   { LDB(B0, 0, 0); LDA(At, 0, 0); STAGE(SA(1, 1), A, brow + HALF, nt - 1);
;     BAR; WAIT_L(0); MMA(0, 0, At, B0); BAR;
	s_waitcnt lgkmcnt(0)
	v_mfma_f32_16x16x32_bf16 v[60:63], v[162:165], v[178:181], v[60:63]
	v_mfma_f32_16x16x32_bf16 v[56:59], v[170:173], v[178:181], v[56:59]
	v_mfma_f32_16x16x32_bf16 v[52:55], v[162:165], v[186:189], v[52:55]
	v_mfma_f32_16x16x32_bf16 v[48:51], v[170:173], v[186:189], v[48:51]
	v_mfma_f32_16x16x32_bf16 v[44:47], v[162:165], v[198:201], v[44:47]
	v_mfma_f32_16x16x32_bf16 v[40:43], v[170:173], v[198:201], v[40:43]
	v_mfma_f32_16x16x32_bf16 v[36:39], v[162:165], v[206:209], v[36:39]
	v_mfma_f32_16x16x32_bf16 v[32:35], v[170:173], v[206:209], v[32:35]
	v_mfma_f32_16x16x32_bf16 v[60:63], v[166:169], v[182:185], v[60:63]
	v_mfma_f32_16x16x32_bf16 v[56:59], v[174:177], v[182:185], v[56:59]
	v_mfma_f32_16x16x32_bf16 v[52:55], v[166:169], v[194:197], v[52:55]
	v_mfma_f32_16x16x32_bf16 v[48:51], v[174:177], v[194:197], v[48:51]
	v_mfma_f32_16x16x32_bf16 v[44:47], v[166:169], v[202:205], v[44:47]
	v_mfma_f32_16x16x32_bf16 v[40:43], v[174:177], v[202:205], v[40:43]
	v_mfma_f32_16x16x32_bf16 v[36:39], v[166:169], v[222:225], v[36:39]
	v_mfma_f32_16x16x32_bf16 v[32:35], v[174:177], v[222:225], v[32:35]
	s_barrier
	ds_read_b128 v[162:165], v152
	ds_read_b128 v[166:169], v152 offset:1024
	ds_read_b128 v[170:173], v152 offset:2048
	ds_read_b128 v[174:177], v152 offset:3072
	s_add_u32 m0, s3, s31
	s_nop 0
	s_add_u32 vcc_lo, s0, s64
	s_addc_u32 vcc_hi, s1, s65
	global_load_lds_dwordx4 v128, vcc
	v_lshl_add_u64 v[254:255], v[246:247], 0, s[64:65]
	s_add_u32 m0, s3, s31
	s_add_u32 m0, m0, 0x2000
	s_nop 0
	global_load_lds_dwordx4 v130, vcc
	s_waitcnt vmcnt(6)
	s_barrier
	v_mfma_f32_16x16x32_bf16 v[28:31], v[226:229], v[178:181], v[28:31]
	v_mfma_f32_16x16x32_bf16 v[24:27], v[234:237], v[178:181], v[24:27]
	v_mfma_f32_16x16x32_bf16 v[20:23], v[226:229], v[186:189], v[20:23]
	v_mfma_f32_16x16x32_bf16 v[16:19], v[234:237], v[186:189], v[16:19]
	v_mfma_f32_16x16x32_bf16 v[12:15], v[226:229], v[198:201], v[12:15]
	v_mfma_f32_16x16x32_bf16 v[8:11], v[234:237], v[198:201], v[8:11]
	v_mfma_f32_16x16x32_bf16 v[4:7], v[226:229], v[206:209], v[4:7]
	v_mfma_f32_16x16x32_bf16 v[0:3], v[234:237], v[206:209], v[0:3]
	v_mfma_f32_16x16x32_bf16 v[28:31], v[230:233], v[182:185], v[28:31]
	ds_read_b128 v[178:181], v137
	v_mfma_f32_16x16x32_bf16 v[24:27], v[238:241], v[182:185], v[24:27]
	v_mfma_f32_16x16x32_bf16 v[20:23], v[230:233], v[194:197], v[20:23]
	ds_read_b128 v[186:189], v137 offset:2048
	v_mfma_f32_16x16x32_bf16 v[16:19], v[238:241], v[194:197], v[16:19]
	v_mfma_f32_16x16x32_bf16 v[12:15], v[230:233], v[202:205], v[12:15]
	ds_read_b128 v[198:201], v137 offset:4096
	v_mfma_f32_16x16x32_bf16 v[8:11], v[238:241], v[202:205], v[8:11]
	v_mfma_f32_16x16x32_bf16 v[4:7], v[230:233], v[222:225], v[4:7]
	ds_read_b128 v[206:209], v137 offset:6144
	v_mfma_f32_16x16x32_bf16 v[0:3], v[238:241], v[222:225], v[0:3]
	s_add_i32 s2, s2, 2
	s_add_u32 s0, s0, 0x100
	s_addc_u32 s1, s1, 0
	s_cmp_lt_u32 s2, 28
	s_barrier
	s_cbranch_scc1 .LBB0_200
	v_lshlrev_b32_e32 v128, 3, v154
	v_lshlrev_b32_e32 v129, 5, v154
	v_and_b32_e32 v128, 0xffff0, v128
	v_and_b32_e32 v129, 32, v129
	s_or_b32 s0, s24, 0x80
	v_add_u32_e32 v129, v129, v156
	v_add_lshl_u32 v128, v155, v128, 12
	s_ashr_i32 s1, s0, 31
	v_lshl_add_u32 v192, v129, 1, v128
	v_lshlrev_b32_e32 v128, 3, v157
	v_lshlrev_b32_e32 v129, 5, v157
	s_lshl_b64 s[0:1], s[0:1], 12
	v_readlane_b32 s2, v253, 35
	v_and_b32_e32 v128, 0xffff0, v128
	v_and_b32_e32 v129, 32, v129
	v_readlane_b32 s3, v253, 36
	s_add_u32 s0, s2, s0
	v_add_u32_e32 v129, v129, v159
	v_add_lshl_u32 v128, v158, v128, 12
	s_addc_u32 s1, s3, s1
	v_lshl_add_u32 v158, v129, 1, v128
	v_mov_b32_e32 v159, v193
	v_lshl_add_u64 v[190:191], s[0:1], 0, v[192:193]
	s_mov_b64 s[4:5], 0xf80
	v_readfirstlane_b32 s2, v160
	v_lshl_add_u64 v[190:191], v[190:191], 0, s[4:5]
	s_mov_b32 m0, s2
	v_lshl_add_u64 v[158:159], s[0:1], 0, v[158:159]
	v_readfirstlane_b32 s0, v161
	ds_read_b128 v[128:131], v152
	ds_read_b128 v[132:135], v152 offset:1024
	ds_read_b128 v[154:157], v152 offset:2048
	ds_read_b128 v[162:165], v152 offset:3072
	ds_read_b128 v[166:169], v137
	ds_read_b128 v[170:173], v137 offset:1024
	ds_read_b128 v[174:177], v137 offset:2048
	ds_read_b128 v[178:181], v137 offset:3072
	ds_read_b128 v[182:185], v137 offset:4096
	ds_read_b128 v[186:189], v137 offset:5120
	ds_read_b128 v[194:197], v137 offset:6144
	ds_read_b128 v[198:201], v137 offset:7168
	global_load_lds_dwordx4 v[190:191], off
	v_lshl_add_u64 v[158:159], v[158:159], 0, s[4:5]
	s_mov_b32 m0, s0
	s_nop 0
	global_load_lds_dwordx4 v[158:159], off
	s_barrier
	s_waitcnt lgkmcnt(0)
	s_setprio 1
	s_waitcnt lgkmcnt(0)
	v_mfma_f32_16x16x32_bf16 v[124:127], v[128:131], v[166:169], v[124:127]
	v_mfma_f32_16x16x32_bf16 v[116:119], v[128:131], v[174:177], v[116:119]
	v_mfma_f32_16x16x32_bf16 v[108:111], v[128:131], v[182:185], v[108:111]
	v_mfma_f32_16x16x32_bf16 v[100:103], v[128:131], v[194:197], v[100:103]
	v_mfma_f32_16x16x32_bf16 v[124:127], v[132:135], v[170:173], v[124:127]
	v_mfma_f32_16x16x32_bf16 v[120:123], v[154:157], v[166:169], v[120:123]
	v_mfma_f32_16x16x32_bf16 v[116:119], v[132:135], v[178:181], v[116:119]
	v_mfma_f32_16x16x32_bf16 v[112:115], v[154:157], v[174:177], v[112:115]
	v_mfma_f32_16x16x32_bf16 v[108:111], v[132:135], v[186:189], v[108:111]
	v_mfma_f32_16x16x32_bf16 v[104:107], v[154:157], v[182:185], v[104:107]
	v_mfma_f32_16x16x32_bf16 v[100:103], v[132:135], v[198:201], v[100:103]
	v_mfma_f32_16x16x32_bf16 v[96:99], v[154:157], v[194:197], v[96:99]
	v_mfma_f32_16x16x32_bf16 v[158:161], v[162:165], v[170:173], v[120:123]
	v_mfma_f32_16x16x32_bf16 v[202:205], v[162:165], v[178:181], v[112:115]
	v_mfma_f32_16x16x32_bf16 v[206:209], v[162:165], v[186:189], v[104:107]
	v_mfma_f32_16x16x32_bf16 v[222:225], v[162:165], v[198:201], v[96:99]
	s_setprio 0
	s_barrier
; #define WAIT_V(n) asm volatile("s_waitcnt vmcnt(" #n ")" ::: "memory")
; #define WAIT_L(n) asm volatile("s_waitcnt lgkmcnt(" #n ")" ::: "memory")
; #define BAR __builtin_amdgcn_s_barrier()
; #define LDA(dst, b, h) _Pragma("unroll") for (int m = 0; m < 4; ++m) _Pragma("unroll") for (int k = 0; k < 2; ++k) \
;     dst[m][k] = *reinterpret_cast<const bf16x8*>((char*)shm + abase + (((b) * 2 + (h)) * 16384 + (m * 2 + k) * 1024))
; #define LDB(dst, b, h) _Pragma("unroll") for (int n = 0; n < 2; ++n) _Pragma("unroll") for (int k = 0; k < 2; ++k) \
;     dst[n][k] = *reinterpret_cast<const bf16x8*>((char*)shm + bbase + (((b) * 2 + (h)) * 16384 + (n * 2 + k) * 1024))
; template <bool SWAP>
; __device__ __forceinline__ void gemm_main(const u16* __restrict__ A, const u16* __restrict__ Bt, int brow, int bcol,
;                                           u16* shm, f32x4 (&acc)[2][2][4][2]) {
;     ...
;     LDB(B1, 0, 1); BAR; WAIT_L(0); MMA(0, 1, At, B1); BAR;
;     LDA(At, 0, 1); WAIT_V(4); BAR; WAIT_L(0); MMA(1, 0, At, B0); MMA(1, 1, At, B1); BAR; }
;   { LDB(B0, 1, 0); LDA(At, 1, 0); WAIT_V(2); BAR; WAIT_L(0); MMA(0, 0, At, B0); BAR;
	s_nop 1
	ds_read_b128 v[96:99], v152 offset:16384
	ds_read_b128 v[104:107], v152 offset:17408
	ds_read_b128 v[112:115], v152 offset:18432
	ds_read_b128 v[120:123], v152 offset:19456
	s_barrier
	s_waitcnt lgkmcnt(0)
	s_setprio 1
	s_waitcnt lgkmcnt(0)
	v_mfma_f32_16x16x32_bf16 v[92:95], v[96:99], v[166:169], v[92:95]
	v_mfma_f32_16x16x32_bf16 v[84:87], v[96:99], v[174:177], v[84:87]
	v_mfma_f32_16x16x32_bf16 v[76:79], v[96:99], v[182:185], v[76:79]
	v_mfma_f32_16x16x32_bf16 v[68:71], v[96:99], v[194:197], v[68:71]
	v_mfma_f32_16x16x32_bf16 v[92:95], v[104:107], v[170:173], v[92:95]
	v_mfma_f32_16x16x32_bf16 v[88:91], v[112:115], v[166:169], v[88:91]
	v_mfma_f32_16x16x32_bf16 v[84:87], v[104:107], v[178:181], v[84:87]
	v_mfma_f32_16x16x32_bf16 v[80:83], v[112:115], v[174:177], v[80:83]
	v_mfma_f32_16x16x32_bf16 v[76:79], v[104:107], v[186:189], v[76:79]
	v_mfma_f32_16x16x32_bf16 v[72:75], v[112:115], v[182:185], v[72:75]
	v_mfma_f32_16x16x32_bf16 v[68:71], v[104:107], v[198:201], v[68:71]
	v_mfma_f32_16x16x32_bf16 v[64:67], v[112:115], v[194:197], v[64:67]
	v_mfma_f32_16x16x32_bf16 v[166:169], v[120:123], v[170:173], v[88:91]
	v_mfma_f32_16x16x32_bf16 v[170:173], v[120:123], v[178:181], v[80:83]
	v_mfma_f32_16x16x32_bf16 v[174:177], v[120:123], v[186:189], v[72:75]
	v_mfma_f32_16x16x32_bf16 v[178:181], v[120:123], v[198:201], v[64:67]
	s_setprio 0
	s_barrier
	s_nop 1
	ds_read_b128 v[64:67], v137 offset:16384
	ds_read_b128 v[72:75], v137 offset:17408
	ds_read_b128 v[80:83], v137 offset:18432
	ds_read_b128 v[88:91], v137 offset:19456
	ds_read_b128 v[182:185], v137 offset:20480
	ds_read_b128 v[186:189], v137 offset:21504
	ds_read_b128 v[194:197], v137 offset:22528
	ds_read_b128 v[198:201], v137 offset:23552
	s_waitcnt vmcnt(4)
	s_barrier
	s_waitcnt lgkmcnt(0)
	s_setprio 1
	s_waitcnt lgkmcnt(0)
	v_mfma_f32_16x16x32_bf16 v[60:63], v[128:131], v[64:67], v[60:63]
	v_mfma_f32_16x16x32_bf16 v[52:55], v[128:131], v[80:83], v[52:55]
	v_mfma_f32_16x16x32_bf16 v[44:47], v[128:131], v[182:185], v[44:47]
	v_mfma_f32_16x16x32_bf16 v[36:39], v[128:131], v[194:197], v[36:39]
	v_mfma_f32_16x16x32_bf16 v[60:63], v[132:135], v[72:75], v[60:63]
	v_mfma_f32_16x16x32_bf16 v[56:59], v[154:157], v[64:67], v[56:59]
	v_mfma_f32_16x16x32_bf16 v[52:55], v[132:135], v[88:91], v[52:55]
	v_mfma_f32_16x16x32_bf16 v[48:51], v[154:157], v[80:83], v[48:51]
	v_mfma_f32_16x16x32_bf16 v[44:47], v[132:135], v[186:189], v[44:47]
	v_mfma_f32_16x16x32_bf16 v[40:43], v[154:157], v[182:185], v[40:43]
	v_mfma_f32_16x16x32_bf16 v[36:39], v[132:135], v[198:201], v[36:39]
	v_mfma_f32_16x16x32_bf16 v[32:35], v[154:157], v[194:197], v[32:35]
	v_mfma_f32_16x16x32_bf16 v[226:229], v[162:165], v[72:75], v[56:59]
	v_mfma_f32_16x16x32_bf16 v[230:233], v[162:165], v[88:91], v[48:51]
	v_mfma_f32_16x16x32_bf16 v[234:237], v[162:165], v[186:189], v[40:43]
	v_mfma_f32_16x16x32_bf16 v[128:131], v[162:165], v[198:201], v[32:35]
	s_setprio 0
	s_setprio 1
	v_mfma_f32_16x16x32_bf16 v[28:31], v[96:99], v[64:67], v[28:31]
	v_mfma_f32_16x16x32_bf16 v[20:23], v[96:99], v[80:83], v[20:23]
	v_mfma_f32_16x16x32_bf16 v[12:15], v[96:99], v[182:185], v[12:15]
	v_mfma_f32_16x16x32_bf16 v[4:7], v[96:99], v[194:197], v[4:7]
	v_mfma_f32_16x16x32_bf16 v[28:31], v[104:107], v[72:75], v[28:31]
	v_mfma_f32_16x16x32_bf16 v[24:27], v[112:115], v[64:67], v[24:27]
	v_mfma_f32_16x16x32_bf16 v[20:23], v[104:107], v[88:91], v[20:23]
	v_mfma_f32_16x16x32_bf16 v[16:19], v[112:115], v[80:83], v[16:19]
	v_mfma_f32_16x16x32_bf16 v[12:15], v[104:107], v[186:189], v[12:15]
	v_mfma_f32_16x16x32_bf16 v[8:11], v[112:115], v[182:185], v[8:11]
	v_mfma_f32_16x16x32_bf16 v[4:7], v[104:107], v[198:201], v[4:7]
	v_mfma_f32_16x16x32_bf16 v[0:3], v[112:115], v[194:197], v[0:3]
	v_mfma_f32_16x16x32_bf16 v[132:135], v[120:123], v[72:75], v[24:27]
	v_mfma_f32_16x16x32_bf16 v[154:157], v[120:123], v[88:91], v[16:19]
	v_mfma_f32_16x16x32_bf16 v[162:165], v[120:123], v[186:189], v[8:11]
	v_mfma_f32_16x16x32_bf16 v[182:185], v[120:123], v[198:201], v[0:3]
	s_setprio 0
	s_barrier
	s_nop 1
	ds_read_b128 v[0:3], v152 offset:32768
	ds_read_b128 v[8:11], v152 offset:33792
	ds_read_b128 v[16:19], v152 offset:34816
	ds_read_b128 v[24:27], v152 offset:35840
	ds_read_b128 v[32:35], v137 offset:32768
	ds_read_b128 v[40:43], v137 offset:33792
	ds_read_b128 v[48:51], v137 offset:34816
	ds_read_b128 v[56:59], v137 offset:35840
	ds_read_b128 v[64:67], v137 offset:36864
	ds_read_b128 v[186:189], v137 offset:37888
	ds_read_b128 v[194:197], v137 offset:38912
	ds_read_b128 v[198:201], v137 offset:39936
	s_waitcnt vmcnt(2)
	s_barrier
; #define WAIT_V(n) asm volatile("s_waitcnt vmcnt(" #n ")" ::: "memory")
; #define WAIT_L(n) asm volatile("s_waitcnt lgkmcnt(" #n ")" ::: "memory")
; #define BAR __builtin_amdgcn_s_barrier()
; #define LDA(dst, b, h) _Pragma("unroll") for (int m = 0; m < 4; ++m) _Pragma("unroll") for (int k = 0; k < 2; ++k) \
;     dst[m][k] = *reinterpret_cast<const bf16x8*>((char*)shm + abase + (((b) * 2 + (h)) * 16384 + (m * 2 + k) * 1024))
; #define LDB(dst, b, h) _Pragma("unroll") for (int n = 0; n < 2; ++n) _Pragma("unroll") for (int k = 0; k < 2; ++k) \
;     dst[n][k] = *reinterpret_cast<const bf16x8*>((char*)shm + bbase + (((b) * 2 + (h)) * 16384 + (n * 2 + k) * 1024))
; template <bool SWAP>
; __device__ __forceinline__ void gemm_main(const u16* __restrict__ A, const u16* __restrict__ Bt, int brow, int bcol,
;                                           u16* shm, f32x4 (&acc)[2][2][4][2]) {
;     ...
;   { LDB(B0, 1, 0); LDA(At, 1, 0); WAIT_V(2); BAR; WAIT_L(0); MMA(0, 0, At, B0); BAR;
;     LDB(B1, 1, 1); WAIT_V(0); BAR; WAIT_L(0); MMA(0, 1, At, B1); BAR;
;     LDA(At, 1, 1); BAR; WAIT_L(0); MMA(1, 0, At, B0); MMA(1, 1, At, B1); BAR; }
;   if (wr == 0) BAR;
	s_waitcnt lgkmcnt(0)
	s_setprio 1
	s_waitcnt lgkmcnt(0)
	v_mfma_f32_16x16x32_bf16 v[72:75], v[0:3], v[32:35], v[124:127]
	v_mfma_f32_16x16x32_bf16 v[120:123], v[8:11], v[40:43], v[72:75]
	v_mfma_f32_16x16x32_bf16 v[72:75], v[16:19], v[32:35], v[158:161]
	v_mfma_f32_16x16x32_bf16 v[124:127], v[24:27], v[40:43], v[72:75]
	v_mfma_f32_16x16x32_bf16 v[72:75], v[0:3], v[48:51], v[116:119]
	v_mfma_f32_16x16x32_bf16 v[112:115], v[8:11], v[56:59], v[72:75]
	v_mfma_f32_16x16x32_bf16 v[72:75], v[16:19], v[48:51], v[202:205]
	v_mfma_f32_16x16x32_bf16 v[116:119], v[24:27], v[56:59], v[72:75]
	v_mfma_f32_16x16x32_bf16 v[72:75], v[0:3], v[64:67], v[108:111]
	v_mfma_f32_16x16x32_bf16 v[104:107], v[8:11], v[186:189], v[72:75]
	v_mfma_f32_16x16x32_bf16 v[72:75], v[16:19], v[64:67], v[206:209]
	v_mfma_f32_16x16x32_bf16 v[108:111], v[24:27], v[186:189], v[72:75]
	v_mfma_f32_16x16x32_bf16 v[72:75], v[0:3], v[194:197], v[100:103]
	v_mfma_f32_16x16x32_bf16 v[96:99], v[8:11], v[198:201], v[72:75]
	v_mfma_f32_16x16x32_bf16 v[72:75], v[16:19], v[194:197], v[222:225]
	v_mfma_f32_16x16x32_bf16 v[100:103], v[24:27], v[198:201], v[72:75]
	s_setprio 0
	s_barrier
	ds_read_b128 v[158:161], v152 offset:49152
	ds_read_b128 v[202:205], v152 offset:50176
	ds_read_b128 v[206:209], v152 offset:51200
	ds_read_b128 v[222:225], v152 offset:52224
	s_waitcnt vmcnt(0)
	s_barrier
	s_waitcnt lgkmcnt(0)
	s_setprio 1
	s_waitcnt lgkmcnt(0)
	v_mfma_f32_16x16x32_bf16 v[72:75], v[158:161], v[32:35], v[92:95]
	v_mfma_f32_16x16x32_bf16 v[32:35], v[206:209], v[32:35], v[166:169]
	v_mfma_f32_16x16x32_bf16 v[92:95], v[222:225], v[40:43], v[32:35]
	v_mfma_f32_16x16x32_bf16 v[32:35], v[158:161], v[48:51], v[84:87]
	v_mfma_f32_16x16x32_bf16 v[80:83], v[202:205], v[56:59], v[32:35]
	v_mfma_f32_16x16x32_bf16 v[32:35], v[206:209], v[48:51], v[170:173]
	v_mfma_f32_16x16x32_bf16 v[84:87], v[222:225], v[56:59], v[32:35]
	v_mfma_f32_16x16x32_bf16 v[32:35], v[158:161], v[64:67], v[76:79]
	v_mfma_f32_16x16x32_bf16 v[88:91], v[202:205], v[40:43], v[72:75]
	v_mfma_f32_16x16x32_bf16 v[72:75], v[202:205], v[186:189], v[32:35]
	v_mfma_f32_16x16x32_bf16 v[32:35], v[206:209], v[64:67], v[174:177]
	v_mfma_f32_16x16x32_bf16 v[76:79], v[222:225], v[186:189], v[32:35]
	v_mfma_f32_16x16x32_bf16 v[32:35], v[158:161], v[194:197], v[68:71]
	v_mfma_f32_16x16x32_bf16 v[64:67], v[202:205], v[198:201], v[32:35]
	v_mfma_f32_16x16x32_bf16 v[32:35], v[206:209], v[194:197], v[178:181]
	v_mfma_f32_16x16x32_bf16 v[68:71], v[222:225], v[198:201], v[32:35]
	s_setprio 0
	s_barrier
	ds_read_b128 v[166:169], v137 offset:49152
	ds_read_b128 v[170:173], v137 offset:50176
	ds_read_b128 v[174:177], v137 offset:51200
	ds_read_b128 v[178:181], v137 offset:52224
	ds_read_b128 v[186:189], v137 offset:53248
	ds_read_b128 v[194:197], v137 offset:54272
	ds_read_b128 v[198:201], v137 offset:55296
	ds_read_b128 v[238:241], v137 offset:56320
	s_barrier
	s_waitcnt lgkmcnt(0)
	s_setprio 1
	s_waitcnt lgkmcnt(0)
	v_mfma_f32_16x16x32_bf16 v[32:35], v[0:3], v[166:169], v[60:63]
	v_mfma_f32_16x16x32_bf16 v[56:59], v[8:11], v[170:173], v[32:35]
	v_mfma_f32_16x16x32_bf16 v[32:35], v[16:19], v[166:169], v[226:229]
	v_mfma_f32_16x16x32_bf16 v[60:63], v[24:27], v[170:173], v[32:35]
	v_mfma_f32_16x16x32_bf16 v[32:35], v[0:3], v[174:177], v[52:55]
	v_mfma_f32_16x16x32_bf16 v[48:51], v[8:11], v[178:181], v[32:35]
	v_mfma_f32_16x16x32_bf16 v[32:35], v[16:19], v[174:177], v[230:233]
	v_mfma_f32_16x16x32_bf16 v[52:55], v[24:27], v[178:181], v[32:35]
	v_mfma_f32_16x16x32_bf16 v[32:35], v[0:3], v[186:189], v[44:47]
	v_mfma_f32_16x16x32_bf16 v[40:43], v[8:11], v[194:197], v[32:35]
	v_mfma_f32_16x16x32_bf16 v[32:35], v[16:19], v[186:189], v[234:237]
	v_mfma_f32_16x16x32_bf16 v[0:3], v[0:3], v[198:201], v[36:39]
	v_mfma_f32_16x16x32_bf16 v[44:47], v[24:27], v[194:197], v[32:35]
	v_mfma_f32_16x16x32_bf16 v[32:35], v[8:11], v[238:241], v[0:3]
	v_mfma_f32_16x16x32_bf16 v[0:3], v[16:19], v[198:201], v[128:131]
	v_mfma_f32_16x16x32_bf16 v[36:39], v[24:27], v[238:241], v[0:3]
	s_setprio 0
	s_setprio 1
	v_mfma_f32_16x16x32_bf16 v[0:3], v[158:161], v[166:169], v[28:31]
	v_mfma_f32_16x16x32_bf16 v[24:27], v[202:205], v[170:173], v[0:3]
	v_mfma_f32_16x16x32_bf16 v[0:3], v[206:209], v[166:169], v[132:135]
	v_mfma_f32_16x16x32_bf16 v[28:31], v[222:225], v[170:173], v[0:3]
	v_mfma_f32_16x16x32_bf16 v[0:3], v[158:161], v[174:177], v[20:23]
	v_mfma_f32_16x16x32_bf16 v[16:19], v[202:205], v[178:181], v[0:3]
	v_mfma_f32_16x16x32_bf16 v[0:3], v[206:209], v[174:177], v[154:157]
	v_mfma_f32_16x16x32_bf16 v[20:23], v[222:225], v[178:181], v[0:3]
	v_mfma_f32_16x16x32_bf16 v[0:3], v[158:161], v[186:189], v[12:15]
	v_mfma_f32_16x16x32_bf16 v[8:11], v[202:205], v[194:197], v[0:3]
	v_mfma_f32_16x16x32_bf16 v[0:3], v[206:209], v[186:189], v[162:165]
	v_mfma_f32_16x16x32_bf16 v[12:15], v[222:225], v[194:197], v[0:3]
	v_mfma_f32_16x16x32_bf16 v[0:3], v[158:161], v[198:201], v[4:7]
	v_mfma_f32_16x16x32_bf16 v[4:7], v[206:209], v[198:201], v[182:185]
	v_mfma_f32_16x16x32_bf16 v[0:3], v[202:205], v[238:241], v[0:3]
	v_mfma_f32_16x16x32_bf16 v[4:7], v[222:225], v[238:241], v[4:7]
	s_setprio 0
	s_movk_i32 s0, 0x100
	v_cmp_gt_u32_e32 vcc, s0, v136
	s_barrier
	s_and_saveexec_b64 s[0:1], vcc
	s_cbranch_execz .LBB0_203
	s_barrier

; #define WAIT_V(n) asm volatile("s_waitcnt vmcnt(" #n ")" ::: "memory")
; #define WAIT_L(n) asm volatile("s_waitcnt lgkmcnt(" #n ")" ::: "memory")
; #define BAR __builtin_amdgcn_s_barrier()
; #define SCHED __builtin_amdgcn_sched_barrier(0)
; #define STAGE(P, BASE, br, kt) do { const char* _g = (const char*)((BASE) + (size_t)(br) * GK + (kt) * BK); \
;     __builtin_amdgcn_global_load_lds((const unsigned*)(_g + voff0), (unsigned*)((char*)(P) + tx * 16), 16, 0, 0); \
;     __builtin_amdgcn_global_load_lds((const unsigned*)(_g + voff1), (unsigned*)((char*)(P) + tx * 16 + 8192), 16, 0, 0); } while (0)
; #define LDA(dst, b, h) _Pragma("unroll") for (int m = 0; m < 4; ++m) _Pragma("unroll") for (int k = 0; k < 2; ++k) \
;     dst[m][k] = *reinterpret_cast<const bf16x8*>((char*)shm + abase + (((b) * 2 + (h)) * 16384 + (m * 2 + k) * 1024))
; #define LDB(dst, b, h) _Pragma("unroll") for (int n = 0; n < 2; ++n) _Pragma("unroll") for (int k = 0; k < 2; ++k) \
;     dst[n][k] = *reinterpret_cast<const bf16x8*>((char*)shm + bbase + (((b) * 2 + (h)) * 16384 + (n * 2 + k) * 1024))
; template <bool SWAP>
; __device__ __forceinline__ void gemm_main(const u16* __restrict__ A, const u16* __restrict__ Bt, int brow, int bcol,
;                                           u16* shm, f32x4 (&acc)[2][2][4][2]) {
;     ...
;   for (int t = 0; t < nt - 2; t += 2) {
;     LDB(B0, 0, 0); SCHED; LDA(At, 0, 0); STAGE(SA(1, 1), A, brow + HALF, t + 1);
;     WAIT_L(8); BAR; WAIT_L(0); MMA(0, 0, At, B0); BAR; SCHED;
;     LDB(B1, 0, 1); STAGE(SB(0, 0), Bt, bcol, t + 2);
;     BAR; WAIT_L(0); MMA(0, 1, At, B1); BAR;
;     LDA(At, 0, 1); STAGE(SA(0, 0), A, brow, t + 2);
;     BAR; WAIT_L(0); MMA(1, 0, At, B0); BAR; SCHED;
;     STAGE(SB(0, 1), Bt, bcol + HALF, t + 2);
;     WAIT_V(6); BAR; MMA(1, 1, At, B1); BAR;
;     LDB(B0, 1, 0); SCHED; LDA(At, 1, 0); STAGE(SA(0, 1), A, brow + HALF, t + 2);
.LBB0_436:
	ds_read_b128 v[170:173], v137 offset:1024
	ds_read_b128 v[178:181], v137 offset:3072
	ds_read_b128 v[186:189], v137 offset:5120
	ds_read_b128 v[198:201], v137 offset:7168
	v_add_u32_e32 v192, 0, v139
	v_add_u32_e32 v148, 0xc000, v192
	v_add_u32_e32 v149, 0xe000, v192
	s_add_u32 m0, s2, 0xc000
	v_lshl_add_u64 v[232:233], s[50:51], 0, v[134:135]
	s_add_u32 vcc_lo, s50, s82
	s_addc_u32 vcc_hi, s51, s83
	global_load_lds_dwordx4 v132, vcc
	s_add_u32 m0, s2, 0xe000
	s_nop 0
	global_load_lds_dwordx4 v134, vcc
	s_waitcnt lgkmcnt(8)
	s_barrier
	s_waitcnt lgkmcnt(0)
	v_mfma_f32_16x16x32_bf16 v[124:127], v[150:153], v[166:169], v[124:127]
	v_mfma_f32_16x16x32_bf16 v[120:123], v[158:161], v[166:169], v[120:123]
	v_mfma_f32_16x16x32_bf16 v[116:119], v[150:153], v[174:177], v[116:119]
	v_mfma_f32_16x16x32_bf16 v[112:115], v[158:161], v[174:177], v[112:115]
	v_mfma_f32_16x16x32_bf16 v[108:111], v[150:153], v[182:185], v[108:111]
	v_mfma_f32_16x16x32_bf16 v[104:107], v[158:161], v[182:185], v[104:107]
	v_mfma_f32_16x16x32_bf16 v[100:103], v[150:153], v[194:197], v[100:103]
	v_mfma_f32_16x16x32_bf16 v[96:99], v[158:161], v[194:197], v[96:99]
	v_mfma_f32_16x16x32_bf16 v[124:127], v[154:157], v[170:173], v[124:127]
	v_mfma_f32_16x16x32_bf16 v[120:123], v[162:165], v[170:173], v[120:123]
	v_mfma_f32_16x16x32_bf16 v[116:119], v[154:157], v[178:181], v[116:119]
	v_mfma_f32_16x16x32_bf16 v[112:115], v[162:165], v[178:181], v[112:115]
	v_mfma_f32_16x16x32_bf16 v[108:111], v[154:157], v[186:189], v[108:111]
	v_mfma_f32_16x16x32_bf16 v[104:107], v[162:165], v[186:189], v[104:107]
	v_mfma_f32_16x16x32_bf16 v[100:103], v[154:157], v[198:201], v[100:103]
	v_mfma_f32_16x16x32_bf16 v[96:99], v[162:165], v[198:201], v[96:99]
	s_barrier
	ds_read_b128 v[202:205], v138 offset:16384
	ds_read_b128 v[206:209], v138 offset:17408
	ds_read_b128 v[224:227], v138 offset:18432
	ds_read_b128 v[228:231], v138 offset:19456
	s_add_u32 m0, s2, s28
	s_nop 0
	s_add_u32 vcc_lo, s50, s74
	s_addc_u32 vcc_hi, s51, s75
	global_load_lds_dwordx4 v128, vcc
	v_lshl_add_u64 v[236:237], s[50:51], 0, v[130:131]
	s_add_u32 m0, s2, s28
	s_add_u32 m0, m0, 0x2000
	s_nop 0
	global_load_lds_dwordx4 v130, vcc
	s_barrier
	s_waitcnt lgkmcnt(0)
	v_mfma_f32_16x16x32_bf16 v[92:95], v[202:205], v[166:169], v[92:95]
	v_mfma_f32_16x16x32_bf16 v[88:91], v[224:227], v[166:169], v[88:91]
	v_mfma_f32_16x16x32_bf16 v[84:87], v[202:205], v[174:177], v[84:87]
	v_mfma_f32_16x16x32_bf16 v[80:83], v[224:227], v[174:177], v[80:83]
	v_mfma_f32_16x16x32_bf16 v[76:79], v[202:205], v[182:185], v[76:79]
	v_mfma_f32_16x16x32_bf16 v[72:75], v[224:227], v[182:185], v[72:75]
	v_mfma_f32_16x16x32_bf16 v[68:71], v[202:205], v[194:197], v[68:71]
	v_mfma_f32_16x16x32_bf16 v[64:67], v[224:227], v[194:197], v[64:67]
	v_mfma_f32_16x16x32_bf16 v[92:95], v[206:209], v[170:173], v[92:95]
	ds_read_b128 v[166:169], v137 offset:16384
	v_mfma_f32_16x16x32_bf16 v[88:91], v[228:231], v[170:173], v[88:91]
	v_mfma_f32_16x16x32_bf16 v[84:87], v[206:209], v[178:181], v[84:87]
	ds_read_b128 v[174:177], v137 offset:18432
	v_mfma_f32_16x16x32_bf16 v[80:83], v[228:231], v[178:181], v[80:83]
	v_mfma_f32_16x16x32_bf16 v[76:79], v[206:209], v[186:189], v[76:79]
	ds_read_b128 v[182:185], v137 offset:20480
	v_mfma_f32_16x16x32_bf16 v[72:75], v[228:231], v[186:189], v[72:75]
	v_mfma_f32_16x16x32_bf16 v[68:71], v[206:209], v[198:201], v[68:71]
	ds_read_b128 v[194:197], v137 offset:22528
	v_mfma_f32_16x16x32_bf16 v[64:67], v[228:231], v[198:201], v[64:67]
	s_barrier
	ds_read_b128 v[170:173], v137 offset:17408
	ds_read_b128 v[178:181], v137 offset:19456
	ds_read_b128 v[186:189], v137 offset:21504
	ds_read_b128 v[198:201], v137 offset:23552
	s_add_u32 m0, s2, 0x0
	s_nop 0
	s_add_u32 vcc_lo, s50, s76
	s_addc_u32 vcc_hi, s51, s77
	global_load_lds_dwordx4 v132, vcc
	s_add_u32 m0, s2, 0x2000
	s_nop 0
	global_load_lds_dwordx4 v134, vcc
	s_waitcnt vmcnt(8)
	s_barrier
	s_waitcnt lgkmcnt(0)
	v_mfma_f32_16x16x32_bf16 v[60:63], v[150:153], v[166:169], v[60:63]
	v_mfma_f32_16x16x32_bf16 v[56:59], v[158:161], v[166:169], v[56:59]
	v_mfma_f32_16x16x32_bf16 v[52:55], v[150:153], v[174:177], v[52:55]
	v_mfma_f32_16x16x32_bf16 v[48:51], v[158:161], v[174:177], v[48:51]
	v_mfma_f32_16x16x32_bf16 v[44:47], v[150:153], v[182:185], v[44:47]
	v_mfma_f32_16x16x32_bf16 v[40:43], v[158:161], v[182:185], v[40:43]
	v_mfma_f32_16x16x32_bf16 v[36:39], v[150:153], v[194:197], v[36:39]
	v_mfma_f32_16x16x32_bf16 v[32:35], v[158:161], v[194:197], v[32:35]
	v_mfma_f32_16x16x32_bf16 v[60:63], v[154:157], v[170:173], v[60:63]
	v_mfma_f32_16x16x32_bf16 v[56:59], v[162:165], v[170:173], v[56:59]
	v_mfma_f32_16x16x32_bf16 v[52:55], v[154:157], v[178:181], v[52:55]
	v_mfma_f32_16x16x32_bf16 v[48:51], v[162:165], v[178:181], v[48:51]
	v_mfma_f32_16x16x32_bf16 v[44:47], v[154:157], v[186:189], v[44:47]
	v_mfma_f32_16x16x32_bf16 v[40:43], v[162:165], v[186:189], v[40:43]
	v_mfma_f32_16x16x32_bf16 v[36:39], v[154:157], v[198:201], v[36:39]
	v_mfma_f32_16x16x32_bf16 v[32:35], v[162:165], v[198:201], v[32:35]
	s_barrier
	ds_read_b128 v[150:153], v138 offset:32768
	ds_read_b128 v[154:157], v138 offset:33792
	ds_read_b128 v[158:161], v138 offset:34816
	ds_read_b128 v[162:165], v138 offset:35840
	s_add_u32 m0, s2, s29
	s_nop 0
	s_add_u32 vcc_lo, s50, s70
	s_addc_u32 vcc_hi, s51, s71
	global_load_lds_dwordx4 v128, vcc
	s_add_u32 m0, s2, s29
	s_add_u32 m0, m0, 0x2000
	s_nop 0
	global_load_lds_dwordx4 v130, vcc
	s_waitcnt vmcnt(6)
	s_barrier
; #define WAIT_V(n) asm volatile("s_waitcnt vmcnt(" #n ")" ::: "memory")
; #define WAIT_L(n) asm volatile("s_waitcnt lgkmcnt(" #n ")" ::: "memory")
; #define BAR __builtin_amdgcn_s_barrier()
; #define SCHED __builtin_amdgcn_sched_barrier(0)
; #define STAGE(P, BASE, br, kt) do { const char* _g = (const char*)((BASE) + (size_t)(br) * GK + (kt) * BK); \
;     __builtin_amdgcn_global_load_lds((const unsigned*)(_g + voff0), (unsigned*)((char*)(P) + tx * 16), 16, 0, 0); \
;     __builtin_amdgcn_global_load_lds((const unsigned*)(_g + voff1), (unsigned*)((char*)(P) + tx * 16 + 8192), 16, 0, 0); } while (0)
; #define LDA(dst, b, h) _Pragma("unroll") for (int m = 0; m < 4; ++m) _Pragma("unroll") for (int k = 0; k < 2; ++k) \
;     dst[m][k] = *reinterpret_cast<const bf16x8*>((char*)shm + abase + (((b) * 2 + (h)) * 16384 + (m * 2 + k) * 1024))
; #define LDB(dst, b, h) _Pragma("unroll") for (int n = 0; n < 2; ++n) _Pragma("unroll") for (int k = 0; k < 2; ++k) \
;     dst[n][k] = *reinterpret_cast<const bf16x8*>((char*)shm + bbase + (((b) * 2 + (h)) * 16384 + (n * 2 + k) * 1024))
; template <bool SWAP>
; __device__ __forceinline__ void gemm_main(const u16* __restrict__ A, const u16* __restrict__ Bt, int brow, int bcol,
;                                           u16* shm, f32x4 (&acc)[2][2][4][2]) {
;     ...
;     WAIT_V(6); BAR; MMA(1, 1, At, B1); BAR;
;     LDB(B0, 1, 0); SCHED; LDA(At, 1, 0); STAGE(SA(0, 1), A, brow + HALF, t + 2);
;     WAIT_L(8); BAR; WAIT_L(0); MMA(0, 0, At, B0); BAR; SCHED;
;     LDB(B1, 1, 1); STAGE(SB(1, 0), Bt, bcol, t + 3);
;     BAR; WAIT_L(0); MMA(0, 1, At, B1); BAR;
;     LDA(At, 1, 1); STAGE(SA(1, 0), A, brow, t + 3);
;     BAR; WAIT_L(0); MMA(1, 0, At, B0); BAR; SCHED;
	v_mfma_f32_16x16x32_bf16 v[28:31], v[202:205], v[166:169], v[28:31]
	v_mfma_f32_16x16x32_bf16 v[24:27], v[224:227], v[166:169], v[24:27]
	v_mfma_f32_16x16x32_bf16 v[20:23], v[202:205], v[174:177], v[20:23]
	v_mfma_f32_16x16x32_bf16 v[16:19], v[224:227], v[174:177], v[16:19]
	v_mfma_f32_16x16x32_bf16 v[12:15], v[202:205], v[182:185], v[12:15]
	v_mfma_f32_16x16x32_bf16 v[8:11], v[224:227], v[182:185], v[8:11]
	v_mfma_f32_16x16x32_bf16 v[4:7], v[202:205], v[194:197], v[4:7]
	v_mfma_f32_16x16x32_bf16 v[0:3], v[224:227], v[194:197], v[0:3]
	v_mfma_f32_16x16x32_bf16 v[28:31], v[206:209], v[170:173], v[28:31]
	ds_read_b128 v[166:169], v137 offset:32768
	v_mfma_f32_16x16x32_bf16 v[24:27], v[228:231], v[170:173], v[24:27]
	v_mfma_f32_16x16x32_bf16 v[20:23], v[206:209], v[178:181], v[20:23]
	ds_read_b128 v[174:177], v137 offset:34816
	v_mfma_f32_16x16x32_bf16 v[16:19], v[228:231], v[178:181], v[16:19]
	v_mfma_f32_16x16x32_bf16 v[12:15], v[206:209], v[186:189], v[12:15]
	ds_read_b128 v[182:185], v137 offset:36864
	v_mfma_f32_16x16x32_bf16 v[8:11], v[228:231], v[186:189], v[8:11]
	v_mfma_f32_16x16x32_bf16 v[4:7], v[206:209], v[198:201], v[4:7]
	ds_read_b128 v[194:197], v137 offset:38912
	v_mfma_f32_16x16x32_bf16 v[0:3], v[228:231], v[198:201], v[0:3]
	s_barrier
	ds_read_b128 v[170:173], v137 offset:33792
	ds_read_b128 v[178:181], v137 offset:35840
	ds_read_b128 v[186:189], v137 offset:37888
	ds_read_b128 v[198:201], v137 offset:39936
	s_add_u32 m0, s2, 0x4000
	s_nop 0
	s_add_u32 vcc_lo, s50, s96
	s_addc_u32 vcc_hi, s51, s97
	global_load_lds_dwordx4 v132, vcc
	s_add_u32 m0, s2, 0x6000
	s_nop 0
	global_load_lds_dwordx4 v134, vcc
	s_waitcnt lgkmcnt(8)
	s_barrier
	s_waitcnt lgkmcnt(0)
	v_mfma_f32_16x16x32_bf16 v[124:127], v[150:153], v[166:169], v[124:127]
	v_mfma_f32_16x16x32_bf16 v[120:123], v[158:161], v[166:169], v[120:123]
	v_mfma_f32_16x16x32_bf16 v[116:119], v[150:153], v[174:177], v[116:119]
	v_mfma_f32_16x16x32_bf16 v[112:115], v[158:161], v[174:177], v[112:115]
	v_mfma_f32_16x16x32_bf16 v[108:111], v[150:153], v[182:185], v[108:111]
	v_mfma_f32_16x16x32_bf16 v[104:107], v[158:161], v[182:185], v[104:107]
	v_mfma_f32_16x16x32_bf16 v[100:103], v[150:153], v[194:197], v[100:103]
	v_mfma_f32_16x16x32_bf16 v[96:99], v[158:161], v[194:197], v[96:99]
	v_mfma_f32_16x16x32_bf16 v[124:127], v[154:157], v[170:173], v[124:127]
	v_mfma_f32_16x16x32_bf16 v[120:123], v[162:165], v[170:173], v[120:123]
	v_mfma_f32_16x16x32_bf16 v[116:119], v[154:157], v[178:181], v[116:119]
	v_mfma_f32_16x16x32_bf16 v[112:115], v[162:165], v[178:181], v[112:115]
	v_mfma_f32_16x16x32_bf16 v[108:111], v[154:157], v[186:189], v[108:111]
	v_mfma_f32_16x16x32_bf16 v[104:107], v[162:165], v[186:189], v[104:107]
	v_mfma_f32_16x16x32_bf16 v[100:103], v[154:157], v[198:201], v[100:103]
	v_mfma_f32_16x16x32_bf16 v[96:99], v[162:165], v[198:201], v[96:99]
	s_barrier
	ds_read_b128 v[202:205], v138 offset:49152
	ds_read_b128 v[206:209], v138 offset:50176
	ds_read_b128 v[224:227], v138 offset:51200
	ds_read_b128 v[228:231], v138 offset:52224
	s_add_u32 m0, s2, s30
	s_nop 0
	s_add_u32 vcc_lo, s50, s34
	s_addc_u32 vcc_hi, s51, s35
	global_load_lds_dwordx4 v128, vcc
	v_lshl_add_u64 v[238:239], v[236:237], 0, s[34:35]
	s_add_u32 m0, s2, s30
	s_add_u32 m0, m0, 0x2000
	s_nop 0
	global_load_lds_dwordx4 v130, vcc
	s_barrier
	s_waitcnt lgkmcnt(0)
	v_mfma_f32_16x16x32_bf16 v[92:95], v[202:205], v[166:169], v[92:95]
	v_mfma_f32_16x16x32_bf16 v[88:91], v[224:227], v[166:169], v[88:91]
	v_mfma_f32_16x16x32_bf16 v[84:87], v[202:205], v[174:177], v[84:87]
	v_mfma_f32_16x16x32_bf16 v[80:83], v[224:227], v[174:177], v[80:83]
	v_mfma_f32_16x16x32_bf16 v[76:79], v[202:205], v[182:185], v[76:79]
	v_mfma_f32_16x16x32_bf16 v[72:75], v[224:227], v[182:185], v[72:75]
	v_mfma_f32_16x16x32_bf16 v[68:71], v[202:205], v[194:197], v[68:71]
	v_mfma_f32_16x16x32_bf16 v[64:67], v[224:227], v[194:197], v[64:67]
	v_mfma_f32_16x16x32_bf16 v[92:95], v[206:209], v[170:173], v[92:95]
	ds_read_b128 v[166:169], v137 offset:49152
	v_mfma_f32_16x16x32_bf16 v[88:91], v[228:231], v[170:173], v[88:91]
	v_mfma_f32_16x16x32_bf16 v[84:87], v[206:209], v[178:181], v[84:87]
	ds_read_b128 v[174:177], v137 offset:51200
	v_mfma_f32_16x16x32_bf16 v[80:83], v[228:231], v[178:181], v[80:83]
	v_mfma_f32_16x16x32_bf16 v[76:79], v[206:209], v[186:189], v[76:79]
	ds_read_b128 v[182:185], v137 offset:53248
	v_mfma_f32_16x16x32_bf16 v[72:75], v[228:231], v[186:189], v[72:75]
	v_mfma_f32_16x16x32_bf16 v[68:71], v[206:209], v[198:201], v[68:71]
	ds_read_b128 v[194:197], v137 offset:55296
	v_mfma_f32_16x16x32_bf16 v[64:67], v[228:231], v[198:201], v[64:67]
	s_barrier
	ds_read_b128 v[170:173], v137 offset:50176
	ds_read_b128 v[178:181], v137 offset:52224
	ds_read_b128 v[186:189], v137 offset:54272
	ds_read_b128 v[198:201], v137 offset:56320
	v_add_u32_e32 v223, 0x8000, v192
	s_add_u32 m0, s2, 0x8000
	s_nop 0
	s_add_u32 vcc_lo, s50, s36
	s_addc_u32 vcc_hi, s51, s37
	global_load_lds_dwordx4 v132, vcc
	v_lshl_add_u64 v[190:191], v[232:233], 0, s[36:37]
	s_add_u32 m0, s2, 0xa000
	s_nop 0
	global_load_lds_dwordx4 v134, vcc
	s_waitcnt vmcnt(8)
	s_barrier
; #define WAIT_V(n) asm volatile("s_waitcnt vmcnt(" #n ")" ::: "memory")
; #define WAIT_L(n) asm volatile("s_waitcnt lgkmcnt(" #n ")" ::: "memory")
; #define BAR __builtin_amdgcn_s_barrier()
; #define SCHED __builtin_amdgcn_sched_barrier(0)
; #define STAGE(P, BASE, br, kt) do { const char* _g = (const char*)((BASE) + (size_t)(br) * GK + (kt) * BK); \
;     __builtin_amdgcn_global_load_lds((const unsigned*)(_g + voff0), (unsigned*)((char*)(P) + tx * 16), 16, 0, 0); \
;     __builtin_amdgcn_global_load_lds((const unsigned*)(_g + voff1), (unsigned*)((char*)(P) + tx * 16 + 8192), 16, 0, 0); } while (0)
; #define LDA(dst, b, h) _Pragma("unroll") for (int m = 0; m < 4; ++m) _Pragma("unroll") for (int k = 0; k < 2; ++k) \
;     dst[m][k] = *reinterpret_cast<const bf16x8*>((char*)shm + abase + (((b) * 2 + (h)) * 16384 + (m * 2 + k) * 1024))
; #define LDB(dst, b, h) _Pragma("unroll") for (int n = 0; n < 2; ++n) _Pragma("unroll") for (int k = 0; k < 2; ++k) \
;     dst[n][k] = *reinterpret_cast<const bf16x8*>((char*)shm + bbase + (((b) * 2 + (h)) * 16384 + (n * 2 + k) * 1024))
; template <bool SWAP>
; __device__ __forceinline__ void gemm_main(const u16* __restrict__ A, const u16* __restrict__ Bt, int brow, int bcol,
;                                           u16* shm, f32x4 (&acc)[2][2][4][2]) {
;     ...
;     LDA(At, 1, 1); STAGE(SA(1, 0), A, brow, t + 3);
;     BAR; WAIT_L(0); MMA(1, 0, At, B0); BAR; SCHED;
;     STAGE(SB(1, 1), Bt, bcol + HALF, t + 3);
;     WAIT_V(6); BAR; MMA(1, 1, At, B1); BAR;
;   }
;   { LDB(B0, 0, 0); LDA(At, 0, 0); STAGE(SA(1, 1), A, brow + HALF, nt - 1);
;     BAR; WAIT_L(0); MMA(0, 0, At, B0); BAR;
	s_waitcnt lgkmcnt(0)
	v_mfma_f32_16x16x32_bf16 v[60:63], v[150:153], v[166:169], v[60:63]
	v_mfma_f32_16x16x32_bf16 v[56:59], v[158:161], v[166:169], v[56:59]
	v_mfma_f32_16x16x32_bf16 v[52:55], v[150:153], v[174:177], v[52:55]
	v_mfma_f32_16x16x32_bf16 v[48:51], v[158:161], v[174:177], v[48:51]
	v_mfma_f32_16x16x32_bf16 v[44:47], v[150:153], v[182:185], v[44:47]
	v_mfma_f32_16x16x32_bf16 v[40:43], v[158:161], v[182:185], v[40:43]
	v_mfma_f32_16x16x32_bf16 v[36:39], v[150:153], v[194:197], v[36:39]
	v_mfma_f32_16x16x32_bf16 v[32:35], v[158:161], v[194:197], v[32:35]
	v_mfma_f32_16x16x32_bf16 v[60:63], v[154:157], v[170:173], v[60:63]
	v_mfma_f32_16x16x32_bf16 v[56:59], v[162:165], v[170:173], v[56:59]
	v_mfma_f32_16x16x32_bf16 v[52:55], v[154:157], v[178:181], v[52:55]
	v_mfma_f32_16x16x32_bf16 v[48:51], v[162:165], v[178:181], v[48:51]
	v_mfma_f32_16x16x32_bf16 v[44:47], v[154:157], v[186:189], v[44:47]
	v_mfma_f32_16x16x32_bf16 v[40:43], v[162:165], v[186:189], v[40:43]
	v_mfma_f32_16x16x32_bf16 v[36:39], v[154:157], v[198:201], v[36:39]
	v_mfma_f32_16x16x32_bf16 v[32:35], v[162:165], v[198:201], v[32:35]
	s_barrier
	ds_read_b128 v[150:153], v138
	ds_read_b128 v[154:157], v138 offset:1024
	ds_read_b128 v[158:161], v138 offset:2048
	ds_read_b128 v[162:165], v138 offset:3072
	s_add_u32 m0, s2, s31
	s_nop 0
	s_add_u32 vcc_lo, s50, s64
	s_addc_u32 vcc_hi, s51, s65
	global_load_lds_dwordx4 v128, vcc
	v_lshl_add_u64 v[254:255], v[236:237], 0, s[64:65]
	s_add_u32 m0, s2, s31
	s_add_u32 m0, m0, 0x2000
	s_nop 0
	global_load_lds_dwordx4 v130, vcc
	s_waitcnt vmcnt(6)
	s_barrier
	v_mfma_f32_16x16x32_bf16 v[28:31], v[202:205], v[166:169], v[28:31]
	v_mfma_f32_16x16x32_bf16 v[24:27], v[224:227], v[166:169], v[24:27]
	v_mfma_f32_16x16x32_bf16 v[20:23], v[202:205], v[174:177], v[20:23]
	v_mfma_f32_16x16x32_bf16 v[16:19], v[224:227], v[174:177], v[16:19]
	v_mfma_f32_16x16x32_bf16 v[12:15], v[202:205], v[182:185], v[12:15]
	v_mfma_f32_16x16x32_bf16 v[8:11], v[224:227], v[182:185], v[8:11]
	v_mfma_f32_16x16x32_bf16 v[4:7], v[202:205], v[194:197], v[4:7]
	v_mfma_f32_16x16x32_bf16 v[0:3], v[224:227], v[194:197], v[0:3]
	v_mfma_f32_16x16x32_bf16 v[28:31], v[206:209], v[170:173], v[28:31]
	ds_read_b128 v[166:169], v137
	v_mfma_f32_16x16x32_bf16 v[24:27], v[228:231], v[170:173], v[24:27]
	v_mfma_f32_16x16x32_bf16 v[20:23], v[206:209], v[178:181], v[20:23]
	ds_read_b128 v[174:177], v137 offset:2048
	v_mfma_f32_16x16x32_bf16 v[16:19], v[228:231], v[178:181], v[16:19]
	v_mfma_f32_16x16x32_bf16 v[12:15], v[206:209], v[186:189], v[12:15]
	ds_read_b128 v[182:185], v137 offset:4096
	v_mfma_f32_16x16x32_bf16 v[8:11], v[228:231], v[186:189], v[8:11]
	v_mfma_f32_16x16x32_bf16 v[4:7], v[206:209], v[198:201], v[4:7]
	ds_read_b128 v[194:197], v137 offset:6144
	v_mfma_f32_16x16x32_bf16 v[0:3], v[228:231], v[198:201], v[0:3]
	s_add_i32 s1, s1, 2
	v_lshl_add_u64 v[128:129], v[128:129], 0, s[74:75]
	v_lshl_add_u64 v[130:131], v[130:131], 0, s[74:75]
	v_lshl_add_u64 v[132:133], v[132:133], 0, s[74:75]
	s_cmp_lt_u32 s1, 28
	v_lshl_add_u64 v[134:135], v[134:135], 0, s[74:75]
	s_barrier
	s_cbranch_scc1 .LBB0_436
	v_lshlrev_b32_e32 v128, 3, v142
	v_lshlrev_b32_e32 v129, 5, v142
	v_and_b32_e32 v128, 0xffff0, v128
	v_and_b32_e32 v129, 32, v129
	s_or_b32 s2, s0, 0x80
	v_add_u32_e32 v129, v129, v144
	v_add_lshl_u32 v128, v143, v128, 12
	s_ashr_i32 s3, s2, 31
	v_lshl_add_u32 v192, v129, 1, v128
	v_lshlrev_b32_e32 v128, 3, v145
	v_lshlrev_b32_e32 v129, 5, v145
	s_lshl_b64 s[2:3], s[2:3], 12
	v_and_b32_e32 v128, 0xffff0, v128
	v_and_b32_e32 v129, 32, v129
	s_add_u32 s2, s16, s2
	v_add_u32_e32 v129, v129, v147
	v_add_lshl_u32 v128, v146, v128, 12
	s_addc_u32 s3, s17, s3
	v_lshl_add_u32 v146, v129, 1, v128
	v_mov_b32_e32 v147, v193
	v_lshl_add_u64 v[186:187], s[2:3], 0, v[192:193]
	s_mov_b64 s[8:9], 0xf80
	v_readfirstlane_b32 s1, v148
	v_lshl_add_u64 v[186:187], v[186:187], 0, s[8:9]
	s_mov_b32 m0, s1
	v_lshl_add_u64 v[146:147], s[2:3], 0, v[146:147]
	v_readfirstlane_b32 s1, v149
	ds_read_b128 v[128:131], v138
	ds_read_b128 v[132:135], v138 offset:1024
	ds_read_b128 v[142:145], v138 offset:2048
	ds_read_b128 v[150:153], v138 offset:3072
	ds_read_b128 v[154:157], v137
	ds_read_b128 v[158:161], v137 offset:1024
	ds_read_b128 v[162:165], v137 offset:2048
	ds_read_b128 v[166:169], v137 offset:3072
	ds_read_b128 v[170:173], v137 offset:4096
	ds_read_b128 v[174:177], v137 offset:5120
	ds_read_b128 v[178:181], v137 offset:6144
	ds_read_b128 v[182:185], v137 offset:7168
	global_load_lds_dwordx4 v[186:187], off
	v_lshl_add_u64 v[146:147], v[146:147], 0, s[8:9]
	s_mov_b32 m0, s1
	s_nop 0
	global_load_lds_dwordx4 v[146:147], off
	s_barrier
	s_waitcnt lgkmcnt(0)
	s_setprio 1
	s_waitcnt lgkmcnt(0)
	v_mfma_f32_16x16x32_bf16 v[124:127], v[128:131], v[154:157], v[124:127]
	v_mfma_f32_16x16x32_bf16 v[112:115], v[142:145], v[162:165], v[112:115]
	v_mfma_f32_16x16x32_bf16 v[104:107], v[142:145], v[170:173], v[104:107]
	v_mfma_f32_16x16x32_bf16 v[96:99], v[142:145], v[178:181], v[96:99]
	v_mfma_f32_16x16x32_bf16 v[124:127], v[132:135], v[158:161], v[124:127]
	v_mfma_f32_16x16x32_bf16 v[120:123], v[142:145], v[154:157], v[120:123]
	v_mfma_f32_16x16x32_bf16 v[116:119], v[128:131], v[162:165], v[116:119]
	v_mfma_f32_16x16x32_bf16 v[112:115], v[150:153], v[166:169], v[112:115]
	v_mfma_f32_16x16x32_bf16 v[108:111], v[128:131], v[170:173], v[108:111]
	v_mfma_f32_16x16x32_bf16 v[104:107], v[150:153], v[174:177], v[104:107]
	v_mfma_f32_16x16x32_bf16 v[100:103], v[128:131], v[178:181], v[100:103]
	v_mfma_f32_16x16x32_bf16 v[96:99], v[150:153], v[182:185], v[96:99]
	v_mfma_f32_16x16x32_bf16 v[146:149], v[150:153], v[158:161], v[120:123]
	v_mfma_f32_16x16x32_bf16 v[186:189], v[132:135], v[166:169], v[116:119]
	v_mfma_f32_16x16x32_bf16 v[194:197], v[132:135], v[174:177], v[108:111]
	v_mfma_f32_16x16x32_bf16 v[198:201], v[132:135], v[182:185], v[100:103]
	s_setprio 0
	s_barrier
; #define WAIT_V(n) asm volatile("s_waitcnt vmcnt(" #n ")" ::: "memory")
; #define WAIT_L(n) asm volatile("s_waitcnt lgkmcnt(" #n ")" ::: "memory")
; #define BAR __builtin_amdgcn_s_barrier()
; #define LDA(dst, b, h) _Pragma("unroll") for (int m = 0; m < 4; ++m) _Pragma("unroll") for (int k = 0; k < 2; ++k) \
;     dst[m][k] = *reinterpret_cast<const bf16x8*>((char*)shm + abase + (((b) * 2 + (h)) * 16384 + (m * 2 + k) * 1024))
; #define LDB(dst, b, h) _Pragma("unroll") for (int n = 0; n < 2; ++n) _Pragma("unroll") for (int k = 0; k < 2; ++k) \
;     dst[n][k] = *reinterpret_cast<const bf16x8*>((char*)shm + bbase + (((b) * 2 + (h)) * 16384 + (n * 2 + k) * 1024))
; template <bool SWAP>
; __device__ __forceinline__ void gemm_main(const u16* __restrict__ A, const u16* __restrict__ Bt, int brow, int bcol,
;                                           u16* shm, f32x4 (&acc)[2][2][4][2]) {
;     ...
;     BAR; WAIT_L(0); MMA(0, 0, At, B0); BAR;
;     LDB(B1, 0, 1); BAR; WAIT_L(0); MMA(0, 1, At, B1); BAR;
;     LDA(At, 0, 1); WAIT_V(4); BAR; WAIT_L(0); MMA(1, 0, At, B0); MMA(1, 1, At, B1); BAR; }
;   { LDB(B0, 1, 0); LDA(At, 1, 0); WAIT_V(2); BAR; WAIT_L(0); MMA(0, 0, At, B0); BAR;
;     LDB(B1, 1, 1); WAIT_V(0); BAR; WAIT_L(0); MMA(0, 1, At, B1); BAR;
	s_nop 0
	ds_read_b128 v[100:103], v138 offset:16384
	ds_read_b128 v[108:111], v138 offset:17408
	ds_read_b128 v[116:119], v138 offset:18432
	ds_read_b128 v[120:123], v138 offset:19456
	s_barrier
	s_waitcnt lgkmcnt(0)
	s_setprio 1
	s_waitcnt lgkmcnt(0)
	v_mfma_f32_16x16x32_bf16 v[88:91], v[116:119], v[154:157], v[88:91]
	v_mfma_f32_16x16x32_bf16 v[80:83], v[116:119], v[162:165], v[80:83]
	v_mfma_f32_16x16x32_bf16 v[72:75], v[116:119], v[170:173], v[72:75]
	v_mfma_f32_16x16x32_bf16 v[64:67], v[116:119], v[178:181], v[64:67]
	v_mfma_f32_16x16x32_bf16 v[92:95], v[100:103], v[154:157], v[92:95]
	v_mfma_f32_16x16x32_bf16 v[88:91], v[120:123], v[158:161], v[88:91]
	v_mfma_f32_16x16x32_bf16 v[84:87], v[100:103], v[162:165], v[84:87]
	v_mfma_f32_16x16x32_bf16 v[80:83], v[120:123], v[166:169], v[80:83]
	v_mfma_f32_16x16x32_bf16 v[76:79], v[100:103], v[170:173], v[76:79]
	v_mfma_f32_16x16x32_bf16 v[72:75], v[120:123], v[174:177], v[72:75]
	v_mfma_f32_16x16x32_bf16 v[68:71], v[100:103], v[178:181], v[68:71]
	v_mfma_f32_16x16x32_bf16 v[64:67], v[120:123], v[182:185], v[64:67]
	v_mfma_f32_16x16x32_bf16 v[202:205], v[108:111], v[158:161], v[92:95]
	v_mfma_f32_16x16x32_bf16 v[154:157], v[108:111], v[166:169], v[84:87]
	v_mfma_f32_16x16x32_bf16 v[158:161], v[108:111], v[174:177], v[76:79]
	v_mfma_f32_16x16x32_bf16 v[162:165], v[108:111], v[182:185], v[68:71]
	s_setprio 0
	s_barrier
	s_nop 0
	ds_read_b128 v[68:71], v137 offset:16384
	ds_read_b128 v[76:79], v137 offset:17408
	ds_read_b128 v[84:87], v137 offset:18432
	ds_read_b128 v[92:95], v137 offset:19456
	ds_read_b128 v[166:169], v137 offset:20480
	ds_read_b128 v[170:173], v137 offset:21504
	ds_read_b128 v[174:177], v137 offset:22528
	ds_read_b128 v[178:181], v137 offset:23552
	s_waitcnt vmcnt(4)
	s_barrier
	s_waitcnt lgkmcnt(0)
	s_setprio 1
	s_waitcnt lgkmcnt(0)
	v_mfma_f32_16x16x32_bf16 v[60:63], v[128:131], v[68:71], v[60:63]
	v_mfma_f32_16x16x32_bf16 v[56:59], v[142:145], v[68:71], v[56:59]
	v_mfma_f32_16x16x32_bf16 v[48:51], v[142:145], v[84:87], v[48:51]
	v_mfma_f32_16x16x32_bf16 v[40:43], v[142:145], v[166:169], v[40:43]
	v_mfma_f32_16x16x32_bf16 v[32:35], v[142:145], v[174:177], v[32:35]
	v_mfma_f32_16x16x32_bf16 v[60:63], v[132:135], v[76:79], v[60:63]
	v_mfma_f32_16x16x32_bf16 v[56:59], v[150:153], v[76:79], v[56:59]
	v_mfma_f32_16x16x32_bf16 v[52:55], v[128:131], v[84:87], v[52:55]
	v_mfma_f32_16x16x32_bf16 v[48:51], v[150:153], v[92:95], v[48:51]
	v_mfma_f32_16x16x32_bf16 v[44:47], v[128:131], v[166:169], v[44:47]
	v_mfma_f32_16x16x32_bf16 v[40:43], v[150:153], v[170:173], v[40:43]
	v_mfma_f32_16x16x32_bf16 v[36:39], v[128:131], v[174:177], v[36:39]
	v_mfma_f32_16x16x32_bf16 v[32:35], v[150:153], v[178:181], v[32:35]
	v_mfma_f32_16x16x32_bf16 v[182:185], v[132:135], v[92:95], v[52:55]
	v_mfma_f32_16x16x32_bf16 v[206:209], v[132:135], v[170:173], v[44:47]
	v_mfma_f32_16x16x32_bf16 v[128:131], v[132:135], v[178:181], v[36:39]
	s_setprio 0
	s_setprio 1
	v_mfma_f32_16x16x32_bf16 v[24:27], v[116:119], v[68:71], v[24:27]
	v_mfma_f32_16x16x32_bf16 v[16:19], v[116:119], v[84:87], v[16:19]
	v_mfma_f32_16x16x32_bf16 v[8:11], v[116:119], v[166:169], v[8:11]
	v_mfma_f32_16x16x32_bf16 v[0:3], v[116:119], v[174:177], v[0:3]
	v_mfma_f32_16x16x32_bf16 v[28:31], v[100:103], v[68:71], v[28:31]
	v_mfma_f32_16x16x32_bf16 v[24:27], v[120:123], v[76:79], v[24:27]
	v_mfma_f32_16x16x32_bf16 v[20:23], v[100:103], v[84:87], v[20:23]
	v_mfma_f32_16x16x32_bf16 v[16:19], v[120:123], v[92:95], v[16:19]
	v_mfma_f32_16x16x32_bf16 v[12:15], v[100:103], v[166:169], v[12:15]
	v_mfma_f32_16x16x32_bf16 v[8:11], v[120:123], v[170:173], v[8:11]
	v_mfma_f32_16x16x32_bf16 v[4:7], v[100:103], v[174:177], v[4:7]
	v_mfma_f32_16x16x32_bf16 v[0:3], v[120:123], v[178:181], v[0:3]
	v_mfma_f32_16x16x32_bf16 v[132:135], v[108:111], v[76:79], v[28:31]
	v_mfma_f32_16x16x32_bf16 v[142:145], v[108:111], v[92:95], v[20:23]
	v_mfma_f32_16x16x32_bf16 v[150:153], v[108:111], v[170:173], v[12:15]
	v_mfma_f32_16x16x32_bf16 v[166:169], v[108:111], v[178:181], v[4:7]
	s_setprio 0
	s_barrier
	s_nop 0
	ds_read_b128 v[4:7], v138 offset:32768
	ds_read_b128 v[12:15], v138 offset:33792
	ds_read_b128 v[170:173], v138 offset:34816
	ds_read_b128 v[174:177], v138 offset:35840
	ds_read_b128 v[20:23], v137 offset:32768
	ds_read_b128 v[28:31], v137 offset:33792
	ds_read_b128 v[36:39], v137 offset:34816
	ds_read_b128 v[44:47], v137 offset:35840
	ds_read_b128 v[52:55], v137 offset:36864
	ds_read_b128 v[178:181], v137 offset:37888
	ds_read_b128 v[224:227], v137 offset:38912
	ds_read_b128 v[228:231], v137 offset:39936
	s_waitcnt vmcnt(2)
	s_barrier
; #define WAIT_V(n) asm volatile("s_waitcnt vmcnt(" #n ")" ::: "memory")
; #define WAIT_L(n) asm volatile("s_waitcnt lgkmcnt(" #n ")" ::: "memory")
; #define BAR __builtin_amdgcn_s_barrier()
; #define LDA(dst, b, h) _Pragma("unroll") for (int m = 0; m < 4; ++m) _Pragma("unroll") for (int k = 0; k < 2; ++k) \
;     dst[m][k] = *reinterpret_cast<const bf16x8*>((char*)shm + abase + (((b) * 2 + (h)) * 16384 + (m * 2 + k) * 1024))
; #define LDB(dst, b, h) _Pragma("unroll") for (int n = 0; n < 2; ++n) _Pragma("unroll") for (int k = 0; k < 2; ++k) \
;     dst[n][k] = *reinterpret_cast<const bf16x8*>((char*)shm + bbase + (((b) * 2 + (h)) * 16384 + (n * 2 + k) * 1024))
; template <bool SWAP>
; __device__ __forceinline__ void gemm_main(const u16* __restrict__ A, const u16* __restrict__ Bt, int brow, int bcol,
;                                           u16* shm, f32x4 (&acc)[2][2][4][2]) {
;     ...
;     LDA(At, 0, 1); WAIT_V(4); BAR; WAIT_L(0); MMA(1, 0, At, B0); MMA(1, 1, At, B1); BAR; }
;   { LDB(B0, 1, 0); LDA(At, 1, 0); WAIT_V(2); BAR; WAIT_L(0); MMA(0, 0, At, B0); BAR;
;     LDB(B1, 1, 1); WAIT_V(0); BAR; WAIT_L(0); MMA(0, 1, At, B1); BAR;
;     LDA(At, 1, 1); BAR; WAIT_L(0); MMA(1, 0, At, B0); MMA(1, 1, At, B1); BAR; }
;   if (wr == 0) BAR;
	s_waitcnt lgkmcnt(0)
	s_setprio 1
	s_waitcnt lgkmcnt(0)
	v_mfma_f32_16x16x32_bf16 v[68:71], v[4:7], v[20:23], v[124:127]
	v_mfma_f32_16x16x32_bf16 v[120:123], v[12:15], v[28:31], v[68:71]
	v_mfma_f32_16x16x32_bf16 v[68:71], v[170:173], v[20:23], v[146:149]
	v_mfma_f32_16x16x32_bf16 v[116:119], v[174:177], v[28:31], v[68:71]
	v_mfma_f32_16x16x32_bf16 v[68:71], v[4:7], v[36:39], v[186:189]
	v_mfma_f32_16x16x32_bf16 v[108:111], v[12:15], v[44:47], v[68:71]
	v_mfma_f32_16x16x32_bf16 v[68:71], v[170:173], v[36:39], v[112:115]
	v_mfma_f32_16x16x32_bf16 v[100:103], v[174:177], v[44:47], v[68:71]
	v_mfma_f32_16x16x32_bf16 v[68:71], v[4:7], v[52:55], v[194:197]
	v_mfma_f32_16x16x32_bf16 v[92:95], v[12:15], v[178:181], v[68:71]
	v_mfma_f32_16x16x32_bf16 v[68:71], v[170:173], v[52:55], v[104:107]
	v_mfma_f32_16x16x32_bf16 v[84:87], v[174:177], v[178:181], v[68:71]
	v_mfma_f32_16x16x32_bf16 v[68:71], v[4:7], v[224:227], v[198:201]
	v_mfma_f32_16x16x32_bf16 v[76:79], v[12:15], v[228:231], v[68:71]
	v_mfma_f32_16x16x32_bf16 v[68:71], v[170:173], v[224:227], v[96:99]
	v_mfma_f32_16x16x32_bf16 v[68:71], v[174:177], v[228:231], v[68:71]
	s_setprio 0
	s_barrier
	ds_read_b128 v[146:149], v138 offset:49152
	ds_read_b128 v[186:189], v138 offset:50176
	ds_read_b128 v[194:197], v138 offset:51200
	ds_read_b128 v[198:201], v138 offset:52224
	s_waitcnt vmcnt(0)
	s_barrier
	s_waitcnt lgkmcnt(0)
	s_setprio 1
	s_waitcnt lgkmcnt(0)
	v_mfma_f32_16x16x32_bf16 v[96:99], v[146:149], v[20:23], v[202:205]
	v_mfma_f32_16x16x32_bf16 v[20:23], v[194:197], v[20:23], v[88:91]
	v_mfma_f32_16x16x32_bf16 v[112:115], v[198:201], v[28:31], v[20:23]
	v_mfma_f32_16x16x32_bf16 v[20:23], v[146:149], v[36:39], v[154:157]
	v_mfma_f32_16x16x32_bf16 v[104:107], v[186:189], v[44:47], v[20:23]
	v_mfma_f32_16x16x32_bf16 v[20:23], v[194:197], v[36:39], v[80:83]
	v_mfma_f32_16x16x32_bf16 v[124:127], v[186:189], v[28:31], v[96:99]
	v_mfma_f32_16x16x32_bf16 v[96:99], v[198:201], v[44:47], v[20:23]
	v_mfma_f32_16x16x32_bf16 v[20:23], v[146:149], v[52:55], v[158:161]
	v_mfma_f32_16x16x32_bf16 v[88:91], v[186:189], v[178:181], v[20:23]
	v_mfma_f32_16x16x32_bf16 v[20:23], v[194:197], v[52:55], v[72:75]
	v_mfma_f32_16x16x32_bf16 v[80:83], v[198:201], v[178:181], v[20:23]
	v_mfma_f32_16x16x32_bf16 v[20:23], v[146:149], v[224:227], v[162:165]
	v_mfma_f32_16x16x32_bf16 v[72:75], v[186:189], v[228:231], v[20:23]
	v_mfma_f32_16x16x32_bf16 v[20:23], v[194:197], v[224:227], v[64:67]
	v_mfma_f32_16x16x32_bf16 v[64:67], v[198:201], v[228:231], v[20:23]
	s_setprio 0
	s_barrier
	ds_read_b128 v[154:157], v137 offset:49152
	ds_read_b128 v[158:161], v137 offset:50176
	ds_read_b128 v[162:165], v137 offset:51200
	ds_read_b128 v[178:181], v137 offset:52224
	ds_read_b128 v[202:205], v137 offset:53248
	ds_read_b128 v[224:227], v137 offset:54272
	ds_read_b128 v[228:231], v137 offset:55296
	ds_read_b128 v[232:235], v137 offset:56320
	s_barrier
	s_waitcnt lgkmcnt(0)
	s_setprio 1
	s_waitcnt lgkmcnt(0)
	v_mfma_f32_16x16x32_bf16 v[20:23], v[4:7], v[154:157], v[60:63]
	v_mfma_f32_16x16x32_bf16 v[60:63], v[12:15], v[158:161], v[20:23]
	v_mfma_f32_16x16x32_bf16 v[20:23], v[170:173], v[154:157], v[56:59]
	v_mfma_f32_16x16x32_bf16 v[52:55], v[174:177], v[158:161], v[20:23]
	v_mfma_f32_16x16x32_bf16 v[20:23], v[4:7], v[162:165], v[182:185]
	v_mfma_f32_16x16x32_bf16 v[44:47], v[12:15], v[178:181], v[20:23]
	v_mfma_f32_16x16x32_bf16 v[20:23], v[170:173], v[162:165], v[48:51]
	v_mfma_f32_16x16x32_bf16 v[36:39], v[174:177], v[178:181], v[20:23]
	v_mfma_f32_16x16x32_bf16 v[20:23], v[4:7], v[202:205], v[206:209]
	v_mfma_f32_16x16x32_bf16 v[4:7], v[4:7], v[228:231], v[128:131]
	v_mfma_f32_16x16x32_bf16 v[28:31], v[12:15], v[224:227], v[20:23]
	v_mfma_f32_16x16x32_bf16 v[20:23], v[170:173], v[202:205], v[40:43]
	v_mfma_f32_16x16x32_bf16 v[12:15], v[12:15], v[232:235], v[4:7]
	v_mfma_f32_16x16x32_bf16 v[4:7], v[170:173], v[228:231], v[32:35]
	v_mfma_f32_16x16x32_bf16 v[20:23], v[174:177], v[224:227], v[20:23]
	v_mfma_f32_16x16x32_bf16 v[4:7], v[174:177], v[232:235], v[4:7]
	s_setprio 0
	s_setprio 1
	v_mfma_f32_16x16x32_bf16 v[32:35], v[146:149], v[154:157], v[132:135]
	v_mfma_f32_16x16x32_bf16 v[24:27], v[194:197], v[154:157], v[24:27]
	v_mfma_f32_16x16x32_bf16 v[16:19], v[194:197], v[162:165], v[16:19]
	v_mfma_f32_16x16x32_bf16 v[56:59], v[186:189], v[158:161], v[32:35]
	v_mfma_f32_16x16x32_bf16 v[48:51], v[198:201], v[158:161], v[24:27]
	v_mfma_f32_16x16x32_bf16 v[24:27], v[146:149], v[162:165], v[142:145]
	v_mfma_f32_16x16x32_bf16 v[32:35], v[198:201], v[178:181], v[16:19]
	v_mfma_f32_16x16x32_bf16 v[16:19], v[146:149], v[202:205], v[150:153]
	v_mfma_f32_16x16x32_bf16 v[8:11], v[194:197], v[202:205], v[8:11]
	v_mfma_f32_16x16x32_bf16 v[40:43], v[186:189], v[178:181], v[24:27]
	v_mfma_f32_16x16x32_bf16 v[24:27], v[186:189], v[224:227], v[16:19]
	v_mfma_f32_16x16x32_bf16 v[16:19], v[198:201], v[224:227], v[8:11]
	v_mfma_f32_16x16x32_bf16 v[8:11], v[146:149], v[228:231], v[166:169]
	v_mfma_f32_16x16x32_bf16 v[0:3], v[194:197], v[228:231], v[0:3]
	v_mfma_f32_16x16x32_bf16 v[8:11], v[186:189], v[232:235], v[8:11]
	v_mfma_f32_16x16x32_bf16 v[0:3], v[198:201], v[232:235], v[0:3]
	s_setprio 0
	s_movk_i32 s1, 0x100
	v_cmp_gt_u32_e32 vcc, s1, v136
	s_barrier
	s_and_saveexec_b64 s[8:9], vcc
	s_cbranch_execz .LBB0_439
	s_barrier

; #define WAIT_V(n) asm volatile("s_waitcnt vmcnt(" #n ")" ::: "memory")
; #define WAIT_L(n) asm volatile("s_waitcnt lgkmcnt(" #n ")" ::: "memory")
; #define BAR __builtin_amdgcn_s_barrier()
; #define SCHED __builtin_amdgcn_sched_barrier(0)
; #define STAGE(P, BASE, br, kt) do { const char* _g = (const char*)((BASE) + (size_t)(br) * GK + (kt) * BK); \
;     __builtin_amdgcn_global_load_lds((const unsigned*)(_g + voff0), (unsigned*)((char*)(P) + tx * 16), 16, 0, 0); \
;     __builtin_amdgcn_global_load_lds((const unsigned*)(_g + voff1), (unsigned*)((char*)(P) + tx * 16 + 8192), 16, 0, 0); } while (0)
; #define LDA(dst, b, h) _Pragma("unroll") for (int m = 0; m < 4; ++m) _Pragma("unroll") for (int k = 0; k < 2; ++k) \
;     dst[m][k] = *reinterpret_cast<const bf16x8*>((char*)shm + abase + (((b) * 2 + (h)) * 16384 + (m * 2 + k) * 1024))
; #define LDB(dst, b, h) _Pragma("unroll") for (int n = 0; n < 2; ++n) _Pragma("unroll") for (int k = 0; k < 2; ++k) \
;     dst[n][k] = *reinterpret_cast<const bf16x8*>((char*)shm + bbase + (((b) * 2 + (h)) * 16384 + (n * 2 + k) * 1024))
; template <bool SWAP>
; __device__ __forceinline__ void gemm_main(const u16* __restrict__ A, const u16* __restrict__ Bt, int brow, int bcol,
;                                           u16* shm, f32x4 (&acc)[2][2][4][2]) {
;     ...
;     LDB(B0, 0, 0); SCHED; LDA(At, 0, 0); STAGE(SA(1, 1), A, brow + HALF, t + 1);
;     WAIT_L(8); BAR; WAIT_L(0); MMA(0, 0, At, B0); BAR; SCHED;
;     LDB(B1, 0, 1); STAGE(SB(0, 0), Bt, bcol, t + 2);
;     BAR; WAIT_L(0); MMA(0, 1, At, B1); BAR;
;     LDA(At, 0, 1); STAGE(SA(0, 0), A, brow, t + 2);
;     BAR; WAIT_L(0); MMA(1, 0, At, B0); BAR; SCHED;
;     STAGE(SB(0, 1), Bt, bcol + HALF, t + 2);
;     WAIT_V(6); BAR; MMA(1, 1, At, B1); BAR;
.LBB0_564:
	ds_read_b128 v[168:171], v137 offset:1024
	ds_read_b128 v[176:179], v137 offset:3072
	ds_read_b128 v[184:187], v137 offset:5120
	ds_read_b128 v[194:197], v137 offset:7168
	v_add_u32_e32 v192, 0, v141
	v_add_u32_e32 v146, 0xc000, v192
	v_lshl_add_u64 v[230:231], s[0:1], 0, v[132:133]
	v_add_u32_e32 v147, 0xe000, v192
	v_lshl_add_u64 v[198:199], v[230:231], 0, s[8:9]
	s_add_u32 m0, s4, 0xc000
	v_lshl_add_u64 v[232:233], s[0:1], 0, v[134:135]
	global_load_lds_dwordx4 v[198:199], off
	v_lshl_add_u64 v[198:199], v[232:233], 0, s[8:9]
	s_add_u32 m0, s4, 0xe000
	s_nop 0
	global_load_lds_dwordx4 v[198:199], off
	s_waitcnt lgkmcnt(8)
	s_barrier
	s_waitcnt lgkmcnt(0)
	v_mfma_f32_16x16x32_bf16 v[124:127], v[148:151], v[164:167], v[124:127]
	v_mfma_f32_16x16x32_bf16 v[120:123], v[156:159], v[164:167], v[120:123]
	v_mfma_f32_16x16x32_bf16 v[116:119], v[148:151], v[172:175], v[116:119]
	v_mfma_f32_16x16x32_bf16 v[112:115], v[156:159], v[172:175], v[112:115]
	v_mfma_f32_16x16x32_bf16 v[108:111], v[148:151], v[180:183], v[108:111]
	v_mfma_f32_16x16x32_bf16 v[104:107], v[156:159], v[180:183], v[104:107]
	v_mfma_f32_16x16x32_bf16 v[100:103], v[148:151], v[188:191], v[100:103]
	v_mfma_f32_16x16x32_bf16 v[96:99], v[156:159], v[188:191], v[96:99]
	v_mfma_f32_16x16x32_bf16 v[124:127], v[152:155], v[168:171], v[124:127]
	v_mfma_f32_16x16x32_bf16 v[120:123], v[160:163], v[168:171], v[120:123]
	v_mfma_f32_16x16x32_bf16 v[116:119], v[152:155], v[176:179], v[116:119]
	v_mfma_f32_16x16x32_bf16 v[112:115], v[160:163], v[176:179], v[112:115]
	v_mfma_f32_16x16x32_bf16 v[108:111], v[152:155], v[184:187], v[108:111]
	v_mfma_f32_16x16x32_bf16 v[104:107], v[160:163], v[184:187], v[104:107]
	v_mfma_f32_16x16x32_bf16 v[100:103], v[152:155], v[194:197], v[100:103]
	v_mfma_f32_16x16x32_bf16 v[96:99], v[160:163], v[194:197], v[96:99]
	s_barrier
	ds_read_b128 v[198:201], v138 offset:16384
	ds_read_b128 v[202:205], v138 offset:17408
	ds_read_b128 v[206:209], v138 offset:18432
	ds_read_b128 v[226:229], v138 offset:19456
	v_lshl_add_u64 v[234:235], s[0:1], 0, v[128:129]
	v_lshl_add_u64 v[236:237], v[234:235], 0, s[12:13]
	s_add_u32 m0, s4, s28
	s_nop 0
	global_load_lds_dwordx4 v[236:237], off
	v_lshl_add_u64 v[236:237], s[0:1], 0, v[130:131]
	v_lshl_add_u64 v[238:239], v[236:237], 0, s[12:13]
	s_add_u32 m0, s4, s28
	s_add_u32 m0, m0, 0x2000
	s_nop 0
	global_load_lds_dwordx4 v[238:239], off
	s_barrier
	s_waitcnt lgkmcnt(0)
	v_mfma_f32_16x16x32_bf16 v[92:95], v[198:201], v[164:167], v[92:95]
	v_mfma_f32_16x16x32_bf16 v[88:91], v[206:209], v[164:167], v[88:91]
	v_mfma_f32_16x16x32_bf16 v[84:87], v[198:201], v[172:175], v[84:87]
	v_mfma_f32_16x16x32_bf16 v[80:83], v[206:209], v[172:175], v[80:83]
	v_mfma_f32_16x16x32_bf16 v[76:79], v[198:201], v[180:183], v[76:79]
	v_mfma_f32_16x16x32_bf16 v[72:75], v[206:209], v[180:183], v[72:75]
	v_mfma_f32_16x16x32_bf16 v[68:71], v[198:201], v[188:191], v[68:71]
	v_mfma_f32_16x16x32_bf16 v[64:67], v[206:209], v[188:191], v[64:67]
	v_mfma_f32_16x16x32_bf16 v[92:95], v[202:205], v[168:171], v[92:95]
	ds_read_b128 v[164:167], v137 offset:16384
	v_mfma_f32_16x16x32_bf16 v[88:91], v[226:229], v[168:171], v[88:91]
	v_mfma_f32_16x16x32_bf16 v[84:87], v[202:205], v[176:179], v[84:87]
	ds_read_b128 v[172:175], v137 offset:18432
	v_mfma_f32_16x16x32_bf16 v[80:83], v[226:229], v[176:179], v[80:83]
	v_mfma_f32_16x16x32_bf16 v[76:79], v[202:205], v[184:187], v[76:79]
	ds_read_b128 v[180:183], v137 offset:20480
	v_mfma_f32_16x16x32_bf16 v[72:75], v[226:229], v[184:187], v[72:75]
	v_mfma_f32_16x16x32_bf16 v[68:71], v[202:205], v[194:197], v[68:71]
	ds_read_b128 v[188:191], v137 offset:22528
	v_mfma_f32_16x16x32_bf16 v[64:67], v[226:229], v[194:197], v[64:67]
	s_barrier
	ds_read_b128 v[168:171], v137 offset:17408
	ds_read_b128 v[176:179], v137 offset:19456
	ds_read_b128 v[184:187], v137 offset:21504
	ds_read_b128 v[194:197], v137 offset:23552
	v_lshl_add_u64 v[238:239], v[230:231], 0, s[14:15]
	s_add_u32 m0, s4, 0x0
	s_nop 0
	global_load_lds_dwordx4 v[238:239], off
	v_lshl_add_u64 v[238:239], v[232:233], 0, s[14:15]
	s_add_u32 m0, s4, 0x2000
	s_nop 0
	global_load_lds_dwordx4 v[238:239], off
	s_waitcnt vmcnt(8)
	s_barrier
	s_waitcnt lgkmcnt(0)
	v_mfma_f32_16x16x32_bf16 v[60:63], v[148:151], v[164:167], v[60:63]
	v_mfma_f32_16x16x32_bf16 v[56:59], v[156:159], v[164:167], v[56:59]
	v_mfma_f32_16x16x32_bf16 v[52:55], v[148:151], v[172:175], v[52:55]
	v_mfma_f32_16x16x32_bf16 v[48:51], v[156:159], v[172:175], v[48:51]
	v_mfma_f32_16x16x32_bf16 v[44:47], v[148:151], v[180:183], v[44:47]
	v_mfma_f32_16x16x32_bf16 v[40:43], v[156:159], v[180:183], v[40:43]
	v_mfma_f32_16x16x32_bf16 v[36:39], v[148:151], v[188:191], v[36:39]
	v_mfma_f32_16x16x32_bf16 v[32:35], v[156:159], v[188:191], v[32:35]
	v_mfma_f32_16x16x32_bf16 v[60:63], v[152:155], v[168:171], v[60:63]
	v_mfma_f32_16x16x32_bf16 v[56:59], v[160:163], v[168:171], v[56:59]
	v_mfma_f32_16x16x32_bf16 v[52:55], v[152:155], v[176:179], v[52:55]
	v_mfma_f32_16x16x32_bf16 v[48:51], v[160:163], v[176:179], v[48:51]
	v_mfma_f32_16x16x32_bf16 v[44:47], v[152:155], v[184:187], v[44:47]
	v_mfma_f32_16x16x32_bf16 v[40:43], v[160:163], v[184:187], v[40:43]
	v_mfma_f32_16x16x32_bf16 v[36:39], v[152:155], v[194:197], v[36:39]
	v_mfma_f32_16x16x32_bf16 v[32:35], v[160:163], v[194:197], v[32:35]
	s_barrier
	ds_read_b128 v[148:151], v138 offset:32768
	ds_read_b128 v[152:155], v138 offset:33792
	ds_read_b128 v[156:159], v138 offset:34816
	ds_read_b128 v[160:163], v138 offset:35840
	v_lshl_add_u64 v[254:255], v[234:235], 0, s[16:17]
	s_add_u32 m0, s4, s29
	s_nop 0
	global_load_lds_dwordx4 v[254:255], off
	v_lshl_add_u64 v[254:255], v[236:237], 0, s[16:17]
	s_add_u32 m0, s4, s29
	s_add_u32 m0, m0, 0x2000
	s_nop 0
	global_load_lds_dwordx4 v[254:255], off
	s_waitcnt vmcnt(6)
	s_barrier
; #define WAIT_V(n) asm volatile("s_waitcnt vmcnt(" #n ")" ::: "memory")
; #define WAIT_L(n) asm volatile("s_waitcnt lgkmcnt(" #n ")" ::: "memory")
; #define BAR __builtin_amdgcn_s_barrier()
; #define SCHED __builtin_amdgcn_sched_barrier(0)
; #define STAGE(P, BASE, br, kt) do { const char* _g = (const char*)((BASE) + (size_t)(br) * GK + (kt) * BK); \
;     __builtin_amdgcn_global_load_lds((const unsigned*)(_g + voff0), (unsigned*)((char*)(P) + tx * 16), 16, 0, 0); \
;     __builtin_amdgcn_global_load_lds((const unsigned*)(_g + voff1), (unsigned*)((char*)(P) + tx * 16 + 8192), 16, 0, 0); } while (0)
; #define LDA(dst, b, h) _Pragma("unroll") for (int m = 0; m < 4; ++m) _Pragma("unroll") for (int k = 0; k < 2; ++k) \
;     dst[m][k] = *reinterpret_cast<const bf16x8*>((char*)shm + abase + (((b) * 2 + (h)) * 16384 + (m * 2 + k) * 1024))
; #define LDB(dst, b, h) _Pragma("unroll") for (int n = 0; n < 2; ++n) _Pragma("unroll") for (int k = 0; k < 2; ++k) \
;     dst[n][k] = *reinterpret_cast<const bf16x8*>((char*)shm + bbase + (((b) * 2 + (h)) * 16384 + (n * 2 + k) * 1024))
; template <bool SWAP>
; __device__ __forceinline__ void gemm_main(const u16* __restrict__ A, const u16* __restrict__ Bt, int brow, int bcol,
;                                           u16* shm, f32x4 (&acc)[2][2][4][2]) {
;     ...
;     WAIT_V(6); BAR; MMA(1, 1, At, B1); BAR;
;     LDB(B0, 1, 0); SCHED; LDA(At, 1, 0); STAGE(SA(0, 1), A, brow + HALF, t + 2);
;     WAIT_L(8); BAR; WAIT_L(0); MMA(0, 0, At, B0); BAR; SCHED;
;     LDB(B1, 1, 1); STAGE(SB(1, 0), Bt, bcol, t + 3);
;     BAR; WAIT_L(0); MMA(0, 1, At, B1); BAR;
;     LDA(At, 1, 1); STAGE(SA(1, 0), A, brow, t + 3);
;     BAR; WAIT_L(0); MMA(1, 0, At, B0); BAR; SCHED;
	v_mfma_f32_16x16x32_bf16 v[28:31], v[198:201], v[164:167], v[28:31]
	v_mfma_f32_16x16x32_bf16 v[24:27], v[206:209], v[164:167], v[24:27]
	v_mfma_f32_16x16x32_bf16 v[20:23], v[198:201], v[172:175], v[20:23]
	v_mfma_f32_16x16x32_bf16 v[16:19], v[206:209], v[172:175], v[16:19]
	v_mfma_f32_16x16x32_bf16 v[12:15], v[198:201], v[180:183], v[12:15]
	v_mfma_f32_16x16x32_bf16 v[8:11], v[206:209], v[180:183], v[8:11]
	v_mfma_f32_16x16x32_bf16 v[4:7], v[198:201], v[188:191], v[4:7]
	v_mfma_f32_16x16x32_bf16 v[0:3], v[206:209], v[188:191], v[0:3]
	v_mfma_f32_16x16x32_bf16 v[28:31], v[202:205], v[168:171], v[28:31]
	ds_read_b128 v[164:167], v137 offset:32768
	v_mfma_f32_16x16x32_bf16 v[24:27], v[226:229], v[168:171], v[24:27]
	v_mfma_f32_16x16x32_bf16 v[20:23], v[202:205], v[176:179], v[20:23]
	ds_read_b128 v[172:175], v137 offset:34816
	v_mfma_f32_16x16x32_bf16 v[16:19], v[226:229], v[176:179], v[16:19]
	v_mfma_f32_16x16x32_bf16 v[12:15], v[202:205], v[184:187], v[12:15]
	ds_read_b128 v[180:183], v137 offset:36864
	v_mfma_f32_16x16x32_bf16 v[8:11], v[226:229], v[184:187], v[8:11]
	v_mfma_f32_16x16x32_bf16 v[4:7], v[202:205], v[194:197], v[4:7]
	ds_read_b128 v[188:191], v137 offset:38912
	v_mfma_f32_16x16x32_bf16 v[0:3], v[226:229], v[194:197], v[0:3]
	s_barrier
	ds_read_b128 v[168:171], v137 offset:33792
	ds_read_b128 v[176:179], v137 offset:35840
	ds_read_b128 v[184:187], v137 offset:37888
	ds_read_b128 v[194:197], v137 offset:39936
	v_lshl_add_u64 v[198:199], v[230:231], 0, s[18:19]
	s_add_u32 m0, s4, 0x4000
	s_nop 0
	global_load_lds_dwordx4 v[198:199], off
	v_lshl_add_u64 v[198:199], v[232:233], 0, s[18:19]
	s_add_u32 m0, s4, 0x6000
	s_nop 0
	global_load_lds_dwordx4 v[198:199], off
	s_waitcnt lgkmcnt(8)
	s_barrier
	s_waitcnt lgkmcnt(0)
	v_mfma_f32_16x16x32_bf16 v[124:127], v[148:151], v[164:167], v[124:127]
	v_mfma_f32_16x16x32_bf16 v[120:123], v[156:159], v[164:167], v[120:123]
	v_mfma_f32_16x16x32_bf16 v[116:119], v[148:151], v[172:175], v[116:119]
	v_mfma_f32_16x16x32_bf16 v[112:115], v[156:159], v[172:175], v[112:115]
	v_mfma_f32_16x16x32_bf16 v[108:111], v[148:151], v[180:183], v[108:111]
	v_mfma_f32_16x16x32_bf16 v[104:107], v[156:159], v[180:183], v[104:107]
	v_mfma_f32_16x16x32_bf16 v[100:103], v[148:151], v[188:191], v[100:103]
	v_mfma_f32_16x16x32_bf16 v[96:99], v[156:159], v[188:191], v[96:99]
	v_mfma_f32_16x16x32_bf16 v[124:127], v[152:155], v[168:171], v[124:127]
	v_mfma_f32_16x16x32_bf16 v[120:123], v[160:163], v[168:171], v[120:123]
	v_mfma_f32_16x16x32_bf16 v[116:119], v[152:155], v[176:179], v[116:119]
	v_mfma_f32_16x16x32_bf16 v[112:115], v[160:163], v[176:179], v[112:115]
	v_mfma_f32_16x16x32_bf16 v[108:111], v[152:155], v[184:187], v[108:111]
	v_mfma_f32_16x16x32_bf16 v[104:107], v[160:163], v[184:187], v[104:107]
	v_mfma_f32_16x16x32_bf16 v[100:103], v[152:155], v[194:197], v[100:103]
	v_mfma_f32_16x16x32_bf16 v[96:99], v[160:163], v[194:197], v[96:99]
	s_barrier
	ds_read_b128 v[198:201], v138 offset:49152
	ds_read_b128 v[202:205], v138 offset:50176
	ds_read_b128 v[206:209], v138 offset:51200
	ds_read_b128 v[226:229], v138 offset:52224
	v_lshl_add_u64 v[238:239], v[234:235], 0, s[24:25]
	s_add_u32 m0, s4, s30
	s_nop 0
	global_load_lds_dwordx4 v[238:239], off
	v_lshl_add_u64 v[238:239], v[236:237], 0, s[24:25]
	s_add_u32 m0, s4, s30
	s_add_u32 m0, m0, 0x2000
	s_nop 0
	global_load_lds_dwordx4 v[238:239], off
	s_barrier
	s_waitcnt lgkmcnt(0)
	v_mfma_f32_16x16x32_bf16 v[92:95], v[198:201], v[164:167], v[92:95]
	v_mfma_f32_16x16x32_bf16 v[88:91], v[206:209], v[164:167], v[88:91]
	v_mfma_f32_16x16x32_bf16 v[84:87], v[198:201], v[172:175], v[84:87]
	v_mfma_f32_16x16x32_bf16 v[80:83], v[206:209], v[172:175], v[80:83]
	v_mfma_f32_16x16x32_bf16 v[76:79], v[198:201], v[180:183], v[76:79]
	v_mfma_f32_16x16x32_bf16 v[72:75], v[206:209], v[180:183], v[72:75]
	v_mfma_f32_16x16x32_bf16 v[68:71], v[198:201], v[188:191], v[68:71]
	v_mfma_f32_16x16x32_bf16 v[64:67], v[206:209], v[188:191], v[64:67]
	v_mfma_f32_16x16x32_bf16 v[92:95], v[202:205], v[168:171], v[92:95]
	ds_read_b128 v[164:167], v137 offset:49152
	v_mfma_f32_16x16x32_bf16 v[88:91], v[226:229], v[168:171], v[88:91]
	v_mfma_f32_16x16x32_bf16 v[84:87], v[202:205], v[176:179], v[84:87]
	ds_read_b128 v[172:175], v137 offset:51200
	v_mfma_f32_16x16x32_bf16 v[80:83], v[226:229], v[176:179], v[80:83]
	v_mfma_f32_16x16x32_bf16 v[76:79], v[202:205], v[184:187], v[76:79]
	ds_read_b128 v[180:183], v137 offset:53248
	v_mfma_f32_16x16x32_bf16 v[72:75], v[226:229], v[184:187], v[72:75]
	v_mfma_f32_16x16x32_bf16 v[68:71], v[202:205], v[194:197], v[68:71]
	ds_read_b128 v[188:191], v137 offset:55296
	v_mfma_f32_16x16x32_bf16 v[64:67], v[226:229], v[194:197], v[64:67]
	s_barrier
	ds_read_b128 v[168:171], v137 offset:50176
	ds_read_b128 v[176:179], v137 offset:52224
	ds_read_b128 v[184:187], v137 offset:54272
	ds_read_b128 v[194:197], v137 offset:56320
	v_add_u32_e32 v225, 0x8000, v192
	v_lshl_add_u64 v[230:231], v[230:231], 0, vcc
	s_add_u32 m0, s4, 0x8000
	s_nop 0
	global_load_lds_dwordx4 v[230:231], off
	v_lshl_add_u64 v[230:231], v[232:233], 0, vcc
	s_add_u32 m0, s4, 0xa000
	s_nop 0
	global_load_lds_dwordx4 v[230:231], off
	s_waitcnt vmcnt(8)
	s_barrier
; #define WAIT_V(n) asm volatile("s_waitcnt vmcnt(" #n ")" ::: "memory")
; #define WAIT_L(n) asm volatile("s_waitcnt lgkmcnt(" #n ")" ::: "memory")
; #define BAR __builtin_amdgcn_s_barrier()
; #define SCHED __builtin_amdgcn_sched_barrier(0)
; #define STAGE(P, BASE, br, kt) do { const char* _g = (const char*)((BASE) + (size_t)(br) * GK + (kt) * BK); \
;     __builtin_amdgcn_global_load_lds((const unsigned*)(_g + voff0), (unsigned*)((char*)(P) + tx * 16), 16, 0, 0); \
;     __builtin_amdgcn_global_load_lds((const unsigned*)(_g + voff1), (unsigned*)((char*)(P) + tx * 16 + 8192), 16, 0, 0); } while (0)
; #define LDA(dst, b, h) _Pragma("unroll") for (int m = 0; m < 4; ++m) _Pragma("unroll") for (int k = 0; k < 2; ++k) \
;     dst[m][k] = *reinterpret_cast<const bf16x8*>((char*)shm + abase + (((b) * 2 + (h)) * 16384 + (m * 2 + k) * 1024))
; #define LDB(dst, b, h) _Pragma("unroll") for (int n = 0; n < 2; ++n) _Pragma("unroll") for (int k = 0; k < 2; ++k) \
;     dst[n][k] = *reinterpret_cast<const bf16x8*>((char*)shm + bbase + (((b) * 2 + (h)) * 16384 + (n * 2 + k) * 1024))
; template <bool SWAP>
; __device__ __forceinline__ void gemm_main(const u16* __restrict__ A, const u16* __restrict__ Bt, int brow, int bcol,
;                                           u16* shm, f32x4 (&acc)[2][2][4][2]) {
;     ...
;     LDA(At, 1, 1); STAGE(SA(1, 0), A, brow, t + 3);
;     BAR; WAIT_L(0); MMA(1, 0, At, B0); BAR; SCHED;
;     STAGE(SB(1, 1), Bt, bcol + HALF, t + 3);
;     WAIT_V(6); BAR; MMA(1, 1, At, B1); BAR;
;   }
;   { LDB(B0, 0, 0); LDA(At, 0, 0); STAGE(SA(1, 1), A, brow + HALF, nt - 1);
;     BAR; WAIT_L(0); MMA(0, 0, At, B0); BAR;
	s_waitcnt lgkmcnt(0)
	v_mfma_f32_16x16x32_bf16 v[60:63], v[148:151], v[164:167], v[60:63]
	v_mfma_f32_16x16x32_bf16 v[56:59], v[156:159], v[164:167], v[56:59]
	v_mfma_f32_16x16x32_bf16 v[52:55], v[148:151], v[172:175], v[52:55]
	v_mfma_f32_16x16x32_bf16 v[48:51], v[156:159], v[172:175], v[48:51]
	v_mfma_f32_16x16x32_bf16 v[44:47], v[148:151], v[180:183], v[44:47]
	v_mfma_f32_16x16x32_bf16 v[40:43], v[156:159], v[180:183], v[40:43]
	v_mfma_f32_16x16x32_bf16 v[36:39], v[148:151], v[188:191], v[36:39]
	v_mfma_f32_16x16x32_bf16 v[32:35], v[156:159], v[188:191], v[32:35]
	v_mfma_f32_16x16x32_bf16 v[60:63], v[152:155], v[168:171], v[60:63]
	v_mfma_f32_16x16x32_bf16 v[56:59], v[160:163], v[168:171], v[56:59]
	v_mfma_f32_16x16x32_bf16 v[52:55], v[152:155], v[176:179], v[52:55]
	v_mfma_f32_16x16x32_bf16 v[48:51], v[160:163], v[176:179], v[48:51]
	v_mfma_f32_16x16x32_bf16 v[44:47], v[152:155], v[184:187], v[44:47]
	v_mfma_f32_16x16x32_bf16 v[40:43], v[160:163], v[184:187], v[40:43]
	v_mfma_f32_16x16x32_bf16 v[36:39], v[152:155], v[194:197], v[36:39]
	v_mfma_f32_16x16x32_bf16 v[32:35], v[160:163], v[194:197], v[32:35]
	s_barrier
	ds_read_b128 v[148:151], v138
	ds_read_b128 v[152:155], v138 offset:1024
	ds_read_b128 v[156:159], v138 offset:2048
	ds_read_b128 v[160:163], v138 offset:3072
	v_lshl_add_u64 v[254:255], v[234:235], 0, s[42:43]
	s_add_u32 m0, s4, s31
	s_nop 0
	global_load_lds_dwordx4 v[254:255], off
	v_lshl_add_u64 v[254:255], v[236:237], 0, s[42:43]
	s_add_u32 m0, s4, s31
	s_add_u32 m0, m0, 0x2000
	s_nop 0
	global_load_lds_dwordx4 v[254:255], off
	s_waitcnt vmcnt(6)
	s_barrier
	v_mfma_f32_16x16x32_bf16 v[28:31], v[198:201], v[164:167], v[28:31]
	v_mfma_f32_16x16x32_bf16 v[24:27], v[206:209], v[164:167], v[24:27]
	v_mfma_f32_16x16x32_bf16 v[20:23], v[198:201], v[172:175], v[20:23]
	v_mfma_f32_16x16x32_bf16 v[16:19], v[206:209], v[172:175], v[16:19]
	v_mfma_f32_16x16x32_bf16 v[12:15], v[198:201], v[180:183], v[12:15]
	v_mfma_f32_16x16x32_bf16 v[8:11], v[206:209], v[180:183], v[8:11]
	v_mfma_f32_16x16x32_bf16 v[4:7], v[198:201], v[188:191], v[4:7]
	v_mfma_f32_16x16x32_bf16 v[0:3], v[206:209], v[188:191], v[0:3]
	v_mfma_f32_16x16x32_bf16 v[28:31], v[202:205], v[168:171], v[28:31]
	ds_read_b128 v[164:167], v137
	v_mfma_f32_16x16x32_bf16 v[24:27], v[226:229], v[168:171], v[24:27]
	v_mfma_f32_16x16x32_bf16 v[20:23], v[202:205], v[176:179], v[20:23]
	ds_read_b128 v[172:175], v137 offset:2048
	v_mfma_f32_16x16x32_bf16 v[16:19], v[226:229], v[176:179], v[16:19]
	v_mfma_f32_16x16x32_bf16 v[12:15], v[202:205], v[184:187], v[12:15]
	ds_read_b128 v[180:183], v137 offset:4096
	v_mfma_f32_16x16x32_bf16 v[8:11], v[226:229], v[184:187], v[8:11]
	v_mfma_f32_16x16x32_bf16 v[4:7], v[202:205], v[194:197], v[4:7]
	ds_read_b128 v[188:191], v137 offset:6144
	v_mfma_f32_16x16x32_bf16 v[0:3], v[226:229], v[194:197], v[0:3]
	s_add_i32 s3, s3, 2
	s_add_u32 s0, s0, 0x100
	s_addc_u32 s1, s1, 0
	s_cmp_lt_u32 s3, 28
	s_barrier
	s_cbranch_scc1 .LBB0_564
	s_and_b32 s0, s2, 0xffffe0
	s_and_b32 s1, s54, 31
	s_or_b32 s0, s0, s1
	s_lshl_b32 s8, s0, 8
	v_lshlrev_b32_e32 v128, 3, v139
	v_lshlrev_b32_e32 v129, 5, v139
	v_and_b32_e32 v128, 0xffff0, v128
	v_and_b32_e32 v129, 32, v129
	s_or_b32 s0, s8, 0x80
	v_add_u32_e32 v129, v129, v142
	v_add_lshl_u32 v128, v140, v128, 12
	s_ashr_i32 s1, s0, 31
	v_lshl_add_u32 v192, v129, 1, v128
	v_lshlrev_b32_e32 v128, 3, v143
	v_lshlrev_b32_e32 v129, 5, v143
	s_lshl_b64 s[12:13], s[0:1], 12
	v_readlane_b32 s0, v251, 36
	v_and_b32_e32 v128, 0xffff0, v128
	v_and_b32_e32 v129, 32, v129
	v_readlane_b32 s1, v251, 37
	s_add_u32 s0, s0, s12
	v_add_u32_e32 v129, v129, v145
	v_add_lshl_u32 v128, v144, v128, 12
	s_addc_u32 s1, s1, s13
	v_lshl_add_u32 v144, v129, 1, v128
	v_mov_b32_e32 v145, v193
	v_lshl_add_u64 v[184:185], s[0:1], 0, v[192:193]
	s_mov_b64 s[4:5], 0xf80
	v_readfirstlane_b32 s2, v146
	v_lshl_add_u64 v[184:185], v[184:185], 0, s[4:5]
	s_mov_b32 m0, s2
	v_lshl_add_u64 v[144:145], s[0:1], 0, v[144:145]
	v_readfirstlane_b32 s0, v147
	ds_read_b128 v[128:131], v138
	ds_read_b128 v[132:135], v138 offset:1024
	ds_read_b128 v[140:143], v138 offset:2048
	ds_read_b128 v[148:151], v138 offset:3072
	ds_read_b128 v[152:155], v137
	ds_read_b128 v[156:159], v137 offset:1024
	ds_read_b128 v[160:163], v137 offset:2048
	ds_read_b128 v[164:167], v137 offset:3072
	ds_read_b128 v[168:171], v137 offset:4096
	ds_read_b128 v[172:175], v137 offset:5120
	ds_read_b128 v[176:179], v137 offset:6144
	ds_read_b128 v[180:183], v137 offset:7168
	global_load_lds_dwordx4 v[184:185], off
	v_lshl_add_u64 v[144:145], v[144:145], 0, s[4:5]
	s_mov_b32 m0, s0
	s_nop 0
	global_load_lds_dwordx4 v[144:145], off
	s_barrier
	s_waitcnt lgkmcnt(0)
	s_setprio 1
	s_waitcnt lgkmcnt(0)
	v_mfma_f32_16x16x32_bf16 v[124:127], v[128:131], v[152:155], v[124:127]
	v_mfma_f32_16x16x32_bf16 v[116:119], v[128:131], v[160:163], v[116:119]
	v_mfma_f32_16x16x32_bf16 v[112:115], v[140:143], v[160:163], v[112:115]
	v_mfma_f32_16x16x32_bf16 v[108:111], v[128:131], v[168:171], v[108:111]
	v_mfma_f32_16x16x32_bf16 v[104:107], v[140:143], v[168:171], v[104:107]
	v_mfma_f32_16x16x32_bf16 v[100:103], v[128:131], v[176:179], v[100:103]
	v_mfma_f32_16x16x32_bf16 v[96:99], v[140:143], v[176:179], v[96:99]
	v_mfma_f32_16x16x32_bf16 v[124:127], v[132:135], v[156:159], v[124:127]
	v_mfma_f32_16x16x32_bf16 v[120:123], v[140:143], v[152:155], v[120:123]
	v_mfma_f32_16x16x32_bf16 v[116:119], v[132:135], v[164:167], v[116:119]
	v_mfma_f32_16x16x32_bf16 v[112:115], v[148:151], v[164:167], v[112:115]
	v_mfma_f32_16x16x32_bf16 v[108:111], v[132:135], v[172:175], v[108:111]
	v_mfma_f32_16x16x32_bf16 v[104:107], v[148:151], v[172:175], v[104:107]
	v_mfma_f32_16x16x32_bf16 v[100:103], v[132:135], v[180:183], v[100:103]
	v_mfma_f32_16x16x32_bf16 v[96:99], v[148:151], v[180:183], v[96:99]
	v_mfma_f32_16x16x32_bf16 v[120:123], v[148:151], v[156:159], v[120:123]
	s_setprio 0
	s_barrier
; #define WAIT_V(n) asm volatile("s_waitcnt vmcnt(" #n ")" ::: "memory")
; #define WAIT_L(n) asm volatile("s_waitcnt lgkmcnt(" #n ")" ::: "memory")
; #define BAR __builtin_amdgcn_s_barrier()
; #define LDA(dst, b, h) _Pragma("unroll") for (int m = 0; m < 4; ++m) _Pragma("unroll") for (int k = 0; k < 2; ++k) \
;     dst[m][k] = *reinterpret_cast<const bf16x8*>((char*)shm + abase + (((b) * 2 + (h)) * 16384 + (m * 2 + k) * 1024))
; #define LDB(dst, b, h) _Pragma("unroll") for (int n = 0; n < 2; ++n) _Pragma("unroll") for (int k = 0; k < 2; ++k) \
;     dst[n][k] = *reinterpret_cast<const bf16x8*>((char*)shm + bbase + (((b) * 2 + (h)) * 16384 + (n * 2 + k) * 1024))
; template <bool SWAP>
; __device__ __forceinline__ void gemm_main(const u16* __restrict__ A, const u16* __restrict__ Bt, int brow, int bcol,
;                                           u16* shm, f32x4 (&acc)[2][2][4][2]) {
;     ...
;     BAR; WAIT_L(0); MMA(0, 0, At, B0); BAR;
;     LDB(B1, 0, 1); BAR; WAIT_L(0); MMA(0, 1, At, B1); BAR;
;     LDA(At, 0, 1); WAIT_V(4); BAR; WAIT_L(0); MMA(1, 0, At, B0); MMA(1, 1, At, B1); BAR; }
;   { LDB(B0, 1, 0); LDA(At, 1, 0); WAIT_V(2); BAR; WAIT_L(0); MMA(0, 0, At, B0); BAR;
;     LDB(B1, 1, 1); WAIT_V(0); BAR; WAIT_L(0); MMA(0, 1, At, B1); BAR;
	ds_read_b128 v[144:147], v138 offset:16384
	ds_read_b128 v[184:187], v138 offset:17408
	ds_read_b128 v[188:191], v138 offset:18432
	ds_read_b128 v[194:197], v138 offset:19456
	s_barrier
	s_waitcnt lgkmcnt(0)
	s_setprio 1
	s_waitcnt lgkmcnt(0)
	v_mfma_f32_16x16x32_bf16 v[92:95], v[144:147], v[152:155], v[92:95]
	v_mfma_f32_16x16x32_bf16 v[88:91], v[188:191], v[152:155], v[88:91]
	v_mfma_f32_16x16x32_bf16 v[84:87], v[144:147], v[160:163], v[84:87]
	v_mfma_f32_16x16x32_bf16 v[80:83], v[188:191], v[160:163], v[80:83]
	v_mfma_f32_16x16x32_bf16 v[76:79], v[144:147], v[168:171], v[76:79]
	v_mfma_f32_16x16x32_bf16 v[72:75], v[188:191], v[168:171], v[72:75]
	v_mfma_f32_16x16x32_bf16 v[68:71], v[144:147], v[176:179], v[68:71]
	v_mfma_f32_16x16x32_bf16 v[64:67], v[188:191], v[176:179], v[64:67]
	v_mfma_f32_16x16x32_bf16 v[92:95], v[184:187], v[156:159], v[92:95]
	v_mfma_f32_16x16x32_bf16 v[88:91], v[194:197], v[156:159], v[88:91]
	v_mfma_f32_16x16x32_bf16 v[84:87], v[184:187], v[164:167], v[84:87]
	v_mfma_f32_16x16x32_bf16 v[80:83], v[194:197], v[164:167], v[80:83]
	v_mfma_f32_16x16x32_bf16 v[76:79], v[184:187], v[172:175], v[76:79]
	v_mfma_f32_16x16x32_bf16 v[72:75], v[194:197], v[172:175], v[72:75]
	v_mfma_f32_16x16x32_bf16 v[68:71], v[184:187], v[180:183], v[68:71]
	v_mfma_f32_16x16x32_bf16 v[64:67], v[194:197], v[180:183], v[64:67]
	s_setprio 0
	s_barrier
	ds_read_b128 v[152:155], v137 offset:16384
	ds_read_b128 v[156:159], v137 offset:17408
	ds_read_b128 v[160:163], v137 offset:18432
	ds_read_b128 v[164:167], v137 offset:19456
	ds_read_b128 v[168:171], v137 offset:20480
	ds_read_b128 v[172:175], v137 offset:21504
	ds_read_b128 v[176:179], v137 offset:22528
	ds_read_b128 v[180:183], v137 offset:23552
	s_waitcnt vmcnt(4)
	s_barrier
	s_waitcnt lgkmcnt(0)
	s_setprio 1
	s_waitcnt lgkmcnt(0)
	v_mfma_f32_16x16x32_bf16 v[60:63], v[128:131], v[152:155], v[60:63]
	v_mfma_f32_16x16x32_bf16 v[56:59], v[140:143], v[152:155], v[56:59]
	v_mfma_f32_16x16x32_bf16 v[52:55], v[128:131], v[160:163], v[52:55]
	v_mfma_f32_16x16x32_bf16 v[48:51], v[140:143], v[160:163], v[48:51]
	v_mfma_f32_16x16x32_bf16 v[44:47], v[128:131], v[168:171], v[44:47]
	v_mfma_f32_16x16x32_bf16 v[40:43], v[140:143], v[168:171], v[40:43]
	v_mfma_f32_16x16x32_bf16 v[36:39], v[128:131], v[176:179], v[36:39]
	v_mfma_f32_16x16x32_bf16 v[32:35], v[140:143], v[176:179], v[32:35]
	v_mfma_f32_16x16x32_bf16 v[60:63], v[132:135], v[156:159], v[60:63]
	v_mfma_f32_16x16x32_bf16 v[56:59], v[148:151], v[156:159], v[56:59]
	v_mfma_f32_16x16x32_bf16 v[52:55], v[132:135], v[164:167], v[52:55]
	v_mfma_f32_16x16x32_bf16 v[48:51], v[148:151], v[164:167], v[48:51]
	v_mfma_f32_16x16x32_bf16 v[44:47], v[132:135], v[172:175], v[44:47]
	v_mfma_f32_16x16x32_bf16 v[40:43], v[148:151], v[172:175], v[40:43]
	v_mfma_f32_16x16x32_bf16 v[36:39], v[132:135], v[180:183], v[36:39]
	v_mfma_f32_16x16x32_bf16 v[32:35], v[148:151], v[180:183], v[32:35]
	s_setprio 0
	s_setprio 1
	v_mfma_f32_16x16x32_bf16 v[28:31], v[144:147], v[152:155], v[28:31]
	v_mfma_f32_16x16x32_bf16 v[24:27], v[188:191], v[152:155], v[24:27]
	v_mfma_f32_16x16x32_bf16 v[20:23], v[144:147], v[160:163], v[20:23]
	v_mfma_f32_16x16x32_bf16 v[16:19], v[188:191], v[160:163], v[16:19]
	v_mfma_f32_16x16x32_bf16 v[12:15], v[144:147], v[168:171], v[12:15]
	v_mfma_f32_16x16x32_bf16 v[8:11], v[188:191], v[168:171], v[8:11]
	v_mfma_f32_16x16x32_bf16 v[4:7], v[144:147], v[176:179], v[4:7]
	v_mfma_f32_16x16x32_bf16 v[0:3], v[188:191], v[176:179], v[0:3]
	v_mfma_f32_16x16x32_bf16 v[28:31], v[184:187], v[156:159], v[28:31]
	v_mfma_f32_16x16x32_bf16 v[24:27], v[194:197], v[156:159], v[24:27]
	v_mfma_f32_16x16x32_bf16 v[20:23], v[184:187], v[164:167], v[20:23]
	v_mfma_f32_16x16x32_bf16 v[16:19], v[194:197], v[164:167], v[16:19]
	v_mfma_f32_16x16x32_bf16 v[12:15], v[184:187], v[172:175], v[12:15]
	v_mfma_f32_16x16x32_bf16 v[8:11], v[194:197], v[172:175], v[8:11]
	v_mfma_f32_16x16x32_bf16 v[4:7], v[184:187], v[180:183], v[4:7]
	v_mfma_f32_16x16x32_bf16 v[0:3], v[194:197], v[180:183], v[0:3]
	s_setprio 0
	s_barrier
	ds_read_b128 v[132:135], v138 offset:32768
	ds_read_b128 v[140:143], v138 offset:33792
	ds_read_b128 v[144:147], v138 offset:34816
	ds_read_b128 v[148:151], v138 offset:35840
	ds_read_b128 v[152:155], v137 offset:32768
	ds_read_b128 v[156:159], v137 offset:33792
	ds_read_b128 v[160:163], v137 offset:34816
	ds_read_b128 v[164:167], v137 offset:35840
	ds_read_b128 v[168:171], v137 offset:36864
	ds_read_b128 v[172:175], v137 offset:37888
	ds_read_b128 v[176:179], v137 offset:38912
	ds_read_b128 v[180:183], v137 offset:39936
	s_waitcnt vmcnt(2)
	s_barrier
; #define WAIT_V(n) asm volatile("s_waitcnt vmcnt(" #n ")" ::: "memory")
; #define WAIT_L(n) asm volatile("s_waitcnt lgkmcnt(" #n ")" ::: "memory")
; #define BAR __builtin_amdgcn_s_barrier()
; #define LDA(dst, b, h) _Pragma("unroll") for (int m = 0; m < 4; ++m) _Pragma("unroll") for (int k = 0; k < 2; ++k) \
;     dst[m][k] = *reinterpret_cast<const bf16x8*>((char*)shm + abase + (((b) * 2 + (h)) * 16384 + (m * 2 + k) * 1024))
; #define LDB(dst, b, h) _Pragma("unroll") for (int n = 0; n < 2; ++n) _Pragma("unroll") for (int k = 0; k < 2; ++k) \
;     dst[n][k] = *reinterpret_cast<const bf16x8*>((char*)shm + bbase + (((b) * 2 + (h)) * 16384 + (n * 2 + k) * 1024))
; template <bool SWAP>
; __device__ __forceinline__ void gemm_main(const u16* __restrict__ A, const u16* __restrict__ Bt, int brow, int bcol,
;                                           u16* shm, f32x4 (&acc)[2][2][4][2]) {
;     ...
;     LDA(At, 0, 1); WAIT_V(4); BAR; WAIT_L(0); MMA(1, 0, At, B0); MMA(1, 1, At, B1); BAR; }
;   { LDB(B0, 1, 0); LDA(At, 1, 0); WAIT_V(2); BAR; WAIT_L(0); MMA(0, 0, At, B0); BAR;
;     LDB(B1, 1, 1); WAIT_V(0); BAR; WAIT_L(0); MMA(0, 1, At, B1); BAR;
;     LDA(At, 1, 1); BAR; WAIT_L(0); MMA(1, 0, At, B0); MMA(1, 1, At, B1); BAR; }
;   if (wr == 0) BAR;
	s_waitcnt lgkmcnt(0)
	s_setprio 1
	s_waitcnt lgkmcnt(0)
	v_mfma_f32_16x16x32_bf16 v[124:127], v[132:135], v[152:155], v[124:127]
	v_mfma_f32_16x16x32_bf16 v[120:123], v[144:147], v[152:155], v[120:123]
	v_mfma_f32_16x16x32_bf16 v[116:119], v[132:135], v[160:163], v[116:119]
	v_mfma_f32_16x16x32_bf16 v[112:115], v[144:147], v[160:163], v[112:115]
	v_mfma_f32_16x16x32_bf16 v[108:111], v[132:135], v[168:171], v[108:111]
	v_mfma_f32_16x16x32_bf16 v[104:107], v[144:147], v[168:171], v[104:107]
	v_mfma_f32_16x16x32_bf16 v[100:103], v[132:135], v[176:179], v[100:103]
	v_mfma_f32_16x16x32_bf16 v[96:99], v[144:147], v[176:179], v[96:99]
	v_mfma_f32_16x16x32_bf16 v[128:131], v[140:143], v[156:159], v[124:127]
	v_mfma_f32_16x16x32_bf16 v[124:127], v[148:151], v[156:159], v[120:123]
	v_mfma_f32_16x16x32_bf16 v[116:119], v[140:143], v[164:167], v[116:119]
	v_mfma_f32_16x16x32_bf16 v[112:115], v[148:151], v[164:167], v[112:115]
	v_mfma_f32_16x16x32_bf16 v[108:111], v[140:143], v[172:175], v[108:111]
	v_mfma_f32_16x16x32_bf16 v[104:107], v[148:151], v[172:175], v[104:107]
	v_mfma_f32_16x16x32_bf16 v[100:103], v[140:143], v[180:183], v[100:103]
	v_mfma_f32_16x16x32_bf16 v[96:99], v[148:151], v[180:183], v[96:99]
	s_setprio 0
	s_barrier
	ds_read_b128 v[120:123], v138 offset:49152
	ds_read_b128 v[184:187], v138 offset:50176
	ds_read_b128 v[188:191], v138 offset:51200
	ds_read_b128 v[194:197], v138 offset:52224
	s_waitcnt vmcnt(0)
	s_barrier
	s_waitcnt lgkmcnt(0)
	s_setprio 1
	s_waitcnt lgkmcnt(0)
	v_mfma_f32_16x16x32_bf16 v[92:95], v[120:123], v[152:155], v[92:95]
	v_mfma_f32_16x16x32_bf16 v[88:91], v[188:191], v[152:155], v[88:91]
	v_mfma_f32_16x16x32_bf16 v[84:87], v[120:123], v[160:163], v[84:87]
	v_mfma_f32_16x16x32_bf16 v[80:83], v[188:191], v[160:163], v[80:83]
	v_mfma_f32_16x16x32_bf16 v[76:79], v[120:123], v[168:171], v[76:79]
	v_mfma_f32_16x16x32_bf16 v[72:75], v[188:191], v[168:171], v[72:75]
	v_mfma_f32_16x16x32_bf16 v[68:71], v[120:123], v[176:179], v[68:71]
	v_mfma_f32_16x16x32_bf16 v[64:67], v[188:191], v[176:179], v[64:67]
	v_mfma_f32_16x16x32_bf16 v[92:95], v[184:187], v[156:159], v[92:95]
	v_mfma_f32_16x16x32_bf16 v[88:91], v[194:197], v[156:159], v[88:91]
	v_mfma_f32_16x16x32_bf16 v[84:87], v[184:187], v[164:167], v[84:87]
	v_mfma_f32_16x16x32_bf16 v[80:83], v[194:197], v[164:167], v[80:83]
	v_mfma_f32_16x16x32_bf16 v[76:79], v[184:187], v[172:175], v[76:79]
	v_mfma_f32_16x16x32_bf16 v[72:75], v[194:197], v[172:175], v[72:75]
	v_mfma_f32_16x16x32_bf16 v[68:71], v[184:187], v[180:183], v[68:71]
	v_mfma_f32_16x16x32_bf16 v[64:67], v[194:197], v[180:183], v[64:67]
	s_setprio 0
	s_barrier
	ds_read_b128 v[152:155], v137 offset:49152
	ds_read_b128 v[156:159], v137 offset:50176
	ds_read_b128 v[160:163], v137 offset:51200
	ds_read_b128 v[164:167], v137 offset:52224
	ds_read_b128 v[168:171], v137 offset:53248
	ds_read_b128 v[172:175], v137 offset:54272
	ds_read_b128 v[176:179], v137 offset:55296
	ds_read_b128 v[180:183], v137 offset:56320
	s_barrier
	s_waitcnt lgkmcnt(0)
	s_setprio 1
	s_waitcnt lgkmcnt(0)
	v_mfma_f32_16x16x32_bf16 v[60:63], v[132:135], v[152:155], v[60:63]
	v_mfma_f32_16x16x32_bf16 v[56:59], v[144:147], v[152:155], v[56:59]
	v_mfma_f32_16x16x32_bf16 v[52:55], v[132:135], v[160:163], v[52:55]
	v_mfma_f32_16x16x32_bf16 v[48:51], v[144:147], v[160:163], v[48:51]
	v_mfma_f32_16x16x32_bf16 v[44:47], v[132:135], v[168:171], v[44:47]
	v_mfma_f32_16x16x32_bf16 v[40:43], v[144:147], v[168:171], v[40:43]
	v_mfma_f32_16x16x32_bf16 v[36:39], v[132:135], v[176:179], v[36:39]
	v_mfma_f32_16x16x32_bf16 v[32:35], v[144:147], v[176:179], v[32:35]
	v_mfma_f32_16x16x32_bf16 v[60:63], v[140:143], v[156:159], v[60:63]
	v_mfma_f32_16x16x32_bf16 v[56:59], v[148:151], v[156:159], v[56:59]
	v_mfma_f32_16x16x32_bf16 v[52:55], v[140:143], v[164:167], v[52:55]
	v_mfma_f32_16x16x32_bf16 v[48:51], v[148:151], v[164:167], v[48:51]
	v_mfma_f32_16x16x32_bf16 v[44:47], v[140:143], v[172:175], v[44:47]
	v_mfma_f32_16x16x32_bf16 v[40:43], v[148:151], v[172:175], v[40:43]
	v_mfma_f32_16x16x32_bf16 v[36:39], v[140:143], v[180:183], v[36:39]
	v_mfma_f32_16x16x32_bf16 v[32:35], v[148:151], v[180:183], v[32:35]
	s_setprio 0
	s_setprio 1
	v_mfma_f32_16x16x32_bf16 v[28:31], v[120:123], v[152:155], v[28:31]
	v_mfma_f32_16x16x32_bf16 v[24:27], v[188:191], v[152:155], v[24:27]
	v_mfma_f32_16x16x32_bf16 v[20:23], v[120:123], v[160:163], v[20:23]
	v_mfma_f32_16x16x32_bf16 v[16:19], v[188:191], v[160:163], v[16:19]
	v_mfma_f32_16x16x32_bf16 v[12:15], v[120:123], v[168:171], v[12:15]
	v_mfma_f32_16x16x32_bf16 v[8:11], v[188:191], v[168:171], v[8:11]
	v_mfma_f32_16x16x32_bf16 v[4:7], v[120:123], v[176:179], v[4:7]
	v_mfma_f32_16x16x32_bf16 v[0:3], v[188:191], v[176:179], v[0:3]
	v_mfma_f32_16x16x32_bf16 v[28:31], v[184:187], v[156:159], v[28:31]
	v_mfma_f32_16x16x32_bf16 v[24:27], v[194:197], v[156:159], v[24:27]
	v_mfma_f32_16x16x32_bf16 v[20:23], v[184:187], v[164:167], v[20:23]
	v_mfma_f32_16x16x32_bf16 v[16:19], v[194:197], v[164:167], v[16:19]
	v_mfma_f32_16x16x32_bf16 v[12:15], v[184:187], v[172:175], v[12:15]
	v_mfma_f32_16x16x32_bf16 v[8:11], v[194:197], v[172:175], v[8:11]
	v_mfma_f32_16x16x32_bf16 v[4:7], v[184:187], v[180:183], v[4:7]
	v_mfma_f32_16x16x32_bf16 v[0:3], v[194:197], v[180:183], v[0:3]
	s_setprio 0
	s_movk_i32 s0, 0x100
	v_cmp_gt_u32_e32 vcc, s0, v136
	s_barrier
	s_and_saveexec_b64 s[0:1], vcc
	s_cbranch_execz .LBB0_567
	s_barrier

; #define WAIT_V(n) asm volatile("s_waitcnt vmcnt(" #n ")" ::: "memory")
; #define WAIT_L(n) asm volatile("s_waitcnt lgkmcnt(" #n ")" ::: "memory")
; #define BAR __builtin_amdgcn_s_barrier()
; #define SCHED __builtin_amdgcn_sched_barrier(0)
; #define STAGE(P, BASE, br, kt) do { const char* _g = (const char*)((BASE) + (size_t)(br) * GK + (kt) * BK); \
;     __builtin_amdgcn_global_load_lds((const unsigned*)(_g + voff0), (unsigned*)((char*)(P) + tx * 16), 16, 0, 0); \
;     __builtin_amdgcn_global_load_lds((const unsigned*)(_g + voff1), (unsigned*)((char*)(P) + tx * 16 + 8192), 16, 0, 0); } while (0)
; #define LDA(dst, b, h) _Pragma("unroll") for (int m = 0; m < 4; ++m) _Pragma("unroll") for (int k = 0; k < 2; ++k) \
;     dst[m][k] = *reinterpret_cast<const bf16x8*>((char*)shm + abase + (((b) * 2 + (h)) * 16384 + (m * 2 + k) * 1024))
; #define LDB(dst, b, h) _Pragma("unroll") for (int n = 0; n < 2; ++n) _Pragma("unroll") for (int k = 0; k < 2; ++k) \
;     dst[n][k] = *reinterpret_cast<const bf16x8*>((char*)shm + bbase + (((b) * 2 + (h)) * 16384 + (n * 2 + k) * 1024))
; template <bool SWAP>
; __device__ __forceinline__ void gemm_main(const u16* __restrict__ A, const u16* __restrict__ Bt, int brow, int bcol,
;                                           u16* shm, f32x4 (&acc)[2][2][4][2]) {
;     ...
;     LDB(B0, 0, 0); SCHED; LDA(At, 0, 0); STAGE(SA(1, 1), A, brow + HALF, t + 1);
;     WAIT_L(8); BAR; WAIT_L(0); MMA(0, 0, At, B0); BAR; SCHED;
;     LDB(B1, 0, 1); STAGE(SB(0, 0), Bt, bcol, t + 2);
;     BAR; WAIT_L(0); MMA(0, 1, At, B1); BAR;
;     LDA(At, 0, 1); STAGE(SA(0, 0), A, brow, t + 2);
;     BAR; WAIT_L(0); MMA(1, 0, At, B0); BAR; SCHED;
;     STAGE(SB(0, 1), Bt, bcol + HALF, t + 2);
;     WAIT_V(6); BAR; MMA(1, 1, At, B1); BAR;
.LBB0_570:
	ds_read_b128 v[168:171], v137 offset:1024
	ds_read_b128 v[176:179], v137 offset:3072
	ds_read_b128 v[184:187], v137 offset:5120
	ds_read_b128 v[194:197], v137 offset:7168
	v_add_u32_e32 v192, 0, v140
	v_add_u32_e32 v146, 0xc000, v192
	v_lshl_add_u64 v[230:231], vcc, 0, v[132:133]
	v_add_u32_e32 v147, 0xe000, v192
	v_lshl_add_u64 v[198:199], v[230:231], 0, s[14:15]
	s_add_u32 m0, s24, 0xc000
	v_lshl_add_u64 v[232:233], vcc, 0, v[134:135]
	global_load_lds_dwordx4 v[198:199], off
	v_lshl_add_u64 v[198:199], v[232:233], 0, s[14:15]
	s_add_u32 m0, s24, 0xe000
	s_nop 0
	global_load_lds_dwordx4 v[198:199], off
	s_waitcnt lgkmcnt(8)
	s_barrier
	s_waitcnt lgkmcnt(0)
	v_mfma_f32_16x16x32_bf16 v[124:127], v[148:151], v[164:167], v[124:127]
	v_mfma_f32_16x16x32_bf16 v[120:123], v[156:159], v[164:167], v[120:123]
	v_mfma_f32_16x16x32_bf16 v[116:119], v[148:151], v[172:175], v[116:119]
	v_mfma_f32_16x16x32_bf16 v[112:115], v[156:159], v[172:175], v[112:115]
	v_mfma_f32_16x16x32_bf16 v[108:111], v[148:151], v[180:183], v[108:111]
	v_mfma_f32_16x16x32_bf16 v[104:107], v[156:159], v[180:183], v[104:107]
	v_mfma_f32_16x16x32_bf16 v[100:103], v[148:151], v[188:191], v[100:103]
	v_mfma_f32_16x16x32_bf16 v[96:99], v[156:159], v[188:191], v[96:99]
	v_mfma_f32_16x16x32_bf16 v[124:127], v[152:155], v[168:171], v[124:127]
	v_mfma_f32_16x16x32_bf16 v[120:123], v[160:163], v[168:171], v[120:123]
	v_mfma_f32_16x16x32_bf16 v[116:119], v[152:155], v[176:179], v[116:119]
	v_mfma_f32_16x16x32_bf16 v[112:115], v[160:163], v[176:179], v[112:115]
	v_mfma_f32_16x16x32_bf16 v[108:111], v[152:155], v[184:187], v[108:111]
	v_mfma_f32_16x16x32_bf16 v[104:107], v[160:163], v[184:187], v[104:107]
	v_mfma_f32_16x16x32_bf16 v[100:103], v[152:155], v[194:197], v[100:103]
	v_mfma_f32_16x16x32_bf16 v[96:99], v[160:163], v[194:197], v[96:99]
	s_barrier
	ds_read_b128 v[198:201], v138 offset:16384
	ds_read_b128 v[202:205], v138 offset:17408
	ds_read_b128 v[206:209], v138 offset:18432
	ds_read_b128 v[226:229], v138 offset:19456
	v_lshl_add_u64 v[234:235], vcc, 0, v[128:129]
	v_lshl_add_u64 v[236:237], v[234:235], 0, s[16:17]
	s_add_u32 m0, s24, s28
	s_nop 0
	global_load_lds_dwordx4 v[236:237], off
	v_lshl_add_u64 v[236:237], vcc, 0, v[130:131]
	v_lshl_add_u64 v[238:239], v[236:237], 0, s[16:17]
	s_add_u32 m0, s24, s28
	s_add_u32 m0, m0, 0x2000
	s_nop 0
	global_load_lds_dwordx4 v[238:239], off
	s_barrier
	s_waitcnt lgkmcnt(0)
	v_mfma_f32_16x16x32_bf16 v[92:95], v[198:201], v[164:167], v[92:95]
	v_mfma_f32_16x16x32_bf16 v[88:91], v[206:209], v[164:167], v[88:91]
	v_mfma_f32_16x16x32_bf16 v[84:87], v[198:201], v[172:175], v[84:87]
	v_mfma_f32_16x16x32_bf16 v[80:83], v[206:209], v[172:175], v[80:83]
	v_mfma_f32_16x16x32_bf16 v[76:79], v[198:201], v[180:183], v[76:79]
	v_mfma_f32_16x16x32_bf16 v[72:75], v[206:209], v[180:183], v[72:75]
	v_mfma_f32_16x16x32_bf16 v[68:71], v[198:201], v[188:191], v[68:71]
	v_mfma_f32_16x16x32_bf16 v[64:67], v[206:209], v[188:191], v[64:67]
	v_mfma_f32_16x16x32_bf16 v[92:95], v[202:205], v[168:171], v[92:95]
	ds_read_b128 v[164:167], v137 offset:16384
	v_mfma_f32_16x16x32_bf16 v[88:91], v[226:229], v[168:171], v[88:91]
	v_mfma_f32_16x16x32_bf16 v[84:87], v[202:205], v[176:179], v[84:87]
	ds_read_b128 v[172:175], v137 offset:18432
	v_mfma_f32_16x16x32_bf16 v[80:83], v[226:229], v[176:179], v[80:83]
	v_mfma_f32_16x16x32_bf16 v[76:79], v[202:205], v[184:187], v[76:79]
	ds_read_b128 v[180:183], v137 offset:20480
	v_mfma_f32_16x16x32_bf16 v[72:75], v[226:229], v[184:187], v[72:75]
	v_mfma_f32_16x16x32_bf16 v[68:71], v[202:205], v[194:197], v[68:71]
	ds_read_b128 v[188:191], v137 offset:22528
	v_mfma_f32_16x16x32_bf16 v[64:67], v[226:229], v[194:197], v[64:67]
	s_barrier
	ds_read_b128 v[168:171], v137 offset:17408
	ds_read_b128 v[176:179], v137 offset:19456
	ds_read_b128 v[184:187], v137 offset:21504
	ds_read_b128 v[194:197], v137 offset:23552
	v_lshl_add_u64 v[238:239], v[230:231], 0, s[18:19]
	s_add_u32 m0, s24, 0x0
	s_nop 0
	global_load_lds_dwordx4 v[238:239], off
	v_lshl_add_u64 v[238:239], v[232:233], 0, s[18:19]
	s_add_u32 m0, s24, 0x2000
	s_nop 0
	global_load_lds_dwordx4 v[238:239], off
	s_waitcnt vmcnt(8)
	s_barrier
	s_waitcnt lgkmcnt(0)
	v_mfma_f32_16x16x32_bf16 v[60:63], v[148:151], v[164:167], v[60:63]
	v_mfma_f32_16x16x32_bf16 v[56:59], v[156:159], v[164:167], v[56:59]
	v_mfma_f32_16x16x32_bf16 v[52:55], v[148:151], v[172:175], v[52:55]
	v_mfma_f32_16x16x32_bf16 v[48:51], v[156:159], v[172:175], v[48:51]
	v_mfma_f32_16x16x32_bf16 v[44:47], v[148:151], v[180:183], v[44:47]
	v_mfma_f32_16x16x32_bf16 v[40:43], v[156:159], v[180:183], v[40:43]
	v_mfma_f32_16x16x32_bf16 v[36:39], v[148:151], v[188:191], v[36:39]
	v_mfma_f32_16x16x32_bf16 v[32:35], v[156:159], v[188:191], v[32:35]
	v_mfma_f32_16x16x32_bf16 v[60:63], v[152:155], v[168:171], v[60:63]
	v_mfma_f32_16x16x32_bf16 v[56:59], v[160:163], v[168:171], v[56:59]
	v_mfma_f32_16x16x32_bf16 v[52:55], v[152:155], v[176:179], v[52:55]
	v_mfma_f32_16x16x32_bf16 v[48:51], v[160:163], v[176:179], v[48:51]
	v_mfma_f32_16x16x32_bf16 v[44:47], v[152:155], v[184:187], v[44:47]
	v_mfma_f32_16x16x32_bf16 v[40:43], v[160:163], v[184:187], v[40:43]
	v_mfma_f32_16x16x32_bf16 v[36:39], v[152:155], v[194:197], v[36:39]
	v_mfma_f32_16x16x32_bf16 v[32:35], v[160:163], v[194:197], v[32:35]
	s_barrier
	ds_read_b128 v[148:151], v138 offset:32768
	ds_read_b128 v[152:155], v138 offset:33792
	ds_read_b128 v[156:159], v138 offset:34816
	ds_read_b128 v[160:163], v138 offset:35840
	v_lshl_add_u64 v[254:255], v[234:235], 0, s[42:43]
	s_add_u32 m0, s24, s29
	s_nop 0
	global_load_lds_dwordx4 v[254:255], off
	v_lshl_add_u64 v[254:255], v[236:237], 0, s[42:43]
	s_add_u32 m0, s24, s29
	s_add_u32 m0, m0, 0x2000
	s_nop 0
	global_load_lds_dwordx4 v[254:255], off
	s_waitcnt vmcnt(6)
	s_barrier
; #define WAIT_V(n) asm volatile("s_waitcnt vmcnt(" #n ")" ::: "memory")
; #define WAIT_L(n) asm volatile("s_waitcnt lgkmcnt(" #n ")" ::: "memory")
; #define BAR __builtin_amdgcn_s_barrier()
; #define SCHED __builtin_amdgcn_sched_barrier(0)
; #define STAGE(P, BASE, br, kt) do { const char* _g = (const char*)((BASE) + (size_t)(br) * GK + (kt) * BK); \
;     __builtin_amdgcn_global_load_lds((const unsigned*)(_g + voff0), (unsigned*)((char*)(P) + tx * 16), 16, 0, 0); \
;     __builtin_amdgcn_global_load_lds((const unsigned*)(_g + voff1), (unsigned*)((char*)(P) + tx * 16 + 8192), 16, 0, 0); } while (0)
; #define LDA(dst, b, h) _Pragma("unroll") for (int m = 0; m < 4; ++m) _Pragma("unroll") for (int k = 0; k < 2; ++k) \
;     dst[m][k] = *reinterpret_cast<const bf16x8*>((char*)shm + abase + (((b) * 2 + (h)) * 16384 + (m * 2 + k) * 1024))
; #define LDB(dst, b, h) _Pragma("unroll") for (int n = 0; n < 2; ++n) _Pragma("unroll") for (int k = 0; k < 2; ++k) \
;     dst[n][k] = *reinterpret_cast<const bf16x8*>((char*)shm + bbase + (((b) * 2 + (h)) * 16384 + (n * 2 + k) * 1024))
; template <bool SWAP>
; __device__ __forceinline__ void gemm_main(const u16* __restrict__ A, const u16* __restrict__ Bt, int brow, int bcol,
;                                           u16* shm, f32x4 (&acc)[2][2][4][2]) {
;     ...
;     WAIT_V(6); BAR; MMA(1, 1, At, B1); BAR;
;     LDB(B0, 1, 0); SCHED; LDA(At, 1, 0); STAGE(SA(0, 1), A, brow + HALF, t + 2);
;     WAIT_L(8); BAR; WAIT_L(0); MMA(0, 0, At, B0); BAR; SCHED;
;     LDB(B1, 1, 1); STAGE(SB(1, 0), Bt, bcol, t + 3);
;     BAR; WAIT_L(0); MMA(0, 1, At, B1); BAR;
;     LDA(At, 1, 1); STAGE(SA(1, 0), A, brow, t + 3);
;     BAR; WAIT_L(0); MMA(1, 0, At, B0); BAR; SCHED;
	v_mfma_f32_16x16x32_bf16 v[28:31], v[198:201], v[164:167], v[28:31]
	v_mfma_f32_16x16x32_bf16 v[24:27], v[206:209], v[164:167], v[24:27]
	v_mfma_f32_16x16x32_bf16 v[20:23], v[198:201], v[172:175], v[20:23]
	v_mfma_f32_16x16x32_bf16 v[16:19], v[206:209], v[172:175], v[16:19]
	v_mfma_f32_16x16x32_bf16 v[12:15], v[198:201], v[180:183], v[12:15]
	v_mfma_f32_16x16x32_bf16 v[8:11], v[206:209], v[180:183], v[8:11]
	v_mfma_f32_16x16x32_bf16 v[4:7], v[198:201], v[188:191], v[4:7]
	v_mfma_f32_16x16x32_bf16 v[0:3], v[206:209], v[188:191], v[0:3]
	v_mfma_f32_16x16x32_bf16 v[28:31], v[202:205], v[168:171], v[28:31]
	ds_read_b128 v[164:167], v137 offset:32768
	v_mfma_f32_16x16x32_bf16 v[24:27], v[226:229], v[168:171], v[24:27]
	v_mfma_f32_16x16x32_bf16 v[20:23], v[202:205], v[176:179], v[20:23]
	ds_read_b128 v[172:175], v137 offset:34816
	v_mfma_f32_16x16x32_bf16 v[16:19], v[226:229], v[176:179], v[16:19]
	v_mfma_f32_16x16x32_bf16 v[12:15], v[202:205], v[184:187], v[12:15]
	ds_read_b128 v[180:183], v137 offset:36864
	v_mfma_f32_16x16x32_bf16 v[8:11], v[226:229], v[184:187], v[8:11]
	v_mfma_f32_16x16x32_bf16 v[4:7], v[202:205], v[194:197], v[4:7]
	ds_read_b128 v[188:191], v137 offset:38912
	v_mfma_f32_16x16x32_bf16 v[0:3], v[226:229], v[194:197], v[0:3]
	s_barrier
	ds_read_b128 v[168:171], v137 offset:33792
	ds_read_b128 v[176:179], v137 offset:35840
	ds_read_b128 v[184:187], v137 offset:37888
	ds_read_b128 v[194:197], v137 offset:39936
	v_lshl_add_u64 v[198:199], v[230:231], 0, s[22:23]
	s_add_u32 m0, s24, 0x4000
	s_nop 0
	global_load_lds_dwordx4 v[198:199], off
	v_lshl_add_u64 v[198:199], v[232:233], 0, s[22:23]
	s_add_u32 m0, s24, 0x6000
	s_nop 0
	global_load_lds_dwordx4 v[198:199], off
	s_waitcnt lgkmcnt(8)
	s_barrier
	s_waitcnt lgkmcnt(0)
	v_mfma_f32_16x16x32_bf16 v[124:127], v[148:151], v[164:167], v[124:127]
	v_mfma_f32_16x16x32_bf16 v[120:123], v[156:159], v[164:167], v[120:123]
	v_mfma_f32_16x16x32_bf16 v[116:119], v[148:151], v[172:175], v[116:119]
	v_mfma_f32_16x16x32_bf16 v[112:115], v[156:159], v[172:175], v[112:115]
	v_mfma_f32_16x16x32_bf16 v[108:111], v[148:151], v[180:183], v[108:111]
	v_mfma_f32_16x16x32_bf16 v[104:107], v[156:159], v[180:183], v[104:107]
	v_mfma_f32_16x16x32_bf16 v[100:103], v[148:151], v[188:191], v[100:103]
	v_mfma_f32_16x16x32_bf16 v[96:99], v[156:159], v[188:191], v[96:99]
	v_mfma_f32_16x16x32_bf16 v[124:127], v[152:155], v[168:171], v[124:127]
	v_mfma_f32_16x16x32_bf16 v[120:123], v[160:163], v[168:171], v[120:123]
	v_mfma_f32_16x16x32_bf16 v[116:119], v[152:155], v[176:179], v[116:119]
	v_mfma_f32_16x16x32_bf16 v[112:115], v[160:163], v[176:179], v[112:115]
	v_mfma_f32_16x16x32_bf16 v[108:111], v[152:155], v[184:187], v[108:111]
	v_mfma_f32_16x16x32_bf16 v[104:107], v[160:163], v[184:187], v[104:107]
	v_mfma_f32_16x16x32_bf16 v[100:103], v[152:155], v[194:197], v[100:103]
	v_mfma_f32_16x16x32_bf16 v[96:99], v[160:163], v[194:197], v[96:99]
	s_barrier
	ds_read_b128 v[198:201], v138 offset:49152
	ds_read_b128 v[202:205], v138 offset:50176
	ds_read_b128 v[206:209], v138 offset:51200
	ds_read_b128 v[226:229], v138 offset:52224
	v_lshl_add_u64 v[238:239], v[234:235], 0, s[20:21]
	s_add_u32 m0, s24, s30
	s_nop 0
	global_load_lds_dwordx4 v[238:239], off
	v_lshl_add_u64 v[238:239], v[236:237], 0, s[20:21]
	s_add_u32 m0, s24, s30
	s_add_u32 m0, m0, 0x2000
	s_nop 0
	global_load_lds_dwordx4 v[238:239], off
	s_barrier
	s_waitcnt lgkmcnt(0)
	v_mfma_f32_16x16x32_bf16 v[92:95], v[198:201], v[164:167], v[92:95]
	v_mfma_f32_16x16x32_bf16 v[88:91], v[206:209], v[164:167], v[88:91]
	v_mfma_f32_16x16x32_bf16 v[84:87], v[198:201], v[172:175], v[84:87]
	v_mfma_f32_16x16x32_bf16 v[80:83], v[206:209], v[172:175], v[80:83]
	v_mfma_f32_16x16x32_bf16 v[76:79], v[198:201], v[180:183], v[76:79]
	v_mfma_f32_16x16x32_bf16 v[72:75], v[206:209], v[180:183], v[72:75]
	v_mfma_f32_16x16x32_bf16 v[68:71], v[198:201], v[188:191], v[68:71]
	v_mfma_f32_16x16x32_bf16 v[64:67], v[206:209], v[188:191], v[64:67]
	v_mfma_f32_16x16x32_bf16 v[92:95], v[202:205], v[168:171], v[92:95]
	ds_read_b128 v[164:167], v137 offset:49152
	v_mfma_f32_16x16x32_bf16 v[88:91], v[226:229], v[168:171], v[88:91]
	v_mfma_f32_16x16x32_bf16 v[84:87], v[202:205], v[176:179], v[84:87]
	ds_read_b128 v[172:175], v137 offset:51200
	v_mfma_f32_16x16x32_bf16 v[80:83], v[226:229], v[176:179], v[80:83]
	v_mfma_f32_16x16x32_bf16 v[76:79], v[202:205], v[184:187], v[76:79]
	ds_read_b128 v[180:183], v137 offset:53248
	v_mfma_f32_16x16x32_bf16 v[72:75], v[226:229], v[184:187], v[72:75]
	v_mfma_f32_16x16x32_bf16 v[68:71], v[202:205], v[194:197], v[68:71]
	ds_read_b128 v[188:191], v137 offset:55296
	v_mfma_f32_16x16x32_bf16 v[64:67], v[226:229], v[194:197], v[64:67]
	s_barrier
	ds_read_b128 v[168:171], v137 offset:50176
	ds_read_b128 v[176:179], v137 offset:52224
	ds_read_b128 v[184:187], v137 offset:54272
	ds_read_b128 v[194:197], v137 offset:56320
	v_lshl_add_u64 v[230:231], v[230:231], 0, s[92:93]
	s_add_u32 m0, s24, 0x8000
	s_nop 0
	global_load_lds_dwordx4 v[230:231], off
	v_lshl_add_u64 v[230:231], v[232:233], 0, s[92:93]
	s_add_u32 m0, s24, 0xa000
	s_nop 0
	global_load_lds_dwordx4 v[230:231], off
	s_waitcnt vmcnt(8)
	s_barrier
; #define WAIT_V(n) asm volatile("s_waitcnt vmcnt(" #n ")" ::: "memory")
; #define WAIT_L(n) asm volatile("s_waitcnt lgkmcnt(" #n ")" ::: "memory")
; #define BAR __builtin_amdgcn_s_barrier()
; #define SCHED __builtin_amdgcn_sched_barrier(0)
; #define STAGE(P, BASE, br, kt) do { const char* _g = (const char*)((BASE) + (size_t)(br) * GK + (kt) * BK); \
;     __builtin_amdgcn_global_load_lds((const unsigned*)(_g + voff0), (unsigned*)((char*)(P) + tx * 16), 16, 0, 0); \
;     __builtin_amdgcn_global_load_lds((const unsigned*)(_g + voff1), (unsigned*)((char*)(P) + tx * 16 + 8192), 16, 0, 0); } while (0)
; #define LDA(dst, b, h) _Pragma("unroll") for (int m = 0; m < 4; ++m) _Pragma("unroll") for (int k = 0; k < 2; ++k) \
;     dst[m][k] = *reinterpret_cast<const bf16x8*>((char*)shm + abase + (((b) * 2 + (h)) * 16384 + (m * 2 + k) * 1024))
; #define LDB(dst, b, h) _Pragma("unroll") for (int n = 0; n < 2; ++n) _Pragma("unroll") for (int k = 0; k < 2; ++k) \
;     dst[n][k] = *reinterpret_cast<const bf16x8*>((char*)shm + bbase + (((b) * 2 + (h)) * 16384 + (n * 2 + k) * 1024))
; template <bool SWAP>
; __device__ __forceinline__ void gemm_main(const u16* __restrict__ A, const u16* __restrict__ Bt, int brow, int bcol,
;                                           u16* shm, f32x4 (&acc)[2][2][4][2]) {
;     ...
;     LDA(At, 1, 1); STAGE(SA(1, 0), A, brow, t + 3);
;     BAR; WAIT_L(0); MMA(1, 0, At, B0); BAR; SCHED;
;     STAGE(SB(1, 1), Bt, bcol + HALF, t + 3);
;     WAIT_V(6); BAR; MMA(1, 1, At, B1); BAR;
;   }
;   { LDB(B0, 0, 0); LDA(At, 0, 0); STAGE(SA(1, 1), A, brow + HALF, nt - 1);
;     BAR; WAIT_L(0); MMA(0, 0, At, B0); BAR;
	s_waitcnt lgkmcnt(0)
	v_mfma_f32_16x16x32_bf16 v[60:63], v[148:151], v[164:167], v[60:63]
	v_mfma_f32_16x16x32_bf16 v[56:59], v[156:159], v[164:167], v[56:59]
	v_mfma_f32_16x16x32_bf16 v[52:55], v[148:151], v[172:175], v[52:55]
	v_mfma_f32_16x16x32_bf16 v[48:51], v[156:159], v[172:175], v[48:51]
	v_mfma_f32_16x16x32_bf16 v[44:47], v[148:151], v[180:183], v[44:47]
	v_mfma_f32_16x16x32_bf16 v[40:43], v[156:159], v[180:183], v[40:43]
	v_mfma_f32_16x16x32_bf16 v[36:39], v[148:151], v[188:191], v[36:39]
	v_mfma_f32_16x16x32_bf16 v[32:35], v[156:159], v[188:191], v[32:35]
	v_mfma_f32_16x16x32_bf16 v[60:63], v[152:155], v[168:171], v[60:63]
	v_mfma_f32_16x16x32_bf16 v[56:59], v[160:163], v[168:171], v[56:59]
	v_mfma_f32_16x16x32_bf16 v[52:55], v[152:155], v[176:179], v[52:55]
	v_mfma_f32_16x16x32_bf16 v[48:51], v[160:163], v[176:179], v[48:51]
	v_mfma_f32_16x16x32_bf16 v[44:47], v[152:155], v[184:187], v[44:47]
	v_mfma_f32_16x16x32_bf16 v[40:43], v[160:163], v[184:187], v[40:43]
	v_mfma_f32_16x16x32_bf16 v[36:39], v[152:155], v[194:197], v[36:39]
	v_mfma_f32_16x16x32_bf16 v[32:35], v[160:163], v[194:197], v[32:35]
	s_barrier
	ds_read_b128 v[148:151], v138
	ds_read_b128 v[152:155], v138 offset:1024
	ds_read_b128 v[156:159], v138 offset:2048
	ds_read_b128 v[160:163], v138 offset:3072
	v_lshl_add_u64 v[254:255], v[234:235], 0, s[72:73]
	s_add_u32 m0, s24, s31
	s_nop 0
	global_load_lds_dwordx4 v[254:255], off
	v_lshl_add_u64 v[254:255], v[236:237], 0, s[72:73]
	s_add_u32 m0, s24, s31
	s_add_u32 m0, m0, 0x2000
	s_nop 0
	global_load_lds_dwordx4 v[254:255], off
	s_waitcnt vmcnt(6)
	s_barrier
	v_mfma_f32_16x16x32_bf16 v[28:31], v[198:201], v[164:167], v[28:31]
	v_mfma_f32_16x16x32_bf16 v[24:27], v[206:209], v[164:167], v[24:27]
	v_mfma_f32_16x16x32_bf16 v[20:23], v[198:201], v[172:175], v[20:23]
	v_mfma_f32_16x16x32_bf16 v[16:19], v[206:209], v[172:175], v[16:19]
	v_mfma_f32_16x16x32_bf16 v[12:15], v[198:201], v[180:183], v[12:15]
	v_mfma_f32_16x16x32_bf16 v[8:11], v[206:209], v[180:183], v[8:11]
	v_mfma_f32_16x16x32_bf16 v[4:7], v[198:201], v[188:191], v[4:7]
	v_mfma_f32_16x16x32_bf16 v[0:3], v[206:209], v[188:191], v[0:3]
	v_mfma_f32_16x16x32_bf16 v[28:31], v[202:205], v[168:171], v[28:31]
	ds_read_b128 v[164:167], v137
	v_mfma_f32_16x16x32_bf16 v[24:27], v[226:229], v[168:171], v[24:27]
	v_mfma_f32_16x16x32_bf16 v[20:23], v[202:205], v[176:179], v[20:23]
	ds_read_b128 v[172:175], v137 offset:2048
	v_mfma_f32_16x16x32_bf16 v[16:19], v[226:229], v[176:179], v[16:19]
	v_mfma_f32_16x16x32_bf16 v[12:15], v[202:205], v[184:187], v[12:15]
	ds_read_b128 v[180:183], v137 offset:4096
	v_mfma_f32_16x16x32_bf16 v[8:11], v[226:229], v[184:187], v[8:11]
	v_mfma_f32_16x16x32_bf16 v[4:7], v[202:205], v[194:197], v[4:7]
	ds_read_b128 v[188:191], v137 offset:6144
	v_mfma_f32_16x16x32_bf16 v[0:3], v[226:229], v[194:197], v[0:3]
	s_add_i32 s3, s3, 2
	s_add_u32 vcc_lo, vcc_lo, 0x100
	s_addc_u32 vcc_hi, vcc_hi, 0
	s_cmp_lt_u32 s3, 28
	s_barrier
	s_cbranch_scc1 .LBB0_570
	v_lshlrev_b32_e32 v128, 3, v139
	v_lshlrev_b32_e32 v129, 5, v139
	v_and_b32_e32 v128, 0xffff0, v128
	v_and_b32_e32 v129, 32, v129
	v_add_u32_e32 v129, v129, v142
	v_add_lshl_u32 v128, v141, v128, 12
	v_lshl_add_u32 v192, v129, 1, v128
	v_lshlrev_b32_e32 v128, 3, v143
	v_lshlrev_b32_e32 v129, 5, v143
	v_and_b32_e32 v128, 0xffff0, v128
	v_and_b32_e32 v129, 32, v129
	v_add_u32_e32 v129, v129, v145
	v_add_lshl_u32 v128, v144, v128, 12
	v_lshl_add_u32 v144, v129, 1, v128
	v_mov_b32_e32 v145, v193
	v_lshl_add_u64 v[184:185], s[4:5], 0, v[192:193]
	s_mov_b64 s[14:15], 0xf80
	v_readfirstlane_b32 s3, v146
	v_lshl_add_u64 v[184:185], v[184:185], 0, s[14:15]
	s_mov_b32 m0, s3
	v_lshl_add_u64 v[144:145], s[4:5], 0, v[144:145]
	v_readfirstlane_b32 s3, v147
	ds_read_b128 v[128:131], v138
	ds_read_b128 v[132:135], v138 offset:1024
	ds_read_b128 v[140:143], v138 offset:2048
	ds_read_b128 v[148:151], v138 offset:3072
	ds_read_b128 v[152:155], v137
	ds_read_b128 v[156:159], v137 offset:1024
	ds_read_b128 v[160:163], v137 offset:2048
	ds_read_b128 v[164:167], v137 offset:3072
	ds_read_b128 v[168:171], v137 offset:4096
	ds_read_b128 v[172:175], v137 offset:5120
	ds_read_b128 v[176:179], v137 offset:6144
	ds_read_b128 v[180:183], v137 offset:7168
	global_load_lds_dwordx4 v[184:185], off
	v_lshl_add_u64 v[144:145], v[144:145], 0, s[14:15]
	s_mov_b32 m0, s3
	s_nop 0
	global_load_lds_dwordx4 v[144:145], off
	s_barrier
	s_waitcnt lgkmcnt(0)
	s_setprio 1
	s_waitcnt lgkmcnt(0)
	v_mfma_f32_16x16x32_bf16 v[116:119], v[128:131], v[160:163], v[116:119]
	v_mfma_f32_16x16x32_bf16 v[112:115], v[140:143], v[160:163], v[112:115]
	v_mfma_f32_16x16x32_bf16 v[100:103], v[128:131], v[176:179], v[100:103]
	v_mfma_f32_16x16x32_bf16 v[96:99], v[140:143], v[176:179], v[96:99]
	v_mfma_f32_16x16x32_bf16 v[124:127], v[128:131], v[152:155], v[124:127]
	v_mfma_f32_16x16x32_bf16 v[120:123], v[140:143], v[152:155], v[120:123]
	v_mfma_f32_16x16x32_bf16 v[116:119], v[132:135], v[164:167], v[116:119]
	v_mfma_f32_16x16x32_bf16 v[112:115], v[148:151], v[164:167], v[112:115]
	v_mfma_f32_16x16x32_bf16 v[108:111], v[128:131], v[168:171], v[108:111]
	v_mfma_f32_16x16x32_bf16 v[104:107], v[140:143], v[168:171], v[104:107]
	v_mfma_f32_16x16x32_bf16 v[100:103], v[132:135], v[180:183], v[100:103]
	v_mfma_f32_16x16x32_bf16 v[96:99], v[148:151], v[180:183], v[96:99]
	v_mfma_f32_16x16x32_bf16 v[124:127], v[132:135], v[156:159], v[124:127]
	v_mfma_f32_16x16x32_bf16 v[120:123], v[148:151], v[156:159], v[120:123]
	v_mfma_f32_16x16x32_bf16 v[108:111], v[132:135], v[172:175], v[108:111]
	v_mfma_f32_16x16x32_bf16 v[104:107], v[148:151], v[172:175], v[104:107]
	s_setprio 0
	s_barrier
; #define WAIT_V(n) asm volatile("s_waitcnt vmcnt(" #n ")" ::: "memory")
; #define WAIT_L(n) asm volatile("s_waitcnt lgkmcnt(" #n ")" ::: "memory")
; #define BAR __builtin_amdgcn_s_barrier()
; #define LDA(dst, b, h) _Pragma("unroll") for (int m = 0; m < 4; ++m) _Pragma("unroll") for (int k = 0; k < 2; ++k) \
;     dst[m][k] = *reinterpret_cast<const bf16x8*>((char*)shm + abase + (((b) * 2 + (h)) * 16384 + (m * 2 + k) * 1024))
; #define LDB(dst, b, h) _Pragma("unroll") for (int n = 0; n < 2; ++n) _Pragma("unroll") for (int k = 0; k < 2; ++k) \
;     dst[n][k] = *reinterpret_cast<const bf16x8*>((char*)shm + bbase + (((b) * 2 + (h)) * 16384 + (n * 2 + k) * 1024))
; template <bool SWAP>
; __device__ __forceinline__ void gemm_main(const u16* __restrict__ A, const u16* __restrict__ Bt, int brow, int bcol,
;                                           u16* shm, f32x4 (&acc)[2][2][4][2]) {
;     ...
;     BAR; WAIT_L(0); MMA(0, 0, At, B0); BAR;
;     LDB(B1, 0, 1); BAR; WAIT_L(0); MMA(0, 1, At, B1); BAR;
;     LDA(At, 0, 1); WAIT_V(4); BAR; WAIT_L(0); MMA(1, 0, At, B0); MMA(1, 1, At, B1); BAR; }
;   { LDB(B0, 1, 0); LDA(At, 1, 0); WAIT_V(2); BAR; WAIT_L(0); MMA(0, 0, At, B0); BAR;
;     LDB(B1, 1, 1); WAIT_V(0); BAR; WAIT_L(0); MMA(0, 1, At, B1); BAR;
	ds_read_b128 v[144:147], v138 offset:16384
	ds_read_b128 v[184:187], v138 offset:17408
	ds_read_b128 v[188:191], v138 offset:18432
	ds_read_b128 v[194:197], v138 offset:19456
	s_barrier
	s_waitcnt lgkmcnt(0)
	s_setprio 1
	s_waitcnt lgkmcnt(0)
	v_mfma_f32_16x16x32_bf16 v[92:95], v[144:147], v[152:155], v[92:95]
	v_mfma_f32_16x16x32_bf16 v[88:91], v[188:191], v[152:155], v[88:91]
	v_mfma_f32_16x16x32_bf16 v[84:87], v[144:147], v[160:163], v[84:87]
	v_mfma_f32_16x16x32_bf16 v[80:83], v[188:191], v[160:163], v[80:83]
	v_mfma_f32_16x16x32_bf16 v[76:79], v[144:147], v[168:171], v[76:79]
	v_mfma_f32_16x16x32_bf16 v[72:75], v[188:191], v[168:171], v[72:75]
	v_mfma_f32_16x16x32_bf16 v[68:71], v[144:147], v[176:179], v[68:71]
	v_mfma_f32_16x16x32_bf16 v[64:67], v[188:191], v[176:179], v[64:67]
	v_mfma_f32_16x16x32_bf16 v[92:95], v[184:187], v[156:159], v[92:95]
	v_mfma_f32_16x16x32_bf16 v[88:91], v[194:197], v[156:159], v[88:91]
	v_mfma_f32_16x16x32_bf16 v[84:87], v[184:187], v[164:167], v[84:87]
	v_mfma_f32_16x16x32_bf16 v[80:83], v[194:197], v[164:167], v[80:83]
	v_mfma_f32_16x16x32_bf16 v[76:79], v[184:187], v[172:175], v[76:79]
	v_mfma_f32_16x16x32_bf16 v[72:75], v[194:197], v[172:175], v[72:75]
	v_mfma_f32_16x16x32_bf16 v[68:71], v[184:187], v[180:183], v[68:71]
	v_mfma_f32_16x16x32_bf16 v[64:67], v[194:197], v[180:183], v[64:67]
	s_setprio 0
	s_barrier
	ds_read_b128 v[152:155], v137 offset:16384
	ds_read_b128 v[156:159], v137 offset:17408
	ds_read_b128 v[160:163], v137 offset:18432
	ds_read_b128 v[164:167], v137 offset:19456
	ds_read_b128 v[168:171], v137 offset:20480
	ds_read_b128 v[172:175], v137 offset:21504
	ds_read_b128 v[176:179], v137 offset:22528
	ds_read_b128 v[180:183], v137 offset:23552
	s_waitcnt vmcnt(4)
	s_barrier
	s_waitcnt lgkmcnt(0)
	s_setprio 1
	s_waitcnt lgkmcnt(0)
	v_mfma_f32_16x16x32_bf16 v[60:63], v[128:131], v[152:155], v[60:63]
	v_mfma_f32_16x16x32_bf16 v[56:59], v[140:143], v[152:155], v[56:59]
	v_mfma_f32_16x16x32_bf16 v[52:55], v[128:131], v[160:163], v[52:55]
	v_mfma_f32_16x16x32_bf16 v[48:51], v[140:143], v[160:163], v[48:51]
	v_mfma_f32_16x16x32_bf16 v[44:47], v[128:131], v[168:171], v[44:47]
	v_mfma_f32_16x16x32_bf16 v[40:43], v[140:143], v[168:171], v[40:43]
	v_mfma_f32_16x16x32_bf16 v[36:39], v[128:131], v[176:179], v[36:39]
	v_mfma_f32_16x16x32_bf16 v[32:35], v[140:143], v[176:179], v[32:35]
	v_mfma_f32_16x16x32_bf16 v[60:63], v[132:135], v[156:159], v[60:63]
	v_mfma_f32_16x16x32_bf16 v[56:59], v[148:151], v[156:159], v[56:59]
	v_mfma_f32_16x16x32_bf16 v[52:55], v[132:135], v[164:167], v[52:55]
	v_mfma_f32_16x16x32_bf16 v[48:51], v[148:151], v[164:167], v[48:51]
	v_mfma_f32_16x16x32_bf16 v[44:47], v[132:135], v[172:175], v[44:47]
	v_mfma_f32_16x16x32_bf16 v[40:43], v[148:151], v[172:175], v[40:43]
	v_mfma_f32_16x16x32_bf16 v[36:39], v[132:135], v[180:183], v[36:39]
	v_mfma_f32_16x16x32_bf16 v[32:35], v[148:151], v[180:183], v[32:35]
	s_setprio 0
	s_setprio 1
	v_mfma_f32_16x16x32_bf16 v[28:31], v[144:147], v[152:155], v[28:31]
	v_mfma_f32_16x16x32_bf16 v[24:27], v[188:191], v[152:155], v[24:27]
	v_mfma_f32_16x16x32_bf16 v[20:23], v[144:147], v[160:163], v[20:23]
	v_mfma_f32_16x16x32_bf16 v[16:19], v[188:191], v[160:163], v[16:19]
	v_mfma_f32_16x16x32_bf16 v[12:15], v[144:147], v[168:171], v[12:15]
	v_mfma_f32_16x16x32_bf16 v[8:11], v[188:191], v[168:171], v[8:11]
	v_mfma_f32_16x16x32_bf16 v[4:7], v[144:147], v[176:179], v[4:7]
	v_mfma_f32_16x16x32_bf16 v[0:3], v[188:191], v[176:179], v[0:3]
	v_mfma_f32_16x16x32_bf16 v[28:31], v[184:187], v[156:159], v[28:31]
	v_mfma_f32_16x16x32_bf16 v[24:27], v[194:197], v[156:159], v[24:27]
	v_mfma_f32_16x16x32_bf16 v[20:23], v[184:187], v[164:167], v[20:23]
	v_mfma_f32_16x16x32_bf16 v[16:19], v[194:197], v[164:167], v[16:19]
	v_mfma_f32_16x16x32_bf16 v[12:15], v[184:187], v[172:175], v[12:15]
	v_mfma_f32_16x16x32_bf16 v[8:11], v[194:197], v[172:175], v[8:11]
	v_mfma_f32_16x16x32_bf16 v[4:7], v[184:187], v[180:183], v[4:7]
	v_mfma_f32_16x16x32_bf16 v[0:3], v[194:197], v[180:183], v[0:3]
	s_setprio 0
	s_barrier
	ds_read_b128 v[140:143], v138 offset:32768
	ds_read_b128 v[152:155], v138 offset:33792
	ds_read_b128 v[156:159], v138 offset:34816
	ds_read_b128 v[160:163], v138 offset:35840
	ds_read_b128 v[164:167], v137 offset:32768
	ds_read_b128 v[168:171], v137 offset:33792
	ds_read_b128 v[172:175], v137 offset:34816
	ds_read_b128 v[176:179], v137 offset:35840
	ds_read_b128 v[180:183], v137 offset:36864
	ds_read_b128 v[184:187], v137 offset:37888
	ds_read_b128 v[188:191], v137 offset:38912
	ds_read_b128 v[194:197], v137 offset:39936
	s_waitcnt vmcnt(2)
	s_barrier
; #define WAIT_V(n) asm volatile("s_waitcnt vmcnt(" #n ")" ::: "memory")
; #define WAIT_L(n) asm volatile("s_waitcnt lgkmcnt(" #n ")" ::: "memory")
; #define BAR __builtin_amdgcn_s_barrier()
; #define LDA(dst, b, h) _Pragma("unroll") for (int m = 0; m < 4; ++m) _Pragma("unroll") for (int k = 0; k < 2; ++k) \
;     dst[m][k] = *reinterpret_cast<const bf16x8*>((char*)shm + abase + (((b) * 2 + (h)) * 16384 + (m * 2 + k) * 1024))
; #define LDB(dst, b, h) _Pragma("unroll") for (int n = 0; n < 2; ++n) _Pragma("unroll") for (int k = 0; k < 2; ++k) \
;     dst[n][k] = *reinterpret_cast<const bf16x8*>((char*)shm + bbase + (((b) * 2 + (h)) * 16384 + (n * 2 + k) * 1024))
; template <bool SWAP>
; __device__ __forceinline__ void gemm_main(const u16* __restrict__ A, const u16* __restrict__ Bt, int brow, int bcol,
;                                           u16* shm, f32x4 (&acc)[2][2][4][2]) {
;     ...
;     LDA(At, 0, 1); WAIT_V(4); BAR; WAIT_L(0); MMA(1, 0, At, B0); MMA(1, 1, At, B1); BAR; }
;   { LDB(B0, 1, 0); LDA(At, 1, 0); WAIT_V(2); BAR; WAIT_L(0); MMA(0, 0, At, B0); BAR;
;     LDB(B1, 1, 1); WAIT_V(0); BAR; WAIT_L(0); MMA(0, 1, At, B1); BAR;
;     LDA(At, 1, 1); BAR; WAIT_L(0); MMA(1, 0, At, B0); MMA(1, 1, At, B1); BAR; }
;   if (wr == 0) BAR;
	s_waitcnt lgkmcnt(0)
	s_setprio 1
	s_waitcnt lgkmcnt(0)
	v_mfma_f32_16x16x32_bf16 v[124:127], v[140:143], v[164:167], v[124:127]
	v_mfma_f32_16x16x32_bf16 v[120:123], v[156:159], v[164:167], v[120:123]
	v_mfma_f32_16x16x32_bf16 v[116:119], v[140:143], v[172:175], v[116:119]
	v_mfma_f32_16x16x32_bf16 v[112:115], v[156:159], v[172:175], v[112:115]
	v_mfma_f32_16x16x32_bf16 v[108:111], v[140:143], v[180:183], v[108:111]
	v_mfma_f32_16x16x32_bf16 v[104:107], v[156:159], v[180:183], v[104:107]
	v_mfma_f32_16x16x32_bf16 v[100:103], v[140:143], v[188:191], v[100:103]
	v_mfma_f32_16x16x32_bf16 v[96:99], v[156:159], v[188:191], v[96:99]
	v_mfma_f32_16x16x32_bf16 v[148:151], v[152:155], v[168:171], v[124:127]
	v_mfma_f32_16x16x32_bf16 v[144:147], v[160:163], v[168:171], v[120:123]
	v_mfma_f32_16x16x32_bf16 v[132:135], v[152:155], v[176:179], v[116:119]
	v_mfma_f32_16x16x32_bf16 v[128:131], v[160:163], v[176:179], v[112:115]
	v_mfma_f32_16x16x32_bf16 v[116:119], v[152:155], v[184:187], v[108:111]
	v_mfma_f32_16x16x32_bf16 v[112:115], v[160:163], v[184:187], v[104:107]
	v_mfma_f32_16x16x32_bf16 v[100:103], v[152:155], v[194:197], v[100:103]
	v_mfma_f32_16x16x32_bf16 v[96:99], v[160:163], v[194:197], v[96:99]
	s_setprio 0
	s_barrier
	ds_read_b128 v[104:107], v138 offset:49152
	ds_read_b128 v[108:111], v138 offset:50176
	ds_read_b128 v[120:123], v138 offset:51200
	ds_read_b128 v[124:127], v138 offset:52224
	s_waitcnt vmcnt(0)
	s_barrier
	s_waitcnt lgkmcnt(0)
	s_setprio 1
	s_waitcnt lgkmcnt(0)
	v_mfma_f32_16x16x32_bf16 v[92:95], v[104:107], v[164:167], v[92:95]
	v_mfma_f32_16x16x32_bf16 v[88:91], v[120:123], v[164:167], v[88:91]
	v_mfma_f32_16x16x32_bf16 v[84:87], v[104:107], v[172:175], v[84:87]
	v_mfma_f32_16x16x32_bf16 v[80:83], v[120:123], v[172:175], v[80:83]
	v_mfma_f32_16x16x32_bf16 v[76:79], v[104:107], v[180:183], v[76:79]
	v_mfma_f32_16x16x32_bf16 v[72:75], v[120:123], v[180:183], v[72:75]
	v_mfma_f32_16x16x32_bf16 v[68:71], v[104:107], v[188:191], v[68:71]
	v_mfma_f32_16x16x32_bf16 v[64:67], v[120:123], v[188:191], v[64:67]
	v_mfma_f32_16x16x32_bf16 v[92:95], v[108:111], v[168:171], v[92:95]
	v_mfma_f32_16x16x32_bf16 v[88:91], v[124:127], v[168:171], v[88:91]
	v_mfma_f32_16x16x32_bf16 v[84:87], v[108:111], v[176:179], v[84:87]
	v_mfma_f32_16x16x32_bf16 v[80:83], v[124:127], v[176:179], v[80:83]
	v_mfma_f32_16x16x32_bf16 v[76:79], v[108:111], v[184:187], v[76:79]
	v_mfma_f32_16x16x32_bf16 v[72:75], v[124:127], v[184:187], v[72:75]
	v_mfma_f32_16x16x32_bf16 v[68:71], v[108:111], v[194:197], v[68:71]
	v_mfma_f32_16x16x32_bf16 v[64:67], v[124:127], v[194:197], v[64:67]
	s_setprio 0
	s_barrier
	ds_read_b128 v[164:167], v137 offset:49152
	ds_read_b128 v[168:171], v137 offset:50176
	ds_read_b128 v[172:175], v137 offset:51200
	ds_read_b128 v[176:179], v137 offset:52224
	ds_read_b128 v[180:183], v137 offset:53248
	ds_read_b128 v[184:187], v137 offset:54272
	ds_read_b128 v[188:191], v137 offset:55296
	ds_read_b128 v[194:197], v137 offset:56320
	s_barrier
	s_waitcnt lgkmcnt(0)
	s_setprio 1
	s_waitcnt lgkmcnt(0)
	v_mfma_f32_16x16x32_bf16 v[60:63], v[140:143], v[164:167], v[60:63]
	v_mfma_f32_16x16x32_bf16 v[56:59], v[156:159], v[164:167], v[56:59]
	v_mfma_f32_16x16x32_bf16 v[52:55], v[140:143], v[172:175], v[52:55]
	v_mfma_f32_16x16x32_bf16 v[48:51], v[156:159], v[172:175], v[48:51]
	v_mfma_f32_16x16x32_bf16 v[44:47], v[140:143], v[180:183], v[44:47]
	v_mfma_f32_16x16x32_bf16 v[40:43], v[156:159], v[180:183], v[40:43]
	v_mfma_f32_16x16x32_bf16 v[36:39], v[140:143], v[188:191], v[36:39]
	v_mfma_f32_16x16x32_bf16 v[32:35], v[156:159], v[188:191], v[32:35]
	v_mfma_f32_16x16x32_bf16 v[60:63], v[152:155], v[168:171], v[60:63]
	v_mfma_f32_16x16x32_bf16 v[56:59], v[160:163], v[168:171], v[56:59]
	v_mfma_f32_16x16x32_bf16 v[52:55], v[152:155], v[176:179], v[52:55]
	v_mfma_f32_16x16x32_bf16 v[48:51], v[160:163], v[176:179], v[48:51]
	v_mfma_f32_16x16x32_bf16 v[44:47], v[152:155], v[184:187], v[44:47]
	v_mfma_f32_16x16x32_bf16 v[40:43], v[160:163], v[184:187], v[40:43]
	v_mfma_f32_16x16x32_bf16 v[36:39], v[152:155], v[194:197], v[36:39]
	v_mfma_f32_16x16x32_bf16 v[32:35], v[160:163], v[194:197], v[32:35]
	s_setprio 0
	s_setprio 1
	v_mfma_f32_16x16x32_bf16 v[28:31], v[104:107], v[164:167], v[28:31]
	v_mfma_f32_16x16x32_bf16 v[24:27], v[120:123], v[164:167], v[24:27]
	v_mfma_f32_16x16x32_bf16 v[20:23], v[104:107], v[172:175], v[20:23]
	v_mfma_f32_16x16x32_bf16 v[16:19], v[120:123], v[172:175], v[16:19]
	v_mfma_f32_16x16x32_bf16 v[12:15], v[104:107], v[180:183], v[12:15]
	v_mfma_f32_16x16x32_bf16 v[8:11], v[120:123], v[180:183], v[8:11]
	v_mfma_f32_16x16x32_bf16 v[4:7], v[104:107], v[188:191], v[4:7]
	v_mfma_f32_16x16x32_bf16 v[0:3], v[120:123], v[188:191], v[0:3]
	v_mfma_f32_16x16x32_bf16 v[28:31], v[108:111], v[168:171], v[28:31]
	v_mfma_f32_16x16x32_bf16 v[24:27], v[124:127], v[168:171], v[24:27]
	v_mfma_f32_16x16x32_bf16 v[20:23], v[108:111], v[176:179], v[20:23]
	v_mfma_f32_16x16x32_bf16 v[16:19], v[124:127], v[176:179], v[16:19]
	v_mfma_f32_16x16x32_bf16 v[12:15], v[108:111], v[184:187], v[12:15]
	v_mfma_f32_16x16x32_bf16 v[8:11], v[124:127], v[184:187], v[8:11]
	v_mfma_f32_16x16x32_bf16 v[4:7], v[108:111], v[194:197], v[4:7]
	v_mfma_f32_16x16x32_bf16 v[0:3], v[124:127], v[194:197], v[0:3]
	s_setprio 0
	s_movk_i32 s3, 0x100
	v_cmp_gt_u32_e32 vcc, s3, v136
	s_barrier
	s_and_saveexec_b64 s[4:5], vcc
	s_cbranch_execz .LBB0_573
	s_barrier

; #define WAIT_V(n) asm volatile("s_waitcnt vmcnt(" #n ")" ::: "memory")
; #define WAIT_L(n) asm volatile("s_waitcnt lgkmcnt(" #n ")" ::: "memory")
; #define BAR __builtin_amdgcn_s_barrier()
; #define SCHED __builtin_amdgcn_sched_barrier(0)
; #define STAGE(P, BASE, br, kt) do { const char* _g = (const char*)((BASE) + (size_t)(br) * GK + (kt) * BK); \
;     __builtin_amdgcn_global_load_lds((const unsigned*)(_g + voff0), (unsigned*)((char*)(P) + tx * 16), 16, 0, 0); \
;     __builtin_amdgcn_global_load_lds((const unsigned*)(_g + voff1), (unsigned*)((char*)(P) + tx * 16 + 8192), 16, 0, 0); } while (0)
; #define LDA(dst, b, h) _Pragma("unroll") for (int m = 0; m < 4; ++m) _Pragma("unroll") for (int k = 0; k < 2; ++k) \
;     dst[m][k] = *reinterpret_cast<const bf16x8*>((char*)shm + abase + (((b) * 2 + (h)) * 16384 + (m * 2 + k) * 1024))
; #define LDB(dst, b, h) _Pragma("unroll") for (int n = 0; n < 2; ++n) _Pragma("unroll") for (int k = 0; k < 2; ++k) \
;     dst[n][k] = *reinterpret_cast<const bf16x8*>((char*)shm + bbase + (((b) * 2 + (h)) * 16384 + (n * 2 + k) * 1024))
; template <bool SWAP>
; __device__ __forceinline__ void gemm_main(const u16* __restrict__ A, const u16* __restrict__ Bt, int brow, int bcol,
;                                           u16* shm, f32x4 (&acc)[2][2][4][2]) {
;     ...
;     LDB(B0, 0, 0); SCHED; LDA(At, 0, 0); STAGE(SA(1, 1), A, brow + HALF, t + 1);
;     WAIT_L(8); BAR; WAIT_L(0); MMA(0, 0, At, B0); BAR; SCHED;
;     LDB(B1, 0, 1); STAGE(SB(0, 0), Bt, bcol, t + 2);
;     BAR; WAIT_L(0); MMA(0, 1, At, B1); BAR;
;     LDA(At, 0, 1); STAGE(SA(0, 0), A, brow, t + 2);
;     BAR; WAIT_L(0); MMA(1, 0, At, B0); BAR; SCHED;
;     STAGE(SB(0, 1), Bt, bcol + HALF, t + 2);
;     WAIT_V(6); BAR; MMA(1, 1, At, B1); BAR;
.LBB0_576:
	ds_read_b128 v[168:171], v137 offset:1024
	ds_read_b128 v[176:179], v137 offset:3072
	ds_read_b128 v[184:187], v137 offset:5120
	ds_read_b128 v[194:197], v137 offset:7168
	v_add_u32_e32 v192, 0, v140
	v_add_u32_e32 v146, 0xc000, v192
	v_add_u32_e32 v147, 0xe000, v192
	s_add_u32 m0, s3, 0xc000
	v_lshl_add_u64 v[232:233], s[4:5], 0, v[134:135]
	s_add_u32 vcc_lo, s4, s10
	s_addc_u32 vcc_hi, s5, s11
	global_load_lds_dwordx4 v132, vcc
	s_add_u32 m0, s3, 0xe000
	s_nop 0
	global_load_lds_dwordx4 v134, vcc
	s_waitcnt lgkmcnt(8)
	s_barrier
	s_waitcnt lgkmcnt(0)
	v_mfma_f32_16x16x32_bf16 v[124:127], v[148:151], v[164:167], v[124:127]
	v_mfma_f32_16x16x32_bf16 v[120:123], v[156:159], v[164:167], v[120:123]
	v_mfma_f32_16x16x32_bf16 v[116:119], v[148:151], v[172:175], v[116:119]
	v_mfma_f32_16x16x32_bf16 v[112:115], v[156:159], v[172:175], v[112:115]
	v_mfma_f32_16x16x32_bf16 v[108:111], v[148:151], v[180:183], v[108:111]
	v_mfma_f32_16x16x32_bf16 v[104:107], v[156:159], v[180:183], v[104:107]
	v_mfma_f32_16x16x32_bf16 v[100:103], v[148:151], v[188:191], v[100:103]
	v_mfma_f32_16x16x32_bf16 v[96:99], v[156:159], v[188:191], v[96:99]
	v_mfma_f32_16x16x32_bf16 v[124:127], v[152:155], v[168:171], v[124:127]
	v_mfma_f32_16x16x32_bf16 v[120:123], v[160:163], v[168:171], v[120:123]
	v_mfma_f32_16x16x32_bf16 v[116:119], v[152:155], v[176:179], v[116:119]
	v_mfma_f32_16x16x32_bf16 v[112:115], v[160:163], v[176:179], v[112:115]
	v_mfma_f32_16x16x32_bf16 v[108:111], v[152:155], v[184:187], v[108:111]
	v_mfma_f32_16x16x32_bf16 v[104:107], v[160:163], v[184:187], v[104:107]
	v_mfma_f32_16x16x32_bf16 v[100:103], v[152:155], v[194:197], v[100:103]
	v_mfma_f32_16x16x32_bf16 v[96:99], v[160:163], v[194:197], v[96:99]
	s_barrier
	ds_read_b128 v[198:201], v138 offset:16384
	ds_read_b128 v[202:205], v138 offset:17408
	ds_read_b128 v[206:209], v138 offset:18432
	ds_read_b128 v[226:229], v138 offset:19456
	v_lshl_add_u64 v[234:235], s[4:5], 0, v[128:129]
	s_add_u32 m0, s3, s28
	s_nop 0
	s_add_u32 vcc_lo, s4, s12
	s_addc_u32 vcc_hi, s5, s13
	global_load_lds_dwordx4 v128, vcc
	v_lshl_add_u64 v[236:237], s[4:5], 0, v[130:131]
	s_add_u32 m0, s3, s28
	s_add_u32 m0, m0, 0x2000
	s_nop 0
	global_load_lds_dwordx4 v130, vcc
	s_barrier
	s_waitcnt lgkmcnt(0)
	v_mfma_f32_16x16x32_bf16 v[92:95], v[198:201], v[164:167], v[92:95]
	v_mfma_f32_16x16x32_bf16 v[88:91], v[206:209], v[164:167], v[88:91]
	v_mfma_f32_16x16x32_bf16 v[84:87], v[198:201], v[172:175], v[84:87]
	v_mfma_f32_16x16x32_bf16 v[80:83], v[206:209], v[172:175], v[80:83]
	v_mfma_f32_16x16x32_bf16 v[76:79], v[198:201], v[180:183], v[76:79]
	v_mfma_f32_16x16x32_bf16 v[72:75], v[206:209], v[180:183], v[72:75]
	v_mfma_f32_16x16x32_bf16 v[68:71], v[198:201], v[188:191], v[68:71]
	v_mfma_f32_16x16x32_bf16 v[64:67], v[206:209], v[188:191], v[64:67]
	v_mfma_f32_16x16x32_bf16 v[92:95], v[202:205], v[168:171], v[92:95]
	ds_read_b128 v[164:167], v137 offset:16384
	v_mfma_f32_16x16x32_bf16 v[88:91], v[226:229], v[168:171], v[88:91]
	v_mfma_f32_16x16x32_bf16 v[84:87], v[202:205], v[176:179], v[84:87]
	ds_read_b128 v[172:175], v137 offset:18432
	v_mfma_f32_16x16x32_bf16 v[80:83], v[226:229], v[176:179], v[80:83]
	v_mfma_f32_16x16x32_bf16 v[76:79], v[202:205], v[184:187], v[76:79]
	ds_read_b128 v[180:183], v137 offset:20480
	v_mfma_f32_16x16x32_bf16 v[72:75], v[226:229], v[184:187], v[72:75]
	v_mfma_f32_16x16x32_bf16 v[68:71], v[202:205], v[194:197], v[68:71]
	ds_read_b128 v[188:191], v137 offset:22528
	v_mfma_f32_16x16x32_bf16 v[64:67], v[226:229], v[194:197], v[64:67]
	s_barrier
	ds_read_b128 v[168:171], v137 offset:17408
	ds_read_b128 v[176:179], v137 offset:19456
	ds_read_b128 v[184:187], v137 offset:21504
	ds_read_b128 v[194:197], v137 offset:23552
	s_add_u32 m0, s3, 0x0
	s_nop 0
	s_add_u32 vcc_lo, s4, s14
	s_addc_u32 vcc_hi, s5, s15
	global_load_lds_dwordx4 v132, vcc
	s_add_u32 m0, s3, 0x2000
	s_nop 0
	global_load_lds_dwordx4 v134, vcc
	s_waitcnt vmcnt(8)
	s_barrier
	s_waitcnt lgkmcnt(0)
	v_mfma_f32_16x16x32_bf16 v[60:63], v[148:151], v[164:167], v[60:63]
	v_mfma_f32_16x16x32_bf16 v[56:59], v[156:159], v[164:167], v[56:59]
	v_mfma_f32_16x16x32_bf16 v[52:55], v[148:151], v[172:175], v[52:55]
	v_mfma_f32_16x16x32_bf16 v[48:51], v[156:159], v[172:175], v[48:51]
	v_mfma_f32_16x16x32_bf16 v[44:47], v[148:151], v[180:183], v[44:47]
	v_mfma_f32_16x16x32_bf16 v[40:43], v[156:159], v[180:183], v[40:43]
	v_mfma_f32_16x16x32_bf16 v[36:39], v[148:151], v[188:191], v[36:39]
	v_mfma_f32_16x16x32_bf16 v[32:35], v[156:159], v[188:191], v[32:35]
	v_mfma_f32_16x16x32_bf16 v[60:63], v[152:155], v[168:171], v[60:63]
	v_mfma_f32_16x16x32_bf16 v[56:59], v[160:163], v[168:171], v[56:59]
	v_mfma_f32_16x16x32_bf16 v[52:55], v[152:155], v[176:179], v[52:55]
	v_mfma_f32_16x16x32_bf16 v[48:51], v[160:163], v[176:179], v[48:51]
	v_mfma_f32_16x16x32_bf16 v[44:47], v[152:155], v[184:187], v[44:47]
	v_mfma_f32_16x16x32_bf16 v[40:43], v[160:163], v[184:187], v[40:43]
	v_mfma_f32_16x16x32_bf16 v[36:39], v[152:155], v[194:197], v[36:39]
	v_mfma_f32_16x16x32_bf16 v[32:35], v[160:163], v[194:197], v[32:35]
	s_barrier
	ds_read_b128 v[148:151], v138 offset:32768
	ds_read_b128 v[152:155], v138 offset:33792
	ds_read_b128 v[156:159], v138 offset:34816
	ds_read_b128 v[160:163], v138 offset:35840
	s_add_u32 m0, s3, s29
	s_nop 0
	s_add_u32 vcc_lo, s4, s80
	s_addc_u32 vcc_hi, s5, s81
	global_load_lds_dwordx4 v128, vcc
	s_add_u32 m0, s3, s29
	s_add_u32 m0, m0, 0x2000
	s_nop 0
	global_load_lds_dwordx4 v130, vcc
	s_waitcnt vmcnt(6)
	s_barrier
; #define WAIT_V(n) asm volatile("s_waitcnt vmcnt(" #n ")" ::: "memory")
; #define WAIT_L(n) asm volatile("s_waitcnt lgkmcnt(" #n ")" ::: "memory")
; #define BAR __builtin_amdgcn_s_barrier()
; #define SCHED __builtin_amdgcn_sched_barrier(0)
; #define STAGE(P, BASE, br, kt) do { const char* _g = (const char*)((BASE) + (size_t)(br) * GK + (kt) * BK); \
;     __builtin_amdgcn_global_load_lds((const unsigned*)(_g + voff0), (unsigned*)((char*)(P) + tx * 16), 16, 0, 0); \
;     __builtin_amdgcn_global_load_lds((const unsigned*)(_g + voff1), (unsigned*)((char*)(P) + tx * 16 + 8192), 16, 0, 0); } while (0)
; #define LDA(dst, b, h) _Pragma("unroll") for (int m = 0; m < 4; ++m) _Pragma("unroll") for (int k = 0; k < 2; ++k) \
;     dst[m][k] = *reinterpret_cast<const bf16x8*>((char*)shm + abase + (((b) * 2 + (h)) * 16384 + (m * 2 + k) * 1024))
; #define LDB(dst, b, h) _Pragma("unroll") for (int n = 0; n < 2; ++n) _Pragma("unroll") for (int k = 0; k < 2; ++k) \
;     dst[n][k] = *reinterpret_cast<const bf16x8*>((char*)shm + bbase + (((b) * 2 + (h)) * 16384 + (n * 2 + k) * 1024))
; template <bool SWAP>
; __device__ __forceinline__ void gemm_main(const u16* __restrict__ A, const u16* __restrict__ Bt, int brow, int bcol,
;                                           u16* shm, f32x4 (&acc)[2][2][4][2]) {
;     ...
;     WAIT_V(6); BAR; MMA(1, 1, At, B1); BAR;
;     LDB(B0, 1, 0); SCHED; LDA(At, 1, 0); STAGE(SA(0, 1), A, brow + HALF, t + 2);
;     WAIT_L(8); BAR; WAIT_L(0); MMA(0, 0, At, B0); BAR; SCHED;
;     LDB(B1, 1, 1); STAGE(SB(1, 0), Bt, bcol, t + 3);
;     BAR; WAIT_L(0); MMA(0, 1, At, B1); BAR;
;     LDA(At, 1, 1); STAGE(SA(1, 0), A, brow, t + 3);
;     BAR; WAIT_L(0); MMA(1, 0, At, B0); BAR; SCHED;
	v_mfma_f32_16x16x32_bf16 v[28:31], v[198:201], v[164:167], v[28:31]
	v_mfma_f32_16x16x32_bf16 v[24:27], v[206:209], v[164:167], v[24:27]
	v_mfma_f32_16x16x32_bf16 v[20:23], v[198:201], v[172:175], v[20:23]
	v_mfma_f32_16x16x32_bf16 v[16:19], v[206:209], v[172:175], v[16:19]
	v_mfma_f32_16x16x32_bf16 v[12:15], v[198:201], v[180:183], v[12:15]
	v_mfma_f32_16x16x32_bf16 v[8:11], v[206:209], v[180:183], v[8:11]
	v_mfma_f32_16x16x32_bf16 v[4:7], v[198:201], v[188:191], v[4:7]
	v_mfma_f32_16x16x32_bf16 v[0:3], v[206:209], v[188:191], v[0:3]
	v_mfma_f32_16x16x32_bf16 v[28:31], v[202:205], v[168:171], v[28:31]
	ds_read_b128 v[164:167], v137 offset:32768
	v_mfma_f32_16x16x32_bf16 v[24:27], v[226:229], v[168:171], v[24:27]
	v_mfma_f32_16x16x32_bf16 v[20:23], v[202:205], v[176:179], v[20:23]
	ds_read_b128 v[172:175], v137 offset:34816
	v_mfma_f32_16x16x32_bf16 v[16:19], v[226:229], v[176:179], v[16:19]
	v_mfma_f32_16x16x32_bf16 v[12:15], v[202:205], v[184:187], v[12:15]
	ds_read_b128 v[180:183], v137 offset:36864
	v_mfma_f32_16x16x32_bf16 v[8:11], v[226:229], v[184:187], v[8:11]
	v_mfma_f32_16x16x32_bf16 v[4:7], v[202:205], v[194:197], v[4:7]
	ds_read_b128 v[188:191], v137 offset:38912
	v_mfma_f32_16x16x32_bf16 v[0:3], v[226:229], v[194:197], v[0:3]
	s_barrier
	ds_read_b128 v[168:171], v137 offset:33792
	ds_read_b128 v[176:179], v137 offset:35840
	ds_read_b128 v[184:187], v137 offset:37888
	ds_read_b128 v[194:197], v137 offset:39936
	s_add_u32 m0, s3, 0x4000
	s_nop 0
	s_add_u32 vcc_lo, s4, s66
	s_addc_u32 vcc_hi, s5, s67
	global_load_lds_dwordx4 v132, vcc
	s_add_u32 m0, s3, 0x6000
	s_nop 0
	global_load_lds_dwordx4 v134, vcc
	s_waitcnt lgkmcnt(8)
	s_barrier
	s_waitcnt lgkmcnt(0)
	v_mfma_f32_16x16x32_bf16 v[124:127], v[148:151], v[164:167], v[124:127]
	v_mfma_f32_16x16x32_bf16 v[120:123], v[156:159], v[164:167], v[120:123]
	v_mfma_f32_16x16x32_bf16 v[116:119], v[148:151], v[172:175], v[116:119]
	v_mfma_f32_16x16x32_bf16 v[112:115], v[156:159], v[172:175], v[112:115]
	v_mfma_f32_16x16x32_bf16 v[108:111], v[148:151], v[180:183], v[108:111]
	v_mfma_f32_16x16x32_bf16 v[104:107], v[156:159], v[180:183], v[104:107]
	v_mfma_f32_16x16x32_bf16 v[100:103], v[148:151], v[188:191], v[100:103]
	v_mfma_f32_16x16x32_bf16 v[96:99], v[156:159], v[188:191], v[96:99]
	v_mfma_f32_16x16x32_bf16 v[124:127], v[152:155], v[168:171], v[124:127]
	v_mfma_f32_16x16x32_bf16 v[120:123], v[160:163], v[168:171], v[120:123]
	v_mfma_f32_16x16x32_bf16 v[116:119], v[152:155], v[176:179], v[116:119]
	v_mfma_f32_16x16x32_bf16 v[112:115], v[160:163], v[176:179], v[112:115]
	v_mfma_f32_16x16x32_bf16 v[108:111], v[152:155], v[184:187], v[108:111]
	v_mfma_f32_16x16x32_bf16 v[104:107], v[160:163], v[184:187], v[104:107]
	v_mfma_f32_16x16x32_bf16 v[100:103], v[152:155], v[194:197], v[100:103]
	v_mfma_f32_16x16x32_bf16 v[96:99], v[160:163], v[194:197], v[96:99]
	s_barrier
	ds_read_b128 v[198:201], v138 offset:49152
	ds_read_b128 v[202:205], v138 offset:50176
	ds_read_b128 v[206:209], v138 offset:51200
	ds_read_b128 v[226:229], v138 offset:52224
	s_add_u32 m0, s3, s30
	s_nop 0
	s_add_u32 vcc_lo, s4, s86
	s_addc_u32 vcc_hi, s5, s87
	global_load_lds_dwordx4 v128, vcc
	v_lshl_add_u64 v[238:239], v[236:237], 0, s[86:87]
	s_add_u32 m0, s3, s30
	s_add_u32 m0, m0, 0x2000
	s_nop 0
	global_load_lds_dwordx4 v130, vcc
	s_barrier
	s_waitcnt lgkmcnt(0)
	v_mfma_f32_16x16x32_bf16 v[92:95], v[198:201], v[164:167], v[92:95]
	v_mfma_f32_16x16x32_bf16 v[88:91], v[206:209], v[164:167], v[88:91]
	v_mfma_f32_16x16x32_bf16 v[84:87], v[198:201], v[172:175], v[84:87]
	v_mfma_f32_16x16x32_bf16 v[80:83], v[206:209], v[172:175], v[80:83]
	v_mfma_f32_16x16x32_bf16 v[76:79], v[198:201], v[180:183], v[76:79]
	v_mfma_f32_16x16x32_bf16 v[72:75], v[206:209], v[180:183], v[72:75]
	v_mfma_f32_16x16x32_bf16 v[68:71], v[198:201], v[188:191], v[68:71]
	v_mfma_f32_16x16x32_bf16 v[64:67], v[206:209], v[188:191], v[64:67]
	v_mfma_f32_16x16x32_bf16 v[92:95], v[202:205], v[168:171], v[92:95]
	ds_read_b128 v[164:167], v137 offset:49152
	v_mfma_f32_16x16x32_bf16 v[88:91], v[226:229], v[168:171], v[88:91]
	v_mfma_f32_16x16x32_bf16 v[84:87], v[202:205], v[176:179], v[84:87]
	ds_read_b128 v[172:175], v137 offset:51200
	v_mfma_f32_16x16x32_bf16 v[80:83], v[226:229], v[176:179], v[80:83]
	v_mfma_f32_16x16x32_bf16 v[76:79], v[202:205], v[184:187], v[76:79]
	ds_read_b128 v[180:183], v137 offset:53248
	v_mfma_f32_16x16x32_bf16 v[72:75], v[226:229], v[184:187], v[72:75]
	v_mfma_f32_16x16x32_bf16 v[68:71], v[202:205], v[194:197], v[68:71]
	ds_read_b128 v[188:191], v137 offset:55296
	v_mfma_f32_16x16x32_bf16 v[64:67], v[226:229], v[194:197], v[64:67]
	s_barrier
	ds_read_b128 v[168:171], v137 offset:50176
	ds_read_b128 v[176:179], v137 offset:52224
	ds_read_b128 v[184:187], v137 offset:54272
	ds_read_b128 v[194:197], v137 offset:56320
	v_add_u32_e32 v225, 0x8000, v192
	s_add_u32 m0, s3, 0x8000
	s_nop 0
	s_add_u32 vcc_lo, s4, s26
	s_addc_u32 vcc_hi, s5, s27
	global_load_lds_dwordx4 v132, vcc
	v_lshl_add_u64 v[230:231], v[232:233], 0, s[26:27]
	s_add_u32 m0, s3, 0xa000
	s_nop 0
	global_load_lds_dwordx4 v134, vcc
	s_waitcnt vmcnt(8)
	s_barrier
; #define WAIT_V(n) asm volatile("s_waitcnt vmcnt(" #n ")" ::: "memory")
; #define WAIT_L(n) asm volatile("s_waitcnt lgkmcnt(" #n ")" ::: "memory")
; #define BAR __builtin_amdgcn_s_barrier()
; #define SCHED __builtin_amdgcn_sched_barrier(0)
; #define STAGE(P, BASE, br, kt) do { const char* _g = (const char*)((BASE) + (size_t)(br) * GK + (kt) * BK); \
;     __builtin_amdgcn_global_load_lds((const unsigned*)(_g + voff0), (unsigned*)((char*)(P) + tx * 16), 16, 0, 0); \
;     __builtin_amdgcn_global_load_lds((const unsigned*)(_g + voff1), (unsigned*)((char*)(P) + tx * 16 + 8192), 16, 0, 0); } while (0)
; #define LDA(dst, b, h) _Pragma("unroll") for (int m = 0; m < 4; ++m) _Pragma("unroll") for (int k = 0; k < 2; ++k) \
;     dst[m][k] = *reinterpret_cast<const bf16x8*>((char*)shm + abase + (((b) * 2 + (h)) * 16384 + (m * 2 + k) * 1024))
; #define LDB(dst, b, h) _Pragma("unroll") for (int n = 0; n < 2; ++n) _Pragma("unroll") for (int k = 0; k < 2; ++k) \
;     dst[n][k] = *reinterpret_cast<const bf16x8*>((char*)shm + bbase + (((b) * 2 + (h)) * 16384 + (n * 2 + k) * 1024))
; template <bool SWAP>
; __device__ __forceinline__ void gemm_main(const u16* __restrict__ A, const u16* __restrict__ Bt, int brow, int bcol,
;                                           u16* shm, f32x4 (&acc)[2][2][4][2]) {
;     ...
;     LDA(At, 1, 1); STAGE(SA(1, 0), A, brow, t + 3);
;     BAR; WAIT_L(0); MMA(1, 0, At, B0); BAR; SCHED;
;     STAGE(SB(1, 1), Bt, bcol + HALF, t + 3);
;     WAIT_V(6); BAR; MMA(1, 1, At, B1); BAR;
;   }
;   { LDB(B0, 0, 0); LDA(At, 0, 0); STAGE(SA(1, 1), A, brow + HALF, nt - 1);
;     BAR; WAIT_L(0); MMA(0, 0, At, B0); BAR;
	s_waitcnt lgkmcnt(0)
	v_mfma_f32_16x16x32_bf16 v[60:63], v[148:151], v[164:167], v[60:63]
	v_mfma_f32_16x16x32_bf16 v[56:59], v[156:159], v[164:167], v[56:59]
	v_mfma_f32_16x16x32_bf16 v[52:55], v[148:151], v[172:175], v[52:55]
	v_mfma_f32_16x16x32_bf16 v[48:51], v[156:159], v[172:175], v[48:51]
	v_mfma_f32_16x16x32_bf16 v[44:47], v[148:151], v[180:183], v[44:47]
	v_mfma_f32_16x16x32_bf16 v[40:43], v[156:159], v[180:183], v[40:43]
	v_mfma_f32_16x16x32_bf16 v[36:39], v[148:151], v[188:191], v[36:39]
	v_mfma_f32_16x16x32_bf16 v[32:35], v[156:159], v[188:191], v[32:35]
	v_mfma_f32_16x16x32_bf16 v[60:63], v[152:155], v[168:171], v[60:63]
	v_mfma_f32_16x16x32_bf16 v[56:59], v[160:163], v[168:171], v[56:59]
	v_mfma_f32_16x16x32_bf16 v[52:55], v[152:155], v[176:179], v[52:55]
	v_mfma_f32_16x16x32_bf16 v[48:51], v[160:163], v[176:179], v[48:51]
	v_mfma_f32_16x16x32_bf16 v[44:47], v[152:155], v[184:187], v[44:47]
	v_mfma_f32_16x16x32_bf16 v[40:43], v[160:163], v[184:187], v[40:43]
	v_mfma_f32_16x16x32_bf16 v[36:39], v[152:155], v[194:197], v[36:39]
	v_mfma_f32_16x16x32_bf16 v[32:35], v[160:163], v[194:197], v[32:35]
	s_barrier
	ds_read_b128 v[148:151], v138
	ds_read_b128 v[152:155], v138 offset:1024
	ds_read_b128 v[156:159], v138 offset:2048
	ds_read_b128 v[160:163], v138 offset:3072
	s_add_u32 m0, s3, s31
	s_nop 0
	s_add_u32 vcc_lo, s4, s56
	s_addc_u32 vcc_hi, s5, s57
	global_load_lds_dwordx4 v128, vcc
	v_lshl_add_u64 v[254:255], v[236:237], 0, s[56:57]
	s_add_u32 m0, s3, s31
	s_add_u32 m0, m0, 0x2000
	s_nop 0
	global_load_lds_dwordx4 v130, vcc
	s_waitcnt vmcnt(6)
	s_barrier
	v_mfma_f32_16x16x32_bf16 v[28:31], v[198:201], v[164:167], v[28:31]
	v_mfma_f32_16x16x32_bf16 v[24:27], v[206:209], v[164:167], v[24:27]
	v_mfma_f32_16x16x32_bf16 v[20:23], v[198:201], v[172:175], v[20:23]
	v_mfma_f32_16x16x32_bf16 v[16:19], v[206:209], v[172:175], v[16:19]
	v_mfma_f32_16x16x32_bf16 v[12:15], v[198:201], v[180:183], v[12:15]
	v_mfma_f32_16x16x32_bf16 v[8:11], v[206:209], v[180:183], v[8:11]
	v_mfma_f32_16x16x32_bf16 v[4:7], v[198:201], v[188:191], v[4:7]
	v_mfma_f32_16x16x32_bf16 v[0:3], v[206:209], v[188:191], v[0:3]
	v_mfma_f32_16x16x32_bf16 v[28:31], v[202:205], v[168:171], v[28:31]
	ds_read_b128 v[164:167], v137
	v_mfma_f32_16x16x32_bf16 v[24:27], v[226:229], v[168:171], v[24:27]
	v_mfma_f32_16x16x32_bf16 v[20:23], v[202:205], v[176:179], v[20:23]
	ds_read_b128 v[172:175], v137 offset:2048
	v_mfma_f32_16x16x32_bf16 v[16:19], v[226:229], v[176:179], v[16:19]
	v_mfma_f32_16x16x32_bf16 v[12:15], v[202:205], v[184:187], v[12:15]
	ds_read_b128 v[180:183], v137 offset:4096
	v_mfma_f32_16x16x32_bf16 v[8:11], v[226:229], v[184:187], v[8:11]
	v_mfma_f32_16x16x32_bf16 v[4:7], v[202:205], v[194:197], v[4:7]
	ds_read_b128 v[188:191], v137 offset:6144
	v_mfma_f32_16x16x32_bf16 v[0:3], v[226:229], v[194:197], v[0:3]
	s_add_i32 s2, s2, 2
	s_add_u32 s4, s4, 0x100
	s_addc_u32 s5, s5, 0
	s_cmp_lt_u32 s2, 28
	s_barrier
	s_cbranch_scc1 .LBB0_576
	v_lshlrev_b32_e32 v128, 3, v139
	v_lshlrev_b32_e32 v129, 5, v139
	v_and_b32_e32 v128, 0xffff0, v128
	v_and_b32_e32 v129, 32, v129
	v_add_u32_e32 v129, v129, v142
	v_add_lshl_u32 v128, v141, v128, 12
	v_lshl_add_u32 v192, v129, 1, v128
	v_lshlrev_b32_e32 v128, 3, v143
	v_lshlrev_b32_e32 v129, 5, v143
	v_and_b32_e32 v128, 0xffff0, v128
	v_and_b32_e32 v129, 32, v129
	v_add_u32_e32 v129, v129, v145
	v_add_lshl_u32 v128, v144, v128, 12
	v_lshl_add_u32 v144, v129, 1, v128
	v_mov_b32_e32 v145, v193
	v_lshl_add_u64 v[184:185], s[0:1], 0, v[192:193]
	s_mov_b64 s[4:5], 0xf80
	v_readfirstlane_b32 s2, v146
	v_lshl_add_u64 v[184:185], v[184:185], 0, s[4:5]
	s_mov_b32 m0, s2
	v_lshl_add_u64 v[144:145], s[0:1], 0, v[144:145]
	v_readfirstlane_b32 s0, v147
	ds_read_b128 v[128:131], v138
	ds_read_b128 v[132:135], v138 offset:1024
	ds_read_b128 v[140:143], v138 offset:2048
	ds_read_b128 v[148:151], v138 offset:3072
	ds_read_b128 v[152:155], v137
	ds_read_b128 v[156:159], v137 offset:1024
	ds_read_b128 v[160:163], v137 offset:2048
	ds_read_b128 v[164:167], v137 offset:3072
	ds_read_b128 v[168:171], v137 offset:4096
	ds_read_b128 v[172:175], v137 offset:5120
	ds_read_b128 v[176:179], v137 offset:6144
	ds_read_b128 v[180:183], v137 offset:7168
	global_load_lds_dwordx4 v[184:185], off
	v_lshl_add_u64 v[144:145], v[144:145], 0, s[4:5]
	s_mov_b32 m0, s0
	s_nop 0
	global_load_lds_dwordx4 v[144:145], off
	s_barrier
	s_waitcnt lgkmcnt(0)
	s_setprio 1
	s_waitcnt lgkmcnt(0)
	v_mfma_f32_16x16x32_bf16 v[124:127], v[128:131], v[152:155], v[124:127]
	v_mfma_f32_16x16x32_bf16 v[120:123], v[140:143], v[152:155], v[120:123]
	v_mfma_f32_16x16x32_bf16 v[116:119], v[128:131], v[160:163], v[116:119]
	v_mfma_f32_16x16x32_bf16 v[112:115], v[140:143], v[160:163], v[112:115]
	v_mfma_f32_16x16x32_bf16 v[108:111], v[128:131], v[168:171], v[108:111]
	v_mfma_f32_16x16x32_bf16 v[104:107], v[140:143], v[168:171], v[104:107]
	v_mfma_f32_16x16x32_bf16 v[100:103], v[128:131], v[176:179], v[100:103]
	v_mfma_f32_16x16x32_bf16 v[96:99], v[140:143], v[176:179], v[96:99]
	v_mfma_f32_16x16x32_bf16 v[124:127], v[132:135], v[156:159], v[124:127]
	v_mfma_f32_16x16x32_bf16 v[120:123], v[148:151], v[156:159], v[120:123]
	v_mfma_f32_16x16x32_bf16 v[116:119], v[132:135], v[164:167], v[116:119]
	v_mfma_f32_16x16x32_bf16 v[112:115], v[148:151], v[164:167], v[112:115]
	v_mfma_f32_16x16x32_bf16 v[108:111], v[132:135], v[172:175], v[108:111]
	v_mfma_f32_16x16x32_bf16 v[104:107], v[148:151], v[172:175], v[104:107]
	v_mfma_f32_16x16x32_bf16 v[100:103], v[132:135], v[180:183], v[100:103]
	v_mfma_f32_16x16x32_bf16 v[96:99], v[148:151], v[180:183], v[96:99]
	s_setprio 0
	s_barrier
; #define WAIT_V(n) asm volatile("s_waitcnt vmcnt(" #n ")" ::: "memory")
; #define WAIT_L(n) asm volatile("s_waitcnt lgkmcnt(" #n ")" ::: "memory")
; #define BAR __builtin_amdgcn_s_barrier()
; #define LDA(dst, b, h) _Pragma("unroll") for (int m = 0; m < 4; ++m) _Pragma("unroll") for (int k = 0; k < 2; ++k) \
;     dst[m][k] = *reinterpret_cast<const bf16x8*>((char*)shm + abase + (((b) * 2 + (h)) * 16384 + (m * 2 + k) * 1024))
; #define LDB(dst, b, h) _Pragma("unroll") for (int n = 0; n < 2; ++n) _Pragma("unroll") for (int k = 0; k < 2; ++k) \
;     dst[n][k] = *reinterpret_cast<const bf16x8*>((char*)shm + bbase + (((b) * 2 + (h)) * 16384 + (n * 2 + k) * 1024))
; template <bool SWAP>
; __device__ __forceinline__ void gemm_main(const u16* __restrict__ A, const u16* __restrict__ Bt, int brow, int bcol,
;                                           u16* shm, f32x4 (&acc)[2][2][4][2]) {
;     ...
;     BAR; WAIT_L(0); MMA(0, 0, At, B0); BAR;
;     LDB(B1, 0, 1); BAR; WAIT_L(0); MMA(0, 1, At, B1); BAR;
;     LDA(At, 0, 1); WAIT_V(4); BAR; WAIT_L(0); MMA(1, 0, At, B0); MMA(1, 1, At, B1); BAR; }
;   { LDB(B0, 1, 0); LDA(At, 1, 0); WAIT_V(2); BAR; WAIT_L(0); MMA(0, 0, At, B0); BAR;
;     LDB(B1, 1, 1); WAIT_V(0); BAR; WAIT_L(0); MMA(0, 1, At, B1); BAR;
	ds_read_b128 v[144:147], v138 offset:16384
	ds_read_b128 v[184:187], v138 offset:17408
	ds_read_b128 v[188:191], v138 offset:18432
	ds_read_b128 v[194:197], v138 offset:19456
	s_barrier
	s_waitcnt lgkmcnt(0)
	s_setprio 1
	s_waitcnt lgkmcnt(0)
	v_mfma_f32_16x16x32_bf16 v[92:95], v[144:147], v[152:155], v[92:95]
	v_mfma_f32_16x16x32_bf16 v[88:91], v[188:191], v[152:155], v[88:91]
	v_mfma_f32_16x16x32_bf16 v[84:87], v[144:147], v[160:163], v[84:87]
	v_mfma_f32_16x16x32_bf16 v[80:83], v[188:191], v[160:163], v[80:83]
	v_mfma_f32_16x16x32_bf16 v[76:79], v[144:147], v[168:171], v[76:79]
	v_mfma_f32_16x16x32_bf16 v[72:75], v[188:191], v[168:171], v[72:75]
	v_mfma_f32_16x16x32_bf16 v[68:71], v[144:147], v[176:179], v[68:71]
	v_mfma_f32_16x16x32_bf16 v[64:67], v[188:191], v[176:179], v[64:67]
	v_mfma_f32_16x16x32_bf16 v[92:95], v[184:187], v[156:159], v[92:95]
	v_mfma_f32_16x16x32_bf16 v[88:91], v[194:197], v[156:159], v[88:91]
	v_mfma_f32_16x16x32_bf16 v[84:87], v[184:187], v[164:167], v[84:87]
	v_mfma_f32_16x16x32_bf16 v[80:83], v[194:197], v[164:167], v[80:83]
	v_mfma_f32_16x16x32_bf16 v[76:79], v[184:187], v[172:175], v[76:79]
	v_mfma_f32_16x16x32_bf16 v[72:75], v[194:197], v[172:175], v[72:75]
	v_mfma_f32_16x16x32_bf16 v[68:71], v[184:187], v[180:183], v[68:71]
	v_mfma_f32_16x16x32_bf16 v[64:67], v[194:197], v[180:183], v[64:67]
	s_setprio 0
	s_barrier
	ds_read_b128 v[152:155], v137 offset:16384
	ds_read_b128 v[156:159], v137 offset:17408
	ds_read_b128 v[160:163], v137 offset:18432
	ds_read_b128 v[164:167], v137 offset:19456
	ds_read_b128 v[168:171], v137 offset:20480
	ds_read_b128 v[172:175], v137 offset:21504
	ds_read_b128 v[176:179], v137 offset:22528
	ds_read_b128 v[180:183], v137 offset:23552
	s_waitcnt vmcnt(4)
	s_barrier
	s_waitcnt lgkmcnt(0)
	s_setprio 1
	s_waitcnt lgkmcnt(0)
	v_mfma_f32_16x16x32_bf16 v[60:63], v[128:131], v[152:155], v[60:63]
	v_mfma_f32_16x16x32_bf16 v[56:59], v[140:143], v[152:155], v[56:59]
	v_mfma_f32_16x16x32_bf16 v[52:55], v[128:131], v[160:163], v[52:55]
	v_mfma_f32_16x16x32_bf16 v[48:51], v[140:143], v[160:163], v[48:51]
	v_mfma_f32_16x16x32_bf16 v[44:47], v[128:131], v[168:171], v[44:47]
	v_mfma_f32_16x16x32_bf16 v[40:43], v[140:143], v[168:171], v[40:43]
	v_mfma_f32_16x16x32_bf16 v[36:39], v[128:131], v[176:179], v[36:39]
	v_mfma_f32_16x16x32_bf16 v[32:35], v[140:143], v[176:179], v[32:35]
	v_mfma_f32_16x16x32_bf16 v[60:63], v[132:135], v[156:159], v[60:63]
	v_mfma_f32_16x16x32_bf16 v[56:59], v[148:151], v[156:159], v[56:59]
	v_mfma_f32_16x16x32_bf16 v[52:55], v[132:135], v[164:167], v[52:55]
	v_mfma_f32_16x16x32_bf16 v[48:51], v[148:151], v[164:167], v[48:51]
	v_mfma_f32_16x16x32_bf16 v[44:47], v[132:135], v[172:175], v[44:47]
	v_mfma_f32_16x16x32_bf16 v[40:43], v[148:151], v[172:175], v[40:43]
	v_mfma_f32_16x16x32_bf16 v[36:39], v[132:135], v[180:183], v[36:39]
	v_mfma_f32_16x16x32_bf16 v[32:35], v[148:151], v[180:183], v[32:35]
	s_setprio 0
	s_setprio 1
	v_mfma_f32_16x16x32_bf16 v[28:31], v[144:147], v[152:155], v[28:31]
	v_mfma_f32_16x16x32_bf16 v[24:27], v[188:191], v[152:155], v[24:27]
	v_mfma_f32_16x16x32_bf16 v[20:23], v[144:147], v[160:163], v[20:23]
	v_mfma_f32_16x16x32_bf16 v[16:19], v[188:191], v[160:163], v[16:19]
	v_mfma_f32_16x16x32_bf16 v[12:15], v[144:147], v[168:171], v[12:15]
	v_mfma_f32_16x16x32_bf16 v[8:11], v[188:191], v[168:171], v[8:11]
	v_mfma_f32_16x16x32_bf16 v[4:7], v[144:147], v[176:179], v[4:7]
	v_mfma_f32_16x16x32_bf16 v[0:3], v[188:191], v[176:179], v[0:3]
	v_mfma_f32_16x16x32_bf16 v[28:31], v[184:187], v[156:159], v[28:31]
	v_mfma_f32_16x16x32_bf16 v[24:27], v[194:197], v[156:159], v[24:27]
	v_mfma_f32_16x16x32_bf16 v[20:23], v[184:187], v[164:167], v[20:23]
	v_mfma_f32_16x16x32_bf16 v[16:19], v[194:197], v[164:167], v[16:19]
	v_mfma_f32_16x16x32_bf16 v[12:15], v[184:187], v[172:175], v[12:15]
	v_mfma_f32_16x16x32_bf16 v[8:11], v[194:197], v[172:175], v[8:11]
	v_mfma_f32_16x16x32_bf16 v[4:7], v[184:187], v[180:183], v[4:7]
	v_mfma_f32_16x16x32_bf16 v[0:3], v[194:197], v[180:183], v[0:3]
	s_setprio 0
	s_barrier
	ds_read_b128 v[128:131], v138 offset:32768
	ds_read_b128 v[132:135], v138 offset:33792
	ds_read_b128 v[140:143], v138 offset:34816
	ds_read_b128 v[144:147], v138 offset:35840
	ds_read_b128 v[148:151], v137 offset:32768
	ds_read_b128 v[152:155], v137 offset:33792
	ds_read_b128 v[156:159], v137 offset:34816
	ds_read_b128 v[160:163], v137 offset:35840
	ds_read_b128 v[164:167], v137 offset:36864
	ds_read_b128 v[168:171], v137 offset:37888
	ds_read_b128 v[172:175], v137 offset:38912
	ds_read_b128 v[176:179], v137 offset:39936
	s_waitcnt vmcnt(2)
	s_barrier
; #define WAIT_V(n) asm volatile("s_waitcnt vmcnt(" #n ")" ::: "memory")
; #define WAIT_L(n) asm volatile("s_waitcnt lgkmcnt(" #n ")" ::: "memory")
; #define BAR __builtin_amdgcn_s_barrier()
; #define LDA(dst, b, h) _Pragma("unroll") for (int m = 0; m < 4; ++m) _Pragma("unroll") for (int k = 0; k < 2; ++k) \
;     dst[m][k] = *reinterpret_cast<const bf16x8*>((char*)shm + abase + (((b) * 2 + (h)) * 16384 + (m * 2 + k) * 1024))
; #define LDB(dst, b, h) _Pragma("unroll") for (int n = 0; n < 2; ++n) _Pragma("unroll") for (int k = 0; k < 2; ++k) \
;     dst[n][k] = *reinterpret_cast<const bf16x8*>((char*)shm + bbase + (((b) * 2 + (h)) * 16384 + (n * 2 + k) * 1024))
; template <bool SWAP>
; __device__ __forceinline__ void gemm_main(const u16* __restrict__ A, const u16* __restrict__ Bt, int brow, int bcol,
;                                           u16* shm, f32x4 (&acc)[2][2][4][2]) {
;     ...
;     LDA(At, 0, 1); WAIT_V(4); BAR; WAIT_L(0); MMA(1, 0, At, B0); MMA(1, 1, At, B1); BAR; }
;   { LDB(B0, 1, 0); LDA(At, 1, 0); WAIT_V(2); BAR; WAIT_L(0); MMA(0, 0, At, B0); BAR;
;     LDB(B1, 1, 1); WAIT_V(0); BAR; WAIT_L(0); MMA(0, 1, At, B1); BAR;
;     LDA(At, 1, 1); BAR; WAIT_L(0); MMA(1, 0, At, B0); MMA(1, 1, At, B1); BAR; }
;   if (wr == 0) BAR;
	s_waitcnt lgkmcnt(0)
	s_setprio 1
	s_waitcnt lgkmcnt(0)
	v_mfma_f32_16x16x32_bf16 v[124:127], v[128:131], v[148:151], v[124:127]
	v_mfma_f32_16x16x32_bf16 v[120:123], v[140:143], v[148:151], v[120:123]
	v_mfma_f32_16x16x32_bf16 v[116:119], v[128:131], v[156:159], v[116:119]
	v_mfma_f32_16x16x32_bf16 v[112:115], v[140:143], v[156:159], v[112:115]
	v_mfma_f32_16x16x32_bf16 v[108:111], v[128:131], v[164:167], v[108:111]
	v_mfma_f32_16x16x32_bf16 v[104:107], v[140:143], v[164:167], v[104:107]
	v_mfma_f32_16x16x32_bf16 v[100:103], v[128:131], v[172:175], v[100:103]
	v_mfma_f32_16x16x32_bf16 v[96:99], v[140:143], v[172:175], v[96:99]
	v_mfma_f32_16x16x32_bf16 v[124:127], v[132:135], v[152:155], v[124:127]
	v_mfma_f32_16x16x32_bf16 v[120:123], v[144:147], v[152:155], v[120:123]
	v_mfma_f32_16x16x32_bf16 v[116:119], v[132:135], v[160:163], v[116:119]
	v_mfma_f32_16x16x32_bf16 v[112:115], v[144:147], v[160:163], v[112:115]
	v_mfma_f32_16x16x32_bf16 v[108:111], v[132:135], v[168:171], v[108:111]
	v_mfma_f32_16x16x32_bf16 v[104:107], v[144:147], v[168:171], v[104:107]
	v_mfma_f32_16x16x32_bf16 v[100:103], v[132:135], v[176:179], v[100:103]
	v_mfma_f32_16x16x32_bf16 v[96:99], v[144:147], v[176:179], v[96:99]
	s_setprio 0
	s_barrier
	ds_read_b128 v[180:183], v138 offset:49152
	ds_read_b128 v[184:187], v138 offset:50176
	ds_read_b128 v[188:191], v138 offset:51200
	ds_read_b128 v[194:197], v138 offset:52224
	s_waitcnt vmcnt(0)
	s_barrier
	s_waitcnt lgkmcnt(0)
	s_setprio 1
	s_waitcnt lgkmcnt(0)
	v_mfma_f32_16x16x32_bf16 v[92:95], v[180:183], v[148:151], v[92:95]
	v_mfma_f32_16x16x32_bf16 v[88:91], v[188:191], v[148:151], v[88:91]
	v_mfma_f32_16x16x32_bf16 v[84:87], v[180:183], v[156:159], v[84:87]
	v_mfma_f32_16x16x32_bf16 v[80:83], v[188:191], v[156:159], v[80:83]
	v_mfma_f32_16x16x32_bf16 v[76:79], v[180:183], v[164:167], v[76:79]
	v_mfma_f32_16x16x32_bf16 v[72:75], v[188:191], v[164:167], v[72:75]
	v_mfma_f32_16x16x32_bf16 v[68:71], v[180:183], v[172:175], v[68:71]
	v_mfma_f32_16x16x32_bf16 v[64:67], v[188:191], v[172:175], v[64:67]
	v_mfma_f32_16x16x32_bf16 v[92:95], v[184:187], v[152:155], v[92:95]
	v_mfma_f32_16x16x32_bf16 v[88:91], v[194:197], v[152:155], v[88:91]
	v_mfma_f32_16x16x32_bf16 v[84:87], v[184:187], v[160:163], v[84:87]
	v_mfma_f32_16x16x32_bf16 v[80:83], v[194:197], v[160:163], v[80:83]
	v_mfma_f32_16x16x32_bf16 v[76:79], v[184:187], v[168:171], v[76:79]
	v_mfma_f32_16x16x32_bf16 v[72:75], v[194:197], v[168:171], v[72:75]
	v_mfma_f32_16x16x32_bf16 v[68:71], v[184:187], v[176:179], v[68:71]
	v_mfma_f32_16x16x32_bf16 v[64:67], v[194:197], v[176:179], v[64:67]
	s_setprio 0
	s_barrier
	ds_read_b128 v[148:151], v137 offset:49152
	ds_read_b128 v[152:155], v137 offset:50176
	ds_read_b128 v[156:159], v137 offset:51200
	ds_read_b128 v[160:163], v137 offset:52224
	ds_read_b128 v[164:167], v137 offset:53248
	ds_read_b128 v[168:171], v137 offset:54272
	ds_read_b128 v[172:175], v137 offset:55296
	ds_read_b128 v[176:179], v137 offset:56320
	s_barrier
	s_waitcnt lgkmcnt(0)
	s_setprio 1
	s_waitcnt lgkmcnt(0)
	v_mfma_f32_16x16x32_bf16 v[60:63], v[128:131], v[148:151], v[60:63]
	v_mfma_f32_16x16x32_bf16 v[56:59], v[140:143], v[148:151], v[56:59]
	v_mfma_f32_16x16x32_bf16 v[52:55], v[128:131], v[156:159], v[52:55]
	v_mfma_f32_16x16x32_bf16 v[48:51], v[140:143], v[156:159], v[48:51]
	v_mfma_f32_16x16x32_bf16 v[44:47], v[128:131], v[164:167], v[44:47]
	v_mfma_f32_16x16x32_bf16 v[40:43], v[140:143], v[164:167], v[40:43]
	v_mfma_f32_16x16x32_bf16 v[36:39], v[128:131], v[172:175], v[36:39]
	v_mfma_f32_16x16x32_bf16 v[32:35], v[140:143], v[172:175], v[32:35]
	v_mfma_f32_16x16x32_bf16 v[60:63], v[132:135], v[152:155], v[60:63]
	v_mfma_f32_16x16x32_bf16 v[56:59], v[144:147], v[152:155], v[56:59]
	v_mfma_f32_16x16x32_bf16 v[52:55], v[132:135], v[160:163], v[52:55]
	v_mfma_f32_16x16x32_bf16 v[48:51], v[144:147], v[160:163], v[48:51]
	v_mfma_f32_16x16x32_bf16 v[44:47], v[132:135], v[168:171], v[44:47]
	v_mfma_f32_16x16x32_bf16 v[40:43], v[144:147], v[168:171], v[40:43]
	v_mfma_f32_16x16x32_bf16 v[36:39], v[132:135], v[176:179], v[36:39]
	v_mfma_f32_16x16x32_bf16 v[32:35], v[144:147], v[176:179], v[32:35]
	s_setprio 0
	s_setprio 1
	v_mfma_f32_16x16x32_bf16 v[28:31], v[180:183], v[148:151], v[28:31]
	v_mfma_f32_16x16x32_bf16 v[24:27], v[188:191], v[148:151], v[24:27]
	v_mfma_f32_16x16x32_bf16 v[20:23], v[180:183], v[156:159], v[20:23]
	v_mfma_f32_16x16x32_bf16 v[16:19], v[188:191], v[156:159], v[16:19]
	v_mfma_f32_16x16x32_bf16 v[12:15], v[180:183], v[164:167], v[12:15]
	v_mfma_f32_16x16x32_bf16 v[8:11], v[188:191], v[164:167], v[8:11]
	v_mfma_f32_16x16x32_bf16 v[4:7], v[180:183], v[172:175], v[4:7]
	v_mfma_f32_16x16x32_bf16 v[0:3], v[188:191], v[172:175], v[0:3]
	v_mfma_f32_16x16x32_bf16 v[28:31], v[184:187], v[152:155], v[28:31]
	v_mfma_f32_16x16x32_bf16 v[24:27], v[194:197], v[152:155], v[24:27]
	v_mfma_f32_16x16x32_bf16 v[20:23], v[184:187], v[160:163], v[20:23]
	v_mfma_f32_16x16x32_bf16 v[16:19], v[194:197], v[160:163], v[16:19]
	v_mfma_f32_16x16x32_bf16 v[12:15], v[184:187], v[168:171], v[12:15]
	v_mfma_f32_16x16x32_bf16 v[8:11], v[194:197], v[168:171], v[8:11]
	v_mfma_f32_16x16x32_bf16 v[4:7], v[184:187], v[176:179], v[4:7]
	v_mfma_f32_16x16x32_bf16 v[0:3], v[194:197], v[176:179], v[0:3]
	s_setprio 0
	s_movk_i32 s0, 0x100
	v_cmp_gt_u32_e32 vcc, s0, v136
	s_barrier
	s_and_saveexec_b64 s[0:1], vcc
	s_cbranch_execz .LBB0_579
	s_barrier

; #define WAIT_V(n) asm volatile("s_waitcnt vmcnt(" #n ")" ::: "memory")
; #define WAIT_L(n) asm volatile("s_waitcnt lgkmcnt(" #n ")" ::: "memory")
; #define BAR __builtin_amdgcn_s_barrier()
; #define SCHED __builtin_amdgcn_sched_barrier(0)
; #define STAGE(P, BASE, br, kt) do { const char* _g = (const char*)((BASE) + (size_t)(br) * GK + (kt) * BK); \
;     __builtin_amdgcn_global_load_lds((const unsigned*)(_g + voff0), (unsigned*)((char*)(P) + tx * 16), 16, 0, 0); \
;     __builtin_amdgcn_global_load_lds((const unsigned*)(_g + voff1), (unsigned*)((char*)(P) + tx * 16 + 8192), 16, 0, 0); } while (0)
; #define LDA(dst, b, h) _Pragma("unroll") for (int m = 0; m < 4; ++m) _Pragma("unroll") for (int k = 0; k < 2; ++k) \
;     dst[m][k] = *reinterpret_cast<const bf16x8*>((char*)shm + abase + (((b) * 2 + (h)) * 16384 + (m * 2 + k) * 1024))
; #define LDB(dst, b, h) _Pragma("unroll") for (int n = 0; n < 2; ++n) _Pragma("unroll") for (int k = 0; k < 2; ++k) \
;     dst[n][k] = *reinterpret_cast<const bf16x8*>((char*)shm + bbase + (((b) * 2 + (h)) * 16384 + (n * 2 + k) * 1024))
; template <bool SWAP>
; __device__ __forceinline__ void gemm_main(const u16* __restrict__ A, const u16* __restrict__ Bt, int brow, int bcol,
;                                           u16* shm, f32x4 (&acc)[2][2][4][2]) {
;     ...
;     LDB(B0, 0, 0); SCHED; LDA(At, 0, 0); STAGE(SA(1, 1), A, brow + HALF, t + 1);
;     WAIT_L(8); BAR; WAIT_L(0); MMA(0, 0, At, B0); BAR; SCHED;
;     LDB(B1, 0, 1); STAGE(SB(0, 0), Bt, bcol, t + 2);
;     BAR; WAIT_L(0); MMA(0, 1, At, B1); BAR;
;     LDA(At, 0, 1); STAGE(SA(0, 0), A, brow, t + 2);
;     BAR; WAIT_L(0); MMA(1, 0, At, B0); BAR; SCHED;
;     STAGE(SB(0, 1), Bt, bcol + HALF, t + 2);
;     WAIT_V(6); BAR; MMA(1, 1, At, B1); BAR;
.LBB0_627:
	ds_read_b128 v[170:173], v139 offset:1024
	ds_read_b128 v[178:181], v139 offset:3072
	ds_read_b128 v[186:189], v139 offset:5120
	ds_read_b128 v[198:201], v139 offset:7168
	v_add_u32_e32 v192, 0, v142
	v_add_u32_e32 v148, 0xc000, v192
	v_add_u32_e32 v149, 0xe000, v192
	s_add_u32 m0, s9, 0xc000
	v_lshl_add_u64 v[232:233], s[4:5], 0, v[134:135]
	s_add_u32 vcc_lo, s4, s68
	s_addc_u32 vcc_hi, s5, s69
	global_load_lds_dwordx4 v132, vcc
	s_add_u32 m0, s9, 0xe000
	s_nop 0
	global_load_lds_dwordx4 v134, vcc
	s_waitcnt lgkmcnt(8)
	s_barrier
	s_waitcnt lgkmcnt(0)
	v_mfma_f32_16x16x32_bf16 v[124:127], v[150:153], v[166:169], v[124:127]
	v_mfma_f32_16x16x32_bf16 v[120:123], v[158:161], v[166:169], v[120:123]
	v_mfma_f32_16x16x32_bf16 v[116:119], v[150:153], v[174:177], v[116:119]
	v_mfma_f32_16x16x32_bf16 v[112:115], v[158:161], v[174:177], v[112:115]
	v_mfma_f32_16x16x32_bf16 v[108:111], v[150:153], v[182:185], v[108:111]
	v_mfma_f32_16x16x32_bf16 v[104:107], v[158:161], v[182:185], v[104:107]
	v_mfma_f32_16x16x32_bf16 v[100:103], v[150:153], v[194:197], v[100:103]
	v_mfma_f32_16x16x32_bf16 v[96:99], v[158:161], v[194:197], v[96:99]
	v_mfma_f32_16x16x32_bf16 v[124:127], v[154:157], v[170:173], v[124:127]
	v_mfma_f32_16x16x32_bf16 v[120:123], v[162:165], v[170:173], v[120:123]
	v_mfma_f32_16x16x32_bf16 v[116:119], v[154:157], v[178:181], v[116:119]
	v_mfma_f32_16x16x32_bf16 v[112:115], v[162:165], v[178:181], v[112:115]
	v_mfma_f32_16x16x32_bf16 v[108:111], v[154:157], v[186:189], v[108:111]
	v_mfma_f32_16x16x32_bf16 v[104:107], v[162:165], v[186:189], v[104:107]
	v_mfma_f32_16x16x32_bf16 v[100:103], v[154:157], v[198:201], v[100:103]
	v_mfma_f32_16x16x32_bf16 v[96:99], v[162:165], v[198:201], v[96:99]
	s_barrier
	ds_read_b128 v[202:205], v140 offset:16384
	ds_read_b128 v[206:209], v140 offset:17408
	ds_read_b128 v[224:227], v140 offset:18432
	ds_read_b128 v[228:231], v140 offset:19456
	v_lshl_add_u64 v[234:235], s[4:5], 0, v[128:129]
	s_add_u32 m0, s9, s28
	s_nop 0
	s_add_u32 vcc_lo, s4, s94
	s_addc_u32 vcc_hi, s5, s95
	global_load_lds_dwordx4 v128, vcc
	v_lshl_add_u64 v[236:237], s[4:5], 0, v[130:131]
	s_add_u32 m0, s9, s28
	s_add_u32 m0, m0, 0x2000
	s_nop 0
	global_load_lds_dwordx4 v130, vcc
	s_barrier
	s_waitcnt lgkmcnt(0)
	v_mfma_f32_16x16x32_bf16 v[92:95], v[202:205], v[166:169], v[92:95]
	v_mfma_f32_16x16x32_bf16 v[88:91], v[224:227], v[166:169], v[88:91]
	v_mfma_f32_16x16x32_bf16 v[84:87], v[202:205], v[174:177], v[84:87]
	v_mfma_f32_16x16x32_bf16 v[80:83], v[224:227], v[174:177], v[80:83]
	v_mfma_f32_16x16x32_bf16 v[76:79], v[202:205], v[182:185], v[76:79]
	v_mfma_f32_16x16x32_bf16 v[72:75], v[224:227], v[182:185], v[72:75]
	v_mfma_f32_16x16x32_bf16 v[68:71], v[202:205], v[194:197], v[68:71]
	v_mfma_f32_16x16x32_bf16 v[64:67], v[224:227], v[194:197], v[64:67]
	v_mfma_f32_16x16x32_bf16 v[92:95], v[206:209], v[170:173], v[92:95]
	ds_read_b128 v[166:169], v139 offset:16384
	v_mfma_f32_16x16x32_bf16 v[88:91], v[228:231], v[170:173], v[88:91]
	v_mfma_f32_16x16x32_bf16 v[84:87], v[206:209], v[178:181], v[84:87]
	ds_read_b128 v[174:177], v139 offset:18432
	v_mfma_f32_16x16x32_bf16 v[80:83], v[228:231], v[178:181], v[80:83]
	v_mfma_f32_16x16x32_bf16 v[76:79], v[206:209], v[186:189], v[76:79]
	ds_read_b128 v[182:185], v139 offset:20480
	v_mfma_f32_16x16x32_bf16 v[72:75], v[228:231], v[186:189], v[72:75]
	v_mfma_f32_16x16x32_bf16 v[68:71], v[206:209], v[198:201], v[68:71]
	ds_read_b128 v[194:197], v139 offset:22528
	v_mfma_f32_16x16x32_bf16 v[64:67], v[228:231], v[198:201], v[64:67]
	s_barrier
	ds_read_b128 v[170:173], v139 offset:17408
	ds_read_b128 v[178:181], v139 offset:19456
	ds_read_b128 v[186:189], v139 offset:21504
	ds_read_b128 v[198:201], v139 offset:23552
	s_add_u32 m0, s9, 0x0
	s_nop 0
	s_add_u32 vcc_lo, s4, s62
	s_addc_u32 vcc_hi, s5, s63
	global_load_lds_dwordx4 v132, vcc
	s_add_u32 m0, s9, 0x2000
	s_nop 0
	global_load_lds_dwordx4 v134, vcc
	s_waitcnt vmcnt(8)
	s_barrier
	s_waitcnt lgkmcnt(0)
	v_mfma_f32_16x16x32_bf16 v[60:63], v[150:153], v[166:169], v[60:63]
	v_mfma_f32_16x16x32_bf16 v[56:59], v[158:161], v[166:169], v[56:59]
	v_mfma_f32_16x16x32_bf16 v[52:55], v[150:153], v[174:177], v[52:55]
	v_mfma_f32_16x16x32_bf16 v[48:51], v[158:161], v[174:177], v[48:51]
	v_mfma_f32_16x16x32_bf16 v[44:47], v[150:153], v[182:185], v[44:47]
	v_mfma_f32_16x16x32_bf16 v[40:43], v[158:161], v[182:185], v[40:43]
	v_mfma_f32_16x16x32_bf16 v[36:39], v[150:153], v[194:197], v[36:39]
	v_mfma_f32_16x16x32_bf16 v[32:35], v[158:161], v[194:197], v[32:35]
	v_mfma_f32_16x16x32_bf16 v[60:63], v[154:157], v[170:173], v[60:63]
	v_mfma_f32_16x16x32_bf16 v[56:59], v[162:165], v[170:173], v[56:59]
	v_mfma_f32_16x16x32_bf16 v[52:55], v[154:157], v[178:181], v[52:55]
	v_mfma_f32_16x16x32_bf16 v[48:51], v[162:165], v[178:181], v[48:51]
	v_mfma_f32_16x16x32_bf16 v[44:47], v[154:157], v[186:189], v[44:47]
	v_mfma_f32_16x16x32_bf16 v[40:43], v[162:165], v[186:189], v[40:43]
	v_mfma_f32_16x16x32_bf16 v[36:39], v[154:157], v[198:201], v[36:39]
	v_mfma_f32_16x16x32_bf16 v[32:35], v[162:165], v[198:201], v[32:35]
	s_barrier
	ds_read_b128 v[150:153], v140 offset:32768
	ds_read_b128 v[154:157], v140 offset:33792
	ds_read_b128 v[158:161], v140 offset:34816
	ds_read_b128 v[162:165], v140 offset:35840
	s_add_u32 m0, s9, s29
	s_nop 0
	s_add_u32 vcc_lo, s4, s78
	s_addc_u32 vcc_hi, s5, s79
	global_load_lds_dwordx4 v128, vcc
	s_add_u32 m0, s9, s29
	s_add_u32 m0, m0, 0x2000
	s_nop 0
	global_load_lds_dwordx4 v130, vcc
	s_waitcnt vmcnt(6)
	s_barrier
; #define WAIT_V(n) asm volatile("s_waitcnt vmcnt(" #n ")" ::: "memory")
; #define WAIT_L(n) asm volatile("s_waitcnt lgkmcnt(" #n ")" ::: "memory")
; #define BAR __builtin_amdgcn_s_barrier()
; #define SCHED __builtin_amdgcn_sched_barrier(0)
; #define STAGE(P, BASE, br, kt) do { const char* _g = (const char*)((BASE) + (size_t)(br) * GK + (kt) * BK); \
;     __builtin_amdgcn_global_load_lds((const unsigned*)(_g + voff0), (unsigned*)((char*)(P) + tx * 16), 16, 0, 0); \
;     __builtin_amdgcn_global_load_lds((const unsigned*)(_g + voff1), (unsigned*)((char*)(P) + tx * 16 + 8192), 16, 0, 0); } while (0)
; #define LDA(dst, b, h) _Pragma("unroll") for (int m = 0; m < 4; ++m) _Pragma("unroll") for (int k = 0; k < 2; ++k) \
;     dst[m][k] = *reinterpret_cast<const bf16x8*>((char*)shm + abase + (((b) * 2 + (h)) * 16384 + (m * 2 + k) * 1024))
; #define LDB(dst, b, h) _Pragma("unroll") for (int n = 0; n < 2; ++n) _Pragma("unroll") for (int k = 0; k < 2; ++k) \
;     dst[n][k] = *reinterpret_cast<const bf16x8*>((char*)shm + bbase + (((b) * 2 + (h)) * 16384 + (n * 2 + k) * 1024))
; template <bool SWAP>
; __device__ __forceinline__ void gemm_main(const u16* __restrict__ A, const u16* __restrict__ Bt, int brow, int bcol,
;                                           u16* shm, f32x4 (&acc)[2][2][4][2]) {
;     ...
;     WAIT_V(6); BAR; MMA(1, 1, At, B1); BAR;
;     LDB(B0, 1, 0); SCHED; LDA(At, 1, 0); STAGE(SA(0, 1), A, brow + HALF, t + 2);
;     WAIT_L(8); BAR; WAIT_L(0); MMA(0, 0, At, B0); BAR; SCHED;
;     LDB(B1, 1, 1); STAGE(SB(1, 0), Bt, bcol, t + 3);
;     BAR; WAIT_L(0); MMA(0, 1, At, B1); BAR;
;     LDA(At, 1, 1); STAGE(SA(1, 0), A, brow, t + 3);
;     BAR; WAIT_L(0); MMA(1, 0, At, B0); BAR; SCHED;
	v_mfma_f32_16x16x32_bf16 v[28:31], v[202:205], v[166:169], v[28:31]
	v_mfma_f32_16x16x32_bf16 v[24:27], v[224:227], v[166:169], v[24:27]
	v_mfma_f32_16x16x32_bf16 v[20:23], v[202:205], v[174:177], v[20:23]
	v_mfma_f32_16x16x32_bf16 v[16:19], v[224:227], v[174:177], v[16:19]
	v_mfma_f32_16x16x32_bf16 v[12:15], v[202:205], v[182:185], v[12:15]
	v_mfma_f32_16x16x32_bf16 v[8:11], v[224:227], v[182:185], v[8:11]
	v_mfma_f32_16x16x32_bf16 v[4:7], v[202:205], v[194:197], v[4:7]
	v_mfma_f32_16x16x32_bf16 v[0:3], v[224:227], v[194:197], v[0:3]
	v_mfma_f32_16x16x32_bf16 v[28:31], v[206:209], v[170:173], v[28:31]
	ds_read_b128 v[166:169], v139 offset:32768
	v_mfma_f32_16x16x32_bf16 v[24:27], v[228:231], v[170:173], v[24:27]
	v_mfma_f32_16x16x32_bf16 v[20:23], v[206:209], v[178:181], v[20:23]
	ds_read_b128 v[174:177], v139 offset:34816
	v_mfma_f32_16x16x32_bf16 v[16:19], v[228:231], v[178:181], v[16:19]
	v_mfma_f32_16x16x32_bf16 v[12:15], v[206:209], v[186:189], v[12:15]
	ds_read_b128 v[182:185], v139 offset:36864
	v_mfma_f32_16x16x32_bf16 v[8:11], v[228:231], v[186:189], v[8:11]
	v_mfma_f32_16x16x32_bf16 v[4:7], v[206:209], v[198:201], v[4:7]
	ds_read_b128 v[194:197], v139 offset:38912
	v_mfma_f32_16x16x32_bf16 v[0:3], v[228:231], v[198:201], v[0:3]
	s_barrier
	ds_read_b128 v[170:173], v139 offset:33792
	ds_read_b128 v[178:181], v139 offset:35840
	ds_read_b128 v[186:189], v139 offset:37888
	ds_read_b128 v[198:201], v139 offset:39936
	s_add_u32 m0, s9, 0x4000
	s_nop 0
	s_add_u32 vcc_lo, s4, s88
	s_addc_u32 vcc_hi, s5, s89
	global_load_lds_dwordx4 v132, vcc
	s_add_u32 m0, s9, 0x6000
	s_nop 0
	global_load_lds_dwordx4 v134, vcc
	s_waitcnt lgkmcnt(8)
	s_barrier
	s_waitcnt lgkmcnt(0)
	v_mfma_f32_16x16x32_bf16 v[124:127], v[150:153], v[166:169], v[124:127]
	v_mfma_f32_16x16x32_bf16 v[120:123], v[158:161], v[166:169], v[120:123]
	v_mfma_f32_16x16x32_bf16 v[116:119], v[150:153], v[174:177], v[116:119]
	v_mfma_f32_16x16x32_bf16 v[112:115], v[158:161], v[174:177], v[112:115]
	v_mfma_f32_16x16x32_bf16 v[108:111], v[150:153], v[182:185], v[108:111]
	v_mfma_f32_16x16x32_bf16 v[104:107], v[158:161], v[182:185], v[104:107]
	v_mfma_f32_16x16x32_bf16 v[100:103], v[150:153], v[194:197], v[100:103]
	v_mfma_f32_16x16x32_bf16 v[96:99], v[158:161], v[194:197], v[96:99]
	v_mfma_f32_16x16x32_bf16 v[124:127], v[154:157], v[170:173], v[124:127]
	v_mfma_f32_16x16x32_bf16 v[120:123], v[162:165], v[170:173], v[120:123]
	v_mfma_f32_16x16x32_bf16 v[116:119], v[154:157], v[178:181], v[116:119]
	v_mfma_f32_16x16x32_bf16 v[112:115], v[162:165], v[178:181], v[112:115]
	v_mfma_f32_16x16x32_bf16 v[108:111], v[154:157], v[186:189], v[108:111]
	v_mfma_f32_16x16x32_bf16 v[104:107], v[162:165], v[186:189], v[104:107]
	v_mfma_f32_16x16x32_bf16 v[100:103], v[154:157], v[198:201], v[100:103]
	v_mfma_f32_16x16x32_bf16 v[96:99], v[162:165], v[198:201], v[96:99]
	s_barrier
	ds_read_b128 v[202:205], v140 offset:49152
	ds_read_b128 v[206:209], v140 offset:50176
	ds_read_b128 v[224:227], v140 offset:51200
	ds_read_b128 v[228:231], v140 offset:52224
	s_add_u32 m0, s9, s30
	s_nop 0
	s_add_u32 vcc_lo, s4, s52
	s_addc_u32 vcc_hi, s5, s53
	global_load_lds_dwordx4 v128, vcc
	v_lshl_add_u64 v[238:239], v[236:237], 0, s[52:53]
	s_add_u32 m0, s9, s30
	s_add_u32 m0, m0, 0x2000
	s_nop 0
	global_load_lds_dwordx4 v130, vcc
	s_barrier
	s_waitcnt lgkmcnt(0)
	v_mfma_f32_16x16x32_bf16 v[92:95], v[202:205], v[166:169], v[92:95]
	v_mfma_f32_16x16x32_bf16 v[88:91], v[224:227], v[166:169], v[88:91]
	v_mfma_f32_16x16x32_bf16 v[84:87], v[202:205], v[174:177], v[84:87]
	v_mfma_f32_16x16x32_bf16 v[80:83], v[224:227], v[174:177], v[80:83]
	v_mfma_f32_16x16x32_bf16 v[76:79], v[202:205], v[182:185], v[76:79]
	v_mfma_f32_16x16x32_bf16 v[72:75], v[224:227], v[182:185], v[72:75]
	v_mfma_f32_16x16x32_bf16 v[68:71], v[202:205], v[194:197], v[68:71]
	v_mfma_f32_16x16x32_bf16 v[64:67], v[224:227], v[194:197], v[64:67]
	v_mfma_f32_16x16x32_bf16 v[92:95], v[206:209], v[170:173], v[92:95]
	ds_read_b128 v[166:169], v139 offset:49152
	v_mfma_f32_16x16x32_bf16 v[88:91], v[228:231], v[170:173], v[88:91]
	v_mfma_f32_16x16x32_bf16 v[84:87], v[206:209], v[178:181], v[84:87]
	ds_read_b128 v[174:177], v139 offset:51200
	v_mfma_f32_16x16x32_bf16 v[80:83], v[228:231], v[178:181], v[80:83]
	v_mfma_f32_16x16x32_bf16 v[76:79], v[206:209], v[186:189], v[76:79]
	ds_read_b128 v[182:185], v139 offset:53248
	v_mfma_f32_16x16x32_bf16 v[72:75], v[228:231], v[186:189], v[72:75]
	v_mfma_f32_16x16x32_bf16 v[68:71], v[206:209], v[198:201], v[68:71]
	ds_read_b128 v[194:197], v139 offset:55296
	v_mfma_f32_16x16x32_bf16 v[64:67], v[228:231], v[198:201], v[64:67]
	s_barrier
	ds_read_b128 v[170:173], v139 offset:50176
	ds_read_b128 v[178:181], v139 offset:52224
	ds_read_b128 v[186:189], v139 offset:54272
	ds_read_b128 v[198:201], v139 offset:56320
	v_add_u32_e32 v223, 0x8000, v192
	s_add_u32 m0, s9, 0x8000
	s_nop 0
	s_add_u32 vcc_lo, s4, s44
	s_addc_u32 vcc_hi, s5, s45
	global_load_lds_dwordx4 v132, vcc
	v_lshl_add_u64 v[190:191], v[232:233], 0, s[44:45]
	s_add_u32 m0, s9, 0xa000
	s_nop 0
	global_load_lds_dwordx4 v134, vcc
	s_waitcnt vmcnt(8)
	s_barrier
; #define WAIT_V(n) asm volatile("s_waitcnt vmcnt(" #n ")" ::: "memory")
; #define WAIT_L(n) asm volatile("s_waitcnt lgkmcnt(" #n ")" ::: "memory")
; #define BAR __builtin_amdgcn_s_barrier()
; #define SCHED __builtin_amdgcn_sched_barrier(0)
; #define STAGE(P, BASE, br, kt) do { const char* _g = (const char*)((BASE) + (size_t)(br) * GK + (kt) * BK); \
;     __builtin_amdgcn_global_load_lds((const unsigned*)(_g + voff0), (unsigned*)((char*)(P) + tx * 16), 16, 0, 0); \
;     __builtin_amdgcn_global_load_lds((const unsigned*)(_g + voff1), (unsigned*)((char*)(P) + tx * 16 + 8192), 16, 0, 0); } while (0)
; #define LDA(dst, b, h) _Pragma("unroll") for (int m = 0; m < 4; ++m) _Pragma("unroll") for (int k = 0; k < 2; ++k) \
;     dst[m][k] = *reinterpret_cast<const bf16x8*>((char*)shm + abase + (((b) * 2 + (h)) * 16384 + (m * 2 + k) * 1024))
; #define LDB(dst, b, h) _Pragma("unroll") for (int n = 0; n < 2; ++n) _Pragma("unroll") for (int k = 0; k < 2; ++k) \
;     dst[n][k] = *reinterpret_cast<const bf16x8*>((char*)shm + bbase + (((b) * 2 + (h)) * 16384 + (n * 2 + k) * 1024))
; template <bool SWAP>
; __device__ __forceinline__ void gemm_main(const u16* __restrict__ A, const u16* __restrict__ Bt, int brow, int bcol,
;                                           u16* shm, f32x4 (&acc)[2][2][4][2]) {
;     ...
;     LDA(At, 1, 1); STAGE(SA(1, 0), A, brow, t + 3);
;     BAR; WAIT_L(0); MMA(1, 0, At, B0); BAR; SCHED;
;     STAGE(SB(1, 1), Bt, bcol + HALF, t + 3);
;     WAIT_V(6); BAR; MMA(1, 1, At, B1); BAR;
;   }
;   { LDB(B0, 0, 0); LDA(At, 0, 0); STAGE(SA(1, 1), A, brow + HALF, nt - 1);
;     BAR; WAIT_L(0); MMA(0, 0, At, B0); BAR;
	s_waitcnt lgkmcnt(0)
	v_mfma_f32_16x16x32_bf16 v[60:63], v[150:153], v[166:169], v[60:63]
	v_mfma_f32_16x16x32_bf16 v[56:59], v[158:161], v[166:169], v[56:59]
	v_mfma_f32_16x16x32_bf16 v[52:55], v[150:153], v[174:177], v[52:55]
	v_mfma_f32_16x16x32_bf16 v[48:51], v[158:161], v[174:177], v[48:51]
	v_mfma_f32_16x16x32_bf16 v[44:47], v[150:153], v[182:185], v[44:47]
	v_mfma_f32_16x16x32_bf16 v[40:43], v[158:161], v[182:185], v[40:43]
	v_mfma_f32_16x16x32_bf16 v[36:39], v[150:153], v[194:197], v[36:39]
	v_mfma_f32_16x16x32_bf16 v[32:35], v[158:161], v[194:197], v[32:35]
	v_mfma_f32_16x16x32_bf16 v[60:63], v[154:157], v[170:173], v[60:63]
	v_mfma_f32_16x16x32_bf16 v[56:59], v[162:165], v[170:173], v[56:59]
	v_mfma_f32_16x16x32_bf16 v[52:55], v[154:157], v[178:181], v[52:55]
	v_mfma_f32_16x16x32_bf16 v[48:51], v[162:165], v[178:181], v[48:51]
	v_mfma_f32_16x16x32_bf16 v[44:47], v[154:157], v[186:189], v[44:47]
	v_mfma_f32_16x16x32_bf16 v[40:43], v[162:165], v[186:189], v[40:43]
	v_mfma_f32_16x16x32_bf16 v[36:39], v[154:157], v[198:201], v[36:39]
	v_mfma_f32_16x16x32_bf16 v[32:35], v[162:165], v[198:201], v[32:35]
	s_barrier
	ds_read_b128 v[150:153], v140
	ds_read_b128 v[154:157], v140 offset:1024
	ds_read_b128 v[158:161], v140 offset:2048
	ds_read_b128 v[162:165], v140 offset:3072
	s_add_u32 m0, s9, s31
	s_nop 0
	s_add_u32 vcc_lo, s4, s38
	s_addc_u32 vcc_hi, s5, s39
	global_load_lds_dwordx4 v128, vcc
	v_lshl_add_u64 v[254:255], v[236:237], 0, s[38:39]
	s_add_u32 m0, s9, s31
	s_add_u32 m0, m0, 0x2000
	s_nop 0
	global_load_lds_dwordx4 v130, vcc
	s_waitcnt vmcnt(6)
	s_barrier
	v_mfma_f32_16x16x32_bf16 v[28:31], v[202:205], v[166:169], v[28:31]
	v_mfma_f32_16x16x32_bf16 v[24:27], v[224:227], v[166:169], v[24:27]
	v_mfma_f32_16x16x32_bf16 v[20:23], v[202:205], v[174:177], v[20:23]
	v_mfma_f32_16x16x32_bf16 v[16:19], v[224:227], v[174:177], v[16:19]
	v_mfma_f32_16x16x32_bf16 v[12:15], v[202:205], v[182:185], v[12:15]
	v_mfma_f32_16x16x32_bf16 v[8:11], v[224:227], v[182:185], v[8:11]
	v_mfma_f32_16x16x32_bf16 v[4:7], v[202:205], v[194:197], v[4:7]
	v_mfma_f32_16x16x32_bf16 v[0:3], v[224:227], v[194:197], v[0:3]
	v_mfma_f32_16x16x32_bf16 v[28:31], v[206:209], v[170:173], v[28:31]
	ds_read_b128 v[166:169], v139
	v_mfma_f32_16x16x32_bf16 v[24:27], v[228:231], v[170:173], v[24:27]
	v_mfma_f32_16x16x32_bf16 v[20:23], v[206:209], v[178:181], v[20:23]
	ds_read_b128 v[174:177], v139 offset:2048
	v_mfma_f32_16x16x32_bf16 v[16:19], v[228:231], v[178:181], v[16:19]
	v_mfma_f32_16x16x32_bf16 v[12:15], v[206:209], v[186:189], v[12:15]
	ds_read_b128 v[182:185], v139 offset:4096
	v_mfma_f32_16x16x32_bf16 v[8:11], v[228:231], v[186:189], v[8:11]
	v_mfma_f32_16x16x32_bf16 v[4:7], v[206:209], v[198:201], v[4:7]
	ds_read_b128 v[194:197], v139 offset:6144
	v_mfma_f32_16x16x32_bf16 v[0:3], v[228:231], v[198:201], v[0:3]
	s_add_i32 s8, s8, 2
	s_add_u32 s4, s4, 0x100
	s_addc_u32 s5, s5, 0
	s_cmp_lt_u32 s8, 28
	s_barrier
	s_cbranch_scc1 .LBB0_627
	s_and_b32 s4, s7, 0xffffe0
	s_and_b32 s5, s6, 31
	s_or_b32 s4, s4, s5
	s_lshl_b32 s10, s4, 8
	v_lshlrev_b32_e32 v128, 3, v141
	v_lshlrev_b32_e32 v129, 5, v141
	v_and_b32_e32 v128, 0xffff0, v128
	v_and_b32_e32 v129, 32, v129
	s_or_b32 s4, s10, 0x80
	v_add_u32_e32 v129, v129, v144
	v_add_lshl_u32 v128, v143, v128, 12
	s_ashr_i32 s5, s4, 31
	v_lshl_add_u32 v192, v129, 1, v128
	v_lshlrev_b32_e32 v128, 3, v145
	v_lshlrev_b32_e32 v129, 5, v145
	s_lshl_b64 s[4:5], s[4:5], 12
	v_and_b32_e32 v128, 0xffff0, v128
	v_and_b32_e32 v129, 32, v129
	s_add_u32 s4, s84, s4
	v_add_u32_e32 v129, v129, v147
	v_add_lshl_u32 v128, v146, v128, 12
	s_addc_u32 s5, s85, s5
	v_lshl_add_u32 v146, v129, 1, v128
	v_mov_b32_e32 v147, v193
	v_lshl_add_u64 v[186:187], s[4:5], 0, v[192:193]
	s_mov_b64 s[8:9], 0xf80
	v_readfirstlane_b32 s7, v148
	v_lshl_add_u64 v[186:187], v[186:187], 0, s[8:9]
	s_mov_b32 m0, s7
	v_lshl_add_u64 v[146:147], s[4:5], 0, v[146:147]
	v_readfirstlane_b32 s4, v149
	ds_read_b128 v[128:131], v140
	ds_read_b128 v[132:135], v140 offset:1024
	ds_read_b128 v[142:145], v140 offset:2048
	ds_read_b128 v[150:153], v140 offset:3072
	ds_read_b128 v[154:157], v139
	ds_read_b128 v[158:161], v139 offset:1024
	ds_read_b128 v[162:165], v139 offset:2048
	ds_read_b128 v[166:169], v139 offset:3072
	ds_read_b128 v[170:173], v139 offset:4096
	ds_read_b128 v[174:177], v139 offset:5120
	ds_read_b128 v[178:181], v139 offset:6144
	ds_read_b128 v[182:185], v139 offset:7168
	global_load_lds_dwordx4 v[186:187], off
	v_lshl_add_u64 v[146:147], v[146:147], 0, s[8:9]
	s_mov_b32 m0, s4
	s_nop 0
	global_load_lds_dwordx4 v[146:147], off
	s_barrier
	s_waitcnt lgkmcnt(0)
	s_setprio 1
	s_waitcnt lgkmcnt(0)
	v_mfma_f32_16x16x32_bf16 v[124:127], v[128:131], v[154:157], v[124:127]
	v_mfma_f32_16x16x32_bf16 v[116:119], v[128:131], v[162:165], v[116:119]
	v_mfma_f32_16x16x32_bf16 v[108:111], v[128:131], v[170:173], v[108:111]
	v_mfma_f32_16x16x32_bf16 v[100:103], v[128:131], v[178:181], v[100:103]
	v_mfma_f32_16x16x32_bf16 v[124:127], v[132:135], v[158:161], v[124:127]
	v_mfma_f32_16x16x32_bf16 v[120:123], v[142:145], v[154:157], v[120:123]
	v_mfma_f32_16x16x32_bf16 v[116:119], v[132:135], v[166:169], v[116:119]
	v_mfma_f32_16x16x32_bf16 v[112:115], v[142:145], v[162:165], v[112:115]
	v_mfma_f32_16x16x32_bf16 v[108:111], v[132:135], v[174:177], v[108:111]
	v_mfma_f32_16x16x32_bf16 v[104:107], v[142:145], v[170:173], v[104:107]
	v_mfma_f32_16x16x32_bf16 v[100:103], v[132:135], v[182:185], v[100:103]
	v_mfma_f32_16x16x32_bf16 v[96:99], v[142:145], v[178:181], v[96:99]
	v_mfma_f32_16x16x32_bf16 v[146:149], v[150:153], v[158:161], v[120:123]
	v_mfma_f32_16x16x32_bf16 v[186:189], v[150:153], v[166:169], v[112:115]
	v_mfma_f32_16x16x32_bf16 v[194:197], v[150:153], v[174:177], v[104:107]
	v_mfma_f32_16x16x32_bf16 v[198:201], v[150:153], v[182:185], v[96:99]
	s_setprio 0
	s_barrier
; #define WAIT_V(n) asm volatile("s_waitcnt vmcnt(" #n ")" ::: "memory")
; #define WAIT_L(n) asm volatile("s_waitcnt lgkmcnt(" #n ")" ::: "memory")
; #define BAR __builtin_amdgcn_s_barrier()
; #define LDA(dst, b, h) _Pragma("unroll") for (int m = 0; m < 4; ++m) _Pragma("unroll") for (int k = 0; k < 2; ++k) \
;     dst[m][k] = *reinterpret_cast<const bf16x8*>((char*)shm + abase + (((b) * 2 + (h)) * 16384 + (m * 2 + k) * 1024))
; #define LDB(dst, b, h) _Pragma("unroll") for (int n = 0; n < 2; ++n) _Pragma("unroll") for (int k = 0; k < 2; ++k) \
;     dst[n][k] = *reinterpret_cast<const bf16x8*>((char*)shm + bbase + (((b) * 2 + (h)) * 16384 + (n * 2 + k) * 1024))
; template <bool SWAP>
; __device__ __forceinline__ void gemm_main(const u16* __restrict__ A, const u16* __restrict__ Bt, int brow, int bcol,
;                                           u16* shm, f32x4 (&acc)[2][2][4][2]) {
;     ...
;     BAR; WAIT_L(0); MMA(0, 0, At, B0); BAR;
;     LDB(B1, 0, 1); BAR; WAIT_L(0); MMA(0, 1, At, B1); BAR;
;     LDA(At, 0, 1); WAIT_V(4); BAR; WAIT_L(0); MMA(1, 0, At, B0); MMA(1, 1, At, B1); BAR; }
;   { LDB(B0, 1, 0); LDA(At, 1, 0); WAIT_V(2); BAR; WAIT_L(0); MMA(0, 0, At, B0); BAR;
;     LDB(B1, 1, 1); WAIT_V(0); BAR; WAIT_L(0); MMA(0, 1, At, B1); BAR;
	s_nop 1
	ds_read_b128 v[96:99], v140 offset:16384
	ds_read_b128 v[104:107], v140 offset:17408
	ds_read_b128 v[112:115], v140 offset:18432
	ds_read_b128 v[120:123], v140 offset:19456
	s_barrier
	s_waitcnt lgkmcnt(0)
	s_setprio 1
	s_waitcnt lgkmcnt(0)
	v_mfma_f32_16x16x32_bf16 v[92:95], v[96:99], v[154:157], v[92:95]
	v_mfma_f32_16x16x32_bf16 v[84:87], v[96:99], v[162:165], v[84:87]
	v_mfma_f32_16x16x32_bf16 v[76:79], v[96:99], v[170:173], v[76:79]
	v_mfma_f32_16x16x32_bf16 v[68:71], v[96:99], v[178:181], v[68:71]
	v_mfma_f32_16x16x32_bf16 v[92:95], v[104:107], v[158:161], v[92:95]
	v_mfma_f32_16x16x32_bf16 v[88:91], v[112:115], v[154:157], v[88:91]
	v_mfma_f32_16x16x32_bf16 v[84:87], v[104:107], v[166:169], v[84:87]
	v_mfma_f32_16x16x32_bf16 v[80:83], v[112:115], v[162:165], v[80:83]
	v_mfma_f32_16x16x32_bf16 v[76:79], v[104:107], v[174:177], v[76:79]
	v_mfma_f32_16x16x32_bf16 v[72:75], v[112:115], v[170:173], v[72:75]
	v_mfma_f32_16x16x32_bf16 v[68:71], v[104:107], v[182:185], v[68:71]
	v_mfma_f32_16x16x32_bf16 v[64:67], v[112:115], v[178:181], v[64:67]
	v_mfma_f32_16x16x32_bf16 v[154:157], v[120:123], v[158:161], v[88:91]
	v_mfma_f32_16x16x32_bf16 v[158:161], v[120:123], v[166:169], v[80:83]
	v_mfma_f32_16x16x32_bf16 v[162:165], v[120:123], v[174:177], v[72:75]
	v_mfma_f32_16x16x32_bf16 v[166:169], v[120:123], v[182:185], v[64:67]
	s_setprio 0
	s_barrier
	s_nop 1
	ds_read_b128 v[64:67], v139 offset:16384
	ds_read_b128 v[72:75], v139 offset:17408
	ds_read_b128 v[80:83], v139 offset:18432
	ds_read_b128 v[88:91], v139 offset:19456
	ds_read_b128 v[170:173], v139 offset:20480
	ds_read_b128 v[174:177], v139 offset:21504
	ds_read_b128 v[178:181], v139 offset:22528
	ds_read_b128 v[182:185], v139 offset:23552
	s_waitcnt vmcnt(4)
	s_barrier
	s_waitcnt lgkmcnt(0)
	s_setprio 1
	s_waitcnt lgkmcnt(0)
	v_mfma_f32_16x16x32_bf16 v[60:63], v[128:131], v[64:67], v[60:63]
	v_mfma_f32_16x16x32_bf16 v[52:55], v[128:131], v[80:83], v[52:55]
	v_mfma_f32_16x16x32_bf16 v[44:47], v[128:131], v[170:173], v[44:47]
	v_mfma_f32_16x16x32_bf16 v[36:39], v[128:131], v[178:181], v[36:39]
	v_mfma_f32_16x16x32_bf16 v[60:63], v[132:135], v[72:75], v[60:63]
	v_mfma_f32_16x16x32_bf16 v[56:59], v[142:145], v[64:67], v[56:59]
	v_mfma_f32_16x16x32_bf16 v[52:55], v[132:135], v[88:91], v[52:55]
	v_mfma_f32_16x16x32_bf16 v[48:51], v[142:145], v[80:83], v[48:51]
	v_mfma_f32_16x16x32_bf16 v[44:47], v[132:135], v[174:177], v[44:47]
	v_mfma_f32_16x16x32_bf16 v[40:43], v[142:145], v[170:173], v[40:43]
	v_mfma_f32_16x16x32_bf16 v[36:39], v[132:135], v[182:185], v[36:39]
	v_mfma_f32_16x16x32_bf16 v[32:35], v[142:145], v[178:181], v[32:35]
	v_mfma_f32_16x16x32_bf16 v[202:205], v[150:153], v[72:75], v[56:59]
	v_mfma_f32_16x16x32_bf16 v[206:209], v[150:153], v[88:91], v[48:51]
	v_mfma_f32_16x16x32_bf16 v[224:227], v[150:153], v[174:177], v[40:43]
	v_mfma_f32_16x16x32_bf16 v[128:131], v[150:153], v[182:185], v[32:35]
	s_setprio 0
	s_setprio 1
	v_mfma_f32_16x16x32_bf16 v[28:31], v[96:99], v[64:67], v[28:31]
	v_mfma_f32_16x16x32_bf16 v[20:23], v[96:99], v[80:83], v[20:23]
	v_mfma_f32_16x16x32_bf16 v[12:15], v[96:99], v[170:173], v[12:15]
	v_mfma_f32_16x16x32_bf16 v[4:7], v[96:99], v[178:181], v[4:7]
	v_mfma_f32_16x16x32_bf16 v[28:31], v[104:107], v[72:75], v[28:31]
	v_mfma_f32_16x16x32_bf16 v[24:27], v[112:115], v[64:67], v[24:27]
	v_mfma_f32_16x16x32_bf16 v[20:23], v[104:107], v[88:91], v[20:23]
	v_mfma_f32_16x16x32_bf16 v[16:19], v[112:115], v[80:83], v[16:19]
	v_mfma_f32_16x16x32_bf16 v[12:15], v[104:107], v[174:177], v[12:15]
	v_mfma_f32_16x16x32_bf16 v[8:11], v[112:115], v[170:173], v[8:11]
	v_mfma_f32_16x16x32_bf16 v[4:7], v[104:107], v[182:185], v[4:7]
	v_mfma_f32_16x16x32_bf16 v[0:3], v[112:115], v[178:181], v[0:3]
	v_mfma_f32_16x16x32_bf16 v[132:135], v[120:123], v[72:75], v[24:27]
	v_mfma_f32_16x16x32_bf16 v[142:145], v[120:123], v[88:91], v[16:19]
	v_mfma_f32_16x16x32_bf16 v[150:153], v[120:123], v[174:177], v[8:11]
	v_mfma_f32_16x16x32_bf16 v[170:173], v[120:123], v[182:185], v[0:3]
	s_setprio 0
	s_barrier
	s_nop 1
	ds_read_b128 v[0:3], v140 offset:32768
	ds_read_b128 v[8:11], v140 offset:33792
	ds_read_b128 v[16:19], v140 offset:34816
	ds_read_b128 v[24:27], v140 offset:35840
	ds_read_b128 v[32:35], v139 offset:32768
	ds_read_b128 v[40:43], v139 offset:33792
	ds_read_b128 v[48:51], v139 offset:34816
	ds_read_b128 v[56:59], v139 offset:35840
	ds_read_b128 v[64:67], v139 offset:36864
	ds_read_b128 v[174:177], v139 offset:37888
	ds_read_b128 v[178:181], v139 offset:38912
	ds_read_b128 v[182:185], v139 offset:39936
	s_waitcnt vmcnt(2)
	s_barrier
; #define WAIT_V(n) asm volatile("s_waitcnt vmcnt(" #n ")" ::: "memory")
; #define WAIT_L(n) asm volatile("s_waitcnt lgkmcnt(" #n ")" ::: "memory")
; #define BAR __builtin_amdgcn_s_barrier()
; #define LDA(dst, b, h) _Pragma("unroll") for (int m = 0; m < 4; ++m) _Pragma("unroll") for (int k = 0; k < 2; ++k) \
;     dst[m][k] = *reinterpret_cast<const bf16x8*>((char*)shm + abase + (((b) * 2 + (h)) * 16384 + (m * 2 + k) * 1024))
; #define LDB(dst, b, h) _Pragma("unroll") for (int n = 0; n < 2; ++n) _Pragma("unroll") for (int k = 0; k < 2; ++k) \
;     dst[n][k] = *reinterpret_cast<const bf16x8*>((char*)shm + bbase + (((b) * 2 + (h)) * 16384 + (n * 2 + k) * 1024))
; template <bool SWAP>
; __device__ __forceinline__ void gemm_main(const u16* __restrict__ A, const u16* __restrict__ Bt, int brow, int bcol,
;                                           u16* shm, f32x4 (&acc)[2][2][4][2]) {
;     ...
;     LDA(At, 0, 1); WAIT_V(4); BAR; WAIT_L(0); MMA(1, 0, At, B0); MMA(1, 1, At, B1); BAR; }
;   { LDB(B0, 1, 0); LDA(At, 1, 0); WAIT_V(2); BAR; WAIT_L(0); MMA(0, 0, At, B0); BAR;
;     LDB(B1, 1, 1); WAIT_V(0); BAR; WAIT_L(0); MMA(0, 1, At, B1); BAR;
;     LDA(At, 1, 1); BAR; WAIT_L(0); MMA(1, 0, At, B0); MMA(1, 1, At, B1); BAR; }
;   if (wr == 0) BAR;
	s_waitcnt lgkmcnt(0)
	s_setprio 1
	s_waitcnt lgkmcnt(0)
	v_mfma_f32_16x16x32_bf16 v[72:75], v[0:3], v[32:35], v[124:127]
	v_mfma_f32_16x16x32_bf16 v[120:123], v[8:11], v[40:43], v[72:75]
	v_mfma_f32_16x16x32_bf16 v[72:75], v[16:19], v[32:35], v[146:149]
	v_mfma_f32_16x16x32_bf16 v[124:127], v[24:27], v[40:43], v[72:75]
	v_mfma_f32_16x16x32_bf16 v[72:75], v[0:3], v[48:51], v[116:119]
	v_mfma_f32_16x16x32_bf16 v[112:115], v[8:11], v[56:59], v[72:75]
	v_mfma_f32_16x16x32_bf16 v[72:75], v[16:19], v[48:51], v[186:189]
	v_mfma_f32_16x16x32_bf16 v[116:119], v[24:27], v[56:59], v[72:75]
	v_mfma_f32_16x16x32_bf16 v[72:75], v[0:3], v[64:67], v[108:111]
	v_mfma_f32_16x16x32_bf16 v[104:107], v[8:11], v[174:177], v[72:75]
	v_mfma_f32_16x16x32_bf16 v[72:75], v[16:19], v[64:67], v[194:197]
	v_mfma_f32_16x16x32_bf16 v[108:111], v[24:27], v[174:177], v[72:75]
	v_mfma_f32_16x16x32_bf16 v[72:75], v[0:3], v[178:181], v[100:103]
	v_mfma_f32_16x16x32_bf16 v[96:99], v[8:11], v[182:185], v[72:75]
	v_mfma_f32_16x16x32_bf16 v[72:75], v[16:19], v[178:181], v[198:201]
	v_mfma_f32_16x16x32_bf16 v[100:103], v[24:27], v[182:185], v[72:75]
	s_setprio 0
	s_barrier
	ds_read_b128 v[146:149], v140 offset:49152
	ds_read_b128 v[186:189], v140 offset:50176
	ds_read_b128 v[194:197], v140 offset:51200
	ds_read_b128 v[198:201], v140 offset:52224
	s_waitcnt vmcnt(0)
	s_barrier
	s_waitcnt lgkmcnt(0)
	s_setprio 1
	s_waitcnt lgkmcnt(0)
	v_mfma_f32_16x16x32_bf16 v[72:75], v[146:149], v[32:35], v[92:95]
	v_mfma_f32_16x16x32_bf16 v[32:35], v[194:197], v[32:35], v[154:157]
	v_mfma_f32_16x16x32_bf16 v[92:95], v[198:201], v[40:43], v[32:35]
	v_mfma_f32_16x16x32_bf16 v[32:35], v[146:149], v[48:51], v[84:87]
	v_mfma_f32_16x16x32_bf16 v[80:83], v[186:189], v[56:59], v[32:35]
	v_mfma_f32_16x16x32_bf16 v[32:35], v[194:197], v[48:51], v[158:161]
	v_mfma_f32_16x16x32_bf16 v[84:87], v[198:201], v[56:59], v[32:35]
	v_mfma_f32_16x16x32_bf16 v[32:35], v[146:149], v[64:67], v[76:79]
	v_mfma_f32_16x16x32_bf16 v[88:91], v[186:189], v[40:43], v[72:75]
	v_mfma_f32_16x16x32_bf16 v[72:75], v[186:189], v[174:177], v[32:35]
	v_mfma_f32_16x16x32_bf16 v[32:35], v[194:197], v[64:67], v[162:165]
	v_mfma_f32_16x16x32_bf16 v[76:79], v[198:201], v[174:177], v[32:35]
	v_mfma_f32_16x16x32_bf16 v[32:35], v[146:149], v[178:181], v[68:71]
	v_mfma_f32_16x16x32_bf16 v[64:67], v[186:189], v[182:185], v[32:35]
	v_mfma_f32_16x16x32_bf16 v[32:35], v[194:197], v[178:181], v[166:169]
	v_mfma_f32_16x16x32_bf16 v[68:71], v[198:201], v[182:185], v[32:35]
	s_setprio 0
	s_barrier
	ds_read_b128 v[154:157], v139 offset:49152
	ds_read_b128 v[158:161], v139 offset:50176
	ds_read_b128 v[162:165], v139 offset:51200
	ds_read_b128 v[166:169], v139 offset:52224
	ds_read_b128 v[174:177], v139 offset:53248
	ds_read_b128 v[178:181], v139 offset:54272
	ds_read_b128 v[182:185], v139 offset:55296
	ds_read_b128 v[228:231], v139 offset:56320
	s_barrier
	s_waitcnt lgkmcnt(0)
	s_setprio 1
	s_waitcnt lgkmcnt(0)
	v_mfma_f32_16x16x32_bf16 v[32:35], v[0:3], v[154:157], v[60:63]
	v_mfma_f32_16x16x32_bf16 v[56:59], v[8:11], v[158:161], v[32:35]
	v_mfma_f32_16x16x32_bf16 v[32:35], v[16:19], v[154:157], v[202:205]
	v_mfma_f32_16x16x32_bf16 v[60:63], v[24:27], v[158:161], v[32:35]
	v_mfma_f32_16x16x32_bf16 v[32:35], v[0:3], v[162:165], v[52:55]
	v_mfma_f32_16x16x32_bf16 v[48:51], v[8:11], v[166:169], v[32:35]
	v_mfma_f32_16x16x32_bf16 v[32:35], v[16:19], v[162:165], v[206:209]
	v_mfma_f32_16x16x32_bf16 v[52:55], v[24:27], v[166:169], v[32:35]
	v_mfma_f32_16x16x32_bf16 v[32:35], v[0:3], v[174:177], v[44:47]
	v_mfma_f32_16x16x32_bf16 v[40:43], v[8:11], v[178:181], v[32:35]
	v_mfma_f32_16x16x32_bf16 v[32:35], v[16:19], v[174:177], v[224:227]
	v_mfma_f32_16x16x32_bf16 v[0:3], v[0:3], v[182:185], v[36:39]
	v_mfma_f32_16x16x32_bf16 v[44:47], v[24:27], v[178:181], v[32:35]
	v_mfma_f32_16x16x32_bf16 v[32:35], v[8:11], v[228:231], v[0:3]
	v_mfma_f32_16x16x32_bf16 v[0:3], v[16:19], v[182:185], v[128:131]
	v_mfma_f32_16x16x32_bf16 v[36:39], v[24:27], v[228:231], v[0:3]
	s_setprio 0
	s_setprio 1
	v_mfma_f32_16x16x32_bf16 v[0:3], v[146:149], v[154:157], v[28:31]
	v_mfma_f32_16x16x32_bf16 v[24:27], v[186:189], v[158:161], v[0:3]
	v_mfma_f32_16x16x32_bf16 v[0:3], v[194:197], v[154:157], v[132:135]
	v_mfma_f32_16x16x32_bf16 v[28:31], v[198:201], v[158:161], v[0:3]
	v_mfma_f32_16x16x32_bf16 v[0:3], v[146:149], v[162:165], v[20:23]
	v_mfma_f32_16x16x32_bf16 v[16:19], v[186:189], v[166:169], v[0:3]
	v_mfma_f32_16x16x32_bf16 v[0:3], v[194:197], v[162:165], v[142:145]
	v_mfma_f32_16x16x32_bf16 v[20:23], v[198:201], v[166:169], v[0:3]
	v_mfma_f32_16x16x32_bf16 v[0:3], v[146:149], v[174:177], v[12:15]
	v_mfma_f32_16x16x32_bf16 v[8:11], v[186:189], v[178:181], v[0:3]
	v_mfma_f32_16x16x32_bf16 v[0:3], v[194:197], v[174:177], v[150:153]
	v_mfma_f32_16x16x32_bf16 v[12:15], v[198:201], v[178:181], v[0:3]
	v_mfma_f32_16x16x32_bf16 v[0:3], v[146:149], v[182:185], v[4:7]
	v_mfma_f32_16x16x32_bf16 v[4:7], v[194:197], v[182:185], v[170:173]
	v_mfma_f32_16x16x32_bf16 v[0:3], v[186:189], v[228:231], v[0:3]
	v_mfma_f32_16x16x32_bf16 v[4:7], v[198:201], v[228:231], v[4:7]
	s_setprio 0
	s_movk_i32 s4, 0x100
	v_cmp_gt_u32_e32 vcc, s4, v138
	s_barrier
	s_and_saveexec_b64 s[4:5], vcc
	s_cbranch_execz .LBB0_630
	s_barrier
